# all 7 GEMM K-loops rescheduled from 8 phases (16 MFMA per barrier interval) to 4 phases (32 MFMA per interval), LDS reads completed before the pre-MMA barrier, vmcnt(8) per slot
# speedup vs baseline: 1.0297x; 1.0223x over previous
; #define STAGE_A(P, br, kt) do { const char* _g = (const char*)(A + (long)(br) * lda + (long)(kt) * BK); \
;     __builtin_amdgcn_global_load_lds((const unsigned*)(_g + (size_t)offA0), (unsigned*)((char*)(P) + sb0), 16, 0, 0); \
;     __builtin_amdgcn_global_load_lds((const unsigned*)(_g + (size_t)lda * 128 + (size_t)offA0), (unsigned*)((char*)(P) + sb1), 16, 0, 0); } while (0)
; #define STAGE_B(P, br, kt) do { const char* _g = (const char*)(B + (long)(br) * ldb + (long)(kt) * BK); \
;     __builtin_amdgcn_global_load_lds((const unsigned*)(_g + (size_t)offB0), (unsigned*)((char*)(P) + sb0), 16, 0, 0); \
;     __builtin_amdgcn_global_load_lds((const unsigned*)(_g + (size_t)ldb * 128 + (size_t)offB0), (unsigned*)((char*)(P) + sb1), 16, 0, 0); } while (0)
; #define LDA(dst, b, h) for (int m = 0; m < 4; ++m) for (int k = 0; k < 2; ++k) \
;     dst[m][k] = *reinterpret_cast<const bf16x8*>((char*)SA(b, h) + lds_byte(wr * 64 + m * 16 + fr, k * 32 + fq * 8))
; #define LDB(dst, b, h) for (int n = 0; n < 2; ++n) for (int k = 0; k < 2; ++k) \
;     dst[n][k] = *reinterpret_cast<const bf16x8*>((char*)SB(b, h) + lds_byte(wc * 32 + n * 16 + fr, k * 32 + fq * 8))
; #define WAIT_V(n) asm volatile("s_waitcnt vmcnt(" #n ")" ::: "memory")
; #define WAIT_L(n) asm volatile("s_waitcnt lgkmcnt(" #n ")" ::: "memory")
; DI void gemm_core(WVP char* smem, const u16* __restrict__ A, int lda, int ar0, int ar1,
;                   const u16* __restrict__ B, int ldb, int bc0, int K, AccT& acc) {
;     ...
;   __syncthreads();
;   STAGE_B(SB(0, 0), bb0, 0); STAGE_A(SA(0, 0), ac0, 0);
;   STAGE_B(SB(0, 1), bb1, 0); STAGE_A(SA(0, 1), ac1, 0);
;   if (wr == 1) BAR;
;   WAIT_V(4); BAR;
;   STAGE_B(SB(1, 0), bb0, 1); STAGE_A(SA(1, 0), ac0, 1); STAGE_B(SB(1, 1), bb1, 1);
;   WAIT_V(6); BAR;
;   for (int t = 0; t < nt - 2; t += 2) {
;     LDB(B0, 0, 0); SCHED; LDA(At, 0, 0); STAGE_A(SA(1, 1), ac1, t + 1);
;     WAIT_L(8); BAR; WAIT_L(0); MMA(0, 0, At, B0); BAR; SCHED;
;     LDB(B1, 0, 1); STAGE_B(SB(0, 0), bb0, t + 2);
;     BAR; WAIT_L(0); MMA(0, 1, At, B1); BAR;
;     LDA(At, 0, 1); STAGE_A(SA(0, 0), ac0, t + 2);
;     BAR; WAIT_L(0); MMA(1, 0, At, B0); BAR; SCHED;
;     STAGE_B(SB(0, 1), bb1, t + 2);
;     WAIT_V(6); BAR; MMA(1, 1, At, B1); BAR;
;     LDB(B0, 1, 0); SCHED; LDA(At, 1, 0); STAGE_A(SA(0, 1), ac1, t + 2);
;     WAIT_L(8); BAR; WAIT_L(0); MMA(0, 0, At, B0); BAR; SCHED;
.LBB0_93:
	v_add_u32_e32 v141, s61, v11
	s_ashr_i32 s18, s1, 6
	v_readfirstlane_b32 s1, v141
	v_add_u32_e32 v142, 0x2000, v141
	v_lshl_add_u64 v[12:13], v[2:3], 0, s[64:65]
	s_mov_b32 m0, s1
	s_mov_b64 s[20:21], 0x58080
	v_readfirstlane_b32 s1, v142
	v_add_u32_e32 v143, 0x8000, v135
	s_waitcnt vmcnt(2)
	s_barrier
	global_load_lds_dwordx4 v[12:13], off
	v_lshl_add_u64 v[12:13], v[2:3], 0, s[20:21]
	s_mov_b32 m0, s1
	v_readfirstlane_b32 s1, v143
	v_add_u32_e32 v144, 0xa000, v135
	global_load_lds_dwordx4 v[12:13], off
	v_lshl_add_u64 v[12:13], v[4:5], 0, s[64:65]
	s_mov_b32 m0, s1
	v_readfirstlane_b32 s1, v144
	v_add_u32_e32 v145, s84, v11
	global_load_lds_dwordx4 v[12:13], off
	v_lshl_add_u64 v[4:5], v[4:5], 0, s[20:21]
	s_mov_b32 m0, s1
	s_mov_b64 s[20:21], 0xb0080
	v_readfirstlane_b32 s1, v145
	v_add_u32_e32 v147, 0x2000, v145
	global_load_lds_dwordx4 v[4:5], off
	v_lshl_add_u64 v[4:5], v[2:3], 0, s[20:21]
	s_mov_b32 m0, s1
	s_mov_b64 s[20:21], 0x108080
	v_readfirstlane_b32 s1, v147
	global_load_lds_dwordx4 v[4:5], off
	v_lshl_add_u64 v[2:3], v[2:3], 0, s[20:21]
	s_mov_b32 m0, s1
	v_and_b32_e32 v0, 15, v6
	global_load_lds_dwordx4 v[2:3], off
	v_lshlrev_b32_e32 v2, 2, v6
	v_and_b32_e32 v14, 48, v6
	v_lshlrev_b32_e32 v0, 6, v0
	v_and_b32_e32 v2, 32, v2
	v_bitop3_b32 v0, v0, v2, v14 bitop3:0x36
	v_add_u32_e32 v4, s19, v0
	v_add_u32_e32 v5, s60, v0
	v_add_u32_e32 v11, s61, v0
	v_add_u32_e32 v12, s84, v0
	v_add_u32_e32 v13, 0, v0
	v_lshlrev_b32_e32 v0, 6, v6
	v_and_or_b32 v0, v0, s74, v14
	s_movk_i32 s20, 0xb00
	s_lshl_b32 s1, s18, 12
	s_lshl_b32 s23, s0, 13
	v_xad_u32 v148, v0, v2, 0
	v_lshrrev_b32_e32 v2, 1, v7
	v_mul_lo_u32 v0, v9, s20
	s_mov_b32 s20, 0xb000
	s_waitcnt vmcnt(6)
	s_and_b32 s22, s1, 0x3000
	s_or_b32 s0, s23, 0x800
	s_or_b32 s1, s23, 0x1000
	s_or_b32 s19, s23, 0x1800
	v_mad_u64_u32 v[2:3], s[20:21], v2, s20, v[0:1]
	v_or_b32_e32 v0, v2, v8
	s_add_u32 s16, s54, s16
	v_mov_b32_e32 v2, 0
	v_add_lshl_u32 v0, v0, v10, 1
	s_addc_u32 s17, s55, s17
	s_mov_b32 s20, -2
	v_add_u32_e32 v149, s22, v4
	v_add_u32_e32 v132, s23, v13
	v_add_u32_e32 v146, s22, v5
	v_add_u32_e32 v137, s22, v11
	v_add_u32_e32 v133, s22, v12
	v_mov_b32_e32 v3, v2
	v_mov_b32_e32 v4, v2
	v_mov_b32_e32 v5, v2
	v_mov_b32_e32 v6, v2
	v_mov_b32_e32 v7, v2
	v_mov_b32_e32 v8, v2
	v_mov_b32_e32 v9, v2
	v_mov_b32_e32 v10, v2
	v_mov_b32_e32 v11, v2
	v_mov_b32_e32 v12, v2
	v_mov_b32_e32 v13, v2
	v_mov_b32_e32 v14, v2
	v_mov_b32_e32 v15, v2
	s_barrier
.LBB0_94:
	v_add_u32_e32 v150, s0, v148
	v_add_u32_e32 v151, s1, v148
	v_add_u32_e32 v152, s19, v148
	ds_read_b128 v[156:159], v149
	ds_read_b128 v[160:163], v149 offset:1024
	ds_read_b128 v[164:167], v149 offset:2048
	ds_read_b128 v[168:171], v149 offset:3072
	ds_read_b128 v[172:175], v132
	ds_read_b128 v[176:179], v132 offset:1024
	ds_read_b128 v[180:183], v150
	ds_read_b128 v[184:187], v150 offset:1024
	ds_read_b128 v[188:191], v151
	ds_read_b128 v[192:195], v151 offset:1024
	ds_read_b128 v[196:199], v152
	ds_read_b128 v[200:203], v152 offset:1024
	ds_read_b128 v[206:209], v146
	ds_read_b128 v[210:213], v146 offset:1024
	ds_read_b128 v[214:217], v146 offset:2048
	ds_read_b128 v[218:221], v146 offset:3072
	v_add_u32_e32 v153, 0xc000, v135
	v_lshl_add_u64 v[224:225], s[16:17], 0, v[0:1]
	s_mov_b64 s[22:23], 0x1f430080
	v_lshl_add_u64 v[222:223], v[224:225], 0, s[22:23]
	v_readfirstlane_b32 s21, v153
	s_mov_b32 m0, s21
	s_nop 0
	global_load_lds_dwordx4 v[222:223], off
	v_add_u32_e32 v154, 0xe000, v135
	v_lshl_add_u64 v[224:225], s[16:17], 0, v[0:1]
	s_mov_b64 s[22:23], 0x1f488080
	v_lshl_add_u64 v[222:223], v[224:225], 0, s[22:23]
	v_readfirstlane_b32 s21, v154
	s_mov_b32 m0, s21
	s_nop 0
	global_load_lds_dwordx4 v[222:223], off
	s_waitcnt vmcnt(8)
	s_waitcnt lgkmcnt(0)
	s_barrier
	s_setprio 1
	v_mfma_f32_16x16x32_bf16 v[126:129], v[172:175], v[156:159], v[126:129]
	v_mfma_f32_16x16x32_bf16 v[122:125], v[172:175], v[164:167], v[122:125]
	v_mfma_f32_16x16x32_bf16 v[118:121], v[180:183], v[156:159], v[118:121]
	v_mfma_f32_16x16x32_bf16 v[114:117], v[180:183], v[164:167], v[114:117]
	v_mfma_f32_16x16x32_bf16 v[110:113], v[188:191], v[156:159], v[110:113]
	v_mfma_f32_16x16x32_bf16 v[106:109], v[188:191], v[164:167], v[106:109]
	v_mfma_f32_16x16x32_bf16 v[102:105], v[196:199], v[156:159], v[102:105]
	v_mfma_f32_16x16x32_bf16 v[98:101], v[196:199], v[164:167], v[98:101]
	v_mfma_f32_16x16x32_bf16 v[126:129], v[176:179], v[160:163], v[126:129]
	v_mfma_f32_16x16x32_bf16 v[122:125], v[176:179], v[168:171], v[122:125]
	v_mfma_f32_16x16x32_bf16 v[118:121], v[184:187], v[160:163], v[118:121]
	v_mfma_f32_16x16x32_bf16 v[114:117], v[184:187], v[168:171], v[114:117]
	v_mfma_f32_16x16x32_bf16 v[110:113], v[192:195], v[160:163], v[110:113]
	v_mfma_f32_16x16x32_bf16 v[106:109], v[192:195], v[168:171], v[106:109]
	v_mfma_f32_16x16x32_bf16 v[102:105], v[200:203], v[160:163], v[102:105]
	v_mfma_f32_16x16x32_bf16 v[98:101], v[200:203], v[168:171], v[98:101]
	v_mfma_f32_16x16x32_bf16 v[94:97], v[172:175], v[206:209], v[94:97]
	v_mfma_f32_16x16x32_bf16 v[90:93], v[172:175], v[214:217], v[90:93]
	v_mfma_f32_16x16x32_bf16 v[86:89], v[180:183], v[206:209], v[86:89]
	v_mfma_f32_16x16x32_bf16 v[82:85], v[180:183], v[214:217], v[82:85]
	v_mfma_f32_16x16x32_bf16 v[78:81], v[188:191], v[206:209], v[78:81]
	v_mfma_f32_16x16x32_bf16 v[74:77], v[188:191], v[214:217], v[74:77]
	v_mfma_f32_16x16x32_bf16 v[70:73], v[196:199], v[206:209], v[70:73]
	v_mfma_f32_16x16x32_bf16 v[66:69], v[196:199], v[214:217], v[66:69]
	v_mfma_f32_16x16x32_bf16 v[94:97], v[176:179], v[210:213], v[94:97]
	v_mfma_f32_16x16x32_bf16 v[90:93], v[176:179], v[218:221], v[90:93]
	v_mfma_f32_16x16x32_bf16 v[86:89], v[184:187], v[210:213], v[86:89]
	v_mfma_f32_16x16x32_bf16 v[82:85], v[184:187], v[218:221], v[82:85]
	v_mfma_f32_16x16x32_bf16 v[78:81], v[192:195], v[210:213], v[78:81]
	v_mfma_f32_16x16x32_bf16 v[74:77], v[192:195], v[218:221], v[74:77]
	v_mfma_f32_16x16x32_bf16 v[70:73], v[200:203], v[210:213], v[70:73]
	v_mfma_f32_16x16x32_bf16 v[66:69], v[200:203], v[218:221], v[66:69]
	s_setprio 0
	s_barrier
; #define STAGE_A(P, br, kt) do { const char* _g = (const char*)(A + (long)(br) * lda + (long)(kt) * BK); \
;     __builtin_amdgcn_global_load_lds((const unsigned*)(_g + (size_t)offA0), (unsigned*)((char*)(P) + sb0), 16, 0, 0); \
;     __builtin_amdgcn_global_load_lds((const unsigned*)(_g + (size_t)lda * 128 + (size_t)offA0), (unsigned*)((char*)(P) + sb1), 16, 0, 0); } while (0)
; #define STAGE_B(P, br, kt) do { const char* _g = (const char*)(B + (long)(br) * ldb + (long)(kt) * BK); \
;     __builtin_amdgcn_global_load_lds((const unsigned*)(_g + (size_t)offB0), (unsigned*)((char*)(P) + sb0), 16, 0, 0); \
;     __builtin_amdgcn_global_load_lds((const unsigned*)(_g + (size_t)ldb * 128 + (size_t)offB0), (unsigned*)((char*)(P) + sb1), 16, 0, 0); } while (0)
; #define LDA(dst, b, h) for (int m = 0; m < 4; ++m) for (int k = 0; k < 2; ++k) \
;     dst[m][k] = *reinterpret_cast<const bf16x8*>((char*)SA(b, h) + lds_byte(wr * 64 + m * 16 + fr, k * 32 + fq * 8))
; #define LDB(dst, b, h) for (int n = 0; n < 2; ++n) for (int k = 0; k < 2; ++k) \
;     dst[n][k] = *reinterpret_cast<const bf16x8*>((char*)SB(b, h) + lds_byte(wc * 32 + n * 16 + fr, k * 32 + fq * 8))
; #define MMA(ai, bj, At_, Bt_) do { __builtin_amdgcn_s_setprio(1); \
;     for (int m = 0; m < 4; ++m) for (int n = 0; n < 2; ++n) for (int k = 0; k < 2; ++k) \
;       acc[ai][bj][m][n] = MFMA16(At_[m][k], Bt_[n][k], acc[ai][bj][m][n]); \
;     __builtin_amdgcn_s_setprio(0); } while (0)
; #define WAIT_V(n) asm volatile("s_waitcnt vmcnt(" #n ")" ::: "memory")
; #define WAIT_L(n) asm volatile("s_waitcnt lgkmcnt(" #n ")" ::: "memory")
; #define BAR __builtin_amdgcn_s_barrier()
; #define SCHED __builtin_amdgcn_sched_barrier(0)
; DI void gemm_core(WVP char* smem, const u16* __restrict__ A, int lda, int ar0, int ar1,
;                   const u16* __restrict__ B, int ldb, int bc0, int K, AccT& acc) {
;     ...
;     LDA(At, 0, 1); STAGE_A(SA(0, 0), ac0, t + 2);
;     BAR; WAIT_L(0); MMA(1, 0, At, B0); BAR; SCHED;
;     STAGE_B(SB(0, 1), bb1, t + 2);
;     WAIT_V(6); BAR; MMA(1, 1, At, B1); BAR;
;     LDB(B0, 1, 0); SCHED; LDA(At, 1, 0); STAGE_A(SA(0, 1), ac1, t + 2);
;     WAIT_L(8); BAR; WAIT_L(0); MMA(0, 0, At, B0); BAR; SCHED;
;     LDB(B1, 1, 1); STAGE_B(SB(1, 0), bb0, t + 3);
;     BAR; WAIT_L(0); MMA(0, 1, At, B1); BAR;
	ds_read_b128 v[172:175], v132 offset:16384
	ds_read_b128 v[176:179], v132 offset:17408
	ds_read_b128 v[180:183], v150 offset:16384
	ds_read_b128 v[184:187], v150 offset:17408
	ds_read_b128 v[188:191], v151 offset:16384
	ds_read_b128 v[192:195], v151 offset:17408
	ds_read_b128 v[196:199], v152 offset:16384
	ds_read_b128 v[200:203], v152 offset:17408
	v_lshl_add_u64 v[224:225], s[8:9], 0, v[0:1]
	v_lshl_add_u64 v[222:223], v[224:225], 0, s[68:69]
	v_readfirstlane_b32 s21, v134
	s_mov_b32 m0, s21
	s_nop 0
	global_load_lds_dwordx4 v[222:223], off
	v_add_u32_e32 v155, 0x2000, v134
	v_lshl_add_u64 v[224:225], s[8:9], 0, v[0:1]
	s_mov_b64 s[22:23], 0x58100
	v_lshl_add_u64 v[222:223], v[224:225], 0, s[22:23]
	v_readfirstlane_b32 s21, v155
	s_mov_b32 m0, s21
	s_nop 0
	global_load_lds_dwordx4 v[222:223], off
	v_lshl_add_u64 v[224:225], s[16:17], 0, v[0:1]
	s_mov_b64 s[22:23], 0x1f380100
	v_lshl_add_u64 v[222:223], v[224:225], 0, s[22:23]
	v_readfirstlane_b32 s21, v135
	s_mov_b32 m0, s21
	s_nop 0
	global_load_lds_dwordx4 v[222:223], off
	v_lshl_add_u64 v[224:225], s[16:17], 0, v[0:1]
	s_mov_b64 s[22:23], 0x1f3d8100
	v_lshl_add_u64 v[222:223], v[224:225], 0, s[22:23]
	v_readfirstlane_b32 s21, v136
	s_mov_b32 m0, s21
	s_nop 0
	global_load_lds_dwordx4 v[222:223], off
	v_lshl_add_u64 v[224:225], s[8:9], 0, v[0:1]
	s_mov_b64 s[22:23], 0xb0100
	v_lshl_add_u64 v[222:223], v[224:225], 0, s[22:23]
	v_readfirstlane_b32 s21, v138
	s_mov_b32 m0, s21
	s_nop 0
	global_load_lds_dwordx4 v[222:223], off
	v_add_u32_e32 v155, 0x2000, v138
	v_lshl_add_u64 v[224:225], s[8:9], 0, v[0:1]
	s_mov_b64 s[22:23], 0x108100
	v_lshl_add_u64 v[222:223], v[224:225], 0, s[22:23]
	v_readfirstlane_b32 s21, v155
	s_mov_b32 m0, s21
	s_nop 0
	global_load_lds_dwordx4 v[222:223], off
	s_waitcnt vmcnt(8)
	s_waitcnt lgkmcnt(0)
	s_barrier
	s_setprio 1
	v_mfma_f32_16x16x32_bf16 v[62:65], v[172:175], v[156:159], v[62:65]
	v_mfma_f32_16x16x32_bf16 v[58:61], v[172:175], v[164:167], v[58:61]
	v_mfma_f32_16x16x32_bf16 v[54:57], v[180:183], v[156:159], v[54:57]
	v_mfma_f32_16x16x32_bf16 v[50:53], v[180:183], v[164:167], v[50:53]
	v_mfma_f32_16x16x32_bf16 v[46:49], v[188:191], v[156:159], v[46:49]
	v_mfma_f32_16x16x32_bf16 v[42:45], v[188:191], v[164:167], v[42:45]
	v_mfma_f32_16x16x32_bf16 v[38:41], v[196:199], v[156:159], v[38:41]
	v_mfma_f32_16x16x32_bf16 v[34:37], v[196:199], v[164:167], v[34:37]
	v_mfma_f32_16x16x32_bf16 v[62:65], v[176:179], v[160:163], v[62:65]
	v_mfma_f32_16x16x32_bf16 v[58:61], v[176:179], v[168:171], v[58:61]
	v_mfma_f32_16x16x32_bf16 v[54:57], v[184:187], v[160:163], v[54:57]
	v_mfma_f32_16x16x32_bf16 v[50:53], v[184:187], v[168:171], v[50:53]
	v_mfma_f32_16x16x32_bf16 v[46:49], v[192:195], v[160:163], v[46:49]
	v_mfma_f32_16x16x32_bf16 v[42:45], v[192:195], v[168:171], v[42:45]
	v_mfma_f32_16x16x32_bf16 v[38:41], v[200:203], v[160:163], v[38:41]
	v_mfma_f32_16x16x32_bf16 v[34:37], v[200:203], v[168:171], v[34:37]
	v_mfma_f32_16x16x32_bf16 v[30:33], v[172:175], v[206:209], v[30:33]
	v_mfma_f32_16x16x32_bf16 v[26:29], v[172:175], v[214:217], v[26:29]
	v_mfma_f32_16x16x32_bf16 v[22:25], v[180:183], v[206:209], v[22:25]
	v_mfma_f32_16x16x32_bf16 v[18:21], v[180:183], v[214:217], v[18:21]
	v_mfma_f32_16x16x32_bf16 v[14:17], v[188:191], v[206:209], v[14:17]
	v_mfma_f32_16x16x32_bf16 v[10:13], v[188:191], v[214:217], v[10:13]
	v_mfma_f32_16x16x32_bf16 v[6:9], v[196:199], v[206:209], v[6:9]
	v_mfma_f32_16x16x32_bf16 v[2:5], v[196:199], v[214:217], v[2:5]
	v_mfma_f32_16x16x32_bf16 v[30:33], v[176:179], v[210:213], v[30:33]
	v_mfma_f32_16x16x32_bf16 v[26:29], v[176:179], v[218:221], v[26:29]
	v_mfma_f32_16x16x32_bf16 v[22:25], v[184:187], v[210:213], v[22:25]
	v_mfma_f32_16x16x32_bf16 v[18:21], v[184:187], v[218:221], v[18:21]
	v_mfma_f32_16x16x32_bf16 v[14:17], v[192:195], v[210:213], v[14:17]
	v_mfma_f32_16x16x32_bf16 v[10:13], v[192:195], v[218:221], v[10:13]
	v_mfma_f32_16x16x32_bf16 v[6:9], v[200:203], v[210:213], v[6:9]
	v_mfma_f32_16x16x32_bf16 v[2:5], v[200:203], v[218:221], v[2:5]
	s_setprio 0
	s_barrier
	ds_read_b128 v[156:159], v137
	ds_read_b128 v[160:163], v137 offset:1024
	ds_read_b128 v[164:167], v137 offset:2048
	ds_read_b128 v[168:171], v137 offset:3072
	ds_read_b128 v[172:175], v132 offset:32768
	ds_read_b128 v[176:179], v132 offset:33792
	ds_read_b128 v[180:183], v150 offset:32768
	ds_read_b128 v[184:187], v150 offset:33792
	ds_read_b128 v[188:191], v151 offset:32768
	ds_read_b128 v[192:195], v151 offset:33792
	ds_read_b128 v[196:199], v152 offset:32768
	ds_read_b128 v[200:203], v152 offset:33792
	ds_read_b128 v[206:209], v133
	ds_read_b128 v[210:213], v133 offset:1024
	ds_read_b128 v[214:217], v133 offset:2048
	ds_read_b128 v[218:221], v133 offset:3072
	v_lshl_add_u64 v[224:225], s[16:17], 0, v[0:1]
	s_mov_b64 s[22:23], 0x1f430100
	v_lshl_add_u64 v[222:223], v[224:225], 0, s[22:23]
	v_readfirstlane_b32 s21, v139
	s_mov_b32 m0, s21
	s_nop 0
	global_load_lds_dwordx4 v[222:223], off
	v_lshl_add_u64 v[224:225], s[16:17], 0, v[0:1]
	s_mov_b64 s[22:23], 0x1f488100
	v_lshl_add_u64 v[222:223], v[224:225], 0, s[22:23]
	v_readfirstlane_b32 s21, v140
	s_mov_b32 m0, s21
	s_nop 0
	global_load_lds_dwordx4 v[222:223], off
	s_waitcnt vmcnt(8)
	s_waitcnt lgkmcnt(0)
	s_barrier
; #define STAGE_A(P, br, kt) do { const char* _g = (const char*)(A + (long)(br) * lda + (long)(kt) * BK); \
;     __builtin_amdgcn_global_load_lds((const unsigned*)(_g + (size_t)offA0), (unsigned*)((char*)(P) + sb0), 16, 0, 0); \
;     __builtin_amdgcn_global_load_lds((const unsigned*)(_g + (size_t)lda * 128 + (size_t)offA0), (unsigned*)((char*)(P) + sb1), 16, 0, 0); } while (0)
; #define STAGE_B(P, br, kt) do { const char* _g = (const char*)(B + (long)(br) * ldb + (long)(kt) * BK); \
;     __builtin_amdgcn_global_load_lds((const unsigned*)(_g + (size_t)offB0), (unsigned*)((char*)(P) + sb0), 16, 0, 0); \
;     __builtin_amdgcn_global_load_lds((const unsigned*)(_g + (size_t)ldb * 128 + (size_t)offB0), (unsigned*)((char*)(P) + sb1), 16, 0, 0); } while (0)
; #define LDA(dst, b, h) for (int m = 0; m < 4; ++m) for (int k = 0; k < 2; ++k) \
;     dst[m][k] = *reinterpret_cast<const bf16x8*>((char*)SA(b, h) + lds_byte(wr * 64 + m * 16 + fr, k * 32 + fq * 8))
; #define LDB(dst, b, h) for (int n = 0; n < 2; ++n) for (int k = 0; k < 2; ++k) \
;     dst[n][k] = *reinterpret_cast<const bf16x8*>((char*)SB(b, h) + lds_byte(wc * 32 + n * 16 + fr, k * 32 + fq * 8))
; #define MMA(ai, bj, At_, Bt_) do { __builtin_amdgcn_s_setprio(1); \
;     for (int m = 0; m < 4; ++m) for (int n = 0; n < 2; ++n) for (int k = 0; k < 2; ++k) \
;       acc[ai][bj][m][n] = MFMA16(At_[m][k], Bt_[n][k], acc[ai][bj][m][n]); \
;     __builtin_amdgcn_s_setprio(0); } while (0)
; #define WAIT_V(n) asm volatile("s_waitcnt vmcnt(" #n ")" ::: "memory")
; #define WAIT_L(n) asm volatile("s_waitcnt lgkmcnt(" #n ")" ::: "memory")
; #define BAR __builtin_amdgcn_s_barrier()
; #define SCHED __builtin_amdgcn_sched_barrier(0)
; DI void gemm_core(WVP char* smem, const u16* __restrict__ A, int lda, int ar0, int ar1,
;                   const u16* __restrict__ B, int ldb, int bc0, int K, AccT& acc) {
;     ...
;     WAIT_L(8); BAR; WAIT_L(0); MMA(0, 0, At, B0); BAR; SCHED;
;     LDB(B1, 1, 1); STAGE_B(SB(1, 0), bb0, t + 3);
;     BAR; WAIT_L(0); MMA(0, 1, At, B1); BAR;
;     LDA(At, 1, 1); STAGE_A(SA(1, 0), ac0, t + 3);
;     BAR; WAIT_L(0); MMA(1, 0, At, B0); BAR; SCHED;
;     STAGE_B(SB(1, 1), bb1, t + 3);
;     WAIT_V(6); BAR; MMA(1, 1, At, B1); BAR;
;   }
	s_setprio 1
	v_mfma_f32_16x16x32_bf16 v[126:129], v[172:175], v[156:159], v[126:129]
	v_mfma_f32_16x16x32_bf16 v[122:125], v[172:175], v[164:167], v[122:125]
	v_mfma_f32_16x16x32_bf16 v[118:121], v[180:183], v[156:159], v[118:121]
	v_mfma_f32_16x16x32_bf16 v[114:117], v[180:183], v[164:167], v[114:117]
	v_mfma_f32_16x16x32_bf16 v[110:113], v[188:191], v[156:159], v[110:113]
	v_mfma_f32_16x16x32_bf16 v[106:109], v[188:191], v[164:167], v[106:109]
	v_mfma_f32_16x16x32_bf16 v[102:105], v[196:199], v[156:159], v[102:105]
	v_mfma_f32_16x16x32_bf16 v[98:101], v[196:199], v[164:167], v[98:101]
	v_mfma_f32_16x16x32_bf16 v[126:129], v[176:179], v[160:163], v[126:129]
	v_mfma_f32_16x16x32_bf16 v[122:125], v[176:179], v[168:171], v[122:125]
	v_mfma_f32_16x16x32_bf16 v[118:121], v[184:187], v[160:163], v[118:121]
	v_mfma_f32_16x16x32_bf16 v[114:117], v[184:187], v[168:171], v[114:117]
	v_mfma_f32_16x16x32_bf16 v[110:113], v[192:195], v[160:163], v[110:113]
	v_mfma_f32_16x16x32_bf16 v[106:109], v[192:195], v[168:171], v[106:109]
	v_mfma_f32_16x16x32_bf16 v[102:105], v[200:203], v[160:163], v[102:105]
	v_mfma_f32_16x16x32_bf16 v[98:101], v[200:203], v[168:171], v[98:101]
	v_mfma_f32_16x16x32_bf16 v[94:97], v[172:175], v[206:209], v[94:97]
	v_mfma_f32_16x16x32_bf16 v[90:93], v[172:175], v[214:217], v[90:93]
	v_mfma_f32_16x16x32_bf16 v[86:89], v[180:183], v[206:209], v[86:89]
	v_mfma_f32_16x16x32_bf16 v[82:85], v[180:183], v[214:217], v[82:85]
	v_mfma_f32_16x16x32_bf16 v[78:81], v[188:191], v[206:209], v[78:81]
	v_mfma_f32_16x16x32_bf16 v[74:77], v[188:191], v[214:217], v[74:77]
	v_mfma_f32_16x16x32_bf16 v[70:73], v[196:199], v[206:209], v[70:73]
	v_mfma_f32_16x16x32_bf16 v[66:69], v[196:199], v[214:217], v[66:69]
	v_mfma_f32_16x16x32_bf16 v[94:97], v[176:179], v[210:213], v[94:97]
	v_mfma_f32_16x16x32_bf16 v[90:93], v[176:179], v[218:221], v[90:93]
	v_mfma_f32_16x16x32_bf16 v[86:89], v[184:187], v[210:213], v[86:89]
	v_mfma_f32_16x16x32_bf16 v[82:85], v[184:187], v[218:221], v[82:85]
	v_mfma_f32_16x16x32_bf16 v[78:81], v[192:195], v[210:213], v[78:81]
	v_mfma_f32_16x16x32_bf16 v[74:77], v[192:195], v[218:221], v[74:77]
	v_mfma_f32_16x16x32_bf16 v[70:73], v[200:203], v[210:213], v[70:73]
	v_mfma_f32_16x16x32_bf16 v[66:69], v[200:203], v[218:221], v[66:69]
	s_setprio 0
	s_barrier
	ds_read_b128 v[172:175], v132 offset:49152
	ds_read_b128 v[176:179], v132 offset:50176
	ds_read_b128 v[180:183], v150 offset:49152
	ds_read_b128 v[184:187], v150 offset:50176
	ds_read_b128 v[188:191], v151 offset:49152
	ds_read_b128 v[192:195], v151 offset:50176
	ds_read_b128 v[196:199], v152 offset:49152
	ds_read_b128 v[200:203], v152 offset:50176
	v_lshl_add_u64 v[224:225], s[8:9], 0, v[0:1]
	v_lshl_add_u64 v[222:223], v[224:225], 0, s[70:71]
	v_readfirstlane_b32 s21, v141
	s_mov_b32 m0, s21
	s_nop 0
	global_load_lds_dwordx4 v[222:223], off
	v_lshl_add_u64 v[224:225], s[8:9], 0, v[0:1]
	s_mov_b64 s[22:23], 0x58180
	v_lshl_add_u64 v[222:223], v[224:225], 0, s[22:23]
	v_readfirstlane_b32 s21, v142
	s_mov_b32 m0, s21
	s_nop 0
	global_load_lds_dwordx4 v[222:223], off
	v_lshl_add_u64 v[224:225], s[16:17], 0, v[0:1]
	s_mov_b64 s[22:23], 0x1f380180
	v_lshl_add_u64 v[222:223], v[224:225], 0, s[22:23]
	v_readfirstlane_b32 s21, v143
	s_mov_b32 m0, s21
	s_nop 0
	global_load_lds_dwordx4 v[222:223], off
	v_lshl_add_u64 v[224:225], s[16:17], 0, v[0:1]
	s_mov_b64 s[22:23], 0x1f3d8180
	v_lshl_add_u64 v[222:223], v[224:225], 0, s[22:23]
	v_readfirstlane_b32 s21, v144
	s_mov_b32 m0, s21
	s_nop 0
	global_load_lds_dwordx4 v[222:223], off
	v_lshl_add_u64 v[224:225], s[8:9], 0, v[0:1]
	s_mov_b64 s[22:23], 0xb0180
	v_lshl_add_u64 v[222:223], v[224:225], 0, s[22:23]
	v_readfirstlane_b32 s21, v145
	s_mov_b32 m0, s21
	s_nop 0
	global_load_lds_dwordx4 v[222:223], off
	v_lshl_add_u64 v[224:225], s[8:9], 0, v[0:1]
	s_mov_b64 s[22:23], 0x108180
	v_lshl_add_u64 v[222:223], v[224:225], 0, s[22:23]
	v_readfirstlane_b32 s21, v147
	s_mov_b32 m0, s21
	s_nop 0
	global_load_lds_dwordx4 v[222:223], off
	s_waitcnt vmcnt(8)
	s_waitcnt lgkmcnt(0)
	s_barrier
	s_setprio 1
	v_mfma_f32_16x16x32_bf16 v[62:65], v[172:175], v[156:159], v[62:65]
	v_mfma_f32_16x16x32_bf16 v[58:61], v[172:175], v[164:167], v[58:61]
	v_mfma_f32_16x16x32_bf16 v[54:57], v[180:183], v[156:159], v[54:57]
	v_mfma_f32_16x16x32_bf16 v[50:53], v[180:183], v[164:167], v[50:53]
	v_mfma_f32_16x16x32_bf16 v[46:49], v[188:191], v[156:159], v[46:49]
	v_mfma_f32_16x16x32_bf16 v[42:45], v[188:191], v[164:167], v[42:45]
	v_mfma_f32_16x16x32_bf16 v[38:41], v[196:199], v[156:159], v[38:41]
	v_mfma_f32_16x16x32_bf16 v[34:37], v[196:199], v[164:167], v[34:37]
	v_mfma_f32_16x16x32_bf16 v[62:65], v[176:179], v[160:163], v[62:65]
	v_mfma_f32_16x16x32_bf16 v[58:61], v[176:179], v[168:171], v[58:61]
	v_mfma_f32_16x16x32_bf16 v[54:57], v[184:187], v[160:163], v[54:57]
	v_mfma_f32_16x16x32_bf16 v[50:53], v[184:187], v[168:171], v[50:53]
	v_mfma_f32_16x16x32_bf16 v[46:49], v[192:195], v[160:163], v[46:49]
	v_mfma_f32_16x16x32_bf16 v[42:45], v[192:195], v[168:171], v[42:45]
	v_mfma_f32_16x16x32_bf16 v[38:41], v[200:203], v[160:163], v[38:41]
	v_mfma_f32_16x16x32_bf16 v[34:37], v[200:203], v[168:171], v[34:37]
	v_mfma_f32_16x16x32_bf16 v[30:33], v[172:175], v[206:209], v[30:33]
	v_mfma_f32_16x16x32_bf16 v[26:29], v[172:175], v[214:217], v[26:29]
	v_mfma_f32_16x16x32_bf16 v[22:25], v[180:183], v[206:209], v[22:25]
	v_mfma_f32_16x16x32_bf16 v[18:21], v[180:183], v[214:217], v[18:21]
	v_mfma_f32_16x16x32_bf16 v[14:17], v[188:191], v[206:209], v[14:17]
	v_mfma_f32_16x16x32_bf16 v[10:13], v[188:191], v[214:217], v[10:13]
	v_mfma_f32_16x16x32_bf16 v[6:9], v[196:199], v[206:209], v[6:9]
	v_mfma_f32_16x16x32_bf16 v[2:5], v[196:199], v[214:217], v[2:5]
	v_mfma_f32_16x16x32_bf16 v[30:33], v[176:179], v[210:213], v[30:33]
	v_mfma_f32_16x16x32_bf16 v[26:29], v[176:179], v[218:221], v[26:29]
	v_mfma_f32_16x16x32_bf16 v[22:25], v[184:187], v[210:213], v[22:25]
	v_mfma_f32_16x16x32_bf16 v[18:21], v[184:187], v[218:221], v[18:21]
	v_mfma_f32_16x16x32_bf16 v[14:17], v[192:195], v[210:213], v[14:17]
	v_mfma_f32_16x16x32_bf16 v[10:13], v[192:195], v[218:221], v[10:13]
	v_mfma_f32_16x16x32_bf16 v[6:9], v[200:203], v[210:213], v[6:9]
	v_mfma_f32_16x16x32_bf16 v[2:5], v[200:203], v[218:221], v[2:5]
	s_setprio 0
	s_add_i32 s20, s20, 2
	s_add_u32 s8, s8, 0x100
	s_addc_u32 s9, s9, 0
	s_add_u32 s16, s16, 0x100
	s_addc_u32 s17, s17, 0
	s_cmp_lt_u32 s20, 40
	s_barrier
; #define STAGE_A(P, br, kt) do { const char* _g = (const char*)(A + (long)(br) * lda + (long)(kt) * BK); \
;     __builtin_amdgcn_global_load_lds((const unsigned*)(_g + (size_t)offA0), (unsigned*)((char*)(P) + sb0), 16, 0, 0); \
;     __builtin_amdgcn_global_load_lds((const unsigned*)(_g + (size_t)lda * 128 + (size_t)offA0), (unsigned*)((char*)(P) + sb1), 16, 0, 0); } while (0)
; #define LDA(dst, b, h) for (int m = 0; m < 4; ++m) for (int k = 0; k < 2; ++k) \
;     dst[m][k] = *reinterpret_cast<const bf16x8*>((char*)SA(b, h) + lds_byte(wr * 64 + m * 16 + fr, k * 32 + fq * 8))
; #define LDB(dst, b, h) for (int n = 0; n < 2; ++n) for (int k = 0; k < 2; ++k) \
;     dst[n][k] = *reinterpret_cast<const bf16x8*>((char*)SB(b, h) + lds_byte(wc * 32 + n * 16 + fr, k * 32 + fq * 8))
; #define MMA(ai, bj, At_, Bt_) do { __builtin_amdgcn_s_setprio(1); \
;     for (int m = 0; m < 4; ++m) for (int n = 0; n < 2; ++n) for (int k = 0; k < 2; ++k) \
;       acc[ai][bj][m][n] = MFMA16(At_[m][k], Bt_[n][k], acc[ai][bj][m][n]); \
;     __builtin_amdgcn_s_setprio(0); } while (0)
; #define WAIT_V(n) asm volatile("s_waitcnt vmcnt(" #n ")" ::: "memory")
; #define WAIT_L(n) asm volatile("s_waitcnt lgkmcnt(" #n ")" ::: "memory")
; #define BAR __builtin_amdgcn_s_barrier()
; DI void gemm_core(WVP char* smem, const u16* __restrict__ A, int lda, int ar0, int ar1,
;                   const u16* __restrict__ B, int ldb, int bc0, int K, AccT& acc) {
;     ...
;   { LDB(B0, 0, 0); LDA(At, 0, 0); STAGE_A(SA(1, 1), ac1, nt - 1);
;     BAR; WAIT_L(0); MMA(0, 0, At, B0); BAR;
;     LDB(B1, 0, 1); BAR; WAIT_L(0); MMA(0, 1, At, B1); BAR;
;     LDA(At, 0, 1); WAIT_V(4); BAR; WAIT_L(0); MMA(1, 0, At, B0); MMA(1, 1, At, B1); BAR; }
;   { LDB(B0, 1, 0); LDA(At, 1, 0); WAIT_V(2); BAR; WAIT_L(0); MMA(0, 0, At, B0); BAR;
	s_cbranch_scc1 .LBB0_94
	s_mov_b64 s[0:1], 0x1580
	v_lshl_add_u64 v[134:135], v[130:131], 0, s[0:1]
	v_readfirstlane_b32 s0, v153
	s_mov_b32 m0, s0
	s_mov_b64 s[0:1], 0x59580
	v_lshl_add_u64 v[130:131], v[130:131], 0, s[0:1]
	v_readfirstlane_b32 s0, v154
	ds_read_b128 v[138:141], v149
	ds_read_b128 v[142:145], v149 offset:1024
	ds_read_b128 v[156:159], v149 offset:2048
	ds_read_b128 v[160:163], v149 offset:3072
	ds_read_b128 v[164:167], v132
	ds_read_b128 v[168:171], v132 offset:1024
	ds_read_b128 v[172:175], v150
	ds_read_b128 v[176:179], v150 offset:1024
	ds_read_b128 v[180:183], v151
	ds_read_b128 v[184:187], v151 offset:1024
	ds_read_b128 v[188:191], v152
	ds_read_b128 v[192:195], v152 offset:1024
	global_load_lds_dwordx4 v[134:135], off
	s_mov_b32 m0, s0
	s_nop 0
	global_load_lds_dwordx4 v[130:131], off
	s_waitcnt vmcnt(8)
	s_barrier
	s_waitcnt lgkmcnt(0)
	s_setprio 1
	s_waitcnt lgkmcnt(0)
	v_mfma_f32_16x16x32_bf16 v[126:129], v[164:167], v[138:141], v[126:129]
	v_mfma_f32_16x16x32_bf16 v[118:121], v[172:175], v[138:141], v[118:121]
	v_mfma_f32_16x16x32_bf16 v[110:113], v[180:183], v[138:141], v[110:113]
	v_mfma_f32_16x16x32_bf16 v[102:105], v[188:191], v[138:141], v[102:105]
	v_mfma_f32_16x16x32_bf16 v[126:129], v[168:171], v[142:145], v[126:129]
	v_mfma_f32_16x16x32_bf16 v[122:125], v[164:167], v[156:159], v[122:125]
	v_mfma_f32_16x16x32_bf16 v[118:121], v[176:179], v[142:145], v[118:121]
	v_mfma_f32_16x16x32_bf16 v[114:117], v[172:175], v[156:159], v[114:117]
	v_mfma_f32_16x16x32_bf16 v[110:113], v[184:187], v[142:145], v[110:113]
	v_mfma_f32_16x16x32_bf16 v[106:109], v[180:183], v[156:159], v[106:109]
	v_mfma_f32_16x16x32_bf16 v[102:105], v[192:195], v[142:145], v[102:105]
	v_mfma_f32_16x16x32_bf16 v[98:101], v[188:191], v[156:159], v[98:101]
	v_mfma_f32_16x16x32_bf16 v[122:125], v[168:171], v[160:163], v[122:125]
	v_mfma_f32_16x16x32_bf16 v[196:199], v[176:179], v[160:163], v[114:117]
	v_mfma_f32_16x16x32_bf16 v[200:203], v[184:187], v[160:163], v[106:109]
	v_mfma_f32_16x16x32_bf16 v[206:209], v[192:195], v[160:163], v[98:101]
	s_setprio 0
	s_barrier
	s_nop 1
	ds_read_b128 v[98:101], v146
	ds_read_b128 v[106:109], v146 offset:1024
	ds_read_b128 v[114:117], v146 offset:2048
	ds_read_b128 v[146:149], v146 offset:3072
	s_barrier
	s_waitcnt lgkmcnt(0)
	s_setprio 1
	s_waitcnt lgkmcnt(0)
	v_mfma_f32_16x16x32_bf16 v[94:97], v[164:167], v[98:101], v[94:97]
	v_mfma_f32_16x16x32_bf16 v[86:89], v[172:175], v[98:101], v[86:89]
	v_mfma_f32_16x16x32_bf16 v[78:81], v[180:183], v[98:101], v[78:81]
	v_mfma_f32_16x16x32_bf16 v[70:73], v[188:191], v[98:101], v[70:73]
	v_mfma_f32_16x16x32_bf16 v[94:97], v[168:171], v[106:109], v[94:97]
	v_mfma_f32_16x16x32_bf16 v[90:93], v[164:167], v[114:117], v[90:93]
	v_mfma_f32_16x16x32_bf16 v[86:89], v[176:179], v[106:109], v[86:89]
	v_mfma_f32_16x16x32_bf16 v[82:85], v[172:175], v[114:117], v[82:85]
	v_mfma_f32_16x16x32_bf16 v[78:81], v[184:187], v[106:109], v[78:81]
	v_mfma_f32_16x16x32_bf16 v[74:77], v[180:183], v[114:117], v[74:77]
	v_mfma_f32_16x16x32_bf16 v[70:73], v[192:195], v[106:109], v[70:73]
	v_mfma_f32_16x16x32_bf16 v[66:69], v[188:191], v[114:117], v[66:69]
	v_mfma_f32_16x16x32_bf16 v[164:167], v[168:171], v[146:149], v[90:93]
	v_mfma_f32_16x16x32_bf16 v[168:171], v[176:179], v[146:149], v[82:85]
	v_mfma_f32_16x16x32_bf16 v[172:175], v[184:187], v[146:149], v[74:77]
	v_mfma_f32_16x16x32_bf16 v[176:179], v[192:195], v[146:149], v[66:69]
	s_setprio 0
	s_barrier
	s_nop 1
	ds_read_b128 v[66:69], v132 offset:16384
	ds_read_b128 v[74:77], v132 offset:17408
	ds_read_b128 v[82:85], v150 offset:16384
	ds_read_b128 v[90:93], v150 offset:17408
	ds_read_b128 v[180:183], v151 offset:16384
	ds_read_b128 v[184:187], v151 offset:17408
	ds_read_b128 v[188:191], v152 offset:16384
	ds_read_b128 v[192:195], v152 offset:17408
	s_waitcnt vmcnt(4)
	s_barrier
	s_waitcnt lgkmcnt(0)
	s_setprio 1
	s_waitcnt lgkmcnt(0)
	v_mfma_f32_16x16x32_bf16 v[62:65], v[66:69], v[138:141], v[62:65]
	v_mfma_f32_16x16x32_bf16 v[54:57], v[82:85], v[138:141], v[54:57]
	v_mfma_f32_16x16x32_bf16 v[42:45], v[180:183], v[156:159], v[42:45]
	v_mfma_f32_16x16x32_bf16 v[38:41], v[188:191], v[138:141], v[38:41]
	v_mfma_f32_16x16x32_bf16 v[62:65], v[74:77], v[142:145], v[62:65]
	v_mfma_f32_16x16x32_bf16 v[58:61], v[66:69], v[156:159], v[58:61]
	v_mfma_f32_16x16x32_bf16 v[54:57], v[90:93], v[142:145], v[54:57]
	v_mfma_f32_16x16x32_bf16 v[50:53], v[82:85], v[156:159], v[50:53]
	v_mfma_f32_16x16x32_bf16 v[46:49], v[180:183], v[138:141], v[46:49]
	v_mfma_f32_16x16x32_bf16 v[42:45], v[184:187], v[160:163], v[42:45]
	v_mfma_f32_16x16x32_bf16 v[38:41], v[192:195], v[142:145], v[38:41]
	v_mfma_f32_16x16x32_bf16 v[34:37], v[188:191], v[156:159], v[34:37]
	v_mfma_f32_16x16x32_bf16 v[210:213], v[74:77], v[160:163], v[58:61]
	v_mfma_f32_16x16x32_bf16 v[214:217], v[90:93], v[160:163], v[50:53]
	v_mfma_f32_16x16x32_bf16 v[218:221], v[184:187], v[142:145], v[46:49]
	v_mfma_f32_16x16x32_bf16 v[138:141], v[192:195], v[160:163], v[34:37]
	s_setprio 0
	s_setprio 1
	v_mfma_f32_16x16x32_bf16 v[30:33], v[66:69], v[98:101], v[30:33]
	v_mfma_f32_16x16x32_bf16 v[22:25], v[82:85], v[98:101], v[22:25]
	v_mfma_f32_16x16x32_bf16 v[10:13], v[180:183], v[114:117], v[10:13]
	v_mfma_f32_16x16x32_bf16 v[30:33], v[74:77], v[106:109], v[30:33]
	v_mfma_f32_16x16x32_bf16 v[26:29], v[66:69], v[114:117], v[26:29]
	v_mfma_f32_16x16x32_bf16 v[22:25], v[90:93], v[106:109], v[22:25]
	v_mfma_f32_16x16x32_bf16 v[18:21], v[82:85], v[114:117], v[18:21]
	v_mfma_f32_16x16x32_bf16 v[14:17], v[180:183], v[98:101], v[14:17]
	v_mfma_f32_16x16x32_bf16 v[10:13], v[184:187], v[146:149], v[10:13]
	v_mfma_f32_16x16x32_bf16 v[6:9], v[188:191], v[98:101], v[6:9]
	v_mfma_f32_16x16x32_bf16 v[2:5], v[188:191], v[114:117], v[2:5]
	v_mfma_f32_16x16x32_bf16 v[142:145], v[74:77], v[146:149], v[26:29]
	v_mfma_f32_16x16x32_bf16 v[154:157], v[90:93], v[146:149], v[18:21]
	v_mfma_f32_16x16x32_bf16 v[158:161], v[184:187], v[106:109], v[14:17]
	v_mfma_f32_16x16x32_bf16 v[180:183], v[192:195], v[106:109], v[6:9]
	v_mfma_f32_16x16x32_bf16 v[146:149], v[192:195], v[146:149], v[2:5]
	s_setprio 0
	s_barrier
; #define LDA(dst, b, h) for (int m = 0; m < 4; ++m) for (int k = 0; k < 2; ++k) \
;     dst[m][k] = *reinterpret_cast<const bf16x8*>((char*)SA(b, h) + lds_byte(wr * 64 + m * 16 + fr, k * 32 + fq * 8))
; #define LDB(dst, b, h) for (int n = 0; n < 2; ++n) for (int k = 0; k < 2; ++k) \
;     dst[n][k] = *reinterpret_cast<const bf16x8*>((char*)SB(b, h) + lds_byte(wc * 32 + n * 16 + fr, k * 32 + fq * 8))
; #define MMA(ai, bj, At_, Bt_) do { __builtin_amdgcn_s_setprio(1); \
;     for (int m = 0; m < 4; ++m) for (int n = 0; n < 2; ++n) for (int k = 0; k < 2; ++k) \
;       acc[ai][bj][m][n] = MFMA16(At_[m][k], Bt_[n][k], acc[ai][bj][m][n]); \
;     __builtin_amdgcn_s_setprio(0); } while (0)
; #define WAIT_V(n) asm volatile("s_waitcnt vmcnt(" #n ")" ::: "memory")
; #define WAIT_L(n) asm volatile("s_waitcnt lgkmcnt(" #n ")" ::: "memory")
; #define BAR __builtin_amdgcn_s_barrier()
; DI void gemm_core(WVP char* smem, const u16* __restrict__ A, int lda, int ar0, int ar1,
;                   const u16* __restrict__ B, int ldb, int bc0, int K, AccT& acc) {
;     ...
;     LDA(At, 0, 1); WAIT_V(4); BAR; WAIT_L(0); MMA(1, 0, At, B0); MMA(1, 1, At, B1); BAR; }
;   { LDB(B0, 1, 0); LDA(At, 1, 0); WAIT_V(2); BAR; WAIT_L(0); MMA(0, 0, At, B0); BAR;
;     LDB(B1, 1, 1); WAIT_V(0); BAR; WAIT_L(0); MMA(0, 1, At, B1); BAR;
;     LDA(At, 1, 1); BAR; WAIT_L(0); MMA(1, 0, At, B0); MMA(1, 1, At, B1); BAR; }
;   if (wr == 0) BAR;
	ds_read_b128 v[184:187], v137
	ds_read_b128 v[188:191], v137 offset:1024
	ds_read_b128 v[192:195], v137 offset:2048
	ds_read_b128 v[134:137], v137 offset:3072
	ds_read_b128 v[2:5], v132 offset:32768
	ds_read_b128 v[6:9], v132 offset:33792
	ds_read_b128 v[14:17], v150 offset:32768
	ds_read_b128 v[18:21], v150 offset:33792
	ds_read_b128 v[222:225], v151 offset:32768
	ds_read_b128 v[226:229], v151 offset:33792
	ds_read_b128 v[230:233], v152 offset:32768
	ds_read_b128 v[234:237], v152 offset:33792
	s_waitcnt vmcnt(2)
	s_barrier
	s_waitcnt lgkmcnt(0)
	s_setprio 1
	s_waitcnt lgkmcnt(0)
	v_mfma_f32_16x16x32_bf16 v[26:29], v[2:5], v[184:187], v[126:129]
	v_mfma_f32_16x16x32_bf16 v[114:117], v[6:9], v[188:191], v[26:29]
	v_mfma_f32_16x16x32_bf16 v[26:29], v[2:5], v[192:195], v[122:125]
	v_mfma_f32_16x16x32_bf16 v[106:109], v[6:9], v[134:137], v[26:29]
	v_mfma_f32_16x16x32_bf16 v[26:29], v[14:17], v[184:187], v[118:121]
	v_mfma_f32_16x16x32_bf16 v[98:101], v[18:21], v[188:191], v[26:29]
	v_mfma_f32_16x16x32_bf16 v[26:29], v[14:17], v[192:195], v[196:199]
	v_mfma_f32_16x16x32_bf16 v[90:93], v[18:21], v[134:137], v[26:29]
	v_mfma_f32_16x16x32_bf16 v[26:29], v[222:225], v[184:187], v[110:113]
	v_mfma_f32_16x16x32_bf16 v[82:85], v[226:229], v[188:191], v[26:29]
	v_mfma_f32_16x16x32_bf16 v[26:29], v[222:225], v[192:195], v[200:203]
	v_mfma_f32_16x16x32_bf16 v[74:77], v[226:229], v[134:137], v[26:29]
	v_mfma_f32_16x16x32_bf16 v[26:29], v[230:233], v[184:187], v[102:105]
	v_mfma_f32_16x16x32_bf16 v[66:69], v[234:237], v[188:191], v[26:29]
	v_mfma_f32_16x16x32_bf16 v[26:29], v[230:233], v[192:195], v[206:209]
	v_mfma_f32_16x16x32_bf16 v[58:61], v[234:237], v[134:137], v[26:29]
	s_setprio 0
	s_barrier
	ds_read_b128 v[122:125], v133
	ds_read_b128 v[196:199], v133 offset:1024
	ds_read_b128 v[200:203], v133 offset:2048
	ds_read_b128 v[206:209], v133 offset:3072
	s_waitcnt vmcnt(0)
	s_barrier
	s_waitcnt lgkmcnt(0)
	s_setprio 1
	s_waitcnt lgkmcnt(0)
	v_mfma_f32_16x16x32_bf16 v[26:29], v[2:5], v[122:125], v[94:97]
	v_mfma_f32_16x16x32_bf16 v[2:5], v[2:5], v[200:203], v[164:167]
	v_mfma_f32_16x16x32_bf16 v[46:49], v[6:9], v[206:209], v[2:5]
	v_mfma_f32_16x16x32_bf16 v[2:5], v[14:17], v[122:125], v[86:89]
	v_mfma_f32_16x16x32_bf16 v[34:37], v[18:21], v[196:199], v[2:5]
	v_mfma_f32_16x16x32_bf16 v[2:5], v[14:17], v[200:203], v[168:171]
	v_mfma_f32_16x16x32_bf16 v[50:53], v[6:9], v[196:199], v[26:29]
	v_mfma_f32_16x16x32_bf16 v[26:29], v[18:21], v[206:209], v[2:5]
	v_mfma_f32_16x16x32_bf16 v[2:5], v[222:225], v[122:125], v[78:81]
	v_mfma_f32_16x16x32_bf16 v[18:21], v[226:229], v[196:199], v[2:5]
	v_mfma_f32_16x16x32_bf16 v[2:5], v[222:225], v[200:203], v[172:175]
	v_mfma_f32_16x16x32_bf16 v[14:17], v[226:229], v[206:209], v[2:5]
	v_mfma_f32_16x16x32_bf16 v[2:5], v[230:233], v[122:125], v[70:73]
	v_mfma_f32_16x16x32_bf16 v[6:9], v[234:237], v[196:199], v[2:5]
	v_mfma_f32_16x16x32_bf16 v[2:5], v[230:233], v[200:203], v[176:179]
	v_mfma_f32_16x16x32_bf16 v[2:5], v[234:237], v[206:209], v[2:5]
	s_setprio 0
	s_barrier
	ds_read_b128 v[162:165], v132 offset:49152
	ds_read_b128 v[130:133], v132 offset:50176
	ds_read_b128 v[166:169], v150 offset:49152
	ds_read_b128 v[170:173], v150 offset:50176
	ds_read_b128 v[174:177], v151 offset:49152
	ds_read_b128 v[222:225], v151 offset:50176
	ds_read_b128 v[226:229], v152 offset:49152
	ds_read_b128 v[150:153], v152 offset:50176
	s_barrier
	s_waitcnt lgkmcnt(0)
	s_setprio 1
	s_waitcnt lgkmcnt(0)
	v_mfma_f32_16x16x32_bf16 v[54:57], v[166:169], v[184:187], v[54:57]
	v_mfma_f32_16x16x32_bf16 v[62:65], v[162:165], v[184:187], v[62:65]
	v_mfma_f32_16x16x32_bf16 v[110:113], v[170:173], v[188:191], v[54:57]
	v_mfma_f32_16x16x32_bf16 v[54:57], v[166:169], v[192:195], v[214:217]
	v_mfma_f32_16x16x32_bf16 v[38:41], v[226:229], v[184:187], v[38:41]
	v_mfma_f32_16x16x32_bf16 v[118:121], v[130:133], v[188:191], v[62:65]
	v_mfma_f32_16x16x32_bf16 v[62:65], v[162:165], v[192:195], v[210:213]
	v_mfma_f32_16x16x32_bf16 v[102:105], v[170:173], v[134:137], v[54:57]
	v_mfma_f32_16x16x32_bf16 v[54:57], v[174:177], v[184:187], v[218:221]
	v_mfma_f32_16x16x32_bf16 v[42:45], v[174:177], v[192:195], v[42:45]
	v_mfma_f32_16x16x32_bf16 v[78:81], v[150:153], v[188:191], v[38:41]
	v_mfma_f32_16x16x32_bf16 v[38:41], v[226:229], v[192:195], v[138:141]
	v_mfma_f32_16x16x32_bf16 v[126:129], v[130:133], v[134:137], v[62:65]
	v_mfma_f32_16x16x32_bf16 v[86:89], v[222:225], v[188:191], v[54:57]
	v_mfma_f32_16x16x32_bf16 v[94:97], v[222:225], v[134:137], v[42:45]
	v_mfma_f32_16x16x32_bf16 v[70:73], v[150:153], v[134:137], v[38:41]
	s_setprio 0
	s_setprio 1
	v_mfma_f32_16x16x32_bf16 v[30:33], v[162:165], v[122:125], v[30:33]
	v_mfma_f32_16x16x32_bf16 v[22:25], v[166:169], v[122:125], v[22:25]
	v_mfma_f32_16x16x32_bf16 v[54:57], v[130:133], v[196:199], v[30:33]
	v_mfma_f32_16x16x32_bf16 v[30:33], v[162:165], v[200:203], v[142:145]
	v_mfma_f32_16x16x32_bf16 v[42:45], v[170:173], v[196:199], v[22:25]
	v_mfma_f32_16x16x32_bf16 v[22:25], v[166:169], v[200:203], v[154:157]
	v_mfma_f32_16x16x32_bf16 v[10:13], v[174:177], v[200:203], v[10:13]
	v_mfma_f32_16x16x32_bf16 v[62:65], v[130:133], v[206:209], v[30:33]
	v_mfma_f32_16x16x32_bf16 v[38:41], v[170:173], v[206:209], v[22:25]
	v_mfma_f32_16x16x32_bf16 v[22:25], v[174:177], v[122:125], v[158:161]
	v_mfma_f32_16x16x32_bf16 v[30:33], v[222:225], v[206:209], v[10:13]
	v_mfma_f32_16x16x32_bf16 v[10:13], v[226:229], v[122:125], v[180:183]
	v_mfma_f32_16x16x32_bf16 v[122:125], v[226:229], v[200:203], v[146:149]
	v_mfma_f32_16x16x32_bf16 v[22:25], v[222:225], v[196:199], v[22:25]
	v_mfma_f32_16x16x32_bf16 v[10:13], v[150:153], v[196:199], v[10:13]
	v_mfma_f32_16x16x32_bf16 v[130:133], v[150:153], v[206:209], v[122:125]
	s_setprio 0
	s_cmp_gt_u32 s18, 3
	s_barrier
	s_cbranch_scc0 .LBB0_144
	s_mov_b64 s[8:9], -1
	s_and_b64 vcc, exec, s[12:13]
	s_cbranch_vccnz .LBB0_145

; #define STAGE_A(P, br, kt) do { const char* _g = (const char*)(A + (long)(br) * lda + (long)(kt) * BK); \
;     __builtin_amdgcn_global_load_lds((const unsigned*)(_g + (size_t)offA0), (unsigned*)((char*)(P) + sb0), 16, 0, 0); \
;     __builtin_amdgcn_global_load_lds((const unsigned*)(_g + (size_t)lda * 128 + (size_t)offA0), (unsigned*)((char*)(P) + sb1), 16, 0, 0); } while (0)
; #define STAGE_B(P, br, kt) do { const char* _g = (const char*)(B + (long)(br) * ldb + (long)(kt) * BK); \
;     __builtin_amdgcn_global_load_lds((const unsigned*)(_g + (size_t)offB0), (unsigned*)((char*)(P) + sb0), 16, 0, 0); \
;     __builtin_amdgcn_global_load_lds((const unsigned*)(_g + (size_t)ldb * 128 + (size_t)offB0), (unsigned*)((char*)(P) + sb1), 16, 0, 0); } while (0)
; #define LDA(dst, b, h) for (int m = 0; m < 4; ++m) for (int k = 0; k < 2; ++k) \
;     dst[m][k] = *reinterpret_cast<const bf16x8*>((char*)SA(b, h) + lds_byte(wr * 64 + m * 16 + fr, k * 32 + fq * 8))
; #define LDB(dst, b, h) for (int n = 0; n < 2; ++n) for (int k = 0; k < 2; ++k) \
;     dst[n][k] = *reinterpret_cast<const bf16x8*>((char*)SB(b, h) + lds_byte(wc * 32 + n * 16 + fr, k * 32 + fq * 8))
; #define WAIT_V(n) asm volatile("s_waitcnt vmcnt(" #n ")" ::: "memory")
; #define WAIT_L(n) asm volatile("s_waitcnt lgkmcnt(" #n ")" ::: "memory")
; DI void gemm_core(WVP char* smem, const u16* __restrict__ A, int lda, int ar0, int ar1,
;                   const u16* __restrict__ B, int ldb, int bc0, int K, AccT& acc) {
;     ...
;   __syncthreads();
;   STAGE_B(SB(0, 0), bb0, 0); STAGE_A(SA(0, 0), ac0, 0);
;   STAGE_B(SB(0, 1), bb1, 0); STAGE_A(SA(0, 1), ac1, 0);
;   if (wr == 1) BAR;
;   WAIT_V(4); BAR;
;   STAGE_B(SB(1, 0), bb0, 1); STAGE_A(SA(1, 0), ac0, 1); STAGE_B(SB(1, 1), bb1, 1);
;   WAIT_V(6); BAR;
;   for (int t = 0; t < nt - 2; t += 2) {
;     LDB(B0, 0, 0); SCHED; LDA(At, 0, 0); STAGE_A(SA(1, 1), ac1, t + 1);
;     WAIT_L(8); BAR; WAIT_L(0); MMA(0, 0, At, B0); BAR; SCHED;
;     LDB(B1, 0, 1); STAGE_B(SB(0, 0), bb0, t + 2);
;     BAR; WAIT_L(0); MMA(0, 1, At, B1); BAR;
;     LDA(At, 0, 1); STAGE_A(SA(0, 0), ac0, t + 2);
;     BAR; WAIT_L(0); MMA(1, 0, At, B0); BAR; SCHED;
;     STAGE_B(SB(0, 1), bb1, t + 2);
;     WAIT_V(6); BAR; MMA(1, 1, At, B1); BAR;
;     LDB(B0, 1, 0); SCHED; LDA(At, 1, 0); STAGE_A(SA(0, 1), ac1, t + 2);
;     WAIT_L(8); BAR; WAIT_L(0); MMA(0, 0, At, B0); BAR; SCHED;
.LBB0_168:
	v_add_u32_e32 v141, s61, v12
	s_ashr_i32 s5, s1, 6
	v_readfirstlane_b32 s1, v141
	v_add_u32_e32 v142, 0x2000, v141
	v_lshl_add_u64 v[14:15], v[2:3], 0, s[64:65]
	s_mov_b32 m0, s1
	v_readfirstlane_b32 s1, v142
	v_add_u32_e32 v143, 0x8000, v135
	s_waitcnt vmcnt(2)
	s_barrier
	global_load_lds_dwordx4 v[14:15], off
	v_lshl_add_u64 v[2:3], v[2:3], 0, s[78:79]
	s_mov_b32 m0, s1
	v_readfirstlane_b32 s1, v143
	v_add_u32_e32 v144, 0xa000, v135
	global_load_lds_dwordx4 v[2:3], off
	v_lshl_add_u64 v[2:3], v[4:5], 0, s[64:65]
	s_mov_b32 m0, s1
	v_readfirstlane_b32 s1, v144
	v_add_u32_e32 v145, s84, v12
	global_load_lds_dwordx4 v[2:3], off
	v_lshl_add_u64 v[2:3], v[4:5], 0, s[78:79]
	s_mov_b32 m0, s1
	v_readfirstlane_b32 s1, v145
	v_add_u32_e32 v146, 0x2000, v145
	global_load_lds_dwordx4 v[2:3], off
	v_lshl_add_u64 v[2:3], v[6:7], 0, s[64:65]
	s_mov_b32 m0, s1
	v_readfirstlane_b32 s1, v146
	global_load_lds_dwordx4 v[2:3], off
	v_lshl_add_u64 v[2:3], v[6:7], 0, s[78:79]
	s_mov_b32 m0, s1
	v_and_b32_e32 v0, 15, v9
	global_load_lds_dwordx4 v[2:3], off
	v_lshlrev_b32_e32 v2, 2, v9
	v_and_b32_e32 v13, 48, v9
	v_lshlrev_b32_e32 v0, 6, v0
	v_and_b32_e32 v2, 32, v2
	s_lshl_b32 s1, s5, 12
	v_bitop3_b32 v0, v0, v2, v13 bitop3:0x36
	s_lshl_b32 s20, s0, 13
	s_and_b32 s19, s1, 0x3000
	v_add_u32_e32 v3, s9, v0
	s_or_b32 s0, s20, 0x800
	s_or_b32 s1, s20, 0x1000
	s_or_b32 s9, s20, 0x1800
	s_add_u32 s12, s54, s12
	s_addc_u32 s13, s55, s13
	s_sub_i32 s14, s14, s17
	s_lshl_b32 s15, s15, 9
	s_sub_i32 s14, s14, s15
	s_sext_i32_i16 s14, s14
	s_lshl_b32 s14, s14, 7
	s_add_i32 s16, s16, s14
	s_ashr_i32 s17, s16, 31
	v_add_u32_e32 v4, s60, v0
	v_add_u32_e32 v5, s61, v0
	v_add_u32_e32 v6, s84, v0
	v_add_u32_e32 v7, 0, v0
	v_lshlrev_b32_e32 v0, 6, v9
	s_lshl_b64 s[14:15], s[16:17], 11
	v_and_or_b32 v0, v0, s74, v13
	s_add_u32 s14, s54, s14
	v_xad_u32 v148, v0, v2, 0
	v_lshlrev_b32_e32 v0, 14, v8
	s_addc_u32 s15, s55, s15
	s_addk_i32 s16, 0xb00
	v_and_b32_e32 v0, 0xffff8000, v0
	s_ashr_i32 s17, s16, 31
	s_waitcnt vmcnt(6)
	v_lshl_add_u32 v0, v10, 11, v0
	v_and_b32_e32 v2, 1, v8
	s_lshl_b64 s[16:17], s[16:17], 11
	v_lshl_or_b32 v0, v2, 6, v0
	s_add_u32 s16, s54, s16
	v_mov_b32_e32 v2, 0
	v_lshl_add_u32 v0, v11, 1, v0
	s_addc_u32 s17, s55, s17
	s_mov_b32 s18, -2
	v_add_u32_e32 v149, s19, v3
	v_add_u32_e32 v132, s20, v7
	v_add_u32_e32 v147, s19, v4
	v_add_u32_e32 v137, s19, v5
	v_add_u32_e32 v134, s19, v6
	v_mov_b32_e32 v3, v2
	v_mov_b32_e32 v4, v2
	v_mov_b32_e32 v5, v2
	v_mov_b32_e32 v6, v2
	v_mov_b32_e32 v7, v2
	v_mov_b32_e32 v8, v2
	v_mov_b32_e32 v9, v2
	v_mov_b32_e32 v10, v2
	v_mov_b32_e32 v11, v2
	v_mov_b32_e32 v12, v2
	v_mov_b32_e32 v13, v2
	v_mov_b32_e32 v14, v2
	v_mov_b32_e32 v15, v2
	s_mov_b64 s[22:23], 0x1e880100
	s_mov_b64 s[24:25], 0x1e8a0100
	s_barrier
.LBB0_169:
	v_add_u32_e32 v150, s0, v148
	v_add_u32_e32 v151, s1, v148
	v_add_u32_e32 v152, s9, v148
	ds_read_b128 v[156:159], v149
	ds_read_b128 v[160:163], v149 offset:1024
	ds_read_b128 v[164:167], v149 offset:2048
	ds_read_b128 v[168:171], v149 offset:3072
	ds_read_b128 v[172:175], v132
	ds_read_b128 v[176:179], v132 offset:1024
	ds_read_b128 v[180:183], v150
	ds_read_b128 v[184:187], v150 offset:1024
	ds_read_b128 v[188:191], v151
	ds_read_b128 v[192:195], v151 offset:1024
	ds_read_b128 v[196:199], v152
	ds_read_b128 v[200:203], v152 offset:1024
	ds_read_b128 v[206:209], v147
	ds_read_b128 v[210:213], v147 offset:1024
	ds_read_b128 v[214:217], v147 offset:2048
	ds_read_b128 v[218:221], v147 offset:3072
	v_add_u32_e32 v153, 0xc000, v135
	v_lshl_add_u64 v[224:225], s[16:17], 0, v[0:1]
	s_mov_b64 s[20:21], 0x1e880080
	v_lshl_add_u64 v[222:223], v[224:225], 0, s[20:21]
	v_readfirstlane_b32 s19, v153
	s_mov_b32 m0, s19
	s_nop 0
	global_load_lds_dwordx4 v[222:223], off
	v_add_u32_e32 v154, 0xe000, v135
	v_lshl_add_u64 v[224:225], s[16:17], 0, v[0:1]
	s_mov_b64 s[20:21], 0x1e8a0080
	v_lshl_add_u64 v[222:223], v[224:225], 0, s[20:21]
	v_readfirstlane_b32 s19, v154
	s_mov_b32 m0, s19
	s_nop 0
	global_load_lds_dwordx4 v[222:223], off
	s_waitcnt vmcnt(8)
	s_waitcnt lgkmcnt(0)
	s_barrier
	s_setprio 1
	v_mfma_f32_16x16x32_bf16 v[126:129], v[172:175], v[156:159], v[126:129]
	v_mfma_f32_16x16x32_bf16 v[122:125], v[172:175], v[164:167], v[122:125]
	v_mfma_f32_16x16x32_bf16 v[118:121], v[180:183], v[156:159], v[118:121]
	v_mfma_f32_16x16x32_bf16 v[114:117], v[180:183], v[164:167], v[114:117]
	v_mfma_f32_16x16x32_bf16 v[110:113], v[188:191], v[156:159], v[110:113]
	v_mfma_f32_16x16x32_bf16 v[106:109], v[188:191], v[164:167], v[106:109]
	v_mfma_f32_16x16x32_bf16 v[102:105], v[196:199], v[156:159], v[102:105]
	v_mfma_f32_16x16x32_bf16 v[98:101], v[196:199], v[164:167], v[98:101]
	v_mfma_f32_16x16x32_bf16 v[126:129], v[176:179], v[160:163], v[126:129]
	v_mfma_f32_16x16x32_bf16 v[122:125], v[176:179], v[168:171], v[122:125]
	v_mfma_f32_16x16x32_bf16 v[118:121], v[184:187], v[160:163], v[118:121]
	v_mfma_f32_16x16x32_bf16 v[114:117], v[184:187], v[168:171], v[114:117]
	v_mfma_f32_16x16x32_bf16 v[110:113], v[192:195], v[160:163], v[110:113]
	v_mfma_f32_16x16x32_bf16 v[106:109], v[192:195], v[168:171], v[106:109]
	v_mfma_f32_16x16x32_bf16 v[102:105], v[200:203], v[160:163], v[102:105]
	v_mfma_f32_16x16x32_bf16 v[98:101], v[200:203], v[168:171], v[98:101]
	v_mfma_f32_16x16x32_bf16 v[94:97], v[172:175], v[206:209], v[94:97]
	v_mfma_f32_16x16x32_bf16 v[90:93], v[172:175], v[214:217], v[90:93]
	v_mfma_f32_16x16x32_bf16 v[86:89], v[180:183], v[206:209], v[86:89]
	v_mfma_f32_16x16x32_bf16 v[82:85], v[180:183], v[214:217], v[82:85]
	v_mfma_f32_16x16x32_bf16 v[78:81], v[188:191], v[206:209], v[78:81]
	v_mfma_f32_16x16x32_bf16 v[74:77], v[188:191], v[214:217], v[74:77]
	v_mfma_f32_16x16x32_bf16 v[70:73], v[196:199], v[206:209], v[70:73]
	v_mfma_f32_16x16x32_bf16 v[66:69], v[196:199], v[214:217], v[66:69]
	v_mfma_f32_16x16x32_bf16 v[94:97], v[176:179], v[210:213], v[94:97]
	v_mfma_f32_16x16x32_bf16 v[90:93], v[176:179], v[218:221], v[90:93]
	v_mfma_f32_16x16x32_bf16 v[86:89], v[184:187], v[210:213], v[86:89]
	v_mfma_f32_16x16x32_bf16 v[82:85], v[184:187], v[218:221], v[82:85]
	v_mfma_f32_16x16x32_bf16 v[78:81], v[192:195], v[210:213], v[78:81]
	v_mfma_f32_16x16x32_bf16 v[74:77], v[192:195], v[218:221], v[74:77]
	v_mfma_f32_16x16x32_bf16 v[70:73], v[200:203], v[210:213], v[70:73]
	v_mfma_f32_16x16x32_bf16 v[66:69], v[200:203], v[218:221], v[66:69]
	s_setprio 0
	s_barrier
; #define STAGE_A(P, br, kt) do { const char* _g = (const char*)(A + (long)(br) * lda + (long)(kt) * BK); \
;     __builtin_amdgcn_global_load_lds((const unsigned*)(_g + (size_t)offA0), (unsigned*)((char*)(P) + sb0), 16, 0, 0); \
;     __builtin_amdgcn_global_load_lds((const unsigned*)(_g + (size_t)lda * 128 + (size_t)offA0), (unsigned*)((char*)(P) + sb1), 16, 0, 0); } while (0)
; #define STAGE_B(P, br, kt) do { const char* _g = (const char*)(B + (long)(br) * ldb + (long)(kt) * BK); \
;     __builtin_amdgcn_global_load_lds((const unsigned*)(_g + (size_t)offB0), (unsigned*)((char*)(P) + sb0), 16, 0, 0); \
;     __builtin_amdgcn_global_load_lds((const unsigned*)(_g + (size_t)ldb * 128 + (size_t)offB0), (unsigned*)((char*)(P) + sb1), 16, 0, 0); } while (0)
; #define LDA(dst, b, h) for (int m = 0; m < 4; ++m) for (int k = 0; k < 2; ++k) \
;     dst[m][k] = *reinterpret_cast<const bf16x8*>((char*)SA(b, h) + lds_byte(wr * 64 + m * 16 + fr, k * 32 + fq * 8))
; #define LDB(dst, b, h) for (int n = 0; n < 2; ++n) for (int k = 0; k < 2; ++k) \
;     dst[n][k] = *reinterpret_cast<const bf16x8*>((char*)SB(b, h) + lds_byte(wc * 32 + n * 16 + fr, k * 32 + fq * 8))
; #define MMA(ai, bj, At_, Bt_) do { __builtin_amdgcn_s_setprio(1); \
;     for (int m = 0; m < 4; ++m) for (int n = 0; n < 2; ++n) for (int k = 0; k < 2; ++k) \
;       acc[ai][bj][m][n] = MFMA16(At_[m][k], Bt_[n][k], acc[ai][bj][m][n]); \
;     __builtin_amdgcn_s_setprio(0); } while (0)
; #define WAIT_V(n) asm volatile("s_waitcnt vmcnt(" #n ")" ::: "memory")
; #define WAIT_L(n) asm volatile("s_waitcnt lgkmcnt(" #n ")" ::: "memory")
; #define BAR __builtin_amdgcn_s_barrier()
; #define SCHED __builtin_amdgcn_sched_barrier(0)
; DI void gemm_core(WVP char* smem, const u16* __restrict__ A, int lda, int ar0, int ar1,
;                   const u16* __restrict__ B, int ldb, int bc0, int K, AccT& acc) {
;     ...
;     LDA(At, 0, 1); STAGE_A(SA(0, 0), ac0, t + 2);
;     BAR; WAIT_L(0); MMA(1, 0, At, B0); BAR; SCHED;
;     STAGE_B(SB(0, 1), bb1, t + 2);
;     WAIT_V(6); BAR; MMA(1, 1, At, B1); BAR;
;     LDB(B0, 1, 0); SCHED; LDA(At, 1, 0); STAGE_A(SA(0, 1), ac1, t + 2);
;     WAIT_L(8); BAR; WAIT_L(0); MMA(0, 0, At, B0); BAR; SCHED;
;     LDB(B1, 1, 1); STAGE_B(SB(1, 0), bb0, t + 3);
;     BAR; WAIT_L(0); MMA(0, 1, At, B1); BAR;
	ds_read_b128 v[172:175], v132 offset:16384
	ds_read_b128 v[176:179], v132 offset:17408
	ds_read_b128 v[180:183], v150 offset:16384
	ds_read_b128 v[184:187], v150 offset:17408
	ds_read_b128 v[188:191], v151 offset:16384
	ds_read_b128 v[192:195], v151 offset:17408
	ds_read_b128 v[196:199], v152 offset:16384
	ds_read_b128 v[200:203], v152 offset:17408
	v_lshl_add_u64 v[224:225], s[12:13], 0, v[0:1]
	v_lshl_add_u64 v[222:223], v[224:225], 0, s[80:81]
	v_readfirstlane_b32 s19, v133
	s_mov_b32 m0, s19
	s_nop 0
	global_load_lds_dwordx4 v[222:223], off
	v_add_u32_e32 v155, 0x2000, v133
	v_lshl_add_u64 v[224:225], s[12:13], 0, v[0:1]
	v_lshl_add_u64 v[222:223], v[224:225], 0, s[82:83]
	v_readfirstlane_b32 s19, v155
	s_mov_b32 m0, s19
	s_nop 0
	global_load_lds_dwordx4 v[222:223], off
	v_lshl_add_u64 v[224:225], s[14:15], 0, v[0:1]
	v_lshl_add_u64 v[222:223], v[224:225], 0, s[22:23]
	v_readfirstlane_b32 s19, v135
	s_mov_b32 m0, s19
	s_nop 0
	global_load_lds_dwordx4 v[222:223], off
	v_lshl_add_u64 v[224:225], s[14:15], 0, v[0:1]
	v_lshl_add_u64 v[222:223], v[224:225], 0, s[24:25]
	v_readfirstlane_b32 s19, v136
	s_mov_b32 m0, s19
	s_nop 0
	global_load_lds_dwordx4 v[222:223], off
	v_lshl_add_u64 v[224:225], s[12:13], 0, v[0:1]
	v_lshl_add_u64 v[222:223], v[224:225], 0, s[88:89]
	v_readfirstlane_b32 s19, v138
	s_mov_b32 m0, s19
	s_nop 0
	global_load_lds_dwordx4 v[222:223], off
	v_add_u32_e32 v155, 0x2000, v138
	v_lshl_add_u64 v[224:225], s[12:13], 0, v[0:1]
	v_lshl_add_u64 v[222:223], v[224:225], 0, s[90:91]
	v_readfirstlane_b32 s19, v155
	s_mov_b32 m0, s19
	s_nop 0
	global_load_lds_dwordx4 v[222:223], off
	s_waitcnt vmcnt(8)
	s_waitcnt lgkmcnt(0)
	s_barrier
	s_setprio 1
	v_mfma_f32_16x16x32_bf16 v[62:65], v[172:175], v[156:159], v[62:65]
	v_mfma_f32_16x16x32_bf16 v[58:61], v[172:175], v[164:167], v[58:61]
	v_mfma_f32_16x16x32_bf16 v[54:57], v[180:183], v[156:159], v[54:57]
	v_mfma_f32_16x16x32_bf16 v[50:53], v[180:183], v[164:167], v[50:53]
	v_mfma_f32_16x16x32_bf16 v[46:49], v[188:191], v[156:159], v[46:49]
	v_mfma_f32_16x16x32_bf16 v[42:45], v[188:191], v[164:167], v[42:45]
	v_mfma_f32_16x16x32_bf16 v[38:41], v[196:199], v[156:159], v[38:41]
	v_mfma_f32_16x16x32_bf16 v[34:37], v[196:199], v[164:167], v[34:37]
	v_mfma_f32_16x16x32_bf16 v[62:65], v[176:179], v[160:163], v[62:65]
	v_mfma_f32_16x16x32_bf16 v[58:61], v[176:179], v[168:171], v[58:61]
	v_mfma_f32_16x16x32_bf16 v[54:57], v[184:187], v[160:163], v[54:57]
	v_mfma_f32_16x16x32_bf16 v[50:53], v[184:187], v[168:171], v[50:53]
	v_mfma_f32_16x16x32_bf16 v[46:49], v[192:195], v[160:163], v[46:49]
	v_mfma_f32_16x16x32_bf16 v[42:45], v[192:195], v[168:171], v[42:45]
	v_mfma_f32_16x16x32_bf16 v[38:41], v[200:203], v[160:163], v[38:41]
	v_mfma_f32_16x16x32_bf16 v[34:37], v[200:203], v[168:171], v[34:37]
	v_mfma_f32_16x16x32_bf16 v[30:33], v[172:175], v[206:209], v[30:33]
	v_mfma_f32_16x16x32_bf16 v[26:29], v[172:175], v[214:217], v[26:29]
	v_mfma_f32_16x16x32_bf16 v[22:25], v[180:183], v[206:209], v[22:25]
	v_mfma_f32_16x16x32_bf16 v[18:21], v[180:183], v[214:217], v[18:21]
	v_mfma_f32_16x16x32_bf16 v[14:17], v[188:191], v[206:209], v[14:17]
	v_mfma_f32_16x16x32_bf16 v[10:13], v[188:191], v[214:217], v[10:13]
	v_mfma_f32_16x16x32_bf16 v[6:9], v[196:199], v[206:209], v[6:9]
	v_mfma_f32_16x16x32_bf16 v[2:5], v[196:199], v[214:217], v[2:5]
	v_mfma_f32_16x16x32_bf16 v[30:33], v[176:179], v[210:213], v[30:33]
	v_mfma_f32_16x16x32_bf16 v[26:29], v[176:179], v[218:221], v[26:29]
	v_mfma_f32_16x16x32_bf16 v[22:25], v[184:187], v[210:213], v[22:25]
	v_mfma_f32_16x16x32_bf16 v[18:21], v[184:187], v[218:221], v[18:21]
	v_mfma_f32_16x16x32_bf16 v[14:17], v[192:195], v[210:213], v[14:17]
	v_mfma_f32_16x16x32_bf16 v[10:13], v[192:195], v[218:221], v[10:13]
	v_mfma_f32_16x16x32_bf16 v[6:9], v[200:203], v[210:213], v[6:9]
	v_mfma_f32_16x16x32_bf16 v[2:5], v[200:203], v[218:221], v[2:5]
	s_setprio 0
	s_barrier
	ds_read_b128 v[156:159], v137
	ds_read_b128 v[160:163], v137 offset:1024
	ds_read_b128 v[164:167], v137 offset:2048
	ds_read_b128 v[168:171], v137 offset:3072
	ds_read_b128 v[172:175], v132 offset:32768
	ds_read_b128 v[176:179], v132 offset:33792
	ds_read_b128 v[180:183], v150 offset:32768
	ds_read_b128 v[184:187], v150 offset:33792
	ds_read_b128 v[188:191], v151 offset:32768
	ds_read_b128 v[192:195], v151 offset:33792
	ds_read_b128 v[196:199], v152 offset:32768
	ds_read_b128 v[200:203], v152 offset:33792
	ds_read_b128 v[206:209], v134
	ds_read_b128 v[210:213], v134 offset:1024
	ds_read_b128 v[214:217], v134 offset:2048
	ds_read_b128 v[218:221], v134 offset:3072
	v_lshl_add_u64 v[224:225], s[16:17], 0, v[0:1]
	v_lshl_add_u64 v[222:223], v[224:225], 0, s[22:23]
	v_readfirstlane_b32 s19, v139
	s_mov_b32 m0, s19
	s_nop 0
	global_load_lds_dwordx4 v[222:223], off
	v_lshl_add_u64 v[224:225], s[16:17], 0, v[0:1]
	v_lshl_add_u64 v[222:223], v[224:225], 0, s[24:25]
	v_readfirstlane_b32 s19, v140
	s_mov_b32 m0, s19
	s_nop 0
	global_load_lds_dwordx4 v[222:223], off
	s_waitcnt vmcnt(8)
	s_waitcnt lgkmcnt(0)
	s_barrier
; #define STAGE_A(P, br, kt) do { const char* _g = (const char*)(A + (long)(br) * lda + (long)(kt) * BK); \
;     __builtin_amdgcn_global_load_lds((const unsigned*)(_g + (size_t)offA0), (unsigned*)((char*)(P) + sb0), 16, 0, 0); \
;     __builtin_amdgcn_global_load_lds((const unsigned*)(_g + (size_t)lda * 128 + (size_t)offA0), (unsigned*)((char*)(P) + sb1), 16, 0, 0); } while (0)
; #define STAGE_B(P, br, kt) do { const char* _g = (const char*)(B + (long)(br) * ldb + (long)(kt) * BK); \
;     __builtin_amdgcn_global_load_lds((const unsigned*)(_g + (size_t)offB0), (unsigned*)((char*)(P) + sb0), 16, 0, 0); \
;     __builtin_amdgcn_global_load_lds((const unsigned*)(_g + (size_t)ldb * 128 + (size_t)offB0), (unsigned*)((char*)(P) + sb1), 16, 0, 0); } while (0)
; #define LDA(dst, b, h) for (int m = 0; m < 4; ++m) for (int k = 0; k < 2; ++k) \
;     dst[m][k] = *reinterpret_cast<const bf16x8*>((char*)SA(b, h) + lds_byte(wr * 64 + m * 16 + fr, k * 32 + fq * 8))
; #define LDB(dst, b, h) for (int n = 0; n < 2; ++n) for (int k = 0; k < 2; ++k) \
;     dst[n][k] = *reinterpret_cast<const bf16x8*>((char*)SB(b, h) + lds_byte(wc * 32 + n * 16 + fr, k * 32 + fq * 8))
; #define MMA(ai, bj, At_, Bt_) do { __builtin_amdgcn_s_setprio(1); \
;     for (int m = 0; m < 4; ++m) for (int n = 0; n < 2; ++n) for (int k = 0; k < 2; ++k) \
;       acc[ai][bj][m][n] = MFMA16(At_[m][k], Bt_[n][k], acc[ai][bj][m][n]); \
;     __builtin_amdgcn_s_setprio(0); } while (0)
; #define WAIT_V(n) asm volatile("s_waitcnt vmcnt(" #n ")" ::: "memory")
; #define WAIT_L(n) asm volatile("s_waitcnt lgkmcnt(" #n ")" ::: "memory")
; #define BAR __builtin_amdgcn_s_barrier()
; #define SCHED __builtin_amdgcn_sched_barrier(0)
; DI void gemm_core(WVP char* smem, const u16* __restrict__ A, int lda, int ar0, int ar1,
;                   const u16* __restrict__ B, int ldb, int bc0, int K, AccT& acc) {
;     ...
;     WAIT_L(8); BAR; WAIT_L(0); MMA(0, 0, At, B0); BAR; SCHED;
;     LDB(B1, 1, 1); STAGE_B(SB(1, 0), bb0, t + 3);
;     BAR; WAIT_L(0); MMA(0, 1, At, B1); BAR;
;     LDA(At, 1, 1); STAGE_A(SA(1, 0), ac0, t + 3);
;     BAR; WAIT_L(0); MMA(1, 0, At, B0); BAR; SCHED;
;     STAGE_B(SB(1, 1), bb1, t + 3);
;     WAIT_V(6); BAR; MMA(1, 1, At, B1); BAR;
;   }
	s_setprio 1
	v_mfma_f32_16x16x32_bf16 v[126:129], v[172:175], v[156:159], v[126:129]
	v_mfma_f32_16x16x32_bf16 v[122:125], v[172:175], v[164:167], v[122:125]
	v_mfma_f32_16x16x32_bf16 v[118:121], v[180:183], v[156:159], v[118:121]
	v_mfma_f32_16x16x32_bf16 v[114:117], v[180:183], v[164:167], v[114:117]
	v_mfma_f32_16x16x32_bf16 v[110:113], v[188:191], v[156:159], v[110:113]
	v_mfma_f32_16x16x32_bf16 v[106:109], v[188:191], v[164:167], v[106:109]
	v_mfma_f32_16x16x32_bf16 v[102:105], v[196:199], v[156:159], v[102:105]
	v_mfma_f32_16x16x32_bf16 v[98:101], v[196:199], v[164:167], v[98:101]
	v_mfma_f32_16x16x32_bf16 v[126:129], v[176:179], v[160:163], v[126:129]
	v_mfma_f32_16x16x32_bf16 v[122:125], v[176:179], v[168:171], v[122:125]
	v_mfma_f32_16x16x32_bf16 v[118:121], v[184:187], v[160:163], v[118:121]
	v_mfma_f32_16x16x32_bf16 v[114:117], v[184:187], v[168:171], v[114:117]
	v_mfma_f32_16x16x32_bf16 v[110:113], v[192:195], v[160:163], v[110:113]
	v_mfma_f32_16x16x32_bf16 v[106:109], v[192:195], v[168:171], v[106:109]
	v_mfma_f32_16x16x32_bf16 v[102:105], v[200:203], v[160:163], v[102:105]
	v_mfma_f32_16x16x32_bf16 v[98:101], v[200:203], v[168:171], v[98:101]
	v_mfma_f32_16x16x32_bf16 v[94:97], v[172:175], v[206:209], v[94:97]
	v_mfma_f32_16x16x32_bf16 v[90:93], v[172:175], v[214:217], v[90:93]
	v_mfma_f32_16x16x32_bf16 v[86:89], v[180:183], v[206:209], v[86:89]
	v_mfma_f32_16x16x32_bf16 v[82:85], v[180:183], v[214:217], v[82:85]
	v_mfma_f32_16x16x32_bf16 v[78:81], v[188:191], v[206:209], v[78:81]
	v_mfma_f32_16x16x32_bf16 v[74:77], v[188:191], v[214:217], v[74:77]
	v_mfma_f32_16x16x32_bf16 v[70:73], v[196:199], v[206:209], v[70:73]
	v_mfma_f32_16x16x32_bf16 v[66:69], v[196:199], v[214:217], v[66:69]
	v_mfma_f32_16x16x32_bf16 v[94:97], v[176:179], v[210:213], v[94:97]
	v_mfma_f32_16x16x32_bf16 v[90:93], v[176:179], v[218:221], v[90:93]
	v_mfma_f32_16x16x32_bf16 v[86:89], v[184:187], v[210:213], v[86:89]
	v_mfma_f32_16x16x32_bf16 v[82:85], v[184:187], v[218:221], v[82:85]
	v_mfma_f32_16x16x32_bf16 v[78:81], v[192:195], v[210:213], v[78:81]
	v_mfma_f32_16x16x32_bf16 v[74:77], v[192:195], v[218:221], v[74:77]
	v_mfma_f32_16x16x32_bf16 v[70:73], v[200:203], v[210:213], v[70:73]
	v_mfma_f32_16x16x32_bf16 v[66:69], v[200:203], v[218:221], v[66:69]
	s_setprio 0
	s_barrier
	ds_read_b128 v[172:175], v132 offset:49152
	ds_read_b128 v[176:179], v132 offset:50176
	ds_read_b128 v[180:183], v150 offset:49152
	ds_read_b128 v[184:187], v150 offset:50176
	ds_read_b128 v[188:191], v151 offset:49152
	ds_read_b128 v[192:195], v151 offset:50176
	ds_read_b128 v[196:199], v152 offset:49152
	ds_read_b128 v[200:203], v152 offset:50176
	v_lshl_add_u64 v[224:225], s[12:13], 0, v[0:1]
	v_lshl_add_u64 v[222:223], v[224:225], 0, s[92:93]
	v_readfirstlane_b32 s19, v141
	s_mov_b32 m0, s19
	s_nop 0
	global_load_lds_dwordx4 v[222:223], off
	v_lshl_add_u64 v[224:225], s[12:13], 0, v[0:1]
	v_lshl_add_u64 v[222:223], v[224:225], 0, s[94:95]
	v_readfirstlane_b32 s19, v142
	s_mov_b32 m0, s19
	s_nop 0
	global_load_lds_dwordx4 v[222:223], off
	v_lshl_add_u64 v[224:225], s[14:15], 0, v[0:1]
	s_mov_b64 s[20:21], 0x1e880180
	v_lshl_add_u64 v[222:223], v[224:225], 0, s[20:21]
	v_readfirstlane_b32 s19, v143
	s_mov_b32 m0, s19
	s_nop 0
	global_load_lds_dwordx4 v[222:223], off
	v_lshl_add_u64 v[224:225], s[14:15], 0, v[0:1]
	s_mov_b64 s[20:21], 0x1e8a0180
	v_lshl_add_u64 v[222:223], v[224:225], 0, s[20:21]
	v_readfirstlane_b32 s19, v144
	s_mov_b32 m0, s19
	s_nop 0
	global_load_lds_dwordx4 v[222:223], off
	v_lshl_add_u64 v[224:225], s[12:13], 0, v[0:1]
	v_lshl_add_u64 v[222:223], v[224:225], 0, s[96:97]
	v_readfirstlane_b32 s19, v145
	s_mov_b32 m0, s19
	s_nop 0
	global_load_lds_dwordx4 v[222:223], off
	v_lshl_add_u64 v[224:225], s[12:13], 0, v[0:1]
	v_lshl_add_u64 v[222:223], v[224:225], 0, s[72:73]
	v_readfirstlane_b32 s19, v146
	s_mov_b32 m0, s19
	s_nop 0
	global_load_lds_dwordx4 v[222:223], off
	s_waitcnt vmcnt(8)
	s_waitcnt lgkmcnt(0)
	s_barrier
	s_setprio 1
	v_mfma_f32_16x16x32_bf16 v[62:65], v[172:175], v[156:159], v[62:65]
	v_mfma_f32_16x16x32_bf16 v[58:61], v[172:175], v[164:167], v[58:61]
	v_mfma_f32_16x16x32_bf16 v[54:57], v[180:183], v[156:159], v[54:57]
	v_mfma_f32_16x16x32_bf16 v[50:53], v[180:183], v[164:167], v[50:53]
	v_mfma_f32_16x16x32_bf16 v[46:49], v[188:191], v[156:159], v[46:49]
	v_mfma_f32_16x16x32_bf16 v[42:45], v[188:191], v[164:167], v[42:45]
	v_mfma_f32_16x16x32_bf16 v[38:41], v[196:199], v[156:159], v[38:41]
	v_mfma_f32_16x16x32_bf16 v[34:37], v[196:199], v[164:167], v[34:37]
	v_mfma_f32_16x16x32_bf16 v[62:65], v[176:179], v[160:163], v[62:65]
	v_mfma_f32_16x16x32_bf16 v[58:61], v[176:179], v[168:171], v[58:61]
	v_mfma_f32_16x16x32_bf16 v[54:57], v[184:187], v[160:163], v[54:57]
	v_mfma_f32_16x16x32_bf16 v[50:53], v[184:187], v[168:171], v[50:53]
	v_mfma_f32_16x16x32_bf16 v[46:49], v[192:195], v[160:163], v[46:49]
	v_mfma_f32_16x16x32_bf16 v[42:45], v[192:195], v[168:171], v[42:45]
	v_mfma_f32_16x16x32_bf16 v[38:41], v[200:203], v[160:163], v[38:41]
	v_mfma_f32_16x16x32_bf16 v[34:37], v[200:203], v[168:171], v[34:37]
	v_mfma_f32_16x16x32_bf16 v[30:33], v[172:175], v[206:209], v[30:33]
	v_mfma_f32_16x16x32_bf16 v[26:29], v[172:175], v[214:217], v[26:29]
	v_mfma_f32_16x16x32_bf16 v[22:25], v[180:183], v[206:209], v[22:25]
	v_mfma_f32_16x16x32_bf16 v[18:21], v[180:183], v[214:217], v[18:21]
	v_mfma_f32_16x16x32_bf16 v[14:17], v[188:191], v[206:209], v[14:17]
	v_mfma_f32_16x16x32_bf16 v[10:13], v[188:191], v[214:217], v[10:13]
	v_mfma_f32_16x16x32_bf16 v[6:9], v[196:199], v[206:209], v[6:9]
	v_mfma_f32_16x16x32_bf16 v[2:5], v[196:199], v[214:217], v[2:5]
	v_mfma_f32_16x16x32_bf16 v[30:33], v[176:179], v[210:213], v[30:33]
	v_mfma_f32_16x16x32_bf16 v[26:29], v[176:179], v[218:221], v[26:29]
	v_mfma_f32_16x16x32_bf16 v[22:25], v[184:187], v[210:213], v[22:25]
	v_mfma_f32_16x16x32_bf16 v[18:21], v[184:187], v[218:221], v[18:21]
	v_mfma_f32_16x16x32_bf16 v[14:17], v[192:195], v[210:213], v[14:17]
	v_mfma_f32_16x16x32_bf16 v[10:13], v[192:195], v[218:221], v[10:13]
	v_mfma_f32_16x16x32_bf16 v[6:9], v[200:203], v[210:213], v[6:9]
	v_mfma_f32_16x16x32_bf16 v[2:5], v[200:203], v[218:221], v[2:5]
	s_setprio 0
	s_add_i32 s18, s18, 2
	s_add_u32 s12, s12, 0x100
	s_addc_u32 s13, s13, 0
	s_add_u32 s14, s14, 0x100
	s_addc_u32 s15, s15, 0
	s_add_u32 s16, s16, 0x100
	s_addc_u32 s17, s17, 0
	s_cmp_lt_u32 s18, 12
	s_barrier
; #define STAGE_A(P, br, kt) do { const char* _g = (const char*)(A + (long)(br) * lda + (long)(kt) * BK); \
;     __builtin_amdgcn_global_load_lds((const unsigned*)(_g + (size_t)offA0), (unsigned*)((char*)(P) + sb0), 16, 0, 0); \
;     __builtin_amdgcn_global_load_lds((const unsigned*)(_g + (size_t)lda * 128 + (size_t)offA0), (unsigned*)((char*)(P) + sb1), 16, 0, 0); } while (0)
; #define LDA(dst, b, h) for (int m = 0; m < 4; ++m) for (int k = 0; k < 2; ++k) \
;     dst[m][k] = *reinterpret_cast<const bf16x8*>((char*)SA(b, h) + lds_byte(wr * 64 + m * 16 + fr, k * 32 + fq * 8))
; #define LDB(dst, b, h) for (int n = 0; n < 2; ++n) for (int k = 0; k < 2; ++k) \
;     dst[n][k] = *reinterpret_cast<const bf16x8*>((char*)SB(b, h) + lds_byte(wc * 32 + n * 16 + fr, k * 32 + fq * 8))
; #define MMA(ai, bj, At_, Bt_) do { __builtin_amdgcn_s_setprio(1); \
;     for (int m = 0; m < 4; ++m) for (int n = 0; n < 2; ++n) for (int k = 0; k < 2; ++k) \
;       acc[ai][bj][m][n] = MFMA16(At_[m][k], Bt_[n][k], acc[ai][bj][m][n]); \
;     __builtin_amdgcn_s_setprio(0); } while (0)
; #define WAIT_V(n) asm volatile("s_waitcnt vmcnt(" #n ")" ::: "memory")
; #define WAIT_L(n) asm volatile("s_waitcnt lgkmcnt(" #n ")" ::: "memory")
; #define BAR __builtin_amdgcn_s_barrier()
; DI void gemm_core(WVP char* smem, const u16* __restrict__ A, int lda, int ar0, int ar1,
;                   const u16* __restrict__ B, int ldb, int bc0, int K, AccT& acc) {
;     ...
;   { LDB(B0, 0, 0); LDA(At, 0, 0); STAGE_A(SA(1, 1), ac1, nt - 1);
;     BAR; WAIT_L(0); MMA(0, 0, At, B0); BAR;
;     LDB(B1, 0, 1); BAR; WAIT_L(0); MMA(0, 1, At, B1); BAR;
;     LDA(At, 0, 1); WAIT_V(4); BAR; WAIT_L(0); MMA(1, 0, At, B0); MMA(1, 1, At, B1); BAR; }
;   { LDB(B0, 1, 0); LDA(At, 1, 0); WAIT_V(2); BAR; WAIT_L(0); MMA(0, 0, At, B0); BAR;
	s_cbranch_scc1 .LBB0_169
	s_mov_b64 s[0:1], 0x780
	ds_read_b128 v[138:141], v149
	ds_read_b128 v[142:145], v149 offset:1024
	ds_read_b128 v[156:159], v149 offset:2048
	ds_read_b128 v[160:163], v149 offset:3072
	ds_read_b128 v[164:167], v132
	ds_read_b128 v[168:171], v132 offset:1024
	ds_read_b128 v[172:175], v150
	ds_read_b128 v[176:179], v150 offset:1024
	ds_read_b128 v[180:183], v151
	ds_read_b128 v[184:187], v151 offset:1024
	ds_read_b128 v[188:191], v152
	ds_read_b128 v[192:195], v152 offset:1024
	v_lshl_add_u64 v[148:149], v[130:131], 0, s[0:1]
	v_readfirstlane_b32 s0, v153
	s_mov_b32 m0, s0
	s_mov_b64 s[0:1], 0x20780
	v_lshl_add_u64 v[130:131], v[130:131], 0, s[0:1]
	v_readfirstlane_b32 s0, v154
	global_load_lds_dwordx4 v[148:149], off
	s_mov_b32 m0, s0
	s_nop 0
	global_load_lds_dwordx4 v[130:131], off
	s_waitcnt vmcnt(8)
	s_barrier
	s_waitcnt lgkmcnt(0)
	s_setprio 1
	s_waitcnt lgkmcnt(0)
	v_mfma_f32_16x16x32_bf16 v[126:129], v[164:167], v[138:141], v[126:129]
	v_mfma_f32_16x16x32_bf16 v[118:121], v[172:175], v[138:141], v[118:121]
	v_mfma_f32_16x16x32_bf16 v[110:113], v[180:183], v[138:141], v[110:113]
	v_mfma_f32_16x16x32_bf16 v[102:105], v[188:191], v[138:141], v[102:105]
	v_mfma_f32_16x16x32_bf16 v[126:129], v[168:171], v[142:145], v[126:129]
	v_mfma_f32_16x16x32_bf16 v[122:125], v[164:167], v[156:159], v[122:125]
	v_mfma_f32_16x16x32_bf16 v[118:121], v[176:179], v[142:145], v[118:121]
	v_mfma_f32_16x16x32_bf16 v[114:117], v[172:175], v[156:159], v[114:117]
	v_mfma_f32_16x16x32_bf16 v[110:113], v[184:187], v[142:145], v[110:113]
	v_mfma_f32_16x16x32_bf16 v[106:109], v[180:183], v[156:159], v[106:109]
	v_mfma_f32_16x16x32_bf16 v[102:105], v[192:195], v[142:145], v[102:105]
	v_mfma_f32_16x16x32_bf16 v[98:101], v[188:191], v[156:159], v[98:101]
	v_mfma_f32_16x16x32_bf16 v[196:199], v[168:171], v[160:163], v[122:125]
	v_mfma_f32_16x16x32_bf16 v[200:203], v[176:179], v[160:163], v[114:117]
	v_mfma_f32_16x16x32_bf16 v[206:209], v[184:187], v[160:163], v[106:109]
	v_mfma_f32_16x16x32_bf16 v[210:213], v[192:195], v[160:163], v[98:101]
	s_setprio 0
	s_barrier
	s_nop 1
	ds_read_b128 v[98:101], v147
	ds_read_b128 v[106:109], v147 offset:1024
	ds_read_b128 v[114:117], v147 offset:2048
	ds_read_b128 v[122:125], v147 offset:3072
	s_barrier
	s_waitcnt lgkmcnt(0)
	s_setprio 1
	s_waitcnt lgkmcnt(0)
	v_mfma_f32_16x16x32_bf16 v[94:97], v[164:167], v[98:101], v[94:97]
	v_mfma_f32_16x16x32_bf16 v[86:89], v[172:175], v[98:101], v[86:89]
	v_mfma_f32_16x16x32_bf16 v[78:81], v[180:183], v[98:101], v[78:81]
	v_mfma_f32_16x16x32_bf16 v[70:73], v[188:191], v[98:101], v[70:73]
	v_mfma_f32_16x16x32_bf16 v[94:97], v[168:171], v[106:109], v[94:97]
	v_mfma_f32_16x16x32_bf16 v[90:93], v[164:167], v[114:117], v[90:93]
	v_mfma_f32_16x16x32_bf16 v[86:89], v[176:179], v[106:109], v[86:89]
	v_mfma_f32_16x16x32_bf16 v[82:85], v[172:175], v[114:117], v[82:85]
	v_mfma_f32_16x16x32_bf16 v[78:81], v[184:187], v[106:109], v[78:81]
	v_mfma_f32_16x16x32_bf16 v[74:77], v[180:183], v[114:117], v[74:77]
	v_mfma_f32_16x16x32_bf16 v[70:73], v[192:195], v[106:109], v[70:73]
	v_mfma_f32_16x16x32_bf16 v[66:69], v[188:191], v[114:117], v[66:69]
	v_mfma_f32_16x16x32_bf16 v[146:149], v[168:171], v[122:125], v[90:93]
	v_mfma_f32_16x16x32_bf16 v[164:167], v[176:179], v[122:125], v[82:85]
	v_mfma_f32_16x16x32_bf16 v[168:171], v[184:187], v[122:125], v[74:77]
	v_mfma_f32_16x16x32_bf16 v[172:175], v[192:195], v[122:125], v[66:69]
	s_setprio 0
	s_barrier
	s_nop 1
	ds_read_b128 v[66:69], v132 offset:16384
	ds_read_b128 v[74:77], v132 offset:17408
	ds_read_b128 v[82:85], v150 offset:16384
	ds_read_b128 v[90:93], v150 offset:17408
	ds_read_b128 v[176:179], v151 offset:16384
	ds_read_b128 v[180:183], v151 offset:17408
	ds_read_b128 v[184:187], v152 offset:16384
	ds_read_b128 v[188:191], v152 offset:17408
	s_waitcnt vmcnt(4)
	s_barrier
	s_waitcnt lgkmcnt(0)
	s_setprio 1
	s_waitcnt lgkmcnt(0)
	v_mfma_f32_16x16x32_bf16 v[62:65], v[66:69], v[138:141], v[62:65]
	v_mfma_f32_16x16x32_bf16 v[54:57], v[82:85], v[138:141], v[54:57]
	v_mfma_f32_16x16x32_bf16 v[46:49], v[176:179], v[138:141], v[46:49]
	v_mfma_f32_16x16x32_bf16 v[38:41], v[184:187], v[138:141], v[38:41]
	v_mfma_f32_16x16x32_bf16 v[62:65], v[74:77], v[142:145], v[62:65]
	v_mfma_f32_16x16x32_bf16 v[58:61], v[66:69], v[156:159], v[58:61]
	v_mfma_f32_16x16x32_bf16 v[54:57], v[90:93], v[142:145], v[54:57]
	v_mfma_f32_16x16x32_bf16 v[50:53], v[82:85], v[156:159], v[50:53]
	v_mfma_f32_16x16x32_bf16 v[46:49], v[180:183], v[142:145], v[46:49]
	v_mfma_f32_16x16x32_bf16 v[42:45], v[176:179], v[156:159], v[42:45]
	v_mfma_f32_16x16x32_bf16 v[38:41], v[188:191], v[142:145], v[38:41]
	v_mfma_f32_16x16x32_bf16 v[34:37], v[184:187], v[156:159], v[34:37]
	v_mfma_f32_16x16x32_bf16 v[192:195], v[74:77], v[160:163], v[58:61]
	v_mfma_f32_16x16x32_bf16 v[214:217], v[90:93], v[160:163], v[50:53]
	v_mfma_f32_16x16x32_bf16 v[218:221], v[180:183], v[160:163], v[42:45]
	v_mfma_f32_16x16x32_bf16 v[138:141], v[188:191], v[160:163], v[34:37]
	s_setprio 0
	s_setprio 1
	v_mfma_f32_16x16x32_bf16 v[30:33], v[66:69], v[98:101], v[30:33]
	v_mfma_f32_16x16x32_bf16 v[22:25], v[82:85], v[98:101], v[22:25]
	v_mfma_f32_16x16x32_bf16 v[14:17], v[176:179], v[98:101], v[14:17]
	v_mfma_f32_16x16x32_bf16 v[6:9], v[184:187], v[98:101], v[6:9]
	v_mfma_f32_16x16x32_bf16 v[30:33], v[74:77], v[106:109], v[30:33]
	v_mfma_f32_16x16x32_bf16 v[26:29], v[66:69], v[114:117], v[26:29]
	v_mfma_f32_16x16x32_bf16 v[22:25], v[90:93], v[106:109], v[22:25]
	v_mfma_f32_16x16x32_bf16 v[18:21], v[82:85], v[114:117], v[18:21]
	v_mfma_f32_16x16x32_bf16 v[14:17], v[180:183], v[106:109], v[14:17]
	v_mfma_f32_16x16x32_bf16 v[10:13], v[176:179], v[114:117], v[10:13]
	v_mfma_f32_16x16x32_bf16 v[6:9], v[188:191], v[106:109], v[6:9]
	v_mfma_f32_16x16x32_bf16 v[2:5], v[184:187], v[114:117], v[2:5]
	v_mfma_f32_16x16x32_bf16 v[142:145], v[74:77], v[122:125], v[26:29]
	v_mfma_f32_16x16x32_bf16 v[154:157], v[90:93], v[122:125], v[18:21]
	v_mfma_f32_16x16x32_bf16 v[158:161], v[180:183], v[122:125], v[10:13]
	v_mfma_f32_16x16x32_bf16 v[176:179], v[188:191], v[122:125], v[2:5]
	s_setprio 0
	s_barrier
; #define LDA(dst, b, h) for (int m = 0; m < 4; ++m) for (int k = 0; k < 2; ++k) \
;     dst[m][k] = *reinterpret_cast<const bf16x8*>((char*)SA(b, h) + lds_byte(wr * 64 + m * 16 + fr, k * 32 + fq * 8))
; #define LDB(dst, b, h) for (int n = 0; n < 2; ++n) for (int k = 0; k < 2; ++k) \
;     dst[n][k] = *reinterpret_cast<const bf16x8*>((char*)SB(b, h) + lds_byte(wc * 32 + n * 16 + fr, k * 32 + fq * 8))
; #define MMA(ai, bj, At_, Bt_) do { __builtin_amdgcn_s_setprio(1); \
;     for (int m = 0; m < 4; ++m) for (int n = 0; n < 2; ++n) for (int k = 0; k < 2; ++k) \
;       acc[ai][bj][m][n] = MFMA16(At_[m][k], Bt_[n][k], acc[ai][bj][m][n]); \
;     __builtin_amdgcn_s_setprio(0); } while (0)
; #define WAIT_V(n) asm volatile("s_waitcnt vmcnt(" #n ")" ::: "memory")
; #define WAIT_L(n) asm volatile("s_waitcnt lgkmcnt(" #n ")" ::: "memory")
; #define BAR __builtin_amdgcn_s_barrier()
; DI void gemm_core(WVP char* smem, const u16* __restrict__ A, int lda, int ar0, int ar1,
;                   const u16* __restrict__ B, int ldb, int bc0, int K, AccT& acc) {
;     ...
;     LDA(At, 0, 1); WAIT_V(4); BAR; WAIT_L(0); MMA(1, 0, At, B0); MMA(1, 1, At, B1); BAR; }
;   { LDB(B0, 1, 0); LDA(At, 1, 0); WAIT_V(2); BAR; WAIT_L(0); MMA(0, 0, At, B0); BAR;
;     LDB(B1, 1, 1); WAIT_V(0); BAR; WAIT_L(0); MMA(0, 1, At, B1); BAR;
;     LDA(At, 1, 1); BAR; WAIT_L(0); MMA(1, 0, At, B0); MMA(1, 1, At, B1); BAR; }
;   if (wr == 0) BAR;
	ds_read_b128 v[180:183], v137
	ds_read_b128 v[184:187], v137 offset:1024
	ds_read_b128 v[188:191], v137 offset:2048
	ds_read_b128 v[222:225], v137 offset:3072
	ds_read_b128 v[2:5], v132 offset:32768
	ds_read_b128 v[10:13], v132 offset:33792
	ds_read_b128 v[18:21], v150 offset:32768
	ds_read_b128 v[26:29], v150 offset:33792
	ds_read_b128 v[226:229], v151 offset:32768
	ds_read_b128 v[230:233], v151 offset:33792
	ds_read_b128 v[234:237], v152 offset:32768
	ds_read_b128 v[238:241], v152 offset:33792
	s_waitcnt vmcnt(2)
	s_barrier
	s_waitcnt lgkmcnt(0)
	s_setprio 1
	s_waitcnt lgkmcnt(0)
	v_mfma_f32_16x16x32_bf16 v[34:37], v[2:5], v[180:183], v[126:129]
	v_mfma_f32_16x16x32_bf16 v[122:125], v[10:13], v[184:187], v[34:37]
	v_mfma_f32_16x16x32_bf16 v[34:37], v[2:5], v[188:191], v[196:199]
	v_mfma_f32_16x16x32_bf16 v[114:117], v[10:13], v[222:225], v[34:37]
	v_mfma_f32_16x16x32_bf16 v[34:37], v[18:21], v[180:183], v[118:121]
	v_mfma_f32_16x16x32_bf16 v[106:109], v[26:29], v[184:187], v[34:37]
	v_mfma_f32_16x16x32_bf16 v[34:37], v[18:21], v[188:191], v[200:203]
	v_mfma_f32_16x16x32_bf16 v[98:101], v[26:29], v[222:225], v[34:37]
	v_mfma_f32_16x16x32_bf16 v[34:37], v[226:229], v[180:183], v[110:113]
	v_mfma_f32_16x16x32_bf16 v[90:93], v[230:233], v[184:187], v[34:37]
	v_mfma_f32_16x16x32_bf16 v[34:37], v[226:229], v[188:191], v[206:209]
	v_mfma_f32_16x16x32_bf16 v[82:85], v[230:233], v[222:225], v[34:37]
	v_mfma_f32_16x16x32_bf16 v[34:37], v[234:237], v[180:183], v[102:105]
	v_mfma_f32_16x16x32_bf16 v[74:77], v[238:241], v[184:187], v[34:37]
	v_mfma_f32_16x16x32_bf16 v[34:37], v[234:237], v[188:191], v[210:213]
	v_mfma_f32_16x16x32_bf16 v[66:69], v[238:241], v[222:225], v[34:37]
	s_setprio 0
	s_barrier
	ds_read_b128 v[196:199], v134
	ds_read_b128 v[200:203], v134 offset:1024
	ds_read_b128 v[206:209], v134 offset:2048
	ds_read_b128 v[134:137], v134 offset:3072
	s_waitcnt vmcnt(0)
	s_barrier
	s_waitcnt lgkmcnt(0)
	s_setprio 1
	s_waitcnt lgkmcnt(0)
	v_mfma_f32_16x16x32_bf16 v[34:37], v[2:5], v[196:199], v[94:97]
	v_mfma_f32_16x16x32_bf16 v[2:5], v[2:5], v[206:209], v[146:149]
	v_mfma_f32_16x16x32_bf16 v[50:53], v[10:13], v[134:137], v[2:5]
	v_mfma_f32_16x16x32_bf16 v[2:5], v[18:21], v[196:199], v[86:89]
	v_mfma_f32_16x16x32_bf16 v[42:45], v[26:29], v[200:203], v[2:5]
	v_mfma_f32_16x16x32_bf16 v[2:5], v[18:21], v[206:209], v[164:167]
	v_mfma_f32_16x16x32_bf16 v[58:61], v[10:13], v[200:203], v[34:37]
	v_mfma_f32_16x16x32_bf16 v[34:37], v[26:29], v[134:137], v[2:5]
	v_mfma_f32_16x16x32_bf16 v[2:5], v[226:229], v[196:199], v[78:81]
	v_mfma_f32_16x16x32_bf16 v[26:29], v[230:233], v[200:203], v[2:5]
	v_mfma_f32_16x16x32_bf16 v[2:5], v[226:229], v[206:209], v[168:171]
	v_mfma_f32_16x16x32_bf16 v[18:21], v[230:233], v[134:137], v[2:5]
	v_mfma_f32_16x16x32_bf16 v[2:5], v[234:237], v[196:199], v[70:73]
	v_mfma_f32_16x16x32_bf16 v[10:13], v[238:241], v[200:203], v[2:5]
	v_mfma_f32_16x16x32_bf16 v[2:5], v[234:237], v[206:209], v[172:175]
	v_mfma_f32_16x16x32_bf16 v[2:5], v[238:241], v[134:137], v[2:5]
	s_setprio 0
	s_barrier
	ds_read_b128 v[146:149], v132 offset:49152
	ds_read_b128 v[130:133], v132 offset:50176
	ds_read_b128 v[162:165], v150 offset:49152
	ds_read_b128 v[166:169], v150 offset:50176
	ds_read_b128 v[170:173], v151 offset:49152
	ds_read_b128 v[210:213], v151 offset:50176
	ds_read_b128 v[226:229], v152 offset:49152
	ds_read_b128 v[150:153], v152 offset:50176
	s_barrier
	s_waitcnt lgkmcnt(0)
	s_setprio 1
	s_waitcnt lgkmcnt(0)
	v_mfma_f32_16x16x32_bf16 v[62:65], v[146:149], v[180:183], v[62:65]
	v_mfma_f32_16x16x32_bf16 v[54:57], v[162:165], v[180:183], v[54:57]
	v_mfma_f32_16x16x32_bf16 v[46:49], v[170:173], v[180:183], v[46:49]
	v_mfma_f32_16x16x32_bf16 v[38:41], v[226:229], v[180:183], v[38:41]
	v_mfma_f32_16x16x32_bf16 v[126:129], v[130:133], v[184:187], v[62:65]
	v_mfma_f32_16x16x32_bf16 v[62:65], v[146:149], v[188:191], v[192:195]
	v_mfma_f32_16x16x32_bf16 v[110:113], v[166:169], v[184:187], v[54:57]
	v_mfma_f32_16x16x32_bf16 v[54:57], v[162:165], v[188:191], v[214:217]
	v_mfma_f32_16x16x32_bf16 v[94:97], v[210:213], v[184:187], v[46:49]
	v_mfma_f32_16x16x32_bf16 v[46:49], v[170:173], v[188:191], v[218:221]
	v_mfma_f32_16x16x32_bf16 v[78:81], v[150:153], v[184:187], v[38:41]
	v_mfma_f32_16x16x32_bf16 v[38:41], v[226:229], v[188:191], v[138:141]
	v_mfma_f32_16x16x32_bf16 v[118:121], v[130:133], v[222:225], v[62:65]
	v_mfma_f32_16x16x32_bf16 v[102:105], v[166:169], v[222:225], v[54:57]
	v_mfma_f32_16x16x32_bf16 v[86:89], v[210:213], v[222:225], v[46:49]
	v_mfma_f32_16x16x32_bf16 v[70:73], v[150:153], v[222:225], v[38:41]
	s_setprio 0
	s_setprio 1
	v_mfma_f32_16x16x32_bf16 v[30:33], v[146:149], v[196:199], v[30:33]
	v_mfma_f32_16x16x32_bf16 v[62:65], v[130:133], v[200:203], v[30:33]
	v_mfma_f32_16x16x32_bf16 v[30:33], v[146:149], v[206:209], v[142:145]
	v_mfma_f32_16x16x32_bf16 v[22:25], v[162:165], v[196:199], v[22:25]
	v_mfma_f32_16x16x32_bf16 v[14:17], v[170:173], v[196:199], v[14:17]
	v_mfma_f32_16x16x32_bf16 v[54:57], v[130:133], v[134:137], v[30:33]
	v_mfma_f32_16x16x32_bf16 v[46:49], v[166:169], v[200:203], v[22:25]
	v_mfma_f32_16x16x32_bf16 v[22:25], v[162:165], v[206:209], v[154:157]
	v_mfma_f32_16x16x32_bf16 v[30:33], v[210:213], v[200:203], v[14:17]
	v_mfma_f32_16x16x32_bf16 v[14:17], v[170:173], v[206:209], v[158:161]
	v_mfma_f32_16x16x32_bf16 v[6:9], v[226:229], v[196:199], v[6:9]
	v_mfma_f32_16x16x32_bf16 v[38:41], v[166:169], v[134:137], v[22:25]
	v_mfma_f32_16x16x32_bf16 v[22:25], v[210:213], v[134:137], v[14:17]
	v_mfma_f32_16x16x32_bf16 v[14:17], v[150:153], v[200:203], v[6:9]
	v_mfma_f32_16x16x32_bf16 v[6:9], v[226:229], v[206:209], v[176:179]
	v_mfma_f32_16x16x32_bf16 v[6:9], v[150:153], v[134:137], v[6:9]
	s_setprio 0
	s_cmp_gt_u32 s5, 3
	s_movk_i32 s5, 0x1600
	s_barrier
	s_cbranch_scc1 .LBB0_164
	s_barrier
	s_branch .LBB0_164

; #define STAGE_A(P, br, kt) do { const char* _g = (const char*)(A + (long)(br) * lda + (long)(kt) * BK); \
;     __builtin_amdgcn_global_load_lds((const unsigned*)(_g + (size_t)offA0), (unsigned*)((char*)(P) + sb0), 16, 0, 0); \
;     __builtin_amdgcn_global_load_lds((const unsigned*)(_g + (size_t)lda * 128 + (size_t)offA0), (unsigned*)((char*)(P) + sb1), 16, 0, 0); } while (0)
; #define STAGE_B(P, br, kt) do { const char* _g = (const char*)(B + (long)(br) * ldb + (long)(kt) * BK); \
;     __builtin_amdgcn_global_load_lds((const unsigned*)(_g + (size_t)offB0), (unsigned*)((char*)(P) + sb0), 16, 0, 0); \
;     __builtin_amdgcn_global_load_lds((const unsigned*)(_g + (size_t)ldb * 128 + (size_t)offB0), (unsigned*)((char*)(P) + sb1), 16, 0, 0); } while (0)
; #define LDA(dst, b, h) for (int m = 0; m < 4; ++m) for (int k = 0; k < 2; ++k) \
;     dst[m][k] = *reinterpret_cast<const bf16x8*>((char*)SA(b, h) + lds_byte(wr * 64 + m * 16 + fr, k * 32 + fq * 8))
; #define LDB(dst, b, h) for (int n = 0; n < 2; ++n) for (int k = 0; k < 2; ++k) \
;     dst[n][k] = *reinterpret_cast<const bf16x8*>((char*)SB(b, h) + lds_byte(wc * 32 + n * 16 + fr, k * 32 + fq * 8))
; #define WAIT_V(n) asm volatile("s_waitcnt vmcnt(" #n ")" ::: "memory")
; #define WAIT_L(n) asm volatile("s_waitcnt lgkmcnt(" #n ")" ::: "memory")
; DI void gemm_core(WVP char* smem, const u16* __restrict__ A, int lda, int ar0, int ar1,
;                   const u16* __restrict__ B, int ldb, int bc0, int K, AccT& acc) {
;     ...
;   __syncthreads();
;   STAGE_B(SB(0, 0), bb0, 0); STAGE_A(SA(0, 0), ac0, 0);
;   STAGE_B(SB(0, 1), bb1, 0); STAGE_A(SA(0, 1), ac1, 0);
;   if (wr == 1) BAR;
;   WAIT_V(4); BAR;
;   STAGE_B(SB(1, 0), bb0, 1); STAGE_A(SA(1, 0), ac0, 1); STAGE_B(SB(1, 1), bb1, 1);
;   WAIT_V(6); BAR;
;   for (int t = 0; t < nt - 2; t += 2) {
;     LDB(B0, 0, 0); SCHED; LDA(At, 0, 0); STAGE_A(SA(1, 1), ac1, t + 1);
;     WAIT_L(8); BAR; WAIT_L(0); MMA(0, 0, At, B0); BAR; SCHED;
;     LDB(B1, 0, 1); STAGE_B(SB(0, 0), bb0, t + 2);
;     BAR; WAIT_L(0); MMA(0, 1, At, B1); BAR;
;     LDA(At, 0, 1); STAGE_A(SA(0, 0), ac0, t + 2);
;     BAR; WAIT_L(0); MMA(1, 0, At, B0); BAR; SCHED;
;     STAGE_B(SB(0, 1), bb1, t + 2);
;     WAIT_V(6); BAR; MMA(1, 1, At, B1); BAR;
;     LDB(B0, 1, 0); SCHED; LDA(At, 1, 0); STAGE_A(SA(0, 1), ac1, t + 2);
;     WAIT_L(8); BAR; WAIT_L(0); MMA(0, 0, At, B0); BAR; SCHED;
.LBB0_186:
	v_add_u32_e32 v141, s61, v12
	s_ashr_i32 s15, s1, 6
	v_readfirstlane_b32 s1, v141
	v_add_u32_e32 v142, 0x2000, v141
	v_lshl_add_u64 v[14:15], v[2:3], 0, s[64:65]
	s_mov_b32 m0, s1
	v_readfirstlane_b32 s1, v142
	v_add_u32_e32 v143, 0x8000, v135
	s_waitcnt vmcnt(2)
	s_barrier
	global_load_lds_dwordx4 v[14:15], off
	v_lshl_add_u64 v[2:3], v[2:3], 0, s[78:79]
	s_mov_b32 m0, s1
	v_readfirstlane_b32 s1, v143
	v_add_u32_e32 v144, 0xa000, v135
	global_load_lds_dwordx4 v[2:3], off
	v_lshl_add_u64 v[2:3], v[4:5], 0, s[64:65]
	s_mov_b32 m0, s1
	v_readfirstlane_b32 s1, v144
	v_add_u32_e32 v145, s84, v12
	global_load_lds_dwordx4 v[2:3], off
	v_lshl_add_u64 v[2:3], v[4:5], 0, s[78:79]
	s_mov_b32 m0, s1
	v_readfirstlane_b32 s1, v145
	v_add_u32_e32 v147, 0x2000, v145
	global_load_lds_dwordx4 v[2:3], off
	v_lshl_add_u64 v[2:3], v[6:7], 0, s[64:65]
	s_mov_b32 m0, s1
	v_readfirstlane_b32 s1, v147
	global_load_lds_dwordx4 v[2:3], off
	v_lshl_add_u64 v[2:3], v[6:7], 0, s[78:79]
	s_mov_b32 m0, s1
	v_and_b32_e32 v0, 15, v9
	global_load_lds_dwordx4 v[2:3], off
	v_lshlrev_b32_e32 v2, 2, v9
	v_and_b32_e32 v13, 48, v9
	v_lshlrev_b32_e32 v0, 6, v0
	v_and_b32_e32 v2, 32, v2
	v_bitop3_b32 v0, v0, v2, v13 bitop3:0x36
	v_add_u32_e32 v3, s20, v0
	v_add_u32_e32 v4, s60, v0
	v_add_u32_e32 v5, s61, v0
	v_add_u32_e32 v6, s84, v0
	v_add_u32_e32 v7, 0, v0
	v_lshlrev_b32_e32 v0, 6, v9
	s_lshl_b32 s1, s15, 12
	s_lshl_b32 s23, s0, 13
	v_and_or_b32 v0, v0, s74, v13
	s_and_b32 s22, s1, 0x3000
	v_xad_u32 v148, v0, v2, 0
	s_or_b32 s0, s23, 0x800
	s_or_b32 s1, s23, 0x1000
	s_or_b32 s20, s23, 0x1800
	v_lshlrev_b32_e32 v0, 14, v8
	v_and_b32_e32 v0, 0xffff8000, v0
	s_add_u32 s8, s54, s8
	s_waitcnt vmcnt(6)
	v_lshl_add_u32 v0, v10, 11, v0
	v_and_b32_e32 v2, 1, v8
	s_addc_u32 s9, s55, s9
	v_lshl_or_b32 v0, v2, 6, v0
	s_add_u32 s18, s54, s18
	v_mov_b32_e32 v2, 0
	v_lshl_add_u32 v0, v11, 1, v0
	s_addc_u32 s19, s55, s19
	s_mov_b32 s21, -2
	v_add_u32_e32 v149, s22, v3
	v_add_u32_e32 v132, s23, v7
	v_add_u32_e32 v146, s22, v4
	v_add_u32_e32 v137, s22, v5
	v_add_u32_e32 v133, s22, v6
	v_mov_b32_e32 v3, v2
	v_mov_b32_e32 v4, v2
	v_mov_b32_e32 v5, v2
	v_mov_b32_e32 v6, v2
	v_mov_b32_e32 v7, v2
	v_mov_b32_e32 v8, v2
	v_mov_b32_e32 v9, v2
	v_mov_b32_e32 v10, v2
	v_mov_b32_e32 v11, v2
	v_mov_b32_e32 v12, v2
	v_mov_b32_e32 v13, v2
	v_mov_b32_e32 v14, v2
	v_mov_b32_e32 v15, v2
	s_barrier
.LBB0_187:
	v_add_u32_e32 v150, s0, v148
	v_add_u32_e32 v151, s1, v148
	v_add_u32_e32 v152, s20, v148
	ds_read_b128 v[156:159], v149
	ds_read_b128 v[160:163], v149 offset:1024
	ds_read_b128 v[164:167], v149 offset:2048
	ds_read_b128 v[168:171], v149 offset:3072
	ds_read_b128 v[172:175], v132
	ds_read_b128 v[176:179], v132 offset:1024
	ds_read_b128 v[180:183], v150
	ds_read_b128 v[184:187], v150 offset:1024
	ds_read_b128 v[188:191], v151
	ds_read_b128 v[192:195], v151 offset:1024
	ds_read_b128 v[196:199], v152
	ds_read_b128 v[200:203], v152 offset:1024
	ds_read_b128 v[206:209], v146
	ds_read_b128 v[210:213], v146 offset:1024
	ds_read_b128 v[214:217], v146 offset:2048
	ds_read_b128 v[218:221], v146 offset:3072
	v_add_u32_e32 v153, 0xc000, v135
	v_lshl_add_u64 v[224:225], s[18:19], 0, v[0:1]
	s_mov_b64 s[22:23], 0x1e6c0080
	v_lshl_add_u64 v[222:223], v[224:225], 0, s[22:23]
	v_readfirstlane_b32 s22, v153
	s_mov_b32 m0, s22
	s_nop 0
	global_load_lds_dwordx4 v[222:223], off
	v_add_u32_e32 v154, 0xe000, v135
	v_lshl_add_u64 v[224:225], s[18:19], 0, v[0:1]
	s_mov_b64 s[22:23], 0x1e6e0080
	v_lshl_add_u64 v[222:223], v[224:225], 0, s[22:23]
	v_readfirstlane_b32 s22, v154
	s_mov_b32 m0, s22
	s_nop 0
	global_load_lds_dwordx4 v[222:223], off
	s_waitcnt vmcnt(8)
	s_waitcnt lgkmcnt(0)
	s_barrier
	s_setprio 1
	v_mfma_f32_16x16x32_bf16 v[126:129], v[172:175], v[156:159], v[126:129]
	v_mfma_f32_16x16x32_bf16 v[122:125], v[172:175], v[164:167], v[122:125]
	v_mfma_f32_16x16x32_bf16 v[118:121], v[180:183], v[156:159], v[118:121]
	v_mfma_f32_16x16x32_bf16 v[114:117], v[180:183], v[164:167], v[114:117]
	v_mfma_f32_16x16x32_bf16 v[110:113], v[188:191], v[156:159], v[110:113]
	v_mfma_f32_16x16x32_bf16 v[106:109], v[188:191], v[164:167], v[106:109]
	v_mfma_f32_16x16x32_bf16 v[102:105], v[196:199], v[156:159], v[102:105]
	v_mfma_f32_16x16x32_bf16 v[98:101], v[196:199], v[164:167], v[98:101]
	v_mfma_f32_16x16x32_bf16 v[126:129], v[176:179], v[160:163], v[126:129]
	v_mfma_f32_16x16x32_bf16 v[122:125], v[176:179], v[168:171], v[122:125]
	v_mfma_f32_16x16x32_bf16 v[118:121], v[184:187], v[160:163], v[118:121]
	v_mfma_f32_16x16x32_bf16 v[114:117], v[184:187], v[168:171], v[114:117]
	v_mfma_f32_16x16x32_bf16 v[110:113], v[192:195], v[160:163], v[110:113]
	v_mfma_f32_16x16x32_bf16 v[106:109], v[192:195], v[168:171], v[106:109]
	v_mfma_f32_16x16x32_bf16 v[102:105], v[200:203], v[160:163], v[102:105]
	v_mfma_f32_16x16x32_bf16 v[98:101], v[200:203], v[168:171], v[98:101]
	v_mfma_f32_16x16x32_bf16 v[94:97], v[172:175], v[206:209], v[94:97]
	v_mfma_f32_16x16x32_bf16 v[82:85], v[172:175], v[214:217], v[82:85]
	v_mfma_f32_16x16x32_bf16 v[66:69], v[180:183], v[206:209], v[66:69]
	v_mfma_f32_16x16x32_bf16 v[54:57], v[180:183], v[214:217], v[54:57]
	v_mfma_f32_16x16x32_bf16 v[50:53], v[188:191], v[206:209], v[50:53]
	v_mfma_f32_16x16x32_bf16 v[46:49], v[188:191], v[214:217], v[46:49]
	v_mfma_f32_16x16x32_bf16 v[42:45], v[196:199], v[206:209], v[42:45]
	v_mfma_f32_16x16x32_bf16 v[38:41], v[196:199], v[214:217], v[38:41]
	v_mfma_f32_16x16x32_bf16 v[94:97], v[176:179], v[210:213], v[94:97]
	v_mfma_f32_16x16x32_bf16 v[82:85], v[176:179], v[218:221], v[82:85]
	v_mfma_f32_16x16x32_bf16 v[66:69], v[184:187], v[210:213], v[66:69]
	v_mfma_f32_16x16x32_bf16 v[54:57], v[184:187], v[218:221], v[54:57]
	v_mfma_f32_16x16x32_bf16 v[50:53], v[192:195], v[210:213], v[50:53]
	v_mfma_f32_16x16x32_bf16 v[46:49], v[192:195], v[218:221], v[46:49]
	v_mfma_f32_16x16x32_bf16 v[42:45], v[200:203], v[210:213], v[42:45]
	v_mfma_f32_16x16x32_bf16 v[38:41], v[200:203], v[218:221], v[38:41]
	s_setprio 0
	s_barrier
; #define STAGE_A(P, br, kt) do { const char* _g = (const char*)(A + (long)(br) * lda + (long)(kt) * BK); \
;     __builtin_amdgcn_global_load_lds((const unsigned*)(_g + (size_t)offA0), (unsigned*)((char*)(P) + sb0), 16, 0, 0); \
;     __builtin_amdgcn_global_load_lds((const unsigned*)(_g + (size_t)lda * 128 + (size_t)offA0), (unsigned*)((char*)(P) + sb1), 16, 0, 0); } while (0)
; #define STAGE_B(P, br, kt) do { const char* _g = (const char*)(B + (long)(br) * ldb + (long)(kt) * BK); \
;     __builtin_amdgcn_global_load_lds((const unsigned*)(_g + (size_t)offB0), (unsigned*)((char*)(P) + sb0), 16, 0, 0); \
;     __builtin_amdgcn_global_load_lds((const unsigned*)(_g + (size_t)ldb * 128 + (size_t)offB0), (unsigned*)((char*)(P) + sb1), 16, 0, 0); } while (0)
; #define LDA(dst, b, h) for (int m = 0; m < 4; ++m) for (int k = 0; k < 2; ++k) \
;     dst[m][k] = *reinterpret_cast<const bf16x8*>((char*)SA(b, h) + lds_byte(wr * 64 + m * 16 + fr, k * 32 + fq * 8))
; #define LDB(dst, b, h) for (int n = 0; n < 2; ++n) for (int k = 0; k < 2; ++k) \
;     dst[n][k] = *reinterpret_cast<const bf16x8*>((char*)SB(b, h) + lds_byte(wc * 32 + n * 16 + fr, k * 32 + fq * 8))
; #define MMA(ai, bj, At_, Bt_) do { __builtin_amdgcn_s_setprio(1); \
;     for (int m = 0; m < 4; ++m) for (int n = 0; n < 2; ++n) for (int k = 0; k < 2; ++k) \
;       acc[ai][bj][m][n] = MFMA16(At_[m][k], Bt_[n][k], acc[ai][bj][m][n]); \
;     __builtin_amdgcn_s_setprio(0); } while (0)
; #define WAIT_V(n) asm volatile("s_waitcnt vmcnt(" #n ")" ::: "memory")
; #define WAIT_L(n) asm volatile("s_waitcnt lgkmcnt(" #n ")" ::: "memory")
; #define BAR __builtin_amdgcn_s_barrier()
; #define SCHED __builtin_amdgcn_sched_barrier(0)
; DI void gemm_core(WVP char* smem, const u16* __restrict__ A, int lda, int ar0, int ar1,
;                   const u16* __restrict__ B, int ldb, int bc0, int K, AccT& acc) {
;     ...
;     LDA(At, 0, 1); STAGE_A(SA(0, 0), ac0, t + 2);
;     BAR; WAIT_L(0); MMA(1, 0, At, B0); BAR; SCHED;
;     STAGE_B(SB(0, 1), bb1, t + 2);
;     WAIT_V(6); BAR; MMA(1, 1, At, B1); BAR;
;     LDB(B0, 1, 0); SCHED; LDA(At, 1, 0); STAGE_A(SA(0, 1), ac1, t + 2);
;     WAIT_L(8); BAR; WAIT_L(0); MMA(0, 0, At, B0); BAR; SCHED;
;     LDB(B1, 1, 1); STAGE_B(SB(1, 0), bb0, t + 3);
;     BAR; WAIT_L(0); MMA(0, 1, At, B1); BAR;
	ds_read_b128 v[172:175], v132 offset:16384
	ds_read_b128 v[176:179], v132 offset:17408
	ds_read_b128 v[180:183], v150 offset:16384
	ds_read_b128 v[184:187], v150 offset:17408
	ds_read_b128 v[188:191], v151 offset:16384
	ds_read_b128 v[192:195], v151 offset:17408
	ds_read_b128 v[196:199], v152 offset:16384
	ds_read_b128 v[200:203], v152 offset:17408
	v_lshl_add_u64 v[224:225], s[8:9], 0, v[0:1]
	s_mov_b64 s[22:23], 0x19000100
	v_lshl_add_u64 v[222:223], v[224:225], 0, s[22:23]
	v_readfirstlane_b32 s22, v134
	s_mov_b32 m0, s22
	s_nop 0
	global_load_lds_dwordx4 v[222:223], off
	v_add_u32_e32 v155, 0x2000, v134
	v_lshl_add_u64 v[224:225], s[8:9], 0, v[0:1]
	s_mov_b64 s[22:23], 0x19020100
	v_lshl_add_u64 v[222:223], v[224:225], 0, s[22:23]
	v_readfirstlane_b32 s22, v155
	s_mov_b32 m0, s22
	s_nop 0
	global_load_lds_dwordx4 v[222:223], off
	v_lshl_add_u64 v[224:225], s[18:19], 0, v[0:1]
	s_mov_b64 s[22:23], 0x1e680100
	v_lshl_add_u64 v[222:223], v[224:225], 0, s[22:23]
	v_readfirstlane_b32 s22, v135
	s_mov_b32 m0, s22
	s_nop 0
	global_load_lds_dwordx4 v[222:223], off
	v_lshl_add_u64 v[224:225], s[18:19], 0, v[0:1]
	s_mov_b64 s[22:23], 0x1e6a0100
	v_lshl_add_u64 v[222:223], v[224:225], 0, s[22:23]
	v_readfirstlane_b32 s22, v136
	s_mov_b32 m0, s22
	s_nop 0
	global_load_lds_dwordx4 v[222:223], off
	v_lshl_add_u64 v[224:225], s[8:9], 0, v[0:1]
	s_mov_b64 s[22:23], 0x19040100
	v_lshl_add_u64 v[222:223], v[224:225], 0, s[22:23]
	v_readfirstlane_b32 s22, v138
	s_mov_b32 m0, s22
	s_nop 0
	global_load_lds_dwordx4 v[222:223], off
	v_add_u32_e32 v155, 0x2000, v138
	v_lshl_add_u64 v[224:225], s[8:9], 0, v[0:1]
	s_mov_b64 s[22:23], 0x19060100
	v_lshl_add_u64 v[222:223], v[224:225], 0, s[22:23]
	v_readfirstlane_b32 s22, v155
	s_mov_b32 m0, s22
	s_nop 0
	global_load_lds_dwordx4 v[222:223], off
	s_waitcnt vmcnt(8)
	s_waitcnt lgkmcnt(0)
	s_barrier
	s_setprio 1
	v_mfma_f32_16x16x32_bf16 v[34:37], v[172:175], v[156:159], v[34:37]
	v_mfma_f32_16x16x32_bf16 v[30:33], v[172:175], v[164:167], v[30:33]
	v_mfma_f32_16x16x32_bf16 v[26:29], v[180:183], v[156:159], v[26:29]
	v_mfma_f32_16x16x32_bf16 v[22:25], v[180:183], v[164:167], v[22:25]
	v_mfma_f32_16x16x32_bf16 v[18:21], v[188:191], v[156:159], v[18:21]
	v_mfma_f32_16x16x32_bf16 v[14:17], v[188:191], v[164:167], v[14:17]
	v_mfma_f32_16x16x32_bf16 v[10:13], v[196:199], v[156:159], v[10:13]
	v_mfma_f32_16x16x32_bf16 v[6:9], v[196:199], v[164:167], v[6:9]
	v_mfma_f32_16x16x32_bf16 v[34:37], v[176:179], v[160:163], v[34:37]
	v_mfma_f32_16x16x32_bf16 v[30:33], v[176:179], v[168:171], v[30:33]
	v_mfma_f32_16x16x32_bf16 v[26:29], v[184:187], v[160:163], v[26:29]
	v_mfma_f32_16x16x32_bf16 v[22:25], v[184:187], v[168:171], v[22:25]
	v_mfma_f32_16x16x32_bf16 v[18:21], v[192:195], v[160:163], v[18:21]
	v_mfma_f32_16x16x32_bf16 v[14:17], v[192:195], v[168:171], v[14:17]
	v_mfma_f32_16x16x32_bf16 v[10:13], v[200:203], v[160:163], v[10:13]
	v_mfma_f32_16x16x32_bf16 v[6:9], v[200:203], v[168:171], v[6:9]
	v_mfma_f32_16x16x32_bf16 v[2:5], v[172:175], v[206:209], v[2:5]
	v_mfma_f32_16x16x32_bf16 v[58:61], v[172:175], v[214:217], v[58:61]
	v_mfma_f32_16x16x32_bf16 v[62:65], v[180:183], v[206:209], v[62:65]
	v_mfma_f32_16x16x32_bf16 v[70:73], v[180:183], v[214:217], v[70:73]
	v_mfma_f32_16x16x32_bf16 v[74:77], v[188:191], v[206:209], v[74:77]
	v_mfma_f32_16x16x32_bf16 v[78:81], v[188:191], v[214:217], v[78:81]
	v_mfma_f32_16x16x32_bf16 v[86:89], v[196:199], v[206:209], v[86:89]
	v_mfma_f32_16x16x32_bf16 v[90:93], v[196:199], v[214:217], v[90:93]
	v_mfma_f32_16x16x32_bf16 v[2:5], v[176:179], v[210:213], v[2:5]
	v_mfma_f32_16x16x32_bf16 v[58:61], v[176:179], v[218:221], v[58:61]
	v_mfma_f32_16x16x32_bf16 v[62:65], v[184:187], v[210:213], v[62:65]
	v_mfma_f32_16x16x32_bf16 v[70:73], v[184:187], v[218:221], v[70:73]
	v_mfma_f32_16x16x32_bf16 v[74:77], v[192:195], v[210:213], v[74:77]
	v_mfma_f32_16x16x32_bf16 v[78:81], v[192:195], v[218:221], v[78:81]
	v_mfma_f32_16x16x32_bf16 v[86:89], v[200:203], v[210:213], v[86:89]
	v_mfma_f32_16x16x32_bf16 v[90:93], v[200:203], v[218:221], v[90:93]
	s_setprio 0
	s_barrier
	ds_read_b128 v[156:159], v137
	ds_read_b128 v[160:163], v137 offset:1024
	ds_read_b128 v[164:167], v137 offset:2048
	ds_read_b128 v[168:171], v137 offset:3072
	ds_read_b128 v[172:175], v132 offset:32768
	ds_read_b128 v[176:179], v132 offset:33792
	ds_read_b128 v[180:183], v150 offset:32768
	ds_read_b128 v[184:187], v150 offset:33792
	ds_read_b128 v[188:191], v151 offset:32768
	ds_read_b128 v[192:195], v151 offset:33792
	ds_read_b128 v[196:199], v152 offset:32768
	ds_read_b128 v[200:203], v152 offset:33792
	ds_read_b128 v[206:209], v133
	ds_read_b128 v[210:213], v133 offset:1024
	ds_read_b128 v[214:217], v133 offset:2048
	ds_read_b128 v[218:221], v133 offset:3072
	v_lshl_add_u64 v[224:225], s[18:19], 0, v[0:1]
	s_mov_b64 s[22:23], 0x1e6c0100
	v_lshl_add_u64 v[222:223], v[224:225], 0, s[22:23]
	v_readfirstlane_b32 s22, v139
	s_mov_b32 m0, s22
	s_nop 0
	global_load_lds_dwordx4 v[222:223], off
	v_lshl_add_u64 v[224:225], s[18:19], 0, v[0:1]
	s_mov_b64 s[22:23], 0x1e6e0100
	v_lshl_add_u64 v[222:223], v[224:225], 0, s[22:23]
	v_readfirstlane_b32 s22, v140
	s_mov_b32 m0, s22
	s_nop 0
	global_load_lds_dwordx4 v[222:223], off
	s_waitcnt vmcnt(8)
	s_waitcnt lgkmcnt(0)
	s_barrier
; #define STAGE_A(P, br, kt) do { const char* _g = (const char*)(A + (long)(br) * lda + (long)(kt) * BK); \
;     __builtin_amdgcn_global_load_lds((const unsigned*)(_g + (size_t)offA0), (unsigned*)((char*)(P) + sb0), 16, 0, 0); \
;     __builtin_amdgcn_global_load_lds((const unsigned*)(_g + (size_t)lda * 128 + (size_t)offA0), (unsigned*)((char*)(P) + sb1), 16, 0, 0); } while (0)
; #define STAGE_B(P, br, kt) do { const char* _g = (const char*)(B + (long)(br) * ldb + (long)(kt) * BK); \
;     __builtin_amdgcn_global_load_lds((const unsigned*)(_g + (size_t)offB0), (unsigned*)((char*)(P) + sb0), 16, 0, 0); \
;     __builtin_amdgcn_global_load_lds((const unsigned*)(_g + (size_t)ldb * 128 + (size_t)offB0), (unsigned*)((char*)(P) + sb1), 16, 0, 0); } while (0)
; #define LDA(dst, b, h) for (int m = 0; m < 4; ++m) for (int k = 0; k < 2; ++k) \
;     dst[m][k] = *reinterpret_cast<const bf16x8*>((char*)SA(b, h) + lds_byte(wr * 64 + m * 16 + fr, k * 32 + fq * 8))
; #define LDB(dst, b, h) for (int n = 0; n < 2; ++n) for (int k = 0; k < 2; ++k) \
;     dst[n][k] = *reinterpret_cast<const bf16x8*>((char*)SB(b, h) + lds_byte(wc * 32 + n * 16 + fr, k * 32 + fq * 8))
; #define MMA(ai, bj, At_, Bt_) do { __builtin_amdgcn_s_setprio(1); \
;     for (int m = 0; m < 4; ++m) for (int n = 0; n < 2; ++n) for (int k = 0; k < 2; ++k) \
;       acc[ai][bj][m][n] = MFMA16(At_[m][k], Bt_[n][k], acc[ai][bj][m][n]); \
;     __builtin_amdgcn_s_setprio(0); } while (0)
; #define WAIT_V(n) asm volatile("s_waitcnt vmcnt(" #n ")" ::: "memory")
; #define WAIT_L(n) asm volatile("s_waitcnt lgkmcnt(" #n ")" ::: "memory")
; #define BAR __builtin_amdgcn_s_barrier()
; #define SCHED __builtin_amdgcn_sched_barrier(0)
; DI void gemm_core(WVP char* smem, const u16* __restrict__ A, int lda, int ar0, int ar1,
;                   const u16* __restrict__ B, int ldb, int bc0, int K, AccT& acc) {
;     ...
;     WAIT_L(8); BAR; WAIT_L(0); MMA(0, 0, At, B0); BAR; SCHED;
;     LDB(B1, 1, 1); STAGE_B(SB(1, 0), bb0, t + 3);
;     BAR; WAIT_L(0); MMA(0, 1, At, B1); BAR;
;     LDA(At, 1, 1); STAGE_A(SA(1, 0), ac0, t + 3);
;     BAR; WAIT_L(0); MMA(1, 0, At, B0); BAR; SCHED;
;     STAGE_B(SB(1, 1), bb1, t + 3);
;     WAIT_V(6); BAR; MMA(1, 1, At, B1); BAR;
;   }
	s_setprio 1
	v_mfma_f32_16x16x32_bf16 v[126:129], v[172:175], v[156:159], v[126:129]
	v_mfma_f32_16x16x32_bf16 v[122:125], v[172:175], v[164:167], v[122:125]
	v_mfma_f32_16x16x32_bf16 v[118:121], v[180:183], v[156:159], v[118:121]
	v_mfma_f32_16x16x32_bf16 v[114:117], v[180:183], v[164:167], v[114:117]
	v_mfma_f32_16x16x32_bf16 v[110:113], v[188:191], v[156:159], v[110:113]
	v_mfma_f32_16x16x32_bf16 v[106:109], v[188:191], v[164:167], v[106:109]
	v_mfma_f32_16x16x32_bf16 v[102:105], v[196:199], v[156:159], v[102:105]
	v_mfma_f32_16x16x32_bf16 v[98:101], v[196:199], v[164:167], v[98:101]
	v_mfma_f32_16x16x32_bf16 v[126:129], v[176:179], v[160:163], v[126:129]
	v_mfma_f32_16x16x32_bf16 v[122:125], v[176:179], v[168:171], v[122:125]
	v_mfma_f32_16x16x32_bf16 v[118:121], v[184:187], v[160:163], v[118:121]
	v_mfma_f32_16x16x32_bf16 v[114:117], v[184:187], v[168:171], v[114:117]
	v_mfma_f32_16x16x32_bf16 v[110:113], v[192:195], v[160:163], v[110:113]
	v_mfma_f32_16x16x32_bf16 v[106:109], v[192:195], v[168:171], v[106:109]
	v_mfma_f32_16x16x32_bf16 v[102:105], v[200:203], v[160:163], v[102:105]
	v_mfma_f32_16x16x32_bf16 v[98:101], v[200:203], v[168:171], v[98:101]
	v_mfma_f32_16x16x32_bf16 v[94:97], v[172:175], v[206:209], v[94:97]
	v_mfma_f32_16x16x32_bf16 v[82:85], v[172:175], v[214:217], v[82:85]
	v_mfma_f32_16x16x32_bf16 v[66:69], v[180:183], v[206:209], v[66:69]
	v_mfma_f32_16x16x32_bf16 v[54:57], v[180:183], v[214:217], v[54:57]
	v_mfma_f32_16x16x32_bf16 v[50:53], v[188:191], v[206:209], v[50:53]
	v_mfma_f32_16x16x32_bf16 v[46:49], v[188:191], v[214:217], v[46:49]
	v_mfma_f32_16x16x32_bf16 v[42:45], v[196:199], v[206:209], v[42:45]
	v_mfma_f32_16x16x32_bf16 v[38:41], v[196:199], v[214:217], v[38:41]
	v_mfma_f32_16x16x32_bf16 v[94:97], v[176:179], v[210:213], v[94:97]
	v_mfma_f32_16x16x32_bf16 v[82:85], v[176:179], v[218:221], v[82:85]
	v_mfma_f32_16x16x32_bf16 v[66:69], v[184:187], v[210:213], v[66:69]
	v_mfma_f32_16x16x32_bf16 v[54:57], v[184:187], v[218:221], v[54:57]
	v_mfma_f32_16x16x32_bf16 v[50:53], v[192:195], v[210:213], v[50:53]
	v_mfma_f32_16x16x32_bf16 v[46:49], v[192:195], v[218:221], v[46:49]
	v_mfma_f32_16x16x32_bf16 v[42:45], v[200:203], v[210:213], v[42:45]
	v_mfma_f32_16x16x32_bf16 v[38:41], v[200:203], v[218:221], v[38:41]
	s_setprio 0
	s_barrier
	ds_read_b128 v[172:175], v132 offset:49152
	ds_read_b128 v[176:179], v132 offset:50176
	ds_read_b128 v[180:183], v150 offset:49152
	ds_read_b128 v[184:187], v150 offset:50176
	ds_read_b128 v[188:191], v151 offset:49152
	ds_read_b128 v[192:195], v151 offset:50176
	ds_read_b128 v[196:199], v152 offset:49152
	ds_read_b128 v[200:203], v152 offset:50176
	v_lshl_add_u64 v[224:225], s[8:9], 0, v[0:1]
	s_mov_b64 s[22:23], 0x19000180
	v_lshl_add_u64 v[222:223], v[224:225], 0, s[22:23]
	v_readfirstlane_b32 s22, v141
	s_mov_b32 m0, s22
	s_nop 0
	global_load_lds_dwordx4 v[222:223], off
	v_lshl_add_u64 v[224:225], s[8:9], 0, v[0:1]
	s_mov_b64 s[22:23], 0x19020180
	v_lshl_add_u64 v[222:223], v[224:225], 0, s[22:23]
	v_readfirstlane_b32 s22, v142
	s_mov_b32 m0, s22
	s_nop 0
	global_load_lds_dwordx4 v[222:223], off
	v_lshl_add_u64 v[224:225], s[18:19], 0, v[0:1]
	s_mov_b64 s[22:23], 0x1e680180
	v_lshl_add_u64 v[222:223], v[224:225], 0, s[22:23]
	v_readfirstlane_b32 s22, v143
	s_mov_b32 m0, s22
	s_nop 0
	global_load_lds_dwordx4 v[222:223], off
	v_lshl_add_u64 v[224:225], s[18:19], 0, v[0:1]
	s_mov_b64 s[22:23], 0x1e6a0180
	v_lshl_add_u64 v[222:223], v[224:225], 0, s[22:23]
	v_readfirstlane_b32 s22, v144
	s_mov_b32 m0, s22
	s_nop 0
	global_load_lds_dwordx4 v[222:223], off
	v_lshl_add_u64 v[224:225], s[8:9], 0, v[0:1]
	s_mov_b64 s[22:23], 0x19040180
	v_lshl_add_u64 v[222:223], v[224:225], 0, s[22:23]
	v_readfirstlane_b32 s22, v145
	s_mov_b32 m0, s22
	s_nop 0
	global_load_lds_dwordx4 v[222:223], off
	v_lshl_add_u64 v[224:225], s[8:9], 0, v[0:1]
	s_mov_b64 s[22:23], 0x19060180
	v_lshl_add_u64 v[222:223], v[224:225], 0, s[22:23]
	v_readfirstlane_b32 s22, v147
	s_mov_b32 m0, s22
	s_nop 0
	global_load_lds_dwordx4 v[222:223], off
	s_waitcnt vmcnt(8)
	s_waitcnt lgkmcnt(0)
	s_barrier
	s_setprio 1
	v_mfma_f32_16x16x32_bf16 v[34:37], v[172:175], v[156:159], v[34:37]
	v_mfma_f32_16x16x32_bf16 v[30:33], v[172:175], v[164:167], v[30:33]
	v_mfma_f32_16x16x32_bf16 v[26:29], v[180:183], v[156:159], v[26:29]
	v_mfma_f32_16x16x32_bf16 v[22:25], v[180:183], v[164:167], v[22:25]
	v_mfma_f32_16x16x32_bf16 v[18:21], v[188:191], v[156:159], v[18:21]
	v_mfma_f32_16x16x32_bf16 v[14:17], v[188:191], v[164:167], v[14:17]
	v_mfma_f32_16x16x32_bf16 v[10:13], v[196:199], v[156:159], v[10:13]
	v_mfma_f32_16x16x32_bf16 v[6:9], v[196:199], v[164:167], v[6:9]
	v_mfma_f32_16x16x32_bf16 v[34:37], v[176:179], v[160:163], v[34:37]
	v_mfma_f32_16x16x32_bf16 v[30:33], v[176:179], v[168:171], v[30:33]
	v_mfma_f32_16x16x32_bf16 v[26:29], v[184:187], v[160:163], v[26:29]
	v_mfma_f32_16x16x32_bf16 v[22:25], v[184:187], v[168:171], v[22:25]
	v_mfma_f32_16x16x32_bf16 v[18:21], v[192:195], v[160:163], v[18:21]
	v_mfma_f32_16x16x32_bf16 v[14:17], v[192:195], v[168:171], v[14:17]
	v_mfma_f32_16x16x32_bf16 v[10:13], v[200:203], v[160:163], v[10:13]
	v_mfma_f32_16x16x32_bf16 v[6:9], v[200:203], v[168:171], v[6:9]
	v_mfma_f32_16x16x32_bf16 v[2:5], v[172:175], v[206:209], v[2:5]
	v_mfma_f32_16x16x32_bf16 v[58:61], v[172:175], v[214:217], v[58:61]
	v_mfma_f32_16x16x32_bf16 v[62:65], v[180:183], v[206:209], v[62:65]
	v_mfma_f32_16x16x32_bf16 v[70:73], v[180:183], v[214:217], v[70:73]
	v_mfma_f32_16x16x32_bf16 v[74:77], v[188:191], v[206:209], v[74:77]
	v_mfma_f32_16x16x32_bf16 v[78:81], v[188:191], v[214:217], v[78:81]
	v_mfma_f32_16x16x32_bf16 v[86:89], v[196:199], v[206:209], v[86:89]
	v_mfma_f32_16x16x32_bf16 v[90:93], v[196:199], v[214:217], v[90:93]
	v_mfma_f32_16x16x32_bf16 v[2:5], v[176:179], v[210:213], v[2:5]
	v_mfma_f32_16x16x32_bf16 v[58:61], v[176:179], v[218:221], v[58:61]
	v_mfma_f32_16x16x32_bf16 v[62:65], v[184:187], v[210:213], v[62:65]
	v_mfma_f32_16x16x32_bf16 v[70:73], v[184:187], v[218:221], v[70:73]
	v_mfma_f32_16x16x32_bf16 v[74:77], v[192:195], v[210:213], v[74:77]
	v_mfma_f32_16x16x32_bf16 v[78:81], v[192:195], v[218:221], v[78:81]
	v_mfma_f32_16x16x32_bf16 v[86:89], v[200:203], v[210:213], v[86:89]
	v_mfma_f32_16x16x32_bf16 v[90:93], v[200:203], v[218:221], v[90:93]
	s_setprio 0
	s_add_i32 s21, s21, 2
	s_add_u32 s8, s8, 0x100
	s_addc_u32 s9, s9, 0
	s_add_u32 s18, s18, 0x100
	s_addc_u32 s19, s19, 0
	s_cmp_lt_u32 s21, 12
	s_barrier
; #define STAGE_A(P, br, kt) do { const char* _g = (const char*)(A + (long)(br) * lda + (long)(kt) * BK); \
;     __builtin_amdgcn_global_load_lds((const unsigned*)(_g + (size_t)offA0), (unsigned*)((char*)(P) + sb0), 16, 0, 0); \
;     __builtin_amdgcn_global_load_lds((const unsigned*)(_g + (size_t)lda * 128 + (size_t)offA0), (unsigned*)((char*)(P) + sb1), 16, 0, 0); } while (0)
; #define LDA(dst, b, h) for (int m = 0; m < 4; ++m) for (int k = 0; k < 2; ++k) \
;     dst[m][k] = *reinterpret_cast<const bf16x8*>((char*)SA(b, h) + lds_byte(wr * 64 + m * 16 + fr, k * 32 + fq * 8))
; #define LDB(dst, b, h) for (int n = 0; n < 2; ++n) for (int k = 0; k < 2; ++k) \
;     dst[n][k] = *reinterpret_cast<const bf16x8*>((char*)SB(b, h) + lds_byte(wc * 32 + n * 16 + fr, k * 32 + fq * 8))
; #define MMA(ai, bj, At_, Bt_) do { __builtin_amdgcn_s_setprio(1); \
;     for (int m = 0; m < 4; ++m) for (int n = 0; n < 2; ++n) for (int k = 0; k < 2; ++k) \
;       acc[ai][bj][m][n] = MFMA16(At_[m][k], Bt_[n][k], acc[ai][bj][m][n]); \
;     __builtin_amdgcn_s_setprio(0); } while (0)
; #define WAIT_V(n) asm volatile("s_waitcnt vmcnt(" #n ")" ::: "memory")
; #define WAIT_L(n) asm volatile("s_waitcnt lgkmcnt(" #n ")" ::: "memory")
; #define BAR __builtin_amdgcn_s_barrier()
; DI void gemm_core(WVP char* smem, const u16* __restrict__ A, int lda, int ar0, int ar1,
;                   const u16* __restrict__ B, int ldb, int bc0, int K, AccT& acc) {
;     ...
;   { LDB(B0, 0, 0); LDA(At, 0, 0); STAGE_A(SA(1, 1), ac1, nt - 1);
;     BAR; WAIT_L(0); MMA(0, 0, At, B0); BAR;
;     LDB(B1, 0, 1); BAR; WAIT_L(0); MMA(0, 1, At, B1); BAR;
;     LDA(At, 0, 1); WAIT_V(4); BAR; WAIT_L(0); MMA(1, 0, At, B0); MMA(1, 1, At, B1); BAR; }
;   { LDB(B0, 1, 0); LDA(At, 1, 0); WAIT_V(2); BAR; WAIT_L(0); MMA(0, 0, At, B0); BAR;
	s_cbranch_scc1 .LBB0_187
	s_mov_b64 s[0:1], 0x780
	v_lshl_add_u64 v[134:135], v[130:131], 0, s[0:1]
	v_readfirstlane_b32 s0, v153
	s_mov_b32 m0, s0
	s_mov_b64 s[0:1], 0x20780
	v_lshl_add_u64 v[130:131], v[130:131], 0, s[0:1]
	v_readfirstlane_b32 s0, v154
	ds_read_b128 v[138:141], v149
	ds_read_b128 v[142:145], v149 offset:1024
	ds_read_b128 v[156:159], v149 offset:2048
	ds_read_b128 v[160:163], v149 offset:3072
	ds_read_b128 v[164:167], v132
	ds_read_b128 v[168:171], v132 offset:1024
	ds_read_b128 v[172:175], v150
	ds_read_b128 v[176:179], v150 offset:1024
	ds_read_b128 v[180:183], v151
	ds_read_b128 v[184:187], v151 offset:1024
	ds_read_b128 v[188:191], v152
	ds_read_b128 v[192:195], v152 offset:1024
	global_load_lds_dwordx4 v[134:135], off
	s_mov_b32 m0, s0
	s_nop 0
	global_load_lds_dwordx4 v[130:131], off
	s_waitcnt vmcnt(8)
	s_barrier
	s_waitcnt lgkmcnt(0)
	s_setprio 1
	s_waitcnt lgkmcnt(0)
	v_mfma_f32_16x16x32_bf16 v[126:129], v[164:167], v[138:141], v[126:129]
	v_mfma_f32_16x16x32_bf16 v[122:125], v[164:167], v[156:159], v[122:125]
	v_mfma_f32_16x16x32_bf16 v[118:121], v[172:175], v[138:141], v[118:121]
	v_mfma_f32_16x16x32_bf16 v[114:117], v[172:175], v[156:159], v[114:117]
	v_mfma_f32_16x16x32_bf16 v[106:109], v[180:183], v[156:159], v[106:109]
	v_mfma_f32_16x16x32_bf16 v[126:129], v[168:171], v[142:145], v[126:129]
	v_mfma_f32_16x16x32_bf16 v[122:125], v[168:171], v[160:163], v[122:125]
	v_mfma_f32_16x16x32_bf16 v[118:121], v[176:179], v[142:145], v[118:121]
	v_mfma_f32_16x16x32_bf16 v[114:117], v[176:179], v[160:163], v[114:117]
	v_mfma_f32_16x16x32_bf16 v[110:113], v[180:183], v[138:141], v[110:113]
	v_mfma_f32_16x16x32_bf16 v[106:109], v[184:187], v[160:163], v[106:109]
	v_mfma_f32_16x16x32_bf16 v[102:105], v[188:191], v[138:141], v[102:105]
	v_mfma_f32_16x16x32_bf16 v[98:101], v[188:191], v[156:159], v[98:101]
	v_mfma_f32_16x16x32_bf16 v[196:199], v[184:187], v[142:145], v[110:113]
	v_mfma_f32_16x16x32_bf16 v[200:203], v[192:195], v[142:145], v[102:105]
	v_mfma_f32_16x16x32_bf16 v[206:209], v[192:195], v[160:163], v[98:101]
	s_setprio 0
	s_barrier
	s_nop 2
	ds_read_b128 v[98:101], v146
	ds_read_b128 v[102:105], v146 offset:1024
	ds_read_b128 v[110:113], v146 offset:2048
	ds_read_b128 v[146:149], v146 offset:3072
	s_barrier
	s_waitcnt lgkmcnt(0)
	s_setprio 1
	s_waitcnt lgkmcnt(0)
	v_mfma_f32_16x16x32_bf16 v[94:97], v[164:167], v[98:101], v[94:97]
	v_mfma_f32_16x16x32_bf16 v[82:85], v[164:167], v[110:113], v[82:85]
	v_mfma_f32_16x16x32_bf16 v[54:57], v[172:175], v[110:113], v[54:57]
	v_mfma_f32_16x16x32_bf16 v[46:49], v[180:183], v[110:113], v[46:49]
	v_mfma_f32_16x16x32_bf16 v[38:41], v[188:191], v[110:113], v[38:41]
	v_mfma_f32_16x16x32_bf16 v[94:97], v[168:171], v[102:105], v[94:97]
	v_mfma_f32_16x16x32_bf16 v[82:85], v[168:171], v[146:149], v[82:85]
	v_mfma_f32_16x16x32_bf16 v[66:69], v[172:175], v[98:101], v[66:69]
	v_mfma_f32_16x16x32_bf16 v[54:57], v[176:179], v[146:149], v[54:57]
	v_mfma_f32_16x16x32_bf16 v[50:53], v[180:183], v[98:101], v[50:53]
	v_mfma_f32_16x16x32_bf16 v[46:49], v[184:187], v[146:149], v[46:49]
	v_mfma_f32_16x16x32_bf16 v[42:45], v[188:191], v[98:101], v[42:45]
	v_mfma_f32_16x16x32_bf16 v[38:41], v[192:195], v[146:149], v[38:41]
	v_mfma_f32_16x16x32_bf16 v[164:167], v[176:179], v[102:105], v[66:69]
	v_mfma_f32_16x16x32_bf16 v[168:171], v[184:187], v[102:105], v[50:53]
	v_mfma_f32_16x16x32_bf16 v[172:175], v[192:195], v[102:105], v[42:45]
	s_setprio 0
	s_barrier
	s_nop 1
	ds_read_b128 v[42:45], v132 offset:16384
	ds_read_b128 v[50:53], v132 offset:17408
	ds_read_b128 v[66:69], v150 offset:16384
	ds_read_b128 v[176:179], v150 offset:17408
	ds_read_b128 v[180:183], v151 offset:16384
	ds_read_b128 v[184:187], v151 offset:17408
	ds_read_b128 v[188:191], v152 offset:16384
	ds_read_b128 v[192:195], v152 offset:17408
	s_waitcnt vmcnt(4)
	s_barrier
	s_waitcnt lgkmcnt(0)
	s_setprio 1
	s_waitcnt lgkmcnt(0)
	v_mfma_f32_16x16x32_bf16 v[30:33], v[42:45], v[156:159], v[30:33]
	v_mfma_f32_16x16x32_bf16 v[26:29], v[66:69], v[138:141], v[26:29]
	v_mfma_f32_16x16x32_bf16 v[14:17], v[180:183], v[156:159], v[14:17]
	v_mfma_f32_16x16x32_bf16 v[6:9], v[188:191], v[156:159], v[6:9]
	v_mfma_f32_16x16x32_bf16 v[34:37], v[42:45], v[138:141], v[34:37]
	v_mfma_f32_16x16x32_bf16 v[30:33], v[50:53], v[160:163], v[30:33]
	v_mfma_f32_16x16x32_bf16 v[26:29], v[176:179], v[142:145], v[26:29]
	v_mfma_f32_16x16x32_bf16 v[22:25], v[66:69], v[156:159], v[22:25]
	v_mfma_f32_16x16x32_bf16 v[18:21], v[180:183], v[138:141], v[18:21]
	v_mfma_f32_16x16x32_bf16 v[14:17], v[184:187], v[160:163], v[14:17]
	v_mfma_f32_16x16x32_bf16 v[10:13], v[188:191], v[138:141], v[10:13]
	v_mfma_f32_16x16x32_bf16 v[6:9], v[192:195], v[160:163], v[6:9]
	v_mfma_f32_16x16x32_bf16 v[210:213], v[50:53], v[142:145], v[34:37]
	v_mfma_f32_16x16x32_bf16 v[214:217], v[176:179], v[160:163], v[22:25]
	v_mfma_f32_16x16x32_bf16 v[218:221], v[184:187], v[142:145], v[18:21]
	v_mfma_f32_16x16x32_bf16 v[138:141], v[192:195], v[142:145], v[10:13]
	s_setprio 0
	s_setprio 1
	v_mfma_f32_16x16x32_bf16 v[2:5], v[42:45], v[98:101], v[2:5]
	v_mfma_f32_16x16x32_bf16 v[142:145], v[50:53], v[102:105], v[2:5]
	v_mfma_f32_16x16x32_bf16 v[2:5], v[42:45], v[110:113], v[58:61]
	v_mfma_f32_16x16x32_bf16 v[154:157], v[50:53], v[146:149], v[2:5]
	v_mfma_f32_16x16x32_bf16 v[2:5], v[66:69], v[98:101], v[62:65]
	v_mfma_f32_16x16x32_bf16 v[158:161], v[176:179], v[102:105], v[2:5]
	v_mfma_f32_16x16x32_bf16 v[2:5], v[66:69], v[110:113], v[70:73]
	v_mfma_f32_16x16x32_bf16 v[176:179], v[176:179], v[146:149], v[2:5]
	v_mfma_f32_16x16x32_bf16 v[2:5], v[180:183], v[98:101], v[74:77]
	v_mfma_f32_16x16x32_bf16 v[222:225], v[184:187], v[102:105], v[2:5]
	v_mfma_f32_16x16x32_bf16 v[2:5], v[180:183], v[110:113], v[78:81]
	v_mfma_f32_16x16x32_bf16 v[180:183], v[184:187], v[146:149], v[2:5]
	v_mfma_f32_16x16x32_bf16 v[2:5], v[188:191], v[98:101], v[86:89]
	v_mfma_f32_16x16x32_bf16 v[184:187], v[192:195], v[102:105], v[2:5]
	v_mfma_f32_16x16x32_bf16 v[2:5], v[188:191], v[110:113], v[90:93]
	v_mfma_f32_16x16x32_bf16 v[146:149], v[192:195], v[146:149], v[2:5]
	s_setprio 0
	s_barrier
; #define LDA(dst, b, h) for (int m = 0; m < 4; ++m) for (int k = 0; k < 2; ++k) \
;     dst[m][k] = *reinterpret_cast<const bf16x8*>((char*)SA(b, h) + lds_byte(wr * 64 + m * 16 + fr, k * 32 + fq * 8))
; #define LDB(dst, b, h) for (int n = 0; n < 2; ++n) for (int k = 0; k < 2; ++k) \
;     dst[n][k] = *reinterpret_cast<const bf16x8*>((char*)SB(b, h) + lds_byte(wc * 32 + n * 16 + fr, k * 32 + fq * 8))
; #define MMA(ai, bj, At_, Bt_) do { __builtin_amdgcn_s_setprio(1); \
;     for (int m = 0; m < 4; ++m) for (int n = 0; n < 2; ++n) for (int k = 0; k < 2; ++k) \
;       acc[ai][bj][m][n] = MFMA16(At_[m][k], Bt_[n][k], acc[ai][bj][m][n]); \
;     __builtin_amdgcn_s_setprio(0); } while (0)
; #define WAIT_V(n) asm volatile("s_waitcnt vmcnt(" #n ")" ::: "memory")
; #define WAIT_L(n) asm volatile("s_waitcnt lgkmcnt(" #n ")" ::: "memory")
; #define BAR __builtin_amdgcn_s_barrier()
; DI void gemm_core(WVP char* smem, const u16* __restrict__ A, int lda, int ar0, int ar1,
;                   const u16* __restrict__ B, int ldb, int bc0, int K, AccT& acc) {
;     ...
;     LDA(At, 0, 1); WAIT_V(4); BAR; WAIT_L(0); MMA(1, 0, At, B0); MMA(1, 1, At, B1); BAR; }
;   { LDB(B0, 1, 0); LDA(At, 1, 0); WAIT_V(2); BAR; WAIT_L(0); MMA(0, 0, At, B0); BAR;
;     LDB(B1, 1, 1); WAIT_V(0); BAR; WAIT_L(0); MMA(0, 1, At, B1); BAR;
;     LDA(At, 1, 1); BAR; WAIT_L(0); MMA(1, 0, At, B0); MMA(1, 1, At, B1); BAR; }
;   if (wr == 0) BAR;
	ds_read_b128 v[62:65], v137
	ds_read_b128 v[74:77], v137 offset:1024
	ds_read_b128 v[86:89], v137 offset:2048
	ds_read_b128 v[134:137], v137 offset:3072
	s_nop 0
	ds_read_b128 v[2:5], v132 offset:32768
	ds_read_b128 v[10:13], v132 offset:33792
	ds_read_b128 v[18:21], v150 offset:32768
	ds_read_b128 v[22:25], v150 offset:33792
	ds_read_b128 v[188:191], v151 offset:32768
	ds_read_b128 v[192:195], v151 offset:33792
	ds_read_b128 v[226:229], v152 offset:32768
	ds_read_b128 v[230:233], v152 offset:33792
	s_waitcnt vmcnt(2)
	s_barrier
	s_waitcnt lgkmcnt(0)
	s_setprio 1
	s_waitcnt lgkmcnt(0)
	v_mfma_f32_16x16x32_bf16 v[34:37], v[2:5], v[62:65], v[126:129]
	v_mfma_f32_16x16x32_bf16 v[98:101], v[10:13], v[74:77], v[34:37]
	v_mfma_f32_16x16x32_bf16 v[34:37], v[2:5], v[86:89], v[122:125]
	v_mfma_f32_16x16x32_bf16 v[122:125], v[10:13], v[134:137], v[34:37]
	v_mfma_f32_16x16x32_bf16 v[34:37], v[18:21], v[62:65], v[118:121]
	v_mfma_f32_16x16x32_bf16 v[110:113], v[22:25], v[74:77], v[34:37]
	v_mfma_f32_16x16x32_bf16 v[34:37], v[18:21], v[86:89], v[114:117]
	v_mfma_f32_16x16x32_bf16 v[102:105], v[22:25], v[134:137], v[34:37]
	v_mfma_f32_16x16x32_bf16 v[34:37], v[188:191], v[62:65], v[196:199]
	v_mfma_f32_16x16x32_bf16 v[78:81], v[192:195], v[74:77], v[34:37]
	v_mfma_f32_16x16x32_bf16 v[34:37], v[188:191], v[86:89], v[106:109]
	v_mfma_f32_16x16x32_bf16 v[90:93], v[192:195], v[134:137], v[34:37]
	v_mfma_f32_16x16x32_bf16 v[34:37], v[226:229], v[62:65], v[200:203]
	v_mfma_f32_16x16x32_bf16 v[66:69], v[230:233], v[74:77], v[34:37]
	v_mfma_f32_16x16x32_bf16 v[34:37], v[226:229], v[86:89], v[206:209]
	v_mfma_f32_16x16x32_bf16 v[70:73], v[230:233], v[134:137], v[34:37]
	s_setprio 0
	s_barrier
	ds_read_b128 v[196:199], v133
	ds_read_b128 v[200:203], v133 offset:1024
	ds_read_b128 v[206:209], v133 offset:2048
	ds_read_b128 v[234:237], v133 offset:3072
	s_waitcnt vmcnt(0)
	s_barrier
	s_waitcnt lgkmcnt(0)
	s_setprio 1
	s_waitcnt lgkmcnt(0)
	v_mfma_f32_16x16x32_bf16 v[34:37], v[2:5], v[196:199], v[94:97]
	v_mfma_f32_16x16x32_bf16 v[2:5], v[2:5], v[206:209], v[82:85]
	v_mfma_f32_16x16x32_bf16 v[58:61], v[10:13], v[234:237], v[2:5]
	v_mfma_f32_16x16x32_bf16 v[2:5], v[18:21], v[196:199], v[164:167]
	v_mfma_f32_16x16x32_bf16 v[42:45], v[22:25], v[200:203], v[2:5]
	v_mfma_f32_16x16x32_bf16 v[2:5], v[18:21], v[206:209], v[54:57]
	v_mfma_f32_16x16x32_bf16 v[50:53], v[10:13], v[200:203], v[34:37]
	v_mfma_f32_16x16x32_bf16 v[34:37], v[22:25], v[234:237], v[2:5]
	v_mfma_f32_16x16x32_bf16 v[2:5], v[188:191], v[196:199], v[168:171]
	v_mfma_f32_16x16x32_bf16 v[18:21], v[192:195], v[200:203], v[2:5]
	v_mfma_f32_16x16x32_bf16 v[2:5], v[188:191], v[206:209], v[46:49]
	v_mfma_f32_16x16x32_bf16 v[22:25], v[192:195], v[234:237], v[2:5]
	v_mfma_f32_16x16x32_bf16 v[2:5], v[226:229], v[196:199], v[172:175]
	v_mfma_f32_16x16x32_bf16 v[10:13], v[230:233], v[200:203], v[2:5]
	v_mfma_f32_16x16x32_bf16 v[2:5], v[226:229], v[206:209], v[38:41]
	v_mfma_f32_16x16x32_bf16 v[2:5], v[230:233], v[234:237], v[2:5]
	s_setprio 0
	s_barrier
	ds_read_b128 v[38:41], v132 offset:49152
	ds_read_b128 v[46:49], v132 offset:50176
	ds_read_b128 v[130:133], v150 offset:49152
	ds_read_b128 v[162:165], v150 offset:50176
	ds_read_b128 v[166:169], v151 offset:49152
	ds_read_b128 v[170:173], v151 offset:50176
	ds_read_b128 v[188:191], v152 offset:49152
	ds_read_b128 v[150:153], v152 offset:50176
	s_barrier
	s_waitcnt lgkmcnt(0)
	s_setprio 1
	s_waitcnt lgkmcnt(0)
	v_mfma_f32_16x16x32_bf16 v[26:29], v[130:133], v[62:65], v[26:29]
	v_mfma_f32_16x16x32_bf16 v[114:117], v[162:165], v[74:77], v[26:29]
	v_mfma_f32_16x16x32_bf16 v[26:29], v[130:133], v[86:89], v[214:217]
	v_mfma_f32_16x16x32_bf16 v[14:17], v[166:169], v[86:89], v[14:17]
	v_mfma_f32_16x16x32_bf16 v[54:57], v[38:41], v[62:65], v[210:213]
	v_mfma_f32_16x16x32_bf16 v[30:33], v[38:41], v[86:89], v[30:33]
	v_mfma_f32_16x16x32_bf16 v[118:121], v[162:165], v[134:137], v[26:29]
	v_mfma_f32_16x16x32_bf16 v[26:29], v[166:169], v[62:65], v[218:221]
	v_mfma_f32_16x16x32_bf16 v[94:97], v[170:173], v[134:137], v[14:17]
	v_mfma_f32_16x16x32_bf16 v[14:17], v[188:191], v[62:65], v[138:141]
	v_mfma_f32_16x16x32_bf16 v[6:9], v[188:191], v[86:89], v[6:9]
	v_mfma_f32_16x16x32_bf16 v[106:109], v[46:49], v[74:77], v[54:57]
	v_mfma_f32_16x16x32_bf16 v[126:129], v[46:49], v[134:137], v[30:33]
	v_mfma_f32_16x16x32_bf16 v[82:85], v[170:173], v[74:77], v[26:29]
	v_mfma_f32_16x16x32_bf16 v[74:77], v[150:153], v[74:77], v[14:17]
	v_mfma_f32_16x16x32_bf16 v[86:89], v[150:153], v[134:137], v[6:9]
	s_setprio 0
	s_setprio 1
	v_mfma_f32_16x16x32_bf16 v[6:9], v[38:41], v[196:199], v[142:145]
	v_mfma_f32_16x16x32_bf16 v[54:57], v[46:49], v[200:203], v[6:9]
	v_mfma_f32_16x16x32_bf16 v[6:9], v[38:41], v[206:209], v[154:157]
	v_mfma_f32_16x16x32_bf16 v[62:65], v[46:49], v[234:237], v[6:9]
	v_mfma_f32_16x16x32_bf16 v[6:9], v[130:133], v[196:199], v[158:161]
	v_mfma_f32_16x16x32_bf16 v[46:49], v[162:165], v[200:203], v[6:9]
	v_mfma_f32_16x16x32_bf16 v[6:9], v[130:133], v[206:209], v[176:179]
	v_mfma_f32_16x16x32_bf16 v[38:41], v[162:165], v[234:237], v[6:9]
	v_mfma_f32_16x16x32_bf16 v[6:9], v[166:169], v[196:199], v[222:225]
	v_mfma_f32_16x16x32_bf16 v[26:29], v[170:173], v[200:203], v[6:9]
	v_mfma_f32_16x16x32_bf16 v[6:9], v[166:169], v[206:209], v[180:183]
	v_mfma_f32_16x16x32_bf16 v[30:33], v[170:173], v[234:237], v[6:9]
	v_mfma_f32_16x16x32_bf16 v[6:9], v[188:191], v[196:199], v[184:187]
	v_mfma_f32_16x16x32_bf16 v[14:17], v[150:153], v[200:203], v[6:9]
	v_mfma_f32_16x16x32_bf16 v[6:9], v[188:191], v[206:209], v[146:149]
	v_mfma_f32_16x16x32_bf16 v[6:9], v[150:153], v[234:237], v[6:9]
	s_setprio 0
	s_cmp_gt_u32 s15, 3
	s_barrier
	s_cbranch_scc1 .LBB0_190
	s_barrier

; #define STAGE_A(P, br, kt) do { const char* _g = (const char*)(A + (long)(br) * lda + (long)(kt) * BK); \
;     __builtin_amdgcn_global_load_lds((const unsigned*)(_g + (size_t)offA0), (unsigned*)((char*)(P) + sb0), 16, 0, 0); \
;     __builtin_amdgcn_global_load_lds((const unsigned*)(_g + (size_t)lda * 128 + (size_t)offA0), (unsigned*)((char*)(P) + sb1), 16, 0, 0); } while (0)
; #define STAGE_B(P, br, kt) do { const char* _g = (const char*)(B + (long)(br) * ldb + (long)(kt) * BK); \
;     __builtin_amdgcn_global_load_lds((const unsigned*)(_g + (size_t)offB0), (unsigned*)((char*)(P) + sb0), 16, 0, 0); \
;     __builtin_amdgcn_global_load_lds((const unsigned*)(_g + (size_t)ldb * 128 + (size_t)offB0), (unsigned*)((char*)(P) + sb1), 16, 0, 0); } while (0)
; #define LDA(dst, b, h) for (int m = 0; m < 4; ++m) for (int k = 0; k < 2; ++k) \
;     dst[m][k] = *reinterpret_cast<const bf16x8*>((char*)SA(b, h) + lds_byte(wr * 64 + m * 16 + fr, k * 32 + fq * 8))
; #define LDB(dst, b, h) for (int n = 0; n < 2; ++n) for (int k = 0; k < 2; ++k) \
;     dst[n][k] = *reinterpret_cast<const bf16x8*>((char*)SB(b, h) + lds_byte(wc * 32 + n * 16 + fr, k * 32 + fq * 8))
; #define WAIT_V(n) asm volatile("s_waitcnt vmcnt(" #n ")" ::: "memory")
; #define WAIT_L(n) asm volatile("s_waitcnt lgkmcnt(" #n ")" ::: "memory")
; DI void gemm_core(WVP char* smem, const u16* __restrict__ A, int lda, int ar0, int ar1,
;                   const u16* __restrict__ B, int ldb, int bc0, int K, AccT& acc) {
;     ...
;   __syncthreads();
;   STAGE_B(SB(0, 0), bb0, 0); STAGE_A(SA(0, 0), ac0, 0);
;   STAGE_B(SB(0, 1), bb1, 0); STAGE_A(SA(0, 1), ac1, 0);
;   if (wr == 1) BAR;
;   WAIT_V(4); BAR;
;   STAGE_B(SB(1, 0), bb0, 1); STAGE_A(SA(1, 0), ac0, 1); STAGE_B(SB(1, 1), bb1, 1);
;   WAIT_V(6); BAR;
;   for (int t = 0; t < nt - 2; t += 2) {
;     LDB(B0, 0, 0); SCHED; LDA(At, 0, 0); STAGE_A(SA(1, 1), ac1, t + 1);
;     WAIT_L(8); BAR; WAIT_L(0); MMA(0, 0, At, B0); BAR; SCHED;
;     LDB(B1, 0, 1); STAGE_B(SB(0, 0), bb0, t + 2);
;     BAR; WAIT_L(0); MMA(0, 1, At, B1); BAR;
;     LDA(At, 0, 1); STAGE_A(SA(0, 0), ac0, t + 2);
;     BAR; WAIT_L(0); MMA(1, 0, At, B0); BAR; SCHED;
;     STAGE_B(SB(0, 1), bb1, t + 2);
;     WAIT_V(6); BAR; MMA(1, 1, At, B1); BAR;
;     LDB(B0, 1, 0); SCHED; LDA(At, 1, 0); STAGE_A(SA(0, 1), ac1, t + 2);
;     WAIT_L(8); BAR; WAIT_L(0); MMA(0, 0, At, B0); BAR; SCHED;
.LBB0_226:
	v_add_u32_e32 v141, s61, v8
	v_lshl_add_u64 v[10:11], s[22:23], 0, v[0:1]
	s_ashr_i32 s47, s1, 6
	v_readfirstlane_b32 s1, v141
	v_add_u32_e32 v142, 0x2000, v141
	v_lshl_add_u64 v[10:11], v[10:11], 0, s[64:65]
	s_mov_b32 m0, s1
	v_readfirstlane_b32 s1, v142
	v_add_u32_e32 v143, 0x8000, v136
	s_waitcnt vmcnt(2)
	s_barrier
	global_load_lds_dwordx4 v[10:11], off
	v_lshl_add_u64 v[10:11], s[36:37], 0, v[0:1]
	s_mov_b32 m0, s1
	v_readfirstlane_b32 s1, v143
	v_add_u32_e32 v145, 0xa000, v136
	global_load_lds_dwordx4 v[10:11], off
	v_lshl_add_u64 v[10:11], v[2:3], 0, s[64:65]
	s_mov_b32 m0, s1
	v_readfirstlane_b32 s1, v145
	v_add_u32_e32 v146, s84, v8
	v_lshl_add_u64 v[12:13], s[28:29], 0, v[0:1]
	global_load_lds_dwordx4 v[10:11], off
	v_lshl_add_u64 v[2:3], v[2:3], 0, s[78:79]
	s_mov_b32 m0, s1
	v_readfirstlane_b32 s1, v146
	v_add_u32_e32 v147, 0x2000, v146
	global_load_lds_dwordx4 v[2:3], off
	v_lshl_add_u64 v[2:3], v[12:13], 0, s[64:65]
	s_mov_b32 m0, s1
	v_readfirstlane_b32 s1, v147
	global_load_lds_dwordx4 v[2:3], off
	v_lshl_add_u64 v[2:3], s[38:39], 0, v[0:1]
	s_mov_b32 m0, s1
	v_and_b32_e32 v9, 15, v5
	global_load_lds_dwordx4 v[2:3], off
	v_lshlrev_b32_e32 v2, 2, v5
	v_and_b32_e32 v14, 48, v5
	v_lshlrev_b32_e32 v0, 6, v9
	v_and_b32_e32 v2, 32, v2
	v_bitop3_b32 v0, v0, v2, v14 bitop3:0x36
	v_add_u32_e32 v3, s5, v0
	v_add_u32_e32 v8, s60, v0
	v_add_u32_e32 v9, s61, v0
	v_add_u32_e32 v10, s84, v0
	v_add_u32_e32 v11, 0, v0
	v_lshlrev_b32_e32 v0, 6, v5
	v_and_or_b32 v0, v0, s74, v14
	v_xad_u32 v148, v0, v2, 0
	v_lshlrev_b32_e32 v0, 14, v4
	v_and_b32_e32 v0, 0xffff8000, v0
	s_waitcnt vmcnt(6)
	s_lshl_b32 s1, s47, 12
	v_lshl_add_u32 v0, v6, 11, v0
	v_and_b32_e32 v2, 1, v4
	s_and_b32 s52, s1, 0x3000
	s_lshl_b32 s53, s0, 13
	v_lshl_or_b32 v0, v2, 6, v0
	v_mov_b32_e32 v2, 0
	s_or_b32 s0, s53, 0x800
	s_or_b32 s1, s53, 0x1000
	s_or_b32 s50, s53, 0x1800
	v_lshl_add_u32 v0, v7, 1, v0
	s_mov_b32 s57, -2
	v_add_u32_e32 v149, s52, v3
	v_add_u32_e32 v132, s53, v11
	v_add_u32_e32 v144, s52, v8
	v_add_u32_e32 v135, s52, v9
	v_add_u32_e32 v133, s52, v10
	s_mov_b64 s[52:53], s[42:43]
	s_mov_b64 vcc, s[40:41]
	v_mov_b32_e32 v3, v2
	v_mov_b32_e32 v4, v2
	v_mov_b32_e32 v5, v2
	v_mov_b32_e32 v6, v2
	v_mov_b32_e32 v7, v2
	v_mov_b32_e32 v8, v2
	v_mov_b32_e32 v9, v2
	v_mov_b32_e32 v10, v2
	v_mov_b32_e32 v11, v2
	v_mov_b32_e32 v12, v2
	v_mov_b32_e32 v13, v2
	v_mov_b32_e32 v14, v2
	v_mov_b32_e32 v15, v2
	s_barrier
.LBB0_227:
	v_add_u32_e32 v150, s0, v148
	v_add_u32_e32 v151, s1, v148
	v_add_u32_e32 v152, s50, v148
	ds_read_b128 v[156:159], v149
	ds_read_b128 v[160:163], v149 offset:1024
	ds_read_b128 v[164:167], v149 offset:2048
	ds_read_b128 v[168:171], v149 offset:3072
	ds_read_b128 v[172:175], v132
	ds_read_b128 v[176:179], v132 offset:1024
	ds_read_b128 v[180:183], v150
	ds_read_b128 v[184:187], v150 offset:1024
	ds_read_b128 v[188:191], v151
	ds_read_b128 v[192:195], v151 offset:1024
	ds_read_b128 v[196:199], v152
	ds_read_b128 v[200:203], v152 offset:1024
	ds_read_b128 v[206:209], v144
	ds_read_b128 v[210:213], v144 offset:1024
	ds_read_b128 v[214:217], v144 offset:2048
	ds_read_b128 v[218:221], v144 offset:3072
	v_add_u32_e32 v153, 0xc000, v136
	v_lshl_add_u64 v[224:225], s[52:53], 0, v[0:1]
	s_mov_b64 s[74:75], 0x3ff80
	v_lshl_add_u64 v[222:223], v[224:225], 0, s[74:75]
	v_readfirstlane_b32 s58, v153
	s_mov_b32 m0, s58
	s_nop 0
	global_load_lds_dwordx4 v[222:223], off
	v_add_u32_e32 v154, 0xe000, v136
	v_lshl_add_u64 v[224:225], s[52:53], 0, v[0:1]
	s_mov_b64 s[74:75], 0x5ff80
	v_lshl_add_u64 v[222:223], v[224:225], 0, s[74:75]
	v_readfirstlane_b32 s58, v154
	s_mov_b32 m0, s58
	s_nop 0
	global_load_lds_dwordx4 v[222:223], off
	s_waitcnt vmcnt(8)
	s_waitcnt lgkmcnt(0)
	s_barrier
	s_setprio 1
	v_mfma_f32_16x16x32_bf16 v[126:129], v[172:175], v[156:159], v[126:129]
	v_mfma_f32_16x16x32_bf16 v[122:125], v[172:175], v[164:167], v[122:125]
	v_mfma_f32_16x16x32_bf16 v[118:121], v[180:183], v[156:159], v[118:121]
	v_mfma_f32_16x16x32_bf16 v[114:117], v[180:183], v[164:167], v[114:117]
	v_mfma_f32_16x16x32_bf16 v[110:113], v[188:191], v[156:159], v[110:113]
	v_mfma_f32_16x16x32_bf16 v[106:109], v[188:191], v[164:167], v[106:109]
	v_mfma_f32_16x16x32_bf16 v[102:105], v[196:199], v[156:159], v[102:105]
	v_mfma_f32_16x16x32_bf16 v[98:101], v[196:199], v[164:167], v[98:101]
	v_mfma_f32_16x16x32_bf16 v[126:129], v[176:179], v[160:163], v[126:129]
	v_mfma_f32_16x16x32_bf16 v[122:125], v[176:179], v[168:171], v[122:125]
	v_mfma_f32_16x16x32_bf16 v[118:121], v[184:187], v[160:163], v[118:121]
	v_mfma_f32_16x16x32_bf16 v[114:117], v[184:187], v[168:171], v[114:117]
	v_mfma_f32_16x16x32_bf16 v[110:113], v[192:195], v[160:163], v[110:113]
	v_mfma_f32_16x16x32_bf16 v[106:109], v[192:195], v[168:171], v[106:109]
	v_mfma_f32_16x16x32_bf16 v[102:105], v[200:203], v[160:163], v[102:105]
	v_mfma_f32_16x16x32_bf16 v[98:101], v[200:203], v[168:171], v[98:101]
	v_mfma_f32_16x16x32_bf16 v[94:97], v[172:175], v[206:209], v[94:97]
	v_mfma_f32_16x16x32_bf16 v[90:93], v[172:175], v[214:217], v[90:93]
	v_mfma_f32_16x16x32_bf16 v[86:89], v[180:183], v[206:209], v[86:89]
	v_mfma_f32_16x16x32_bf16 v[82:85], v[180:183], v[214:217], v[82:85]
	v_mfma_f32_16x16x32_bf16 v[78:81], v[188:191], v[206:209], v[78:81]
	v_mfma_f32_16x16x32_bf16 v[74:77], v[188:191], v[214:217], v[74:77]
	v_mfma_f32_16x16x32_bf16 v[70:73], v[196:199], v[206:209], v[70:73]
	v_mfma_f32_16x16x32_bf16 v[66:69], v[196:199], v[214:217], v[66:69]
	v_mfma_f32_16x16x32_bf16 v[94:97], v[176:179], v[210:213], v[94:97]
	v_mfma_f32_16x16x32_bf16 v[90:93], v[176:179], v[218:221], v[90:93]
	v_mfma_f32_16x16x32_bf16 v[86:89], v[184:187], v[210:213], v[86:89]
	v_mfma_f32_16x16x32_bf16 v[82:85], v[184:187], v[218:221], v[82:85]
	v_mfma_f32_16x16x32_bf16 v[78:81], v[192:195], v[210:213], v[78:81]
	v_mfma_f32_16x16x32_bf16 v[74:77], v[192:195], v[218:221], v[74:77]
	v_mfma_f32_16x16x32_bf16 v[70:73], v[200:203], v[210:213], v[70:73]
	v_mfma_f32_16x16x32_bf16 v[66:69], v[200:203], v[218:221], v[66:69]
	s_setprio 0
	s_barrier
; #define STAGE_A(P, br, kt) do { const char* _g = (const char*)(A + (long)(br) * lda + (long)(kt) * BK); \
;     __builtin_amdgcn_global_load_lds((const unsigned*)(_g + (size_t)offA0), (unsigned*)((char*)(P) + sb0), 16, 0, 0); \
;     __builtin_amdgcn_global_load_lds((const unsigned*)(_g + (size_t)lda * 128 + (size_t)offA0), (unsigned*)((char*)(P) + sb1), 16, 0, 0); } while (0)
; #define STAGE_B(P, br, kt) do { const char* _g = (const char*)(B + (long)(br) * ldb + (long)(kt) * BK); \
;     __builtin_amdgcn_global_load_lds((const unsigned*)(_g + (size_t)offB0), (unsigned*)((char*)(P) + sb0), 16, 0, 0); \
;     __builtin_amdgcn_global_load_lds((const unsigned*)(_g + (size_t)ldb * 128 + (size_t)offB0), (unsigned*)((char*)(P) + sb1), 16, 0, 0); } while (0)
; #define LDA(dst, b, h) for (int m = 0; m < 4; ++m) for (int k = 0; k < 2; ++k) \
;     dst[m][k] = *reinterpret_cast<const bf16x8*>((char*)SA(b, h) + lds_byte(wr * 64 + m * 16 + fr, k * 32 + fq * 8))
; #define LDB(dst, b, h) for (int n = 0; n < 2; ++n) for (int k = 0; k < 2; ++k) \
;     dst[n][k] = *reinterpret_cast<const bf16x8*>((char*)SB(b, h) + lds_byte(wc * 32 + n * 16 + fr, k * 32 + fq * 8))
; #define MMA(ai, bj, At_, Bt_) do { __builtin_amdgcn_s_setprio(1); \
;     for (int m = 0; m < 4; ++m) for (int n = 0; n < 2; ++n) for (int k = 0; k < 2; ++k) \
;       acc[ai][bj][m][n] = MFMA16(At_[m][k], Bt_[n][k], acc[ai][bj][m][n]); \
;     __builtin_amdgcn_s_setprio(0); } while (0)
; #define WAIT_V(n) asm volatile("s_waitcnt vmcnt(" #n ")" ::: "memory")
; #define WAIT_L(n) asm volatile("s_waitcnt lgkmcnt(" #n ")" ::: "memory")
; #define BAR __builtin_amdgcn_s_barrier()
; #define SCHED __builtin_amdgcn_sched_barrier(0)
; DI void gemm_core(WVP char* smem, const u16* __restrict__ A, int lda, int ar0, int ar1,
;                   const u16* __restrict__ B, int ldb, int bc0, int K, AccT& acc) {
;     ...
;     LDA(At, 0, 1); STAGE_A(SA(0, 0), ac0, t + 2);
;     BAR; WAIT_L(0); MMA(1, 0, At, B0); BAR; SCHED;
;     STAGE_B(SB(0, 1), bb1, t + 2);
;     WAIT_V(6); BAR; MMA(1, 1, At, B1); BAR;
;     LDB(B0, 1, 0); SCHED; LDA(At, 1, 0); STAGE_A(SA(0, 1), ac1, t + 2);
;     WAIT_L(8); BAR; WAIT_L(0); MMA(0, 0, At, B0); BAR; SCHED;
;     LDB(B1, 1, 1); STAGE_B(SB(1, 0), bb0, t + 3);
;     BAR; WAIT_L(0); MMA(0, 1, At, B1); BAR;
	ds_read_b128 v[172:175], v132 offset:16384
	ds_read_b128 v[176:179], v132 offset:17408
	ds_read_b128 v[180:183], v150 offset:16384
	ds_read_b128 v[184:187], v150 offset:17408
	ds_read_b128 v[188:191], v151 offset:16384
	ds_read_b128 v[192:195], v151 offset:17408
	ds_read_b128 v[196:199], v152 offset:16384
	ds_read_b128 v[200:203], v152 offset:17408
	v_lshl_add_u64 v[224:225], vcc, 0, v[0:1]
	v_lshl_add_u64 v[222:223], v[224:225], 0, s[80:81]
	v_readfirstlane_b32 s58, v134
	s_mov_b32 m0, s58
	s_nop 0
	global_load_lds_dwordx4 v[222:223], off
	v_add_u32_e32 v155, 0x2000, v134
	v_lshl_add_u64 v[224:225], vcc, 0, v[0:1]
	v_lshl_add_u64 v[222:223], v[224:225], 0, s[82:83]
	v_readfirstlane_b32 s58, v155
	s_mov_b32 m0, s58
	s_nop 0
	global_load_lds_dwordx4 v[222:223], off
	v_lshl_add_u64 v[222:223], s[52:53], 0, v[0:1]
	v_readfirstlane_b32 s58, v136
	s_mov_b32 m0, s58
	s_nop 0
	global_load_lds_dwordx4 v[222:223], off
	v_lshl_add_u64 v[224:225], s[52:53], 0, v[0:1]
	v_lshl_add_u64 v[222:223], v[224:225], 0, s[76:77]
	v_readfirstlane_b32 s58, v137
	s_mov_b32 m0, s58
	s_nop 0
	global_load_lds_dwordx4 v[222:223], off
	v_lshl_add_u64 v[224:225], vcc, 0, v[0:1]
	v_lshl_add_u64 v[222:223], v[224:225], 0, s[88:89]
	v_readfirstlane_b32 s58, v138
	s_mov_b32 m0, s58
	s_nop 0
	global_load_lds_dwordx4 v[222:223], off
	v_add_u32_e32 v155, 0x2000, v138
	v_lshl_add_u64 v[224:225], vcc, 0, v[0:1]
	v_lshl_add_u64 v[222:223], v[224:225], 0, s[90:91]
	v_readfirstlane_b32 s58, v155
	s_mov_b32 m0, s58
	s_nop 0
	global_load_lds_dwordx4 v[222:223], off
	s_waitcnt vmcnt(8)
	s_waitcnt lgkmcnt(0)
	s_barrier
	s_setprio 1
	v_mfma_f32_16x16x32_bf16 v[62:65], v[172:175], v[156:159], v[62:65]
	v_mfma_f32_16x16x32_bf16 v[58:61], v[172:175], v[164:167], v[58:61]
	v_mfma_f32_16x16x32_bf16 v[54:57], v[180:183], v[156:159], v[54:57]
	v_mfma_f32_16x16x32_bf16 v[50:53], v[180:183], v[164:167], v[50:53]
	v_mfma_f32_16x16x32_bf16 v[46:49], v[188:191], v[156:159], v[46:49]
	v_mfma_f32_16x16x32_bf16 v[42:45], v[188:191], v[164:167], v[42:45]
	v_mfma_f32_16x16x32_bf16 v[38:41], v[196:199], v[156:159], v[38:41]
	v_mfma_f32_16x16x32_bf16 v[34:37], v[196:199], v[164:167], v[34:37]
	v_mfma_f32_16x16x32_bf16 v[62:65], v[176:179], v[160:163], v[62:65]
	v_mfma_f32_16x16x32_bf16 v[58:61], v[176:179], v[168:171], v[58:61]
	v_mfma_f32_16x16x32_bf16 v[54:57], v[184:187], v[160:163], v[54:57]
	v_mfma_f32_16x16x32_bf16 v[50:53], v[184:187], v[168:171], v[50:53]
	v_mfma_f32_16x16x32_bf16 v[46:49], v[192:195], v[160:163], v[46:49]
	v_mfma_f32_16x16x32_bf16 v[42:45], v[192:195], v[168:171], v[42:45]
	v_mfma_f32_16x16x32_bf16 v[38:41], v[200:203], v[160:163], v[38:41]
	v_mfma_f32_16x16x32_bf16 v[34:37], v[200:203], v[168:171], v[34:37]
	v_mfma_f32_16x16x32_bf16 v[30:33], v[172:175], v[206:209], v[30:33]
	v_mfma_f32_16x16x32_bf16 v[26:29], v[172:175], v[214:217], v[26:29]
	v_mfma_f32_16x16x32_bf16 v[22:25], v[180:183], v[206:209], v[22:25]
	v_mfma_f32_16x16x32_bf16 v[18:21], v[180:183], v[214:217], v[18:21]
	v_mfma_f32_16x16x32_bf16 v[14:17], v[188:191], v[206:209], v[14:17]
	v_mfma_f32_16x16x32_bf16 v[10:13], v[188:191], v[214:217], v[10:13]
	v_mfma_f32_16x16x32_bf16 v[6:9], v[196:199], v[206:209], v[6:9]
	v_mfma_f32_16x16x32_bf16 v[2:5], v[196:199], v[214:217], v[2:5]
	v_mfma_f32_16x16x32_bf16 v[30:33], v[176:179], v[210:213], v[30:33]
	v_mfma_f32_16x16x32_bf16 v[26:29], v[176:179], v[218:221], v[26:29]
	v_mfma_f32_16x16x32_bf16 v[22:25], v[184:187], v[210:213], v[22:25]
	v_mfma_f32_16x16x32_bf16 v[18:21], v[184:187], v[218:221], v[18:21]
	v_mfma_f32_16x16x32_bf16 v[14:17], v[192:195], v[210:213], v[14:17]
	v_mfma_f32_16x16x32_bf16 v[10:13], v[192:195], v[218:221], v[10:13]
	v_mfma_f32_16x16x32_bf16 v[6:9], v[200:203], v[210:213], v[6:9]
	v_mfma_f32_16x16x32_bf16 v[2:5], v[200:203], v[218:221], v[2:5]
	s_setprio 0
	s_barrier
	ds_read_b128 v[156:159], v135
	ds_read_b128 v[160:163], v135 offset:1024
	ds_read_b128 v[164:167], v135 offset:2048
	ds_read_b128 v[168:171], v135 offset:3072
	ds_read_b128 v[172:175], v132 offset:32768
	ds_read_b128 v[176:179], v132 offset:33792
	ds_read_b128 v[180:183], v150 offset:32768
	ds_read_b128 v[184:187], v150 offset:33792
	ds_read_b128 v[188:191], v151 offset:32768
	ds_read_b128 v[192:195], v151 offset:33792
	ds_read_b128 v[196:199], v152 offset:32768
	ds_read_b128 v[200:203], v152 offset:33792
	ds_read_b128 v[206:209], v133
	ds_read_b128 v[210:213], v133 offset:1024
	ds_read_b128 v[214:217], v133 offset:2048
	ds_read_b128 v[218:221], v133 offset:3072
	v_lshl_add_u64 v[224:225], s[52:53], 0, v[0:1]
	s_mov_b64 s[74:75], 0x40000
	v_lshl_add_u64 v[222:223], v[224:225], 0, s[74:75]
	v_readfirstlane_b32 s58, v139
	s_mov_b32 m0, s58
	s_nop 0
	global_load_lds_dwordx4 v[222:223], off
	v_lshl_add_u64 v[224:225], s[52:53], 0, v[0:1]
	s_mov_b64 s[74:75], 0x60000
	v_lshl_add_u64 v[222:223], v[224:225], 0, s[74:75]
	v_readfirstlane_b32 s58, v140
	s_mov_b32 m0, s58
	s_nop 0
	global_load_lds_dwordx4 v[222:223], off
	s_waitcnt vmcnt(8)
	s_waitcnt lgkmcnt(0)
	s_barrier
; #define STAGE_A(P, br, kt) do { const char* _g = (const char*)(A + (long)(br) * lda + (long)(kt) * BK); \
;     __builtin_amdgcn_global_load_lds((const unsigned*)(_g + (size_t)offA0), (unsigned*)((char*)(P) + sb0), 16, 0, 0); \
;     __builtin_amdgcn_global_load_lds((const unsigned*)(_g + (size_t)lda * 128 + (size_t)offA0), (unsigned*)((char*)(P) + sb1), 16, 0, 0); } while (0)
; #define STAGE_B(P, br, kt) do { const char* _g = (const char*)(B + (long)(br) * ldb + (long)(kt) * BK); \
;     __builtin_amdgcn_global_load_lds((const unsigned*)(_g + (size_t)offB0), (unsigned*)((char*)(P) + sb0), 16, 0, 0); \
;     __builtin_amdgcn_global_load_lds((const unsigned*)(_g + (size_t)ldb * 128 + (size_t)offB0), (unsigned*)((char*)(P) + sb1), 16, 0, 0); } while (0)
; #define LDA(dst, b, h) for (int m = 0; m < 4; ++m) for (int k = 0; k < 2; ++k) \
;     dst[m][k] = *reinterpret_cast<const bf16x8*>((char*)SA(b, h) + lds_byte(wr * 64 + m * 16 + fr, k * 32 + fq * 8))
; #define LDB(dst, b, h) for (int n = 0; n < 2; ++n) for (int k = 0; k < 2; ++k) \
;     dst[n][k] = *reinterpret_cast<const bf16x8*>((char*)SB(b, h) + lds_byte(wc * 32 + n * 16 + fr, k * 32 + fq * 8))
; #define MMA(ai, bj, At_, Bt_) do { __builtin_amdgcn_s_setprio(1); \
;     for (int m = 0; m < 4; ++m) for (int n = 0; n < 2; ++n) for (int k = 0; k < 2; ++k) \
;       acc[ai][bj][m][n] = MFMA16(At_[m][k], Bt_[n][k], acc[ai][bj][m][n]); \
;     __builtin_amdgcn_s_setprio(0); } while (0)
; #define WAIT_V(n) asm volatile("s_waitcnt vmcnt(" #n ")" ::: "memory")
; #define WAIT_L(n) asm volatile("s_waitcnt lgkmcnt(" #n ")" ::: "memory")
; #define BAR __builtin_amdgcn_s_barrier()
; #define SCHED __builtin_amdgcn_sched_barrier(0)
; DI void gemm_core(WVP char* smem, const u16* __restrict__ A, int lda, int ar0, int ar1,
;                   const u16* __restrict__ B, int ldb, int bc0, int K, AccT& acc) {
;     ...
;     WAIT_V(6); BAR; MMA(1, 1, At, B1); BAR;
;     LDB(B0, 1, 0); SCHED; LDA(At, 1, 0); STAGE_A(SA(0, 1), ac1, t + 2);
;     WAIT_L(8); BAR; WAIT_L(0); MMA(0, 0, At, B0); BAR; SCHED;
;     LDB(B1, 1, 1); STAGE_B(SB(1, 0), bb0, t + 3);
;     BAR; WAIT_L(0); MMA(0, 1, At, B1); BAR;
;     LDA(At, 1, 1); STAGE_A(SA(1, 0), ac0, t + 3);
;     BAR; WAIT_L(0); MMA(1, 0, At, B0); BAR; SCHED;
;     STAGE_B(SB(1, 1), bb1, t + 3);
;     WAIT_V(6); BAR; MMA(1, 1, At, B1); BAR;
	s_setprio 1
	v_mfma_f32_16x16x32_bf16 v[126:129], v[172:175], v[156:159], v[126:129]
	v_mfma_f32_16x16x32_bf16 v[122:125], v[172:175], v[164:167], v[122:125]
	v_mfma_f32_16x16x32_bf16 v[118:121], v[180:183], v[156:159], v[118:121]
	v_mfma_f32_16x16x32_bf16 v[114:117], v[180:183], v[164:167], v[114:117]
	v_mfma_f32_16x16x32_bf16 v[110:113], v[188:191], v[156:159], v[110:113]
	v_mfma_f32_16x16x32_bf16 v[106:109], v[188:191], v[164:167], v[106:109]
	v_mfma_f32_16x16x32_bf16 v[102:105], v[196:199], v[156:159], v[102:105]
	v_mfma_f32_16x16x32_bf16 v[98:101], v[196:199], v[164:167], v[98:101]
	v_mfma_f32_16x16x32_bf16 v[126:129], v[176:179], v[160:163], v[126:129]
	v_mfma_f32_16x16x32_bf16 v[122:125], v[176:179], v[168:171], v[122:125]
	v_mfma_f32_16x16x32_bf16 v[118:121], v[184:187], v[160:163], v[118:121]
	v_mfma_f32_16x16x32_bf16 v[114:117], v[184:187], v[168:171], v[114:117]
	v_mfma_f32_16x16x32_bf16 v[110:113], v[192:195], v[160:163], v[110:113]
	v_mfma_f32_16x16x32_bf16 v[106:109], v[192:195], v[168:171], v[106:109]
	v_mfma_f32_16x16x32_bf16 v[102:105], v[200:203], v[160:163], v[102:105]
	v_mfma_f32_16x16x32_bf16 v[98:101], v[200:203], v[168:171], v[98:101]
	v_mfma_f32_16x16x32_bf16 v[94:97], v[172:175], v[206:209], v[94:97]
	v_mfma_f32_16x16x32_bf16 v[90:93], v[172:175], v[214:217], v[90:93]
	v_mfma_f32_16x16x32_bf16 v[86:89], v[180:183], v[206:209], v[86:89]
	v_mfma_f32_16x16x32_bf16 v[82:85], v[180:183], v[214:217], v[82:85]
	v_mfma_f32_16x16x32_bf16 v[78:81], v[188:191], v[206:209], v[78:81]
	v_mfma_f32_16x16x32_bf16 v[74:77], v[188:191], v[214:217], v[74:77]
	v_mfma_f32_16x16x32_bf16 v[70:73], v[196:199], v[206:209], v[70:73]
	v_mfma_f32_16x16x32_bf16 v[66:69], v[196:199], v[214:217], v[66:69]
	v_mfma_f32_16x16x32_bf16 v[94:97], v[176:179], v[210:213], v[94:97]
	v_mfma_f32_16x16x32_bf16 v[90:93], v[176:179], v[218:221], v[90:93]
	v_mfma_f32_16x16x32_bf16 v[86:89], v[184:187], v[210:213], v[86:89]
	v_mfma_f32_16x16x32_bf16 v[82:85], v[184:187], v[218:221], v[82:85]
	v_mfma_f32_16x16x32_bf16 v[78:81], v[192:195], v[210:213], v[78:81]
	v_mfma_f32_16x16x32_bf16 v[74:77], v[192:195], v[218:221], v[74:77]
	v_mfma_f32_16x16x32_bf16 v[70:73], v[200:203], v[210:213], v[70:73]
	v_mfma_f32_16x16x32_bf16 v[66:69], v[200:203], v[218:221], v[66:69]
	s_setprio 0
	s_barrier
	ds_read_b128 v[172:175], v132 offset:49152
	ds_read_b128 v[176:179], v132 offset:50176
	ds_read_b128 v[180:183], v150 offset:49152
	ds_read_b128 v[184:187], v150 offset:50176
	ds_read_b128 v[188:191], v151 offset:49152
	ds_read_b128 v[192:195], v151 offset:50176
	ds_read_b128 v[196:199], v152 offset:49152
	ds_read_b128 v[200:203], v152 offset:50176
	v_lshl_add_u64 v[224:225], vcc, 0, v[0:1]
	v_lshl_add_u64 v[222:223], v[224:225], 0, s[92:93]
	v_readfirstlane_b32 s58, v141
	s_mov_b32 m0, s58
	s_nop 0
	global_load_lds_dwordx4 v[222:223], off
	v_lshl_add_u64 v[224:225], vcc, 0, v[0:1]
	v_lshl_add_u64 v[222:223], v[224:225], 0, s[94:95]
	v_readfirstlane_b32 s58, v142
	s_mov_b32 m0, s58
	s_nop 0
	global_load_lds_dwordx4 v[222:223], off
	v_lshl_add_u64 v[224:225], s[52:53], 0, v[0:1]
	v_lshl_add_u64 v[222:223], v[224:225], 0, s[64:65]
	v_readfirstlane_b32 s58, v143
	s_mov_b32 m0, s58
	s_nop 0
	global_load_lds_dwordx4 v[222:223], off
	v_lshl_add_u64 v[224:225], s[52:53], 0, v[0:1]
	v_lshl_add_u64 v[222:223], v[224:225], 0, s[78:79]
	v_readfirstlane_b32 s58, v145
	s_mov_b32 m0, s58
	s_nop 0
	global_load_lds_dwordx4 v[222:223], off
	v_lshl_add_u64 v[224:225], vcc, 0, v[0:1]
	v_lshl_add_u64 v[222:223], v[224:225], 0, s[96:97]
	v_readfirstlane_b32 s58, v146
	s_mov_b32 m0, s58
	s_nop 0
	global_load_lds_dwordx4 v[222:223], off
	v_lshl_add_u64 v[224:225], vcc, 0, v[0:1]
	v_lshl_add_u64 v[222:223], v[224:225], 0, s[72:73]
	v_readfirstlane_b32 s58, v147
	s_mov_b32 m0, s58
	s_nop 0
	global_load_lds_dwordx4 v[222:223], off
	s_waitcnt vmcnt(8)
	s_waitcnt lgkmcnt(0)
	s_barrier
	s_setprio 1
	v_mfma_f32_16x16x32_bf16 v[62:65], v[172:175], v[156:159], v[62:65]
	v_mfma_f32_16x16x32_bf16 v[58:61], v[172:175], v[164:167], v[58:61]
	v_mfma_f32_16x16x32_bf16 v[54:57], v[180:183], v[156:159], v[54:57]
	v_mfma_f32_16x16x32_bf16 v[50:53], v[180:183], v[164:167], v[50:53]
	v_mfma_f32_16x16x32_bf16 v[46:49], v[188:191], v[156:159], v[46:49]
	v_mfma_f32_16x16x32_bf16 v[42:45], v[188:191], v[164:167], v[42:45]
	v_mfma_f32_16x16x32_bf16 v[38:41], v[196:199], v[156:159], v[38:41]
	v_mfma_f32_16x16x32_bf16 v[34:37], v[196:199], v[164:167], v[34:37]
	v_mfma_f32_16x16x32_bf16 v[62:65], v[176:179], v[160:163], v[62:65]
	v_mfma_f32_16x16x32_bf16 v[58:61], v[176:179], v[168:171], v[58:61]
	v_mfma_f32_16x16x32_bf16 v[54:57], v[184:187], v[160:163], v[54:57]
	v_mfma_f32_16x16x32_bf16 v[50:53], v[184:187], v[168:171], v[50:53]
	v_mfma_f32_16x16x32_bf16 v[46:49], v[192:195], v[160:163], v[46:49]
	v_mfma_f32_16x16x32_bf16 v[42:45], v[192:195], v[168:171], v[42:45]
	v_mfma_f32_16x16x32_bf16 v[38:41], v[200:203], v[160:163], v[38:41]
	v_mfma_f32_16x16x32_bf16 v[34:37], v[200:203], v[168:171], v[34:37]
	v_mfma_f32_16x16x32_bf16 v[30:33], v[172:175], v[206:209], v[30:33]
	v_mfma_f32_16x16x32_bf16 v[26:29], v[172:175], v[214:217], v[26:29]
	v_mfma_f32_16x16x32_bf16 v[22:25], v[180:183], v[206:209], v[22:25]
	v_mfma_f32_16x16x32_bf16 v[18:21], v[180:183], v[214:217], v[18:21]
	v_mfma_f32_16x16x32_bf16 v[14:17], v[188:191], v[206:209], v[14:17]
	v_mfma_f32_16x16x32_bf16 v[10:13], v[188:191], v[214:217], v[10:13]
	v_mfma_f32_16x16x32_bf16 v[6:9], v[196:199], v[206:209], v[6:9]
	v_mfma_f32_16x16x32_bf16 v[2:5], v[196:199], v[214:217], v[2:5]
	v_mfma_f32_16x16x32_bf16 v[30:33], v[176:179], v[210:213], v[30:33]
	v_mfma_f32_16x16x32_bf16 v[26:29], v[176:179], v[218:221], v[26:29]
	v_mfma_f32_16x16x32_bf16 v[22:25], v[184:187], v[210:213], v[22:25]
	v_mfma_f32_16x16x32_bf16 v[18:21], v[184:187], v[218:221], v[18:21]
	v_mfma_f32_16x16x32_bf16 v[14:17], v[192:195], v[210:213], v[14:17]
	v_mfma_f32_16x16x32_bf16 v[10:13], v[192:195], v[218:221], v[10:13]
	v_mfma_f32_16x16x32_bf16 v[6:9], v[200:203], v[210:213], v[6:9]
	v_mfma_f32_16x16x32_bf16 v[2:5], v[200:203], v[218:221], v[2:5]
	s_setprio 0
	s_add_i32 s57, s57, 2
	s_add_u32 vcc_lo, vcc_lo, 0x100
	s_addc_u32 vcc_hi, vcc_hi, 0
	s_add_u32 s52, s52, 0x100
	s_addc_u32 s53, s53, 0
	s_cmp_lt_u32 s57, 12
	s_barrier
; #define STAGE_A(P, br, kt) do { const char* _g = (const char*)(A + (long)(br) * lda + (long)(kt) * BK); \
;     __builtin_amdgcn_global_load_lds((const unsigned*)(_g + (size_t)offA0), (unsigned*)((char*)(P) + sb0), 16, 0, 0); \
;     __builtin_amdgcn_global_load_lds((const unsigned*)(_g + (size_t)lda * 128 + (size_t)offA0), (unsigned*)((char*)(P) + sb1), 16, 0, 0); } while (0)
; #define LDA(dst, b, h) for (int m = 0; m < 4; ++m) for (int k = 0; k < 2; ++k) \
;     dst[m][k] = *reinterpret_cast<const bf16x8*>((char*)SA(b, h) + lds_byte(wr * 64 + m * 16 + fr, k * 32 + fq * 8))
; #define LDB(dst, b, h) for (int n = 0; n < 2; ++n) for (int k = 0; k < 2; ++k) \
;     dst[n][k] = *reinterpret_cast<const bf16x8*>((char*)SB(b, h) + lds_byte(wc * 32 + n * 16 + fr, k * 32 + fq * 8))
; #define MMA(ai, bj, At_, Bt_) do { __builtin_amdgcn_s_setprio(1); \
;     for (int m = 0; m < 4; ++m) for (int n = 0; n < 2; ++n) for (int k = 0; k < 2; ++k) \
;       acc[ai][bj][m][n] = MFMA16(At_[m][k], Bt_[n][k], acc[ai][bj][m][n]); \
;     __builtin_amdgcn_s_setprio(0); } while (0)
; #define WAIT_V(n) asm volatile("s_waitcnt vmcnt(" #n ")" ::: "memory")
; #define WAIT_L(n) asm volatile("s_waitcnt lgkmcnt(" #n ")" ::: "memory")
; #define BAR __builtin_amdgcn_s_barrier()
; DI void gemm_core(WVP char* smem, const u16* __restrict__ A, int lda, int ar0, int ar1,
;                   const u16* __restrict__ B, int ldb, int bc0, int K, AccT& acc) {
;     ...
;   { LDB(B0, 0, 0); LDA(At, 0, 0); STAGE_A(SA(1, 1), ac1, nt - 1);
;     BAR; WAIT_L(0); MMA(0, 0, At, B0); BAR;
;     LDB(B1, 0, 1); BAR; WAIT_L(0); MMA(0, 1, At, B1); BAR;
;     LDA(At, 0, 1); WAIT_V(4); BAR; WAIT_L(0); MMA(1, 0, At, B0); MMA(1, 1, At, B1); BAR; }
	s_cbranch_scc1 .LBB0_227
	s_mov_b64 s[0:1], 0x780
	v_lshl_add_u64 v[192:193], v[130:131], 0, s[0:1]
	v_readfirstlane_b32 s0, v153
	s_mov_b32 m0, s0
	s_mov_b64 s[0:1], 0x20780
	v_lshl_add_u64 v[130:131], v[130:131], 0, s[0:1]
	v_readfirstlane_b32 s0, v154
	ds_read_b128 v[136:139], v149
	ds_read_b128 v[140:143], v149 offset:1024
	ds_read_b128 v[156:159], v149 offset:2048
	ds_read_b128 v[146:149], v149 offset:3072
	ds_read_b128 v[160:163], v132
	ds_read_b128 v[164:167], v132 offset:1024
	ds_read_b128 v[168:171], v150
	ds_read_b128 v[172:175], v150 offset:1024
	ds_read_b128 v[176:179], v151
	ds_read_b128 v[180:183], v151 offset:1024
	ds_read_b128 v[184:187], v152
	ds_read_b128 v[188:191], v152 offset:1024
	global_load_lds_dwordx4 v[192:193], off
	s_mov_b32 m0, s0
	s_nop 0
	global_load_lds_dwordx4 v[130:131], off
	s_waitcnt vmcnt(8)
	s_barrier
	s_waitcnt lgkmcnt(0)
	s_setprio 1
	s_waitcnt lgkmcnt(0)
	v_mfma_f32_16x16x32_bf16 v[126:129], v[160:163], v[136:139], v[126:129]
	v_mfma_f32_16x16x32_bf16 v[118:121], v[168:171], v[136:139], v[118:121]
	v_mfma_f32_16x16x32_bf16 v[110:113], v[176:179], v[136:139], v[110:113]
	v_mfma_f32_16x16x32_bf16 v[102:105], v[184:187], v[136:139], v[102:105]
	v_mfma_f32_16x16x32_bf16 v[126:129], v[164:167], v[140:143], v[126:129]
	v_mfma_f32_16x16x32_bf16 v[122:125], v[160:163], v[156:159], v[122:125]
	v_mfma_f32_16x16x32_bf16 v[118:121], v[172:175], v[140:143], v[118:121]
	v_mfma_f32_16x16x32_bf16 v[114:117], v[168:171], v[156:159], v[114:117]
	v_mfma_f32_16x16x32_bf16 v[110:113], v[180:183], v[140:143], v[110:113]
	v_mfma_f32_16x16x32_bf16 v[106:109], v[176:179], v[156:159], v[106:109]
	v_mfma_f32_16x16x32_bf16 v[102:105], v[188:191], v[140:143], v[102:105]
	v_mfma_f32_16x16x32_bf16 v[98:101], v[184:187], v[156:159], v[98:101]
	v_mfma_f32_16x16x32_bf16 v[192:195], v[164:167], v[146:149], v[122:125]
	v_mfma_f32_16x16x32_bf16 v[196:199], v[172:175], v[146:149], v[114:117]
	v_mfma_f32_16x16x32_bf16 v[200:203], v[180:183], v[146:149], v[106:109]
	v_mfma_f32_16x16x32_bf16 v[206:209], v[188:191], v[146:149], v[98:101]
	s_setprio 0
	s_barrier
	s_nop 1
	ds_read_b128 v[98:101], v144
	ds_read_b128 v[106:109], v144 offset:1024
	ds_read_b128 v[114:117], v144 offset:2048
	ds_read_b128 v[122:125], v144 offset:3072
	s_barrier
	s_waitcnt lgkmcnt(0)
	s_setprio 1
	s_waitcnt lgkmcnt(0)
	v_mfma_f32_16x16x32_bf16 v[94:97], v[160:163], v[98:101], v[94:97]
	v_mfma_f32_16x16x32_bf16 v[86:89], v[168:171], v[98:101], v[86:89]
	v_mfma_f32_16x16x32_bf16 v[78:81], v[176:179], v[98:101], v[78:81]
	v_mfma_f32_16x16x32_bf16 v[70:73], v[184:187], v[98:101], v[70:73]
	v_mfma_f32_16x16x32_bf16 v[94:97], v[164:167], v[106:109], v[94:97]
	v_mfma_f32_16x16x32_bf16 v[90:93], v[160:163], v[114:117], v[90:93]
	v_mfma_f32_16x16x32_bf16 v[86:89], v[172:175], v[106:109], v[86:89]
	v_mfma_f32_16x16x32_bf16 v[82:85], v[168:171], v[114:117], v[82:85]
	v_mfma_f32_16x16x32_bf16 v[78:81], v[180:183], v[106:109], v[78:81]
	v_mfma_f32_16x16x32_bf16 v[74:77], v[176:179], v[114:117], v[74:77]
	v_mfma_f32_16x16x32_bf16 v[70:73], v[188:191], v[106:109], v[70:73]
	v_mfma_f32_16x16x32_bf16 v[66:69], v[184:187], v[114:117], v[66:69]
	v_mfma_f32_16x16x32_bf16 v[160:163], v[164:167], v[122:125], v[90:93]
	v_mfma_f32_16x16x32_bf16 v[164:167], v[172:175], v[122:125], v[82:85]
	v_mfma_f32_16x16x32_bf16 v[168:171], v[180:183], v[122:125], v[74:77]
	v_mfma_f32_16x16x32_bf16 v[172:175], v[188:191], v[122:125], v[66:69]
	s_setprio 0
	s_barrier
	s_nop 1
	ds_read_b128 v[66:69], v132 offset:16384
	ds_read_b128 v[74:77], v132 offset:17408
	ds_read_b128 v[82:85], v150 offset:16384
	ds_read_b128 v[90:93], v150 offset:17408
	ds_read_b128 v[176:179], v151 offset:16384
	ds_read_b128 v[180:183], v151 offset:17408
	ds_read_b128 v[184:187], v152 offset:16384
	ds_read_b128 v[188:191], v152 offset:17408
	s_waitcnt vmcnt(4)
	s_barrier
	s_waitcnt lgkmcnt(0)
	s_setprio 1
	s_waitcnt lgkmcnt(0)
	v_mfma_f32_16x16x32_bf16 v[62:65], v[66:69], v[136:139], v[62:65]
	v_mfma_f32_16x16x32_bf16 v[54:57], v[82:85], v[136:139], v[54:57]
	v_mfma_f32_16x16x32_bf16 v[46:49], v[176:179], v[136:139], v[46:49]
	v_mfma_f32_16x16x32_bf16 v[38:41], v[184:187], v[136:139], v[38:41]
	v_mfma_f32_16x16x32_bf16 v[62:65], v[74:77], v[140:143], v[62:65]
	v_mfma_f32_16x16x32_bf16 v[58:61], v[66:69], v[156:159], v[58:61]
	v_mfma_f32_16x16x32_bf16 v[54:57], v[90:93], v[140:143], v[54:57]
	v_mfma_f32_16x16x32_bf16 v[50:53], v[82:85], v[156:159], v[50:53]
	v_mfma_f32_16x16x32_bf16 v[46:49], v[180:183], v[140:143], v[46:49]
	v_mfma_f32_16x16x32_bf16 v[42:45], v[176:179], v[156:159], v[42:45]
	v_mfma_f32_16x16x32_bf16 v[38:41], v[188:191], v[140:143], v[38:41]
	v_mfma_f32_16x16x32_bf16 v[34:37], v[184:187], v[156:159], v[34:37]
	v_mfma_f32_16x16x32_bf16 v[210:213], v[74:77], v[146:149], v[58:61]
	v_mfma_f32_16x16x32_bf16 v[214:217], v[90:93], v[146:149], v[50:53]
	v_mfma_f32_16x16x32_bf16 v[218:221], v[180:183], v[146:149], v[42:45]
	v_mfma_f32_16x16x32_bf16 v[136:139], v[188:191], v[146:149], v[34:37]
	s_setprio 0
	s_setprio 1
	v_mfma_f32_16x16x32_bf16 v[30:33], v[66:69], v[98:101], v[30:33]
	v_mfma_f32_16x16x32_bf16 v[22:25], v[82:85], v[98:101], v[22:25]
	v_mfma_f32_16x16x32_bf16 v[14:17], v[176:179], v[98:101], v[14:17]
	v_mfma_f32_16x16x32_bf16 v[6:9], v[184:187], v[98:101], v[6:9]
	v_mfma_f32_16x16x32_bf16 v[30:33], v[74:77], v[106:109], v[30:33]
	v_mfma_f32_16x16x32_bf16 v[26:29], v[66:69], v[114:117], v[26:29]
	v_mfma_f32_16x16x32_bf16 v[22:25], v[90:93], v[106:109], v[22:25]
	v_mfma_f32_16x16x32_bf16 v[18:21], v[82:85], v[114:117], v[18:21]
	v_mfma_f32_16x16x32_bf16 v[14:17], v[180:183], v[106:109], v[14:17]
	v_mfma_f32_16x16x32_bf16 v[10:13], v[176:179], v[114:117], v[10:13]
	v_mfma_f32_16x16x32_bf16 v[6:9], v[188:191], v[106:109], v[6:9]
	v_mfma_f32_16x16x32_bf16 v[2:5], v[184:187], v[114:117], v[2:5]
	v_mfma_f32_16x16x32_bf16 v[140:143], v[74:77], v[122:125], v[26:29]
	v_mfma_f32_16x16x32_bf16 v[144:147], v[90:93], v[122:125], v[18:21]
	v_mfma_f32_16x16x32_bf16 v[154:157], v[180:183], v[122:125], v[10:13]
	v_mfma_f32_16x16x32_bf16 v[176:179], v[188:191], v[122:125], v[2:5]
	s_setprio 0
	s_barrier
; #define LDA(dst, b, h) for (int m = 0; m < 4; ++m) for (int k = 0; k < 2; ++k) \
;     dst[m][k] = *reinterpret_cast<const bf16x8*>((char*)SA(b, h) + lds_byte(wr * 64 + m * 16 + fr, k * 32 + fq * 8))
; #define LDB(dst, b, h) for (int n = 0; n < 2; ++n) for (int k = 0; k < 2; ++k) \
;     dst[n][k] = *reinterpret_cast<const bf16x8*>((char*)SB(b, h) + lds_byte(wc * 32 + n * 16 + fr, k * 32 + fq * 8))
; #define MMA(ai, bj, At_, Bt_) do { __builtin_amdgcn_s_setprio(1); \
;     for (int m = 0; m < 4; ++m) for (int n = 0; n < 2; ++n) for (int k = 0; k < 2; ++k) \
;       acc[ai][bj][m][n] = MFMA16(At_[m][k], Bt_[n][k], acc[ai][bj][m][n]); \
;     __builtin_amdgcn_s_setprio(0); } while (0)
; #define WAIT_V(n) asm volatile("s_waitcnt vmcnt(" #n ")" ::: "memory")
; #define WAIT_L(n) asm volatile("s_waitcnt lgkmcnt(" #n ")" ::: "memory")
; #define BAR __builtin_amdgcn_s_barrier()
; DI void gemm_core(WVP char* smem, const u16* __restrict__ A, int lda, int ar0, int ar1,
;                   const u16* __restrict__ B, int ldb, int bc0, int K, AccT& acc) {
;     ...
;   { LDB(B0, 1, 0); LDA(At, 1, 0); WAIT_V(2); BAR; WAIT_L(0); MMA(0, 0, At, B0); BAR;
;     LDB(B1, 1, 1); WAIT_V(0); BAR; WAIT_L(0); MMA(0, 1, At, B1); BAR;
;     LDA(At, 1, 1); BAR; WAIT_L(0); MMA(1, 0, At, B0); MMA(1, 1, At, B1); BAR; }
;   if (wr == 0) BAR;
	ds_read_b128 v[180:183], v135
	ds_read_b128 v[184:187], v135 offset:1024
	ds_read_b128 v[188:191], v135 offset:2048
	ds_read_b128 v[222:225], v135 offset:3072
	ds_read_b128 v[2:5], v132 offset:32768
	ds_read_b128 v[10:13], v132 offset:33792
	ds_read_b128 v[18:21], v150 offset:32768
	ds_read_b128 v[26:29], v150 offset:33792
	ds_read_b128 v[226:229], v151 offset:32768
	ds_read_b128 v[230:233], v151 offset:33792
	ds_read_b128 v[234:237], v152 offset:32768
	ds_read_b128 v[238:241], v152 offset:33792
	s_waitcnt vmcnt(2)
	s_barrier
	s_waitcnt lgkmcnt(0)
	s_setprio 1
	s_waitcnt lgkmcnt(0)
	v_mfma_f32_16x16x32_bf16 v[34:37], v[2:5], v[180:183], v[126:129]
	v_mfma_f32_16x16x32_bf16 v[122:125], v[10:13], v[184:187], v[34:37]
	v_mfma_f32_16x16x32_bf16 v[34:37], v[2:5], v[188:191], v[192:195]
	v_mfma_f32_16x16x32_bf16 v[114:117], v[10:13], v[222:225], v[34:37]
	v_mfma_f32_16x16x32_bf16 v[34:37], v[18:21], v[180:183], v[118:121]
	v_mfma_f32_16x16x32_bf16 v[106:109], v[26:29], v[184:187], v[34:37]
	v_mfma_f32_16x16x32_bf16 v[34:37], v[18:21], v[188:191], v[196:199]
	v_mfma_f32_16x16x32_bf16 v[98:101], v[26:29], v[222:225], v[34:37]
	v_mfma_f32_16x16x32_bf16 v[34:37], v[226:229], v[180:183], v[110:113]
	v_mfma_f32_16x16x32_bf16 v[90:93], v[230:233], v[184:187], v[34:37]
	v_mfma_f32_16x16x32_bf16 v[34:37], v[226:229], v[188:191], v[200:203]
	v_mfma_f32_16x16x32_bf16 v[82:85], v[230:233], v[222:225], v[34:37]
	v_mfma_f32_16x16x32_bf16 v[34:37], v[234:237], v[180:183], v[102:105]
	v_mfma_f32_16x16x32_bf16 v[74:77], v[238:241], v[184:187], v[34:37]
	v_mfma_f32_16x16x32_bf16 v[34:37], v[234:237], v[188:191], v[206:209]
	v_mfma_f32_16x16x32_bf16 v[66:69], v[238:241], v[222:225], v[34:37]
	s_setprio 0
	s_barrier
	ds_read_b128 v[192:195], v133
	ds_read_b128 v[196:199], v133 offset:1024
	ds_read_b128 v[200:203], v133 offset:2048
	ds_read_b128 v[206:209], v133 offset:3072
	s_waitcnt vmcnt(0)
	s_barrier
	s_waitcnt lgkmcnt(0)
	s_setprio 1
	s_waitcnt lgkmcnt(0)
	v_mfma_f32_16x16x32_bf16 v[34:37], v[2:5], v[192:195], v[94:97]
	v_mfma_f32_16x16x32_bf16 v[2:5], v[2:5], v[200:203], v[160:163]
	v_mfma_f32_16x16x32_bf16 v[50:53], v[10:13], v[206:209], v[2:5]
	v_mfma_f32_16x16x32_bf16 v[2:5], v[18:21], v[192:195], v[86:89]
	v_mfma_f32_16x16x32_bf16 v[42:45], v[26:29], v[196:199], v[2:5]
	v_mfma_f32_16x16x32_bf16 v[2:5], v[18:21], v[200:203], v[164:167]
	v_mfma_f32_16x16x32_bf16 v[58:61], v[10:13], v[196:199], v[34:37]
	v_mfma_f32_16x16x32_bf16 v[34:37], v[26:29], v[206:209], v[2:5]
	v_mfma_f32_16x16x32_bf16 v[2:5], v[226:229], v[192:195], v[78:81]
	v_mfma_f32_16x16x32_bf16 v[26:29], v[230:233], v[196:199], v[2:5]
	v_mfma_f32_16x16x32_bf16 v[2:5], v[226:229], v[200:203], v[168:171]
	v_mfma_f32_16x16x32_bf16 v[18:21], v[230:233], v[206:209], v[2:5]
	v_mfma_f32_16x16x32_bf16 v[2:5], v[234:237], v[192:195], v[70:73]
	v_mfma_f32_16x16x32_bf16 v[10:13], v[238:241], v[196:199], v[2:5]
	v_mfma_f32_16x16x32_bf16 v[2:5], v[234:237], v[200:203], v[172:175]
	v_mfma_f32_16x16x32_bf16 v[2:5], v[238:241], v[206:209], v[2:5]
	s_setprio 0
	s_barrier
	ds_read_b128 v[158:161], v132 offset:49152
	ds_read_b128 v[130:133], v132 offset:50176
	ds_read_b128 v[162:165], v150 offset:49152
	ds_read_b128 v[166:169], v150 offset:50176
	ds_read_b128 v[170:173], v151 offset:49152
	ds_read_b128 v[148:151], v151 offset:50176
	ds_read_b128 v[226:229], v152 offset:49152
	ds_read_b128 v[230:233], v152 offset:50176
	s_barrier
	s_waitcnt lgkmcnt(0)
	s_setprio 1
	s_waitcnt lgkmcnt(0)
	v_mfma_f32_16x16x32_bf16 v[62:65], v[158:161], v[180:183], v[62:65]
	v_mfma_f32_16x16x32_bf16 v[54:57], v[162:165], v[180:183], v[54:57]
	v_mfma_f32_16x16x32_bf16 v[46:49], v[170:173], v[180:183], v[46:49]
	v_mfma_f32_16x16x32_bf16 v[38:41], v[226:229], v[180:183], v[38:41]
	v_mfma_f32_16x16x32_bf16 v[126:129], v[130:133], v[184:187], v[62:65]
	v_mfma_f32_16x16x32_bf16 v[62:65], v[158:161], v[188:191], v[210:213]
	v_mfma_f32_16x16x32_bf16 v[110:113], v[166:169], v[184:187], v[54:57]
	v_mfma_f32_16x16x32_bf16 v[54:57], v[162:165], v[188:191], v[214:217]
	v_mfma_f32_16x16x32_bf16 v[94:97], v[148:151], v[184:187], v[46:49]
	v_mfma_f32_16x16x32_bf16 v[46:49], v[170:173], v[188:191], v[218:221]
	v_mfma_f32_16x16x32_bf16 v[78:81], v[230:233], v[184:187], v[38:41]
	v_mfma_f32_16x16x32_bf16 v[38:41], v[226:229], v[188:191], v[136:139]
	v_mfma_f32_16x16x32_bf16 v[118:121], v[130:133], v[222:225], v[62:65]
	v_mfma_f32_16x16x32_bf16 v[102:105], v[166:169], v[222:225], v[54:57]
	v_mfma_f32_16x16x32_bf16 v[86:89], v[148:151], v[222:225], v[46:49]
	v_mfma_f32_16x16x32_bf16 v[70:73], v[230:233], v[222:225], v[38:41]
	s_setprio 0
	s_setprio 1
	v_mfma_f32_16x16x32_bf16 v[30:33], v[158:161], v[192:195], v[30:33]
	v_mfma_f32_16x16x32_bf16 v[62:65], v[130:133], v[196:199], v[30:33]
	v_mfma_f32_16x16x32_bf16 v[30:33], v[158:161], v[200:203], v[140:143]
	v_mfma_f32_16x16x32_bf16 v[22:25], v[162:165], v[192:195], v[22:25]
	v_mfma_f32_16x16x32_bf16 v[14:17], v[170:173], v[192:195], v[14:17]
	v_mfma_f32_16x16x32_bf16 v[54:57], v[130:133], v[206:209], v[30:33]
	v_mfma_f32_16x16x32_bf16 v[46:49], v[166:169], v[196:199], v[22:25]
	v_mfma_f32_16x16x32_bf16 v[22:25], v[162:165], v[200:203], v[144:147]
	v_mfma_f32_16x16x32_bf16 v[30:33], v[148:151], v[196:199], v[14:17]
	v_mfma_f32_16x16x32_bf16 v[14:17], v[170:173], v[200:203], v[154:157]
	v_mfma_f32_16x16x32_bf16 v[6:9], v[226:229], v[192:195], v[6:9]
	v_mfma_f32_16x16x32_bf16 v[38:41], v[166:169], v[206:209], v[22:25]
	v_mfma_f32_16x16x32_bf16 v[22:25], v[148:151], v[206:209], v[14:17]
	v_mfma_f32_16x16x32_bf16 v[14:17], v[230:233], v[196:199], v[6:9]
	v_mfma_f32_16x16x32_bf16 v[6:9], v[226:229], v[200:203], v[176:179]
	v_mfma_f32_16x16x32_bf16 v[6:9], v[230:233], v[206:209], v[6:9]
	s_setprio 0
	s_cmp_gt_u32 s47, 3
	s_barrier
	s_cbranch_scc1 .LBB0_213
	s_barrier
	s_branch .LBB0_213

; #define STAGE_A(P, br, kt) do { const char* _g = (const char*)(A + (long)(br) * lda + (long)(kt) * BK); \
;     __builtin_amdgcn_global_load_lds((const unsigned*)(_g + (size_t)offA0), (unsigned*)((char*)(P) + sb0), 16, 0, 0); \
;     __builtin_amdgcn_global_load_lds((const unsigned*)(_g + (size_t)lda * 128 + (size_t)offA0), (unsigned*)((char*)(P) + sb1), 16, 0, 0); } while (0)
; #define STAGE_B(P, br, kt) do { const char* _g = (const char*)(B + (long)(br) * ldb + (long)(kt) * BK); \
;     __builtin_amdgcn_global_load_lds((const unsigned*)(_g + (size_t)offB0), (unsigned*)((char*)(P) + sb0), 16, 0, 0); \
;     __builtin_amdgcn_global_load_lds((const unsigned*)(_g + (size_t)ldb * 128 + (size_t)offB0), (unsigned*)((char*)(P) + sb1), 16, 0, 0); } while (0)
; #define LDA(dst, b, h) for (int m = 0; m < 4; ++m) for (int k = 0; k < 2; ++k) \
;     dst[m][k] = *reinterpret_cast<const bf16x8*>((char*)SA(b, h) + lds_byte(wr * 64 + m * 16 + fr, k * 32 + fq * 8))
; #define LDB(dst, b, h) for (int n = 0; n < 2; ++n) for (int k = 0; k < 2; ++k) \
;     dst[n][k] = *reinterpret_cast<const bf16x8*>((char*)SB(b, h) + lds_byte(wc * 32 + n * 16 + fr, k * 32 + fq * 8))
; #define WAIT_V(n) asm volatile("s_waitcnt vmcnt(" #n ")" ::: "memory")
; #define WAIT_L(n) asm volatile("s_waitcnt lgkmcnt(" #n ")" ::: "memory")
; #define BAR __builtin_amdgcn_s_barrier()
; #define SCHED __builtin_amdgcn_sched_barrier(0)
; DI void gemm_core(WVP char* smem, const u16* __restrict__ A, int lda, int ar0, int ar1,
;                   const u16* __restrict__ B, int ldb, int bc0, int K, AccT& acc) {
;     ...
;   const int sb0 = tid * 16, sb1 = sb0 + 8192;
;   int R0, C0; stage_rc(sb0, R0, C0);
;   const unsigned offA0 = (unsigned)(R0 * lda + C0) * 2u, offB0 = (unsigned)(R0 * ldb + C0) * 2u;
;   const int ac0 = ar0, ac1 = ar1, bb0 = bc0, bb1 = bc0 + HALF;
;   bf16x8 At[4][2], B0[2][2], B1[2][2];
;   const int nt = K / BK;
;   __syncthreads();
;   STAGE_B(SB(0, 0), bb0, 0); STAGE_A(SA(0, 0), ac0, 0);
;   STAGE_B(SB(0, 1), bb1, 0); STAGE_A(SA(0, 1), ac1, 0);
;   if (wr == 1) BAR;
;   WAIT_V(4); BAR;
;   STAGE_B(SB(1, 0), bb0, 1); STAGE_A(SA(1, 0), ac0, 1); STAGE_B(SB(1, 1), bb1, 1);
;   WAIT_V(6); BAR;
;   for (int t = 0; t < nt - 2; t += 2) {
;     LDB(B0, 0, 0); SCHED; LDA(At, 0, 0); STAGE_A(SA(1, 1), ac1, t + 1);
;     WAIT_L(8); BAR; WAIT_L(0); MMA(0, 0, At, B0); BAR; SCHED;
.LBB0_236:
	v_add_u32_e32 v155, s61, v150
	v_add_u32_e32 v156, 0x2000, v155
	v_readfirstlane_b32 s35, v155
	v_lshl_add_u64 v[130:131], v[130:131], 0, s[64:65]
	s_mov_b32 m0, s35
	v_readfirstlane_b32 s35, v156
	v_add_u32_e32 v157, 0x8000, v147
	s_waitcnt vmcnt(2)
	s_barrier
	global_load_lds_dwordx4 v[130:131], off
	v_lshl_add_u64 v[130:131], v[132:133], 0, s[64:65]
	s_mov_b32 m0, s35
	v_readfirstlane_b32 s35, v157
	v_add_u32_e32 v158, 0xa000, v147
	global_load_lds_dwordx4 v[130:131], off
	v_lshl_add_u64 v[130:131], v[134:135], 0, s[64:65]
	s_mov_b32 m0, s35
	v_readfirstlane_b32 s35, v158
	v_add_u32_e32 v159, s84, v150
	global_load_lds_dwordx4 v[130:131], off
	v_lshl_add_u64 v[130:131], v[136:137], 0, s[64:65]
	s_mov_b32 m0, s35
	v_readfirstlane_b32 s35, v159
	v_add_u32_e32 v160, 0x2000, v159
	global_load_lds_dwordx4 v[130:131], off
	v_lshl_add_u64 v[130:131], v[138:139], 0, s[64:65]
	s_mov_b32 m0, s35
	v_readfirstlane_b32 s35, v160
	global_load_lds_dwordx4 v[130:131], off
	v_lshl_add_u64 v[130:131], v[140:141], 0, s[64:65]
	s_mov_b32 m0, s35
	v_lshlrev_b32_e32 v132, 2, v142
	global_load_lds_dwordx4 v[130:131], off
	v_and_b32_e32 v130, 15, v142
	v_and_b32_e32 v131, 48, v142
	v_lshlrev_b32_e32 v130, 6, v130
	v_and_b32_e32 v132, 32, v132
	s_ashr_i32 s35, s1, 6
	v_bitop3_b32 v130, v130, v132, v131 bitop3:0x36
	s_lshr_b32 s0, s0, 6
	s_lshl_b32 s38, s35, 12
	v_add_u32_e32 v150, s5, v130
	v_add_u32_e32 v153, s60, v130
	v_add_u32_e32 v154, s61, v130
	v_add_u32_e32 v164, s84, v130
	s_lshl_b32 s47, s37, 13
	v_add_u32_e32 v162, 0, v130
	v_lshlrev_b32_e32 v130, 6, v142
	s_add_i32 s1, s0, -2
	s_and_b32 s46, s38, 0x3000
	v_and_or_b32 v130, v130, s74, v131
	s_or_b32 s37, s47, 0x800
	s_or_b32 s38, s47, 0x1000
	s_or_b32 s39, s47, 0x1800
	s_mul_i32 s44, s22, s41
	v_xad_u32 v161, v130, v132, 0
	s_mul_hi_i32 s45, s22, s41
	v_add_u32_e32 v130, v145, v143
	s_add_u32 s44, s42, s44
	v_add_lshl_u32 v140, v130, v144, 1
	v_mov_b32_e32 v141, v1
	s_addc_u32 s45, s40, s45
	v_lshl_add_u64 v[130:131], s[44:45], 0, v[140:141]
	s_mul_i32 s44, s13, s41
	s_mul_hi_i32 s45, s13, s41
	s_add_u32 s44, s42, s44
	s_addc_u32 s45, s40, s45
	v_lshl_add_u64 v[132:133], s[44:45], 0, v[140:141]
	s_add_u32 s44, s43, s28
	s_addc_u32 s45, 0, s29
	s_add_u32 s44, s54, s44
	s_addc_u32 s45, s55, s45
	v_lshl_add_u64 v[134:135], s[44:45], 0, v[0:1]
	s_add_u32 s44, s36, s43
	s_addc_u32 s45, 0, 0
	s_add_u32 s28, s44, s28
	s_addc_u32 s29, s45, s29
	s_add_u32 s28, s54, s28
	s_addc_u32 s29, s55, s29
	v_lshl_add_u64 v[136:137], s[28:29], 0, v[0:1]
	s_mul_i32 s28, s21, s41
	s_mul_hi_i32 s29, s21, s41
	s_add_u32 s28, s42, s28
	s_addc_u32 s29, s40, s29
	v_lshl_add_u64 v[138:139], s[28:29], 0, v[140:141]
	s_mul_i32 s28, s23, s41
	s_mul_hi_i32 s29, s23, s41
	s_add_u32 s28, s42, s28
	s_addc_u32 s29, s40, s29
	v_lshl_add_u64 v[140:141], s[28:29], 0, v[140:141]
	s_add_u32 s28, s43, s30
	s_addc_u32 s29, 0, s31
	s_add_u32 s28, s54, s28
	s_addc_u32 s29, s55, s29
	v_lshl_add_u64 v[142:143], s[28:29], 0, v[0:1]
	s_add_u32 s28, s44, s30
	s_addc_u32 s29, s45, s31
	s_waitcnt vmcnt(6)
	s_add_u32 s28, s54, s28
	s_addc_u32 s29, s55, s29
	v_lshl_add_u64 v[144:145], s[28:29], 0, v[0:1]
	s_mov_b32 s30, 0
	s_mov_b64 s[28:29], 0
	v_add_u32_e32 v163, s46, v150
	v_add_u32_e32 v150, s47, v162
	v_add_u32_e32 v162, s46, v153
	v_add_u32_e32 v154, s46, v154
	v_add_u32_e32 v153, s46, v164
	s_barrier
.LBB0_237:
	v_add_u32_e32 v164, s37, v161
	v_add_u32_e32 v165, s38, v161
	v_add_u32_e32 v166, s39, v161
	ds_read_b128 v[170:173], v163
	ds_read_b128 v[174:177], v163 offset:1024
	ds_read_b128 v[178:181], v163 offset:2048
	ds_read_b128 v[182:185], v163 offset:3072
	ds_read_b128 v[186:189], v150
	ds_read_b128 v[190:193], v150 offset:1024
	ds_read_b128 v[194:197], v164
	ds_read_b128 v[198:201], v164 offset:1024
	ds_read_b128 v[206:209], v165
	ds_read_b128 v[210:213], v165 offset:1024
	ds_read_b128 v[214:217], v166
	ds_read_b128 v[218:221], v166 offset:1024
	ds_read_b128 v[222:225], v162
	ds_read_b128 v[226:229], v162 offset:1024
	ds_read_b128 v[230:233], v162 offset:2048
	ds_read_b128 v[234:237], v162 offset:3072
	v_add_u32_e32 v168, 0xc000, v147
	v_lshl_add_u64 v[238:239], v[142:143], 0, s[28:29]
	v_lshl_add_u64 v[202:203], v[238:239], 0, s[6:7]
	v_readfirstlane_b32 s31, v168
	s_mov_b32 m0, s31
	s_nop 0
	global_load_lds_dwordx4 v[202:203], off
	v_add_u32_e32 v167, 0xe000, v147
	v_lshl_add_u64 v[238:239], v[144:145], 0, s[28:29]
	v_lshl_add_u64 v[202:203], v[238:239], 0, s[6:7]
	v_readfirstlane_b32 s31, v167
	s_mov_b32 m0, s31
	s_nop 0
	global_load_lds_dwordx4 v[202:203], off
	s_waitcnt vmcnt(8)
	s_waitcnt lgkmcnt(0)
	s_barrier
; #define STAGE_A(P, br, kt) do { const char* _g = (const char*)(A + (long)(br) * lda + (long)(kt) * BK); \
;     __builtin_amdgcn_global_load_lds((const unsigned*)(_g + (size_t)offA0), (unsigned*)((char*)(P) + sb0), 16, 0, 0); \
;     __builtin_amdgcn_global_load_lds((const unsigned*)(_g + (size_t)lda * 128 + (size_t)offA0), (unsigned*)((char*)(P) + sb1), 16, 0, 0); } while (0)
; #define STAGE_B(P, br, kt) do { const char* _g = (const char*)(B + (long)(br) * ldb + (long)(kt) * BK); \
;     __builtin_amdgcn_global_load_lds((const unsigned*)(_g + (size_t)offB0), (unsigned*)((char*)(P) + sb0), 16, 0, 0); \
;     __builtin_amdgcn_global_load_lds((const unsigned*)(_g + (size_t)ldb * 128 + (size_t)offB0), (unsigned*)((char*)(P) + sb1), 16, 0, 0); } while (0)
; #define LDA(dst, b, h) for (int m = 0; m < 4; ++m) for (int k = 0; k < 2; ++k) \
;     dst[m][k] = *reinterpret_cast<const bf16x8*>((char*)SA(b, h) + lds_byte(wr * 64 + m * 16 + fr, k * 32 + fq * 8))
; #define LDB(dst, b, h) for (int n = 0; n < 2; ++n) for (int k = 0; k < 2; ++k) \
;     dst[n][k] = *reinterpret_cast<const bf16x8*>((char*)SB(b, h) + lds_byte(wc * 32 + n * 16 + fr, k * 32 + fq * 8))
; #define MMA(ai, bj, At_, Bt_) do { __builtin_amdgcn_s_setprio(1); \
;     for (int m = 0; m < 4; ++m) for (int n = 0; n < 2; ++n) for (int k = 0; k < 2; ++k) \
;       acc[ai][bj][m][n] = MFMA16(At_[m][k], Bt_[n][k], acc[ai][bj][m][n]); \
;     __builtin_amdgcn_s_setprio(0); } while (0)
; #define WAIT_V(n) asm volatile("s_waitcnt vmcnt(" #n ")" ::: "memory")
; #define WAIT_L(n) asm volatile("s_waitcnt lgkmcnt(" #n ")" ::: "memory")
; #define BAR __builtin_amdgcn_s_barrier()
; #define SCHED __builtin_amdgcn_sched_barrier(0)
; DI void gemm_core(WVP char* smem, const u16* __restrict__ A, int lda, int ar0, int ar1,
;                   const u16* __restrict__ B, int ldb, int bc0, int K, AccT& acc) {
;     ...
;     LDB(B0, 0, 0); SCHED; LDA(At, 0, 0); STAGE_A(SA(1, 1), ac1, t + 1);
;     WAIT_L(8); BAR; WAIT_L(0); MMA(0, 0, At, B0); BAR; SCHED;
;     LDB(B1, 0, 1); STAGE_B(SB(0, 0), bb0, t + 2);
;     BAR; WAIT_L(0); MMA(0, 1, At, B1); BAR;
;     LDA(At, 0, 1); STAGE_A(SA(0, 0), ac0, t + 2);
;     BAR; WAIT_L(0); MMA(1, 0, At, B0); BAR; SCHED;
;     STAGE_B(SB(0, 1), bb1, t + 2);
;     WAIT_V(6); BAR; MMA(1, 1, At, B1); BAR;
	s_setprio 1
	v_mfma_f32_16x16x32_bf16 v[126:129], v[186:189], v[170:173], v[126:129]
	v_mfma_f32_16x16x32_bf16 v[118:121], v[186:189], v[178:181], v[118:121]
	v_mfma_f32_16x16x32_bf16 v[110:113], v[194:197], v[170:173], v[110:113]
	v_mfma_f32_16x16x32_bf16 v[102:105], v[194:197], v[178:181], v[102:105]
	v_mfma_f32_16x16x32_bf16 v[98:101], v[206:209], v[170:173], v[98:101]
	v_mfma_f32_16x16x32_bf16 v[86:89], v[206:209], v[178:181], v[86:89]
	v_mfma_f32_16x16x32_bf16 v[78:81], v[214:217], v[170:173], v[78:81]
	v_mfma_f32_16x16x32_bf16 v[70:73], v[214:217], v[178:181], v[70:73]
	v_mfma_f32_16x16x32_bf16 v[126:129], v[190:193], v[174:177], v[126:129]
	v_mfma_f32_16x16x32_bf16 v[118:121], v[190:193], v[182:185], v[118:121]
	v_mfma_f32_16x16x32_bf16 v[110:113], v[198:201], v[174:177], v[110:113]
	v_mfma_f32_16x16x32_bf16 v[102:105], v[198:201], v[182:185], v[102:105]
	v_mfma_f32_16x16x32_bf16 v[98:101], v[210:213], v[174:177], v[98:101]
	v_mfma_f32_16x16x32_bf16 v[86:89], v[210:213], v[182:185], v[86:89]
	v_mfma_f32_16x16x32_bf16 v[78:81], v[218:221], v[174:177], v[78:81]
	v_mfma_f32_16x16x32_bf16 v[70:73], v[218:221], v[182:185], v[70:73]
	v_mfma_f32_16x16x32_bf16 v[66:69], v[186:189], v[222:225], v[66:69]
	v_mfma_f32_16x16x32_bf16 v[54:57], v[186:189], v[230:233], v[54:57]
	v_mfma_f32_16x16x32_bf16 v[46:49], v[194:197], v[222:225], v[46:49]
	v_mfma_f32_16x16x32_bf16 v[38:41], v[194:197], v[230:233], v[38:41]
	v_mfma_f32_16x16x32_bf16 v[34:37], v[206:209], v[222:225], v[34:37]
	v_mfma_f32_16x16x32_bf16 v[22:25], v[206:209], v[230:233], v[22:25]
	v_mfma_f32_16x16x32_bf16 v[14:17], v[214:217], v[222:225], v[14:17]
	v_mfma_f32_16x16x32_bf16 v[6:9], v[214:217], v[230:233], v[6:9]
	v_mfma_f32_16x16x32_bf16 v[66:69], v[190:193], v[226:229], v[66:69]
	v_mfma_f32_16x16x32_bf16 v[54:57], v[190:193], v[234:237], v[54:57]
	v_mfma_f32_16x16x32_bf16 v[46:49], v[198:201], v[226:229], v[46:49]
	v_mfma_f32_16x16x32_bf16 v[38:41], v[198:201], v[234:237], v[38:41]
	v_mfma_f32_16x16x32_bf16 v[34:37], v[210:213], v[226:229], v[34:37]
	v_mfma_f32_16x16x32_bf16 v[22:25], v[210:213], v[234:237], v[22:25]
	v_mfma_f32_16x16x32_bf16 v[14:17], v[218:221], v[226:229], v[14:17]
	v_mfma_f32_16x16x32_bf16 v[6:9], v[218:221], v[234:237], v[6:9]
	s_setprio 0
	s_barrier
	ds_read_b128 v[186:189], v150 offset:16384
	ds_read_b128 v[190:193], v150 offset:17408
	ds_read_b128 v[194:197], v164 offset:16384
	ds_read_b128 v[198:201], v164 offset:17408
	ds_read_b128 v[206:209], v165 offset:16384
	ds_read_b128 v[210:213], v165 offset:17408
	ds_read_b128 v[214:217], v166 offset:16384
	ds_read_b128 v[218:221], v166 offset:17408
	v_lshl_add_u64 v[238:239], v[130:131], 0, s[28:29]
	v_lshl_add_u64 v[202:203], v[238:239], 0, s[68:69]
	v_readfirstlane_b32 s31, v146
	s_mov_b32 m0, s31
	s_nop 0
	global_load_lds_dwordx4 v[202:203], off
	v_add_u32_e32 v169, 0x2000, v146
	v_lshl_add_u64 v[238:239], v[132:133], 0, s[28:29]
	v_lshl_add_u64 v[202:203], v[238:239], 0, s[68:69]
	v_readfirstlane_b32 s31, v169
	s_mov_b32 m0, s31
	s_nop 0
	global_load_lds_dwordx4 v[202:203], off
	v_lshl_add_u64 v[238:239], v[134:135], 0, s[28:29]
	v_lshl_add_u64 v[202:203], v[238:239], 0, s[48:49]
	v_readfirstlane_b32 s31, v147
	s_mov_b32 m0, s31
	s_nop 0
	global_load_lds_dwordx4 v[202:203], off
	v_lshl_add_u64 v[238:239], v[136:137], 0, s[28:29]
	v_lshl_add_u64 v[202:203], v[238:239], 0, s[48:49]
	v_readfirstlane_b32 s31, v148
	s_mov_b32 m0, s31
	s_nop 0
	global_load_lds_dwordx4 v[202:203], off
	v_lshl_add_u64 v[238:239], v[138:139], 0, s[28:29]
	v_lshl_add_u64 v[202:203], v[238:239], 0, s[68:69]
	v_readfirstlane_b32 s31, v149
	s_mov_b32 m0, s31
	s_nop 0
	global_load_lds_dwordx4 v[202:203], off
	v_add_u32_e32 v169, 0x2000, v149
	v_lshl_add_u64 v[238:239], v[140:141], 0, s[28:29]
	v_lshl_add_u64 v[202:203], v[238:239], 0, s[68:69]
	v_readfirstlane_b32 s31, v169
	s_mov_b32 m0, s31
	s_nop 0
	global_load_lds_dwordx4 v[202:203], off
	s_waitcnt vmcnt(8)
	s_waitcnt lgkmcnt(0)
	s_barrier
	s_setprio 1
	v_mfma_f32_16x16x32_bf16 v[122:125], v[186:189], v[170:173], v[122:125]
	v_mfma_f32_16x16x32_bf16 v[114:117], v[186:189], v[178:181], v[114:117]
	v_mfma_f32_16x16x32_bf16 v[106:109], v[194:197], v[170:173], v[106:109]
	v_mfma_f32_16x16x32_bf16 v[94:97], v[194:197], v[178:181], v[94:97]
	v_mfma_f32_16x16x32_bf16 v[90:93], v[206:209], v[170:173], v[90:93]
	v_mfma_f32_16x16x32_bf16 v[82:85], v[206:209], v[178:181], v[82:85]
	v_mfma_f32_16x16x32_bf16 v[74:77], v[214:217], v[170:173], v[74:77]
	v_mfma_f32_16x16x32_bf16 v[62:65], v[214:217], v[178:181], v[62:65]
	v_mfma_f32_16x16x32_bf16 v[122:125], v[190:193], v[174:177], v[122:125]
	v_mfma_f32_16x16x32_bf16 v[114:117], v[190:193], v[182:185], v[114:117]
	v_mfma_f32_16x16x32_bf16 v[106:109], v[198:201], v[174:177], v[106:109]
	v_mfma_f32_16x16x32_bf16 v[94:97], v[198:201], v[182:185], v[94:97]
	v_mfma_f32_16x16x32_bf16 v[90:93], v[210:213], v[174:177], v[90:93]
	v_mfma_f32_16x16x32_bf16 v[82:85], v[210:213], v[182:185], v[82:85]
	v_mfma_f32_16x16x32_bf16 v[74:77], v[218:221], v[174:177], v[74:77]
	v_mfma_f32_16x16x32_bf16 v[62:65], v[218:221], v[182:185], v[62:65]
	v_mfma_f32_16x16x32_bf16 v[58:61], v[186:189], v[222:225], v[58:61]
	v_mfma_f32_16x16x32_bf16 v[50:53], v[186:189], v[230:233], v[50:53]
	v_mfma_f32_16x16x32_bf16 v[42:45], v[194:197], v[222:225], v[42:45]
	v_mfma_f32_16x16x32_bf16 v[30:33], v[194:197], v[230:233], v[30:33]
	v_mfma_f32_16x16x32_bf16 v[26:29], v[206:209], v[222:225], v[26:29]
	v_mfma_f32_16x16x32_bf16 v[18:21], v[206:209], v[230:233], v[18:21]
	v_mfma_f32_16x16x32_bf16 v[10:13], v[214:217], v[222:225], v[10:13]
	v_mfma_f32_16x16x32_bf16 v[2:5], v[214:217], v[230:233], v[2:5]
	v_mfma_f32_16x16x32_bf16 v[58:61], v[190:193], v[226:229], v[58:61]
	v_mfma_f32_16x16x32_bf16 v[50:53], v[190:193], v[234:237], v[50:53]
	v_mfma_f32_16x16x32_bf16 v[42:45], v[198:201], v[226:229], v[42:45]
	v_mfma_f32_16x16x32_bf16 v[30:33], v[198:201], v[234:237], v[30:33]
	v_mfma_f32_16x16x32_bf16 v[26:29], v[210:213], v[226:229], v[26:29]
	v_mfma_f32_16x16x32_bf16 v[18:21], v[210:213], v[234:237], v[18:21]
	v_mfma_f32_16x16x32_bf16 v[10:13], v[218:221], v[226:229], v[10:13]
	v_mfma_f32_16x16x32_bf16 v[2:5], v[218:221], v[234:237], v[2:5]
	s_setprio 0
	s_barrier
; #define STAGE_A(P, br, kt) do { const char* _g = (const char*)(A + (long)(br) * lda + (long)(kt) * BK); \
;     __builtin_amdgcn_global_load_lds((const unsigned*)(_g + (size_t)offA0), (unsigned*)((char*)(P) + sb0), 16, 0, 0); \
;     __builtin_amdgcn_global_load_lds((const unsigned*)(_g + (size_t)lda * 128 + (size_t)offA0), (unsigned*)((char*)(P) + sb1), 16, 0, 0); } while (0)
; #define STAGE_B(P, br, kt) do { const char* _g = (const char*)(B + (long)(br) * ldb + (long)(kt) * BK); \
;     __builtin_amdgcn_global_load_lds((const unsigned*)(_g + (size_t)offB0), (unsigned*)((char*)(P) + sb0), 16, 0, 0); \
;     __builtin_amdgcn_global_load_lds((const unsigned*)(_g + (size_t)ldb * 128 + (size_t)offB0), (unsigned*)((char*)(P) + sb1), 16, 0, 0); } while (0)
; #define LDA(dst, b, h) for (int m = 0; m < 4; ++m) for (int k = 0; k < 2; ++k) \
;     dst[m][k] = *reinterpret_cast<const bf16x8*>((char*)SA(b, h) + lds_byte(wr * 64 + m * 16 + fr, k * 32 + fq * 8))
; #define LDB(dst, b, h) for (int n = 0; n < 2; ++n) for (int k = 0; k < 2; ++k) \
;     dst[n][k] = *reinterpret_cast<const bf16x8*>((char*)SB(b, h) + lds_byte(wc * 32 + n * 16 + fr, k * 32 + fq * 8))
; #define MMA(ai, bj, At_, Bt_) do { __builtin_amdgcn_s_setprio(1); \
;     for (int m = 0; m < 4; ++m) for (int n = 0; n < 2; ++n) for (int k = 0; k < 2; ++k) \
;       acc[ai][bj][m][n] = MFMA16(At_[m][k], Bt_[n][k], acc[ai][bj][m][n]); \
;     __builtin_amdgcn_s_setprio(0); } while (0)
; #define WAIT_V(n) asm volatile("s_waitcnt vmcnt(" #n ")" ::: "memory")
; #define WAIT_L(n) asm volatile("s_waitcnt lgkmcnt(" #n ")" ::: "memory")
; #define BAR __builtin_amdgcn_s_barrier()
; #define SCHED __builtin_amdgcn_sched_barrier(0)
; DI void gemm_core(WVP char* smem, const u16* __restrict__ A, int lda, int ar0, int ar1,
;                   const u16* __restrict__ B, int ldb, int bc0, int K, AccT& acc) {
;     ...
;     LDB(B0, 1, 0); SCHED; LDA(At, 1, 0); STAGE_A(SA(0, 1), ac1, t + 2);
;     WAIT_L(8); BAR; WAIT_L(0); MMA(0, 0, At, B0); BAR; SCHED;
;     LDB(B1, 1, 1); STAGE_B(SB(1, 0), bb0, t + 3);
;     BAR; WAIT_L(0); MMA(0, 1, At, B1); BAR;
;     LDA(At, 1, 1); STAGE_A(SA(1, 0), ac0, t + 3);
;     BAR; WAIT_L(0); MMA(1, 0, At, B0); BAR; SCHED;
;     STAGE_B(SB(1, 1), bb1, t + 3);
;     WAIT_V(6); BAR; MMA(1, 1, At, B1); BAR;
	ds_read_b128 v[170:173], v154
	ds_read_b128 v[174:177], v154 offset:1024
	ds_read_b128 v[178:181], v154 offset:2048
	ds_read_b128 v[182:185], v154 offset:3072
	ds_read_b128 v[186:189], v150 offset:32768
	ds_read_b128 v[190:193], v150 offset:33792
	ds_read_b128 v[194:197], v164 offset:32768
	ds_read_b128 v[198:201], v164 offset:33792
	ds_read_b128 v[206:209], v165 offset:32768
	ds_read_b128 v[210:213], v165 offset:33792
	ds_read_b128 v[214:217], v166 offset:32768
	ds_read_b128 v[218:221], v166 offset:33792
	ds_read_b128 v[222:225], v153
	ds_read_b128 v[226:229], v153 offset:1024
	ds_read_b128 v[230:233], v153 offset:2048
	ds_read_b128 v[234:237], v153 offset:3072
	v_lshl_add_u64 v[238:239], v[142:143], 0, s[28:29]
	v_lshl_add_u64 v[202:203], v[238:239], 0, s[48:49]
	v_readfirstlane_b32 s31, v151
	s_mov_b32 m0, s31
	s_nop 0
	global_load_lds_dwordx4 v[202:203], off
	v_lshl_add_u64 v[238:239], v[144:145], 0, s[28:29]
	v_lshl_add_u64 v[202:203], v[238:239], 0, s[48:49]
	v_readfirstlane_b32 s31, v152
	s_mov_b32 m0, s31
	s_nop 0
	global_load_lds_dwordx4 v[202:203], off
	s_waitcnt vmcnt(8)
	s_waitcnt lgkmcnt(0)
	s_barrier
	s_setprio 1
	v_mfma_f32_16x16x32_bf16 v[126:129], v[186:189], v[170:173], v[126:129]
	v_mfma_f32_16x16x32_bf16 v[118:121], v[186:189], v[178:181], v[118:121]
	v_mfma_f32_16x16x32_bf16 v[110:113], v[194:197], v[170:173], v[110:113]
	v_mfma_f32_16x16x32_bf16 v[102:105], v[194:197], v[178:181], v[102:105]
	v_mfma_f32_16x16x32_bf16 v[98:101], v[206:209], v[170:173], v[98:101]
	v_mfma_f32_16x16x32_bf16 v[86:89], v[206:209], v[178:181], v[86:89]
	v_mfma_f32_16x16x32_bf16 v[78:81], v[214:217], v[170:173], v[78:81]
	v_mfma_f32_16x16x32_bf16 v[70:73], v[214:217], v[178:181], v[70:73]
	v_mfma_f32_16x16x32_bf16 v[126:129], v[190:193], v[174:177], v[126:129]
	v_mfma_f32_16x16x32_bf16 v[118:121], v[190:193], v[182:185], v[118:121]
	v_mfma_f32_16x16x32_bf16 v[110:113], v[198:201], v[174:177], v[110:113]
	v_mfma_f32_16x16x32_bf16 v[102:105], v[198:201], v[182:185], v[102:105]
	v_mfma_f32_16x16x32_bf16 v[98:101], v[210:213], v[174:177], v[98:101]
	v_mfma_f32_16x16x32_bf16 v[86:89], v[210:213], v[182:185], v[86:89]
	v_mfma_f32_16x16x32_bf16 v[78:81], v[218:221], v[174:177], v[78:81]
	v_mfma_f32_16x16x32_bf16 v[70:73], v[218:221], v[182:185], v[70:73]
	v_mfma_f32_16x16x32_bf16 v[66:69], v[186:189], v[222:225], v[66:69]
	v_mfma_f32_16x16x32_bf16 v[54:57], v[186:189], v[230:233], v[54:57]
	v_mfma_f32_16x16x32_bf16 v[46:49], v[194:197], v[222:225], v[46:49]
	v_mfma_f32_16x16x32_bf16 v[38:41], v[194:197], v[230:233], v[38:41]
	v_mfma_f32_16x16x32_bf16 v[34:37], v[206:209], v[222:225], v[34:37]
	v_mfma_f32_16x16x32_bf16 v[22:25], v[206:209], v[230:233], v[22:25]
	v_mfma_f32_16x16x32_bf16 v[14:17], v[214:217], v[222:225], v[14:17]
	v_mfma_f32_16x16x32_bf16 v[6:9], v[214:217], v[230:233], v[6:9]
	v_mfma_f32_16x16x32_bf16 v[66:69], v[190:193], v[226:229], v[66:69]
	v_mfma_f32_16x16x32_bf16 v[54:57], v[190:193], v[234:237], v[54:57]
	v_mfma_f32_16x16x32_bf16 v[46:49], v[198:201], v[226:229], v[46:49]
	v_mfma_f32_16x16x32_bf16 v[38:41], v[198:201], v[234:237], v[38:41]
	v_mfma_f32_16x16x32_bf16 v[34:37], v[210:213], v[226:229], v[34:37]
	v_mfma_f32_16x16x32_bf16 v[22:25], v[210:213], v[234:237], v[22:25]
	v_mfma_f32_16x16x32_bf16 v[14:17], v[218:221], v[226:229], v[14:17]
	v_mfma_f32_16x16x32_bf16 v[6:9], v[218:221], v[234:237], v[6:9]
	s_setprio 0
	s_barrier
	ds_read_b128 v[186:189], v150 offset:49152
	ds_read_b128 v[190:193], v150 offset:50176
	ds_read_b128 v[194:197], v164 offset:49152
	ds_read_b128 v[198:201], v164 offset:50176
	ds_read_b128 v[206:209], v165 offset:49152
	ds_read_b128 v[210:213], v165 offset:50176
	ds_read_b128 v[214:217], v166 offset:49152
	ds_read_b128 v[218:221], v166 offset:50176
	v_lshl_add_u64 v[238:239], v[130:131], 0, s[28:29]
	v_lshl_add_u64 v[202:203], v[238:239], 0, s[70:71]
	v_readfirstlane_b32 s31, v155
	s_mov_b32 m0, s31
	s_nop 0
	global_load_lds_dwordx4 v[202:203], off
	v_lshl_add_u64 v[238:239], v[132:133], 0, s[28:29]
	v_lshl_add_u64 v[202:203], v[238:239], 0, s[70:71]
	v_readfirstlane_b32 s31, v156
	s_mov_b32 m0, s31
	s_nop 0
	global_load_lds_dwordx4 v[202:203], off
	v_lshl_add_u64 v[238:239], v[134:135], 0, s[28:29]
	v_lshl_add_u64 v[202:203], v[238:239], 0, s[62:63]
	v_readfirstlane_b32 s31, v157
	s_mov_b32 m0, s31
	s_nop 0
	global_load_lds_dwordx4 v[202:203], off
	v_lshl_add_u64 v[238:239], v[136:137], 0, s[28:29]
	v_lshl_add_u64 v[202:203], v[238:239], 0, s[62:63]
	v_readfirstlane_b32 s31, v158
	s_mov_b32 m0, s31
	s_nop 0
	global_load_lds_dwordx4 v[202:203], off
	v_lshl_add_u64 v[238:239], v[138:139], 0, s[28:29]
	v_lshl_add_u64 v[202:203], v[238:239], 0, s[70:71]
	v_readfirstlane_b32 s31, v159
	s_mov_b32 m0, s31
	s_nop 0
	global_load_lds_dwordx4 v[202:203], off
	v_lshl_add_u64 v[238:239], v[140:141], 0, s[28:29]
	v_lshl_add_u64 v[202:203], v[238:239], 0, s[70:71]
	v_readfirstlane_b32 s31, v160
	s_mov_b32 m0, s31
	s_nop 0
	global_load_lds_dwordx4 v[202:203], off
	s_waitcnt vmcnt(8)
	s_waitcnt lgkmcnt(0)
	s_barrier
; #define STAGE_A(P, br, kt) do { const char* _g = (const char*)(A + (long)(br) * lda + (long)(kt) * BK); \
;     __builtin_amdgcn_global_load_lds((const unsigned*)(_g + (size_t)offA0), (unsigned*)((char*)(P) + sb0), 16, 0, 0); \
;     __builtin_amdgcn_global_load_lds((const unsigned*)(_g + (size_t)lda * 128 + (size_t)offA0), (unsigned*)((char*)(P) + sb1), 16, 0, 0); } while (0)
; #define STAGE_B(P, br, kt) do { const char* _g = (const char*)(B + (long)(br) * ldb + (long)(kt) * BK); \
;     __builtin_amdgcn_global_load_lds((const unsigned*)(_g + (size_t)offB0), (unsigned*)((char*)(P) + sb0), 16, 0, 0); \
;     __builtin_amdgcn_global_load_lds((const unsigned*)(_g + (size_t)ldb * 128 + (size_t)offB0), (unsigned*)((char*)(P) + sb1), 16, 0, 0); } while (0)
; #define LDA(dst, b, h) for (int m = 0; m < 4; ++m) for (int k = 0; k < 2; ++k) \
;     dst[m][k] = *reinterpret_cast<const bf16x8*>((char*)SA(b, h) + lds_byte(wr * 64 + m * 16 + fr, k * 32 + fq * 8))
; #define LDB(dst, b, h) for (int n = 0; n < 2; ++n) for (int k = 0; k < 2; ++k) \
;     dst[n][k] = *reinterpret_cast<const bf16x8*>((char*)SB(b, h) + lds_byte(wc * 32 + n * 16 + fr, k * 32 + fq * 8))
; #define MMA(ai, bj, At_, Bt_) do { __builtin_amdgcn_s_setprio(1); \
;     for (int m = 0; m < 4; ++m) for (int n = 0; n < 2; ++n) for (int k = 0; k < 2; ++k) \
;       acc[ai][bj][m][n] = MFMA16(At_[m][k], Bt_[n][k], acc[ai][bj][m][n]); \
;     __builtin_amdgcn_s_setprio(0); } while (0)
; #define WAIT_V(n) asm volatile("s_waitcnt vmcnt(" #n ")" ::: "memory")
; #define WAIT_L(n) asm volatile("s_waitcnt lgkmcnt(" #n ")" ::: "memory")
; #define BAR __builtin_amdgcn_s_barrier()
; #define SCHED __builtin_amdgcn_sched_barrier(0)
; DI void gemm_core(WVP char* smem, const u16* __restrict__ A, int lda, int ar0, int ar1,
;                   const u16* __restrict__ B, int ldb, int bc0, int K, AccT& acc) {
;     ...
;     BAR; WAIT_L(0); MMA(1, 0, At, B0); BAR; SCHED;
;     STAGE_B(SB(1, 1), bb1, t + 3);
;     WAIT_V(6); BAR; MMA(1, 1, At, B1); BAR;
;   }
;   { LDB(B0, 0, 0); LDA(At, 0, 0); STAGE_A(SA(1, 1), ac1, nt - 1);
;     BAR; WAIT_L(0); MMA(0, 0, At, B0); BAR;
;     LDB(B1, 0, 1); BAR; WAIT_L(0); MMA(0, 1, At, B1); BAR;
;     LDA(At, 0, 1); WAIT_V(4); BAR; WAIT_L(0); MMA(1, 0, At, B0); MMA(1, 1, At, B1); BAR; }
	s_setprio 1
	v_mfma_f32_16x16x32_bf16 v[122:125], v[186:189], v[170:173], v[122:125]
	v_mfma_f32_16x16x32_bf16 v[114:117], v[186:189], v[178:181], v[114:117]
	v_mfma_f32_16x16x32_bf16 v[106:109], v[194:197], v[170:173], v[106:109]
	v_mfma_f32_16x16x32_bf16 v[94:97], v[194:197], v[178:181], v[94:97]
	v_mfma_f32_16x16x32_bf16 v[90:93], v[206:209], v[170:173], v[90:93]
	v_mfma_f32_16x16x32_bf16 v[82:85], v[206:209], v[178:181], v[82:85]
	v_mfma_f32_16x16x32_bf16 v[74:77], v[214:217], v[170:173], v[74:77]
	v_mfma_f32_16x16x32_bf16 v[62:65], v[214:217], v[178:181], v[62:65]
	v_mfma_f32_16x16x32_bf16 v[122:125], v[190:193], v[174:177], v[122:125]
	v_mfma_f32_16x16x32_bf16 v[114:117], v[190:193], v[182:185], v[114:117]
	v_mfma_f32_16x16x32_bf16 v[106:109], v[198:201], v[174:177], v[106:109]
	v_mfma_f32_16x16x32_bf16 v[94:97], v[198:201], v[182:185], v[94:97]
	v_mfma_f32_16x16x32_bf16 v[90:93], v[210:213], v[174:177], v[90:93]
	v_mfma_f32_16x16x32_bf16 v[82:85], v[210:213], v[182:185], v[82:85]
	v_mfma_f32_16x16x32_bf16 v[74:77], v[218:221], v[174:177], v[74:77]
	v_mfma_f32_16x16x32_bf16 v[62:65], v[218:221], v[182:185], v[62:65]
	v_mfma_f32_16x16x32_bf16 v[58:61], v[186:189], v[222:225], v[58:61]
	v_mfma_f32_16x16x32_bf16 v[50:53], v[186:189], v[230:233], v[50:53]
	v_mfma_f32_16x16x32_bf16 v[42:45], v[194:197], v[222:225], v[42:45]
	v_mfma_f32_16x16x32_bf16 v[30:33], v[194:197], v[230:233], v[30:33]
	v_mfma_f32_16x16x32_bf16 v[26:29], v[206:209], v[222:225], v[26:29]
	v_mfma_f32_16x16x32_bf16 v[18:21], v[206:209], v[230:233], v[18:21]
	v_mfma_f32_16x16x32_bf16 v[10:13], v[214:217], v[222:225], v[10:13]
	v_mfma_f32_16x16x32_bf16 v[2:5], v[214:217], v[230:233], v[2:5]
	v_mfma_f32_16x16x32_bf16 v[58:61], v[190:193], v[226:229], v[58:61]
	v_mfma_f32_16x16x32_bf16 v[50:53], v[190:193], v[234:237], v[50:53]
	v_mfma_f32_16x16x32_bf16 v[42:45], v[198:201], v[226:229], v[42:45]
	v_mfma_f32_16x16x32_bf16 v[30:33], v[198:201], v[234:237], v[30:33]
	v_mfma_f32_16x16x32_bf16 v[26:29], v[210:213], v[226:229], v[26:29]
	v_mfma_f32_16x16x32_bf16 v[18:21], v[210:213], v[234:237], v[18:21]
	v_mfma_f32_16x16x32_bf16 v[10:13], v[218:221], v[226:229], v[10:13]
	v_mfma_f32_16x16x32_bf16 v[2:5], v[218:221], v[234:237], v[2:5]
	s_setprio 0
	s_add_i32 s30, s30, 2
	s_add_u32 s28, s28, 0x100
	s_addc_u32 s29, s29, 0
	s_cmp_lt_u32 s30, s1
	s_barrier
	s_cbranch_scc1 .LBB0_237
	s_add_i32 s58, s0, -1
	s_lshl_b64 s[0:1], s[58:59], 7
	s_add_u32 s0, s24, s0
	s_addc_u32 s1, s25, s1
	v_lshl_add_u64 v[160:161], s[0:1], 0, v[0:1]
	v_readfirstlane_b32 s24, v168
	s_add_u32 s0, s0, s36
	s_mov_b32 m0, s24
	s_addc_u32 s1, s1, 0
	ds_read_b128 v[130:133], v163
	ds_read_b128 v[134:137], v163 offset:1024
	ds_read_b128 v[138:141], v163 offset:2048
	ds_read_b128 v[142:145], v163 offset:3072
	ds_read_b128 v[146:149], v150
	ds_read_b128 v[156:159], v150 offset:1024
	ds_read_b128 v[170:173], v164
	ds_read_b128 v[174:177], v164 offset:1024
	ds_read_b128 v[178:181], v165
	ds_read_b128 v[182:185], v165 offset:1024
	ds_read_b128 v[186:189], v166
	ds_read_b128 v[190:193], v166 offset:1024
	global_load_lds_dwordx4 v[160:161], off
	v_lshl_add_u64 v[160:161], s[0:1], 0, v[0:1]
	v_readfirstlane_b32 s0, v167
	s_mov_b32 m0, s0
	s_nop 0
	global_load_lds_dwordx4 v[160:161], off
	s_waitcnt vmcnt(8)
	s_barrier
	s_waitcnt lgkmcnt(0)
	s_setprio 1
	s_waitcnt lgkmcnt(0)
	v_mfma_f32_16x16x32_bf16 v[126:129], v[146:149], v[130:133], v[126:129]
	v_mfma_f32_16x16x32_bf16 v[118:121], v[146:149], v[138:141], v[118:121]
	v_mfma_f32_16x16x32_bf16 v[110:113], v[170:173], v[130:133], v[110:113]
	v_mfma_f32_16x16x32_bf16 v[102:105], v[170:173], v[138:141], v[102:105]
	v_mfma_f32_16x16x32_bf16 v[98:101], v[178:181], v[130:133], v[98:101]
	v_mfma_f32_16x16x32_bf16 v[86:89], v[178:181], v[138:141], v[86:89]
	v_mfma_f32_16x16x32_bf16 v[78:81], v[186:189], v[130:133], v[78:81]
	v_mfma_f32_16x16x32_bf16 v[70:73], v[186:189], v[138:141], v[70:73]
	v_mfma_f32_16x16x32_bf16 v[126:129], v[156:159], v[134:137], v[126:129]
	v_mfma_f32_16x16x32_bf16 v[118:121], v[156:159], v[142:145], v[118:121]
	v_mfma_f32_16x16x32_bf16 v[110:113], v[174:177], v[134:137], v[110:113]
	v_mfma_f32_16x16x32_bf16 v[102:105], v[174:177], v[142:145], v[102:105]
	v_mfma_f32_16x16x32_bf16 v[98:101], v[182:185], v[134:137], v[98:101]
	v_mfma_f32_16x16x32_bf16 v[86:89], v[182:185], v[142:145], v[86:89]
	v_mfma_f32_16x16x32_bf16 v[78:81], v[190:193], v[134:137], v[78:81]
	v_mfma_f32_16x16x32_bf16 v[70:73], v[190:193], v[142:145], v[70:73]
	s_setprio 0
	s_barrier
	ds_read_b128 v[194:197], v162
	ds_read_b128 v[198:201], v162 offset:1024
	ds_read_b128 v[206:209], v162 offset:2048
	ds_read_b128 v[160:163], v162 offset:3072
	s_barrier
	s_waitcnt lgkmcnt(0)
	s_setprio 1
	s_waitcnt lgkmcnt(0)
	v_mfma_f32_16x16x32_bf16 v[66:69], v[146:149], v[194:197], v[66:69]
	v_mfma_f32_16x16x32_bf16 v[54:57], v[146:149], v[206:209], v[54:57]
	v_mfma_f32_16x16x32_bf16 v[46:49], v[170:173], v[194:197], v[46:49]
	v_mfma_f32_16x16x32_bf16 v[38:41], v[170:173], v[206:209], v[38:41]
	v_mfma_f32_16x16x32_bf16 v[34:37], v[178:181], v[194:197], v[34:37]
	v_mfma_f32_16x16x32_bf16 v[22:25], v[178:181], v[206:209], v[22:25]
	v_mfma_f32_16x16x32_bf16 v[14:17], v[186:189], v[194:197], v[14:17]
	v_mfma_f32_16x16x32_bf16 v[6:9], v[186:189], v[206:209], v[6:9]
	v_mfma_f32_16x16x32_bf16 v[66:69], v[156:159], v[198:201], v[66:69]
	v_mfma_f32_16x16x32_bf16 v[54:57], v[156:159], v[160:163], v[54:57]
	v_mfma_f32_16x16x32_bf16 v[46:49], v[174:177], v[198:201], v[46:49]
	v_mfma_f32_16x16x32_bf16 v[38:41], v[174:177], v[160:163], v[38:41]
	v_mfma_f32_16x16x32_bf16 v[34:37], v[182:185], v[198:201], v[34:37]
	v_mfma_f32_16x16x32_bf16 v[22:25], v[182:185], v[160:163], v[22:25]
	v_mfma_f32_16x16x32_bf16 v[14:17], v[190:193], v[198:201], v[14:17]
	v_mfma_f32_16x16x32_bf16 v[6:9], v[190:193], v[160:163], v[6:9]
	s_setprio 0
	s_barrier
; #define LDA(dst, b, h) for (int m = 0; m < 4; ++m) for (int k = 0; k < 2; ++k) \
;     dst[m][k] = *reinterpret_cast<const bf16x8*>((char*)SA(b, h) + lds_byte(wr * 64 + m * 16 + fr, k * 32 + fq * 8))
; #define LDB(dst, b, h) for (int n = 0; n < 2; ++n) for (int k = 0; k < 2; ++k) \
;     dst[n][k] = *reinterpret_cast<const bf16x8*>((char*)SB(b, h) + lds_byte(wc * 32 + n * 16 + fr, k * 32 + fq * 8))
; #define MMA(ai, bj, At_, Bt_) do { __builtin_amdgcn_s_setprio(1); \
;     for (int m = 0; m < 4; ++m) for (int n = 0; n < 2; ++n) for (int k = 0; k < 2; ++k) \
;       acc[ai][bj][m][n] = MFMA16(At_[m][k], Bt_[n][k], acc[ai][bj][m][n]); \
;     __builtin_amdgcn_s_setprio(0); } while (0)
; #define WAIT_V(n) asm volatile("s_waitcnt vmcnt(" #n ")" ::: "memory")
; #define WAIT_L(n) asm volatile("s_waitcnt lgkmcnt(" #n ")" ::: "memory")
; #define BAR __builtin_amdgcn_s_barrier()
; DI void gemm_core(WVP char* smem, const u16* __restrict__ A, int lda, int ar0, int ar1,
;                   const u16* __restrict__ B, int ldb, int bc0, int K, AccT& acc) {
;     ...
;     LDA(At, 0, 1); WAIT_V(4); BAR; WAIT_L(0); MMA(1, 0, At, B0); MMA(1, 1, At, B1); BAR; }
;   { LDB(B0, 1, 0); LDA(At, 1, 0); WAIT_V(2); BAR; WAIT_L(0); MMA(0, 0, At, B0); BAR;
	ds_read_b128 v[146:149], v150 offset:16384
	ds_read_b128 v[156:159], v150 offset:17408
	ds_read_b128 v[168:171], v164 offset:16384
	ds_read_b128 v[172:175], v164 offset:17408
	ds_read_b128 v[176:179], v165 offset:16384
	ds_read_b128 v[180:183], v165 offset:17408
	ds_read_b128 v[184:187], v166 offset:16384
	ds_read_b128 v[188:191], v166 offset:17408
	s_waitcnt vmcnt(4)
	s_barrier
	s_waitcnt lgkmcnt(0)
	s_setprio 1
	s_waitcnt lgkmcnt(0)
	v_mfma_f32_16x16x32_bf16 v[122:125], v[146:149], v[130:133], v[122:125]
	v_mfma_f32_16x16x32_bf16 v[114:117], v[146:149], v[138:141], v[114:117]
	v_mfma_f32_16x16x32_bf16 v[106:109], v[168:171], v[130:133], v[106:109]
	v_mfma_f32_16x16x32_bf16 v[94:97], v[168:171], v[138:141], v[94:97]
	v_mfma_f32_16x16x32_bf16 v[90:93], v[176:179], v[130:133], v[90:93]
	v_mfma_f32_16x16x32_bf16 v[82:85], v[176:179], v[138:141], v[82:85]
	v_mfma_f32_16x16x32_bf16 v[74:77], v[184:187], v[130:133], v[74:77]
	v_mfma_f32_16x16x32_bf16 v[62:65], v[184:187], v[138:141], v[62:65]
	v_mfma_f32_16x16x32_bf16 v[122:125], v[156:159], v[134:137], v[122:125]
	v_mfma_f32_16x16x32_bf16 v[114:117], v[156:159], v[142:145], v[114:117]
	v_mfma_f32_16x16x32_bf16 v[106:109], v[172:175], v[134:137], v[106:109]
	v_mfma_f32_16x16x32_bf16 v[94:97], v[172:175], v[142:145], v[94:97]
	v_mfma_f32_16x16x32_bf16 v[90:93], v[180:183], v[134:137], v[90:93]
	v_mfma_f32_16x16x32_bf16 v[82:85], v[180:183], v[142:145], v[82:85]
	v_mfma_f32_16x16x32_bf16 v[74:77], v[188:191], v[134:137], v[74:77]
	v_mfma_f32_16x16x32_bf16 v[62:65], v[188:191], v[142:145], v[62:65]
	s_setprio 0
	s_setprio 1
	v_mfma_f32_16x16x32_bf16 v[58:61], v[146:149], v[194:197], v[58:61]
	v_mfma_f32_16x16x32_bf16 v[50:53], v[146:149], v[206:209], v[50:53]
	v_mfma_f32_16x16x32_bf16 v[42:45], v[168:171], v[194:197], v[42:45]
	v_mfma_f32_16x16x32_bf16 v[30:33], v[168:171], v[206:209], v[30:33]
	v_mfma_f32_16x16x32_bf16 v[26:29], v[176:179], v[194:197], v[26:29]
	v_mfma_f32_16x16x32_bf16 v[18:21], v[176:179], v[206:209], v[18:21]
	v_mfma_f32_16x16x32_bf16 v[10:13], v[184:187], v[194:197], v[10:13]
	v_mfma_f32_16x16x32_bf16 v[2:5], v[184:187], v[206:209], v[2:5]
	v_mfma_f32_16x16x32_bf16 v[58:61], v[156:159], v[198:201], v[58:61]
	v_mfma_f32_16x16x32_bf16 v[50:53], v[156:159], v[160:163], v[50:53]
	v_mfma_f32_16x16x32_bf16 v[42:45], v[172:175], v[198:201], v[42:45]
	v_mfma_f32_16x16x32_bf16 v[30:33], v[172:175], v[160:163], v[30:33]
	v_mfma_f32_16x16x32_bf16 v[26:29], v[180:183], v[198:201], v[26:29]
	v_mfma_f32_16x16x32_bf16 v[18:21], v[180:183], v[160:163], v[18:21]
	v_mfma_f32_16x16x32_bf16 v[10:13], v[188:191], v[198:201], v[10:13]
	v_mfma_f32_16x16x32_bf16 v[2:5], v[188:191], v[160:163], v[2:5]
	s_setprio 0
	s_barrier
	ds_read_b128 v[130:133], v154
	ds_read_b128 v[134:137], v154 offset:1024
	ds_read_b128 v[138:141], v154 offset:2048
	ds_read_b128 v[142:145], v154 offset:3072
	ds_read_b128 v[146:149], v150 offset:32768
	ds_read_b128 v[154:157], v150 offset:33792
	ds_read_b128 v[158:161], v164 offset:32768
	ds_read_b128 v[168:171], v164 offset:33792
	ds_read_b128 v[172:175], v165 offset:32768
	ds_read_b128 v[176:179], v165 offset:33792
	ds_read_b128 v[180:183], v166 offset:32768
	ds_read_b128 v[184:187], v166 offset:33792
	s_waitcnt vmcnt(2)
	s_barrier
	s_waitcnt lgkmcnt(0)
	s_setprio 1
	s_waitcnt lgkmcnt(0)
	v_mfma_f32_16x16x32_bf16 v[126:129], v[146:149], v[130:133], v[126:129]
	v_mfma_f32_16x16x32_bf16 v[118:121], v[146:149], v[138:141], v[118:121]
	v_mfma_f32_16x16x32_bf16 v[110:113], v[158:161], v[130:133], v[110:113]
	v_mfma_f32_16x16x32_bf16 v[102:105], v[158:161], v[138:141], v[102:105]
	v_mfma_f32_16x16x32_bf16 v[98:101], v[172:175], v[130:133], v[98:101]
	v_mfma_f32_16x16x32_bf16 v[86:89], v[172:175], v[138:141], v[86:89]
	v_mfma_f32_16x16x32_bf16 v[78:81], v[180:183], v[130:133], v[78:81]
	v_mfma_f32_16x16x32_bf16 v[70:73], v[180:183], v[138:141], v[70:73]
	v_mfma_f32_16x16x32_bf16 v[126:129], v[154:157], v[134:137], v[126:129]
	v_mfma_f32_16x16x32_bf16 v[118:121], v[154:157], v[142:145], v[118:121]
	v_mfma_f32_16x16x32_bf16 v[110:113], v[168:171], v[134:137], v[110:113]
	v_mfma_f32_16x16x32_bf16 v[102:105], v[168:171], v[142:145], v[102:105]
	v_mfma_f32_16x16x32_bf16 v[98:101], v[176:179], v[134:137], v[98:101]
	v_mfma_f32_16x16x32_bf16 v[86:89], v[176:179], v[142:145], v[86:89]
	v_mfma_f32_16x16x32_bf16 v[78:81], v[184:187], v[134:137], v[78:81]
	v_mfma_f32_16x16x32_bf16 v[70:73], v[184:187], v[142:145], v[70:73]
	s_setprio 0
	s_barrier
; #define LDA(dst, b, h) for (int m = 0; m < 4; ++m) for (int k = 0; k < 2; ++k) \
;     dst[m][k] = *reinterpret_cast<const bf16x8*>((char*)SA(b, h) + lds_byte(wr * 64 + m * 16 + fr, k * 32 + fq * 8))
; #define LDB(dst, b, h) for (int n = 0; n < 2; ++n) for (int k = 0; k < 2; ++k) \
;     dst[n][k] = *reinterpret_cast<const bf16x8*>((char*)SB(b, h) + lds_byte(wc * 32 + n * 16 + fr, k * 32 + fq * 8))
; #define MMA(ai, bj, At_, Bt_) do { __builtin_amdgcn_s_setprio(1); \
;     for (int m = 0; m < 4; ++m) for (int n = 0; n < 2; ++n) for (int k = 0; k < 2; ++k) \
;       acc[ai][bj][m][n] = MFMA16(At_[m][k], Bt_[n][k], acc[ai][bj][m][n]); \
;     __builtin_amdgcn_s_setprio(0); } while (0)
; #define WAIT_V(n) asm volatile("s_waitcnt vmcnt(" #n ")" ::: "memory")
; #define WAIT_L(n) asm volatile("s_waitcnt lgkmcnt(" #n ")" ::: "memory")
; #define BAR __builtin_amdgcn_s_barrier()
; DI void gemm_core(WVP char* smem, const u16* __restrict__ A, int lda, int ar0, int ar1,
;                   const u16* __restrict__ B, int ldb, int bc0, int K, AccT& acc) {
;     ...
;   { LDB(B0, 1, 0); LDA(At, 1, 0); WAIT_V(2); BAR; WAIT_L(0); MMA(0, 0, At, B0); BAR;
;     LDB(B1, 1, 1); WAIT_V(0); BAR; WAIT_L(0); MMA(0, 1, At, B1); BAR;
;     LDA(At, 1, 1); BAR; WAIT_L(0); MMA(1, 0, At, B0); MMA(1, 1, At, B1); BAR; }
;   if (wr == 0) BAR;
	ds_read_b128 v[188:191], v153
	ds_read_b128 v[192:195], v153 offset:1024
	ds_read_b128 v[196:199], v153 offset:2048
	ds_read_b128 v[200:203], v153 offset:3072
	s_waitcnt vmcnt(0)
	s_barrier
	s_waitcnt lgkmcnt(0)
	s_setprio 1
	s_waitcnt lgkmcnt(0)
	v_mfma_f32_16x16x32_bf16 v[66:69], v[146:149], v[188:191], v[66:69]
	v_mfma_f32_16x16x32_bf16 v[54:57], v[146:149], v[196:199], v[54:57]
	v_mfma_f32_16x16x32_bf16 v[46:49], v[158:161], v[188:191], v[46:49]
	v_mfma_f32_16x16x32_bf16 v[38:41], v[158:161], v[196:199], v[38:41]
	v_mfma_f32_16x16x32_bf16 v[34:37], v[172:175], v[188:191], v[34:37]
	v_mfma_f32_16x16x32_bf16 v[22:25], v[172:175], v[196:199], v[22:25]
	v_mfma_f32_16x16x32_bf16 v[14:17], v[180:183], v[188:191], v[14:17]
	v_mfma_f32_16x16x32_bf16 v[6:9], v[180:183], v[196:199], v[6:9]
	v_mfma_f32_16x16x32_bf16 v[66:69], v[154:157], v[192:195], v[66:69]
	v_mfma_f32_16x16x32_bf16 v[54:57], v[154:157], v[200:203], v[54:57]
	v_mfma_f32_16x16x32_bf16 v[46:49], v[168:171], v[192:195], v[46:49]
	v_mfma_f32_16x16x32_bf16 v[38:41], v[168:171], v[200:203], v[38:41]
	v_mfma_f32_16x16x32_bf16 v[34:37], v[176:179], v[192:195], v[34:37]
	v_mfma_f32_16x16x32_bf16 v[22:25], v[176:179], v[200:203], v[22:25]
	v_mfma_f32_16x16x32_bf16 v[14:17], v[184:187], v[192:195], v[14:17]
	v_mfma_f32_16x16x32_bf16 v[6:9], v[184:187], v[200:203], v[6:9]
	s_setprio 0
	s_barrier
	ds_read_b128 v[146:149], v150 offset:49152
	ds_read_b128 v[150:153], v150 offset:50176
	ds_read_b128 v[154:157], v164 offset:49152
	ds_read_b128 v[158:161], v164 offset:50176
	ds_read_b128 v[168:171], v165 offset:49152
	ds_read_b128 v[162:165], v165 offset:50176
	ds_read_b128 v[172:175], v166 offset:49152
	ds_read_b128 v[176:179], v166 offset:50176
	s_barrier
	s_waitcnt lgkmcnt(0)
	s_setprio 1
	s_waitcnt lgkmcnt(0)
	v_mfma_f32_16x16x32_bf16 v[122:125], v[146:149], v[130:133], v[122:125]
	v_mfma_f32_16x16x32_bf16 v[114:117], v[146:149], v[138:141], v[114:117]
	v_mfma_f32_16x16x32_bf16 v[106:109], v[154:157], v[130:133], v[106:109]
	v_mfma_f32_16x16x32_bf16 v[94:97], v[154:157], v[138:141], v[94:97]
	v_mfma_f32_16x16x32_bf16 v[90:93], v[168:171], v[130:133], v[90:93]
	v_mfma_f32_16x16x32_bf16 v[82:85], v[168:171], v[138:141], v[82:85]
	v_mfma_f32_16x16x32_bf16 v[74:77], v[172:175], v[130:133], v[74:77]
	v_mfma_f32_16x16x32_bf16 v[62:65], v[172:175], v[138:141], v[62:65]
	v_mfma_f32_16x16x32_bf16 v[122:125], v[150:153], v[134:137], v[122:125]
	v_mfma_f32_16x16x32_bf16 v[114:117], v[150:153], v[142:145], v[114:117]
	v_mfma_f32_16x16x32_bf16 v[106:109], v[158:161], v[134:137], v[106:109]
	v_mfma_f32_16x16x32_bf16 v[94:97], v[158:161], v[142:145], v[94:97]
	v_mfma_f32_16x16x32_bf16 v[90:93], v[162:165], v[134:137], v[90:93]
	v_mfma_f32_16x16x32_bf16 v[82:85], v[162:165], v[142:145], v[82:85]
	v_mfma_f32_16x16x32_bf16 v[74:77], v[176:179], v[134:137], v[74:77]
	v_mfma_f32_16x16x32_bf16 v[62:65], v[176:179], v[142:145], v[62:65]
	s_setprio 0
	s_setprio 1
	v_mfma_f32_16x16x32_bf16 v[58:61], v[146:149], v[188:191], v[58:61]
	v_mfma_f32_16x16x32_bf16 v[50:53], v[146:149], v[196:199], v[50:53]
	v_mfma_f32_16x16x32_bf16 v[42:45], v[154:157], v[188:191], v[42:45]
	v_mfma_f32_16x16x32_bf16 v[30:33], v[154:157], v[196:199], v[30:33]
	v_mfma_f32_16x16x32_bf16 v[26:29], v[168:171], v[188:191], v[26:29]
	v_mfma_f32_16x16x32_bf16 v[18:21], v[168:171], v[196:199], v[18:21]
	v_mfma_f32_16x16x32_bf16 v[10:13], v[172:175], v[188:191], v[10:13]
	v_mfma_f32_16x16x32_bf16 v[2:5], v[172:175], v[196:199], v[2:5]
	v_mfma_f32_16x16x32_bf16 v[58:61], v[150:153], v[192:195], v[58:61]
	v_mfma_f32_16x16x32_bf16 v[50:53], v[150:153], v[200:203], v[50:53]
	v_mfma_f32_16x16x32_bf16 v[42:45], v[158:161], v[192:195], v[42:45]
	v_mfma_f32_16x16x32_bf16 v[30:33], v[158:161], v[200:203], v[30:33]
	v_mfma_f32_16x16x32_bf16 v[26:29], v[162:165], v[192:195], v[26:29]
	v_mfma_f32_16x16x32_bf16 v[18:21], v[162:165], v[200:203], v[18:21]
	v_mfma_f32_16x16x32_bf16 v[10:13], v[176:179], v[192:195], v[10:13]
	v_mfma_f32_16x16x32_bf16 v[2:5], v[176:179], v[200:203], v[2:5]
	s_setprio 0
	s_cmp_gt_u32 s35, 3
	s_barrier
	s_cbranch_scc0 .LBB0_240
	s_cmp_eq_u32 s34, 3
	s_cbranch_scc1 .LBB0_233
	s_branch .LBB0_241

; #define STAGE_A(P, br, kt) do { const char* _g = (const char*)(A + (long)(br) * lda + (long)(kt) * BK); \
;     __builtin_amdgcn_global_load_lds((const unsigned*)(_g + (size_t)offA0), (unsigned*)((char*)(P) + sb0), 16, 0, 0); \
;     __builtin_amdgcn_global_load_lds((const unsigned*)(_g + (size_t)lda * 128 + (size_t)offA0), (unsigned*)((char*)(P) + sb1), 16, 0, 0); } while (0)
; #define STAGE_B(P, br, kt) do { const char* _g = (const char*)(B + (long)(br) * ldb + (long)(kt) * BK); \
;     __builtin_amdgcn_global_load_lds((const unsigned*)(_g + (size_t)offB0), (unsigned*)((char*)(P) + sb0), 16, 0, 0); \
;     __builtin_amdgcn_global_load_lds((const unsigned*)(_g + (size_t)ldb * 128 + (size_t)offB0), (unsigned*)((char*)(P) + sb1), 16, 0, 0); } while (0)
; #define LDA(dst, b, h) for (int m = 0; m < 4; ++m) for (int k = 0; k < 2; ++k) \
;     dst[m][k] = *reinterpret_cast<const bf16x8*>((char*)SA(b, h) + lds_byte(wr * 64 + m * 16 + fr, k * 32 + fq * 8))
; #define LDB(dst, b, h) for (int n = 0; n < 2; ++n) for (int k = 0; k < 2; ++k) \
;     dst[n][k] = *reinterpret_cast<const bf16x8*>((char*)SB(b, h) + lds_byte(wc * 32 + n * 16 + fr, k * 32 + fq * 8))
; #define WAIT_V(n) asm volatile("s_waitcnt vmcnt(" #n ")" ::: "memory")
; #define WAIT_L(n) asm volatile("s_waitcnt lgkmcnt(" #n ")" ::: "memory")
; #define BAR __builtin_amdgcn_s_barrier()
; #define SCHED __builtin_amdgcn_sched_barrier(0)
; DI void gemm_core(WVP char* smem, const u16* __restrict__ A, int lda, int ar0, int ar1,
;                   const u16* __restrict__ B, int ldb, int bc0, int K, AccT& acc) {
;     ...
;   const int sb0 = tid * 16, sb1 = sb0 + 8192;
;   int R0, C0; stage_rc(sb0, R0, C0);
;   const unsigned offA0 = (unsigned)(R0 * lda + C0) * 2u, offB0 = (unsigned)(R0 * ldb + C0) * 2u;
;   const int ac0 = ar0, ac1 = ar1, bb0 = bc0, bb1 = bc0 + HALF;
;   bf16x8 At[4][2], B0[2][2], B1[2][2];
;   const int nt = K / BK;
;   __syncthreads();
;   STAGE_B(SB(0, 0), bb0, 0); STAGE_A(SA(0, 0), ac0, 0);
;   STAGE_B(SB(0, 1), bb1, 0); STAGE_A(SA(0, 1), ac1, 0);
;   if (wr == 1) BAR;
;   WAIT_V(4); BAR;
;   STAGE_B(SB(1, 0), bb0, 1); STAGE_A(SA(1, 0), ac0, 1); STAGE_B(SB(1, 1), bb1, 1);
;   WAIT_V(6); BAR;
;   for (int t = 0; t < nt - 2; t += 2) {
;     LDB(B0, 0, 0); SCHED; LDA(At, 0, 0); STAGE_A(SA(1, 1), ac1, t + 1);
;     WAIT_L(8); BAR; WAIT_L(0); MMA(0, 0, At, B0); BAR; SCHED;
.LBB0_272:
	v_add_u32_e32 v146, s61, v11
	v_add_u32_e32 v147, 0x2000, v146
	v_readfirstlane_b32 s19, v146
	v_lshl_add_u64 v[12:13], v[2:3], 0, s[64:65]
	s_mov_b32 m0, s19
	s_mov_b64 s[20:21], 0x98080
	v_readfirstlane_b32 s19, v147
	v_add_u32_e32 v148, 0x8000, v140
	s_waitcnt vmcnt(2)
	s_barrier
	global_load_lds_dwordx4 v[12:13], off
	v_lshl_add_u64 v[12:13], v[2:3], 0, s[20:21]
	s_mov_b32 m0, s19
	v_readfirstlane_b32 s19, v148
	v_add_u32_e32 v149, 0xa000, v140
	global_load_lds_dwordx4 v[12:13], off
	v_lshl_add_u64 v[12:13], v[4:5], 0, s[64:65]
	s_mov_b32 m0, s19
	s_mov_b64 s[20:21], 0x10080
	v_readfirstlane_b32 s19, v149
	v_add_u32_e32 v150, s84, v11
	global_load_lds_dwordx4 v[12:13], off
	v_lshl_add_u64 v[4:5], v[4:5], 0, s[20:21]
	s_mov_b32 m0, s19
	s_mov_b64 s[20:21], 0x130080
	v_readfirstlane_b32 s19, v150
	v_add_u32_e32 v152, 0x2000, v150
	global_load_lds_dwordx4 v[4:5], off
	v_lshl_add_u64 v[4:5], v[2:3], 0, s[20:21]
	s_mov_b32 m0, s19
	s_mov_b64 s[20:21], 0x1c8080
	v_readfirstlane_b32 s19, v152
	global_load_lds_dwordx4 v[4:5], off
	v_lshl_add_u64 v[2:3], v[2:3], 0, s[20:21]
	s_mov_b32 m0, s19
	v_and_b32_e32 v0, 15, v7
	global_load_lds_dwordx4 v[2:3], off
	v_lshlrev_b32_e32 v2, 2, v7
	v_and_b32_e32 v14, 48, v7
	v_lshlrev_b32_e32 v0, 6, v0
	v_and_b32_e32 v2, 32, v2
	v_bitop3_b32 v0, v0, v2, v14 bitop3:0x36
	v_add_u32_e32 v4, s1, v0
	v_add_u32_e32 v5, s60, v0
	v_add_u32_e32 v11, s61, v0
	v_add_u32_e32 v12, s84, v0
	v_add_u32_e32 v13, 0, v0
	v_lshlrev_b32_e32 v0, 6, v7
	v_and_or_b32 v0, v0, s74, v14
	s_movk_i32 s20, 0x1300
	v_xad_u32 v153, v0, v2, 0
	v_lshrrev_b32_e32 v7, 1, v6
	v_mul_lo_u32 v0, v8, s20
	s_mov_b32 s20, 0x13000
	v_mad_u64_u32 v[2:3], s[20:21], v7, s20, v[0:1]
	v_or_b32_e32 v0, v2, v10
	v_add_lshl_u32 v0, v0, v9, 1
	v_lshl_add_u64 v[132:133], s[10:11], 0, v[0:1]
	v_lshlrev_b32_e32 v0, 10, v8
	s_ashr_i32 s18, s18, 6
	v_lshl_add_u32 v0, v7, 14, v0
	v_and_b32_e32 v2, 1, v6
	s_waitcnt vmcnt(6)
	s_lshl_b32 s19, s18, 12
	v_lshl_or_b32 v0, v2, 6, v0
	s_and_b32 s22, s19, 0x3000
	s_lshl_b32 s23, s0, 13
	v_lshl_add_u32 v0, v9, 1, v0
	v_mov_b32_e32 v2, 0
	s_or_b32 s0, s23, 0x800
	s_or_b32 s1, s23, 0x1000
	s_or_b32 s19, s23, 0x1800
	v_lshl_add_u64 v[134:135], s[12:13], 0, v[0:1]
	v_lshl_add_u64 v[136:137], s[14:15], 0, v[0:1]
	s_mov_b32 s12, -2
	v_add_u32_e32 v154, s22, v4
	v_add_u32_e32 v0, s23, v13
	v_add_u32_e32 v151, s22, v5
	v_add_u32_e32 v142, s22, v11
	v_add_u32_e32 v139, s22, v12
	s_mov_b64 s[10:11], s[54:55]
	v_mov_b32_e32 v3, v2
	v_mov_b32_e32 v4, v2
	v_mov_b32_e32 v5, v2
	v_mov_b32_e32 v6, v2
	v_mov_b32_e32 v7, v2
	v_mov_b32_e32 v8, v2
	v_mov_b32_e32 v9, v2
	v_mov_b32_e32 v10, v2
	v_mov_b32_e32 v11, v2
	v_mov_b32_e32 v12, v2
	v_mov_b32_e32 v13, v2
	v_mov_b32_e32 v14, v2
	v_mov_b32_e32 v15, v2
	s_mov_b64 s[20:21], 0x1f900100
	s_mov_b64 s[22:23], 0x1f910100
	s_barrier
.LBB0_273:
	v_add_u32_e32 v155, s0, v153
	v_add_u32_e32 v156, s1, v153
	v_add_u32_e32 v157, s19, v153
	ds_read_b128 v[160:163], v154
	ds_read_b128 v[164:167], v154 offset:1024
	ds_read_b128 v[168:171], v154 offset:2048
	ds_read_b128 v[172:175], v154 offset:3072
	ds_read_b128 v[176:179], v0
	ds_read_b128 v[180:183], v0 offset:1024
	ds_read_b128 v[184:187], v155
	ds_read_b128 v[188:191], v155 offset:1024
	ds_read_b128 v[192:195], v156
	ds_read_b128 v[196:199], v156 offset:1024
	ds_read_b128 v[200:203], v157
	ds_read_b128 v[206:209], v157 offset:1024
	ds_read_b128 v[210:213], v151
	ds_read_b128 v[214:217], v151 offset:1024
	ds_read_b128 v[218:221], v151 offset:2048
	ds_read_b128 v[222:225], v151 offset:3072
	v_add_u32_e32 v158, 0xc000, v140
	v_lshl_add_u64 v[228:229], s[10:11], 0, v[136:137]
	s_mov_b64 s[14:15], 0x1f900080
	v_lshl_add_u64 v[226:227], v[228:229], 0, s[14:15]
	v_readfirstlane_b32 s13, v158
	s_mov_b32 m0, s13
	s_nop 0
	global_load_lds_dwordx4 v[226:227], off
	v_add_u32_e32 v159, 0xe000, v140
	v_lshl_add_u64 v[228:229], s[10:11], 0, v[136:137]
	s_mov_b64 s[14:15], 0x1f910080
	v_lshl_add_u64 v[226:227], v[228:229], 0, s[14:15]
	v_readfirstlane_b32 s13, v159
	s_mov_b32 m0, s13
	s_nop 0
	global_load_lds_dwordx4 v[226:227], off
	s_waitcnt vmcnt(8)
	s_waitcnt lgkmcnt(0)
	s_barrier
	s_setprio 1
	v_mfma_f32_16x16x32_bf16 v[126:129], v[176:179], v[160:163], v[126:129]
	v_mfma_f32_16x16x32_bf16 v[122:125], v[176:179], v[168:171], v[122:125]
	v_mfma_f32_16x16x32_bf16 v[118:121], v[184:187], v[160:163], v[118:121]
	v_mfma_f32_16x16x32_bf16 v[114:117], v[184:187], v[168:171], v[114:117]
	v_mfma_f32_16x16x32_bf16 v[110:113], v[192:195], v[160:163], v[110:113]
	v_mfma_f32_16x16x32_bf16 v[106:109], v[192:195], v[168:171], v[106:109]
	v_mfma_f32_16x16x32_bf16 v[102:105], v[200:203], v[160:163], v[102:105]
	v_mfma_f32_16x16x32_bf16 v[98:101], v[200:203], v[168:171], v[98:101]
	v_mfma_f32_16x16x32_bf16 v[126:129], v[180:183], v[164:167], v[126:129]
	v_mfma_f32_16x16x32_bf16 v[122:125], v[180:183], v[172:175], v[122:125]
	v_mfma_f32_16x16x32_bf16 v[118:121], v[188:191], v[164:167], v[118:121]
	v_mfma_f32_16x16x32_bf16 v[114:117], v[188:191], v[172:175], v[114:117]
	v_mfma_f32_16x16x32_bf16 v[110:113], v[196:199], v[164:167], v[110:113]
	v_mfma_f32_16x16x32_bf16 v[106:109], v[196:199], v[172:175], v[106:109]
	v_mfma_f32_16x16x32_bf16 v[102:105], v[206:209], v[164:167], v[102:105]
	v_mfma_f32_16x16x32_bf16 v[98:101], v[206:209], v[172:175], v[98:101]
	v_mfma_f32_16x16x32_bf16 v[94:97], v[176:179], v[210:213], v[94:97]
	v_mfma_f32_16x16x32_bf16 v[90:93], v[176:179], v[218:221], v[90:93]
	v_mfma_f32_16x16x32_bf16 v[86:89], v[184:187], v[210:213], v[86:89]
	v_mfma_f32_16x16x32_bf16 v[82:85], v[184:187], v[218:221], v[82:85]
	v_mfma_f32_16x16x32_bf16 v[78:81], v[192:195], v[210:213], v[78:81]
	v_mfma_f32_16x16x32_bf16 v[74:77], v[192:195], v[218:221], v[74:77]
	v_mfma_f32_16x16x32_bf16 v[70:73], v[200:203], v[210:213], v[70:73]
	v_mfma_f32_16x16x32_bf16 v[66:69], v[200:203], v[218:221], v[66:69]
	v_mfma_f32_16x16x32_bf16 v[94:97], v[180:183], v[214:217], v[94:97]
	v_mfma_f32_16x16x32_bf16 v[90:93], v[180:183], v[222:225], v[90:93]
	v_mfma_f32_16x16x32_bf16 v[86:89], v[188:191], v[214:217], v[86:89]
	v_mfma_f32_16x16x32_bf16 v[82:85], v[188:191], v[222:225], v[82:85]
	v_mfma_f32_16x16x32_bf16 v[78:81], v[196:199], v[214:217], v[78:81]
	v_mfma_f32_16x16x32_bf16 v[74:77], v[196:199], v[222:225], v[74:77]
	v_mfma_f32_16x16x32_bf16 v[70:73], v[206:209], v[214:217], v[70:73]
	v_mfma_f32_16x16x32_bf16 v[66:69], v[206:209], v[222:225], v[66:69]
	s_setprio 0
	s_barrier
; #define STAGE_A(P, br, kt) do { const char* _g = (const char*)(A + (long)(br) * lda + (long)(kt) * BK); \
;     __builtin_amdgcn_global_load_lds((const unsigned*)(_g + (size_t)offA0), (unsigned*)((char*)(P) + sb0), 16, 0, 0); \
;     __builtin_amdgcn_global_load_lds((const unsigned*)(_g + (size_t)lda * 128 + (size_t)offA0), (unsigned*)((char*)(P) + sb1), 16, 0, 0); } while (0)
; #define STAGE_B(P, br, kt) do { const char* _g = (const char*)(B + (long)(br) * ldb + (long)(kt) * BK); \
;     __builtin_amdgcn_global_load_lds((const unsigned*)(_g + (size_t)offB0), (unsigned*)((char*)(P) + sb0), 16, 0, 0); \
;     __builtin_amdgcn_global_load_lds((const unsigned*)(_g + (size_t)ldb * 128 + (size_t)offB0), (unsigned*)((char*)(P) + sb1), 16, 0, 0); } while (0)
; #define LDA(dst, b, h) for (int m = 0; m < 4; ++m) for (int k = 0; k < 2; ++k) \
;     dst[m][k] = *reinterpret_cast<const bf16x8*>((char*)SA(b, h) + lds_byte(wr * 64 + m * 16 + fr, k * 32 + fq * 8))
; #define LDB(dst, b, h) for (int n = 0; n < 2; ++n) for (int k = 0; k < 2; ++k) \
;     dst[n][k] = *reinterpret_cast<const bf16x8*>((char*)SB(b, h) + lds_byte(wc * 32 + n * 16 + fr, k * 32 + fq * 8))
; #define MMA(ai, bj, At_, Bt_) do { __builtin_amdgcn_s_setprio(1); \
;     for (int m = 0; m < 4; ++m) for (int n = 0; n < 2; ++n) for (int k = 0; k < 2; ++k) \
;       acc[ai][bj][m][n] = MFMA16(At_[m][k], Bt_[n][k], acc[ai][bj][m][n]); \
;     __builtin_amdgcn_s_setprio(0); } while (0)
; #define WAIT_V(n) asm volatile("s_waitcnt vmcnt(" #n ")" ::: "memory")
; #define WAIT_L(n) asm volatile("s_waitcnt lgkmcnt(" #n ")" ::: "memory")
; #define BAR __builtin_amdgcn_s_barrier()
; #define SCHED __builtin_amdgcn_sched_barrier(0)
; DI void gemm_core(WVP char* smem, const u16* __restrict__ A, int lda, int ar0, int ar1,
;                   const u16* __restrict__ B, int ldb, int bc0, int K, AccT& acc) {
;     ...
;     LDA(At, 0, 1); STAGE_A(SA(0, 0), ac0, t + 2);
;     BAR; WAIT_L(0); MMA(1, 0, At, B0); BAR; SCHED;
;     STAGE_B(SB(0, 1), bb1, t + 2);
;     WAIT_V(6); BAR; MMA(1, 1, At, B1); BAR;
;     LDB(B0, 1, 0); SCHED; LDA(At, 1, 0); STAGE_A(SA(0, 1), ac1, t + 2);
;     WAIT_L(8); BAR; WAIT_L(0); MMA(0, 0, At, B0); BAR; SCHED;
	ds_read_b128 v[176:179], v0 offset:16384
	ds_read_b128 v[180:183], v0 offset:17408
	ds_read_b128 v[184:187], v155 offset:16384
	ds_read_b128 v[188:191], v155 offset:17408
	ds_read_b128 v[192:195], v156 offset:16384
	ds_read_b128 v[196:199], v156 offset:17408
	ds_read_b128 v[200:203], v157 offset:16384
	ds_read_b128 v[206:209], v157 offset:17408
	v_lshl_add_u64 v[228:229], s[10:11], 0, v[132:133]
	s_mov_b64 s[14:15], 0x2300
	v_lshl_add_u64 v[226:227], v[228:229], 0, s[14:15]
	v_readfirstlane_b32 s13, v138
	s_mov_b32 m0, s13
	s_nop 0
	global_load_lds_dwordx4 v[226:227], off
	v_add_u32_e32 v205, 0x2000, v138
	v_lshl_add_u64 v[228:229], s[10:11], 0, v[132:133]
	s_mov_b64 s[14:15], 0x9a300
	v_lshl_add_u64 v[226:227], v[228:229], 0, s[14:15]
	v_readfirstlane_b32 s13, v205
	s_mov_b32 m0, s13
	s_nop 0
	global_load_lds_dwordx4 v[226:227], off
	v_lshl_add_u64 v[228:229], s[10:11], 0, v[134:135]
	v_lshl_add_u64 v[226:227], v[228:229], 0, s[20:21]
	v_readfirstlane_b32 s13, v140
	s_mov_b32 m0, s13
	s_nop 0
	global_load_lds_dwordx4 v[226:227], off
	v_lshl_add_u64 v[228:229], s[10:11], 0, v[134:135]
	v_lshl_add_u64 v[226:227], v[228:229], 0, s[22:23]
	v_readfirstlane_b32 s13, v141
	s_mov_b32 m0, s13
	s_nop 0
	global_load_lds_dwordx4 v[226:227], off
	v_lshl_add_u64 v[228:229], s[10:11], 0, v[132:133]
	s_mov_b64 s[14:15], 0x132300
	v_lshl_add_u64 v[226:227], v[228:229], 0, s[14:15]
	v_readfirstlane_b32 s13, v143
	s_mov_b32 m0, s13
	s_nop 0
	global_load_lds_dwordx4 v[226:227], off
	v_add_u32_e32 v230, 0x2000, v143
	v_lshl_add_u64 v[228:229], s[10:11], 0, v[132:133]
	s_mov_b64 s[14:15], 0x1ca300
	v_lshl_add_u64 v[226:227], v[228:229], 0, s[14:15]
	v_readfirstlane_b32 s13, v230
	s_mov_b32 m0, s13
	s_nop 0
	global_load_lds_dwordx4 v[226:227], off
	s_waitcnt vmcnt(8)
	s_waitcnt lgkmcnt(0)
	s_barrier
	s_setprio 1
	v_mfma_f32_16x16x32_bf16 v[62:65], v[176:179], v[160:163], v[62:65]
	v_mfma_f32_16x16x32_bf16 v[58:61], v[176:179], v[168:171], v[58:61]
	v_mfma_f32_16x16x32_bf16 v[54:57], v[184:187], v[160:163], v[54:57]
	v_mfma_f32_16x16x32_bf16 v[50:53], v[184:187], v[168:171], v[50:53]
	v_mfma_f32_16x16x32_bf16 v[46:49], v[192:195], v[160:163], v[46:49]
	v_mfma_f32_16x16x32_bf16 v[42:45], v[192:195], v[168:171], v[42:45]
	v_mfma_f32_16x16x32_bf16 v[38:41], v[200:203], v[160:163], v[38:41]
	v_mfma_f32_16x16x32_bf16 v[34:37], v[200:203], v[168:171], v[34:37]
	v_mfma_f32_16x16x32_bf16 v[62:65], v[180:183], v[164:167], v[62:65]
	v_mfma_f32_16x16x32_bf16 v[58:61], v[180:183], v[172:175], v[58:61]
	v_mfma_f32_16x16x32_bf16 v[54:57], v[188:191], v[164:167], v[54:57]
	v_mfma_f32_16x16x32_bf16 v[50:53], v[188:191], v[172:175], v[50:53]
	v_mfma_f32_16x16x32_bf16 v[46:49], v[196:199], v[164:167], v[46:49]
	v_mfma_f32_16x16x32_bf16 v[42:45], v[196:199], v[172:175], v[42:45]
	v_mfma_f32_16x16x32_bf16 v[38:41], v[206:209], v[164:167], v[38:41]
	v_mfma_f32_16x16x32_bf16 v[34:37], v[206:209], v[172:175], v[34:37]
	v_mfma_f32_16x16x32_bf16 v[30:33], v[176:179], v[210:213], v[30:33]
	v_mfma_f32_16x16x32_bf16 v[26:29], v[176:179], v[218:221], v[26:29]
	v_mfma_f32_16x16x32_bf16 v[22:25], v[184:187], v[210:213], v[22:25]
	v_mfma_f32_16x16x32_bf16 v[18:21], v[184:187], v[218:221], v[18:21]
	v_mfma_f32_16x16x32_bf16 v[14:17], v[192:195], v[210:213], v[14:17]
	v_mfma_f32_16x16x32_bf16 v[10:13], v[192:195], v[218:221], v[10:13]
	v_mfma_f32_16x16x32_bf16 v[6:9], v[200:203], v[210:213], v[6:9]
	v_mfma_f32_16x16x32_bf16 v[2:5], v[200:203], v[218:221], v[2:5]
	v_mfma_f32_16x16x32_bf16 v[30:33], v[180:183], v[214:217], v[30:33]
	v_mfma_f32_16x16x32_bf16 v[26:29], v[180:183], v[222:225], v[26:29]
	v_mfma_f32_16x16x32_bf16 v[22:25], v[188:191], v[214:217], v[22:25]
	v_mfma_f32_16x16x32_bf16 v[18:21], v[188:191], v[222:225], v[18:21]
	v_mfma_f32_16x16x32_bf16 v[14:17], v[196:199], v[214:217], v[14:17]
	v_mfma_f32_16x16x32_bf16 v[10:13], v[196:199], v[222:225], v[10:13]
	v_mfma_f32_16x16x32_bf16 v[6:9], v[206:209], v[214:217], v[6:9]
	v_mfma_f32_16x16x32_bf16 v[2:5], v[206:209], v[222:225], v[2:5]
	s_setprio 0
	s_barrier
	ds_read_b128 v[160:163], v142
	ds_read_b128 v[164:167], v142 offset:1024
	ds_read_b128 v[168:171], v142 offset:2048
	ds_read_b128 v[172:175], v142 offset:3072
	ds_read_b128 v[176:179], v0 offset:32768
	ds_read_b128 v[180:183], v0 offset:33792
	ds_read_b128 v[184:187], v155 offset:32768
	ds_read_b128 v[188:191], v155 offset:33792
	ds_read_b128 v[192:195], v156 offset:32768
	ds_read_b128 v[196:199], v156 offset:33792
	ds_read_b128 v[200:203], v157 offset:32768
	ds_read_b128 v[206:209], v157 offset:33792
	ds_read_b128 v[210:213], v139
	ds_read_b128 v[214:217], v139 offset:1024
	ds_read_b128 v[218:221], v139 offset:2048
	ds_read_b128 v[222:225], v139 offset:3072
	v_lshl_add_u64 v[228:229], s[10:11], 0, v[136:137]
	v_lshl_add_u64 v[226:227], v[228:229], 0, s[20:21]
	v_readfirstlane_b32 s13, v144
	s_mov_b32 m0, s13
	s_nop 0
	global_load_lds_dwordx4 v[226:227], off
	v_lshl_add_u64 v[228:229], s[10:11], 0, v[136:137]
	v_lshl_add_u64 v[226:227], v[228:229], 0, s[22:23]
	v_readfirstlane_b32 s13, v145
	s_mov_b32 m0, s13
	s_nop 0
	global_load_lds_dwordx4 v[226:227], off
	s_waitcnt vmcnt(8)
	s_waitcnt lgkmcnt(0)
	s_barrier
; #define STAGE_A(P, br, kt) do { const char* _g = (const char*)(A + (long)(br) * lda + (long)(kt) * BK); \
;     __builtin_amdgcn_global_load_lds((const unsigned*)(_g + (size_t)offA0), (unsigned*)((char*)(P) + sb0), 16, 0, 0); \
;     __builtin_amdgcn_global_load_lds((const unsigned*)(_g + (size_t)lda * 128 + (size_t)offA0), (unsigned*)((char*)(P) + sb1), 16, 0, 0); } while (0)
; #define STAGE_B(P, br, kt) do { const char* _g = (const char*)(B + (long)(br) * ldb + (long)(kt) * BK); \
;     __builtin_amdgcn_global_load_lds((const unsigned*)(_g + (size_t)offB0), (unsigned*)((char*)(P) + sb0), 16, 0, 0); \
;     __builtin_amdgcn_global_load_lds((const unsigned*)(_g + (size_t)ldb * 128 + (size_t)offB0), (unsigned*)((char*)(P) + sb1), 16, 0, 0); } while (0)
; #define LDA(dst, b, h) for (int m = 0; m < 4; ++m) for (int k = 0; k < 2; ++k) \
;     dst[m][k] = *reinterpret_cast<const bf16x8*>((char*)SA(b, h) + lds_byte(wr * 64 + m * 16 + fr, k * 32 + fq * 8))
; #define LDB(dst, b, h) for (int n = 0; n < 2; ++n) for (int k = 0; k < 2; ++k) \
;     dst[n][k] = *reinterpret_cast<const bf16x8*>((char*)SB(b, h) + lds_byte(wc * 32 + n * 16 + fr, k * 32 + fq * 8))
; #define MMA(ai, bj, At_, Bt_) do { __builtin_amdgcn_s_setprio(1); \
;     for (int m = 0; m < 4; ++m) for (int n = 0; n < 2; ++n) for (int k = 0; k < 2; ++k) \
;       acc[ai][bj][m][n] = MFMA16(At_[m][k], Bt_[n][k], acc[ai][bj][m][n]); \
;     __builtin_amdgcn_s_setprio(0); } while (0)
; #define WAIT_V(n) asm volatile("s_waitcnt vmcnt(" #n ")" ::: "memory")
; #define WAIT_L(n) asm volatile("s_waitcnt lgkmcnt(" #n ")" ::: "memory")
; #define BAR __builtin_amdgcn_s_barrier()
; #define SCHED __builtin_amdgcn_sched_barrier(0)
; DI void gemm_core(WVP char* smem, const u16* __restrict__ A, int lda, int ar0, int ar1,
;                   const u16* __restrict__ B, int ldb, int bc0, int K, AccT& acc) {
;     ...
;     LDB(B0, 1, 0); SCHED; LDA(At, 1, 0); STAGE_A(SA(0, 1), ac1, t + 2);
;     WAIT_L(8); BAR; WAIT_L(0); MMA(0, 0, At, B0); BAR; SCHED;
;     LDB(B1, 1, 1); STAGE_B(SB(1, 0), bb0, t + 3);
;     BAR; WAIT_L(0); MMA(0, 1, At, B1); BAR;
;     LDA(At, 1, 1); STAGE_A(SA(1, 0), ac0, t + 3);
;     BAR; WAIT_L(0); MMA(1, 0, At, B0); BAR; SCHED;
;     STAGE_B(SB(1, 1), bb1, t + 3);
;     WAIT_V(6); BAR; MMA(1, 1, At, B1); BAR;
	s_setprio 1
	v_mfma_f32_16x16x32_bf16 v[126:129], v[176:179], v[160:163], v[126:129]
	v_mfma_f32_16x16x32_bf16 v[122:125], v[176:179], v[168:171], v[122:125]
	v_mfma_f32_16x16x32_bf16 v[118:121], v[184:187], v[160:163], v[118:121]
	v_mfma_f32_16x16x32_bf16 v[114:117], v[184:187], v[168:171], v[114:117]
	v_mfma_f32_16x16x32_bf16 v[110:113], v[192:195], v[160:163], v[110:113]
	v_mfma_f32_16x16x32_bf16 v[106:109], v[192:195], v[168:171], v[106:109]
	v_mfma_f32_16x16x32_bf16 v[102:105], v[200:203], v[160:163], v[102:105]
	v_mfma_f32_16x16x32_bf16 v[98:101], v[200:203], v[168:171], v[98:101]
	v_mfma_f32_16x16x32_bf16 v[126:129], v[180:183], v[164:167], v[126:129]
	v_mfma_f32_16x16x32_bf16 v[122:125], v[180:183], v[172:175], v[122:125]
	v_mfma_f32_16x16x32_bf16 v[118:121], v[188:191], v[164:167], v[118:121]
	v_mfma_f32_16x16x32_bf16 v[114:117], v[188:191], v[172:175], v[114:117]
	v_mfma_f32_16x16x32_bf16 v[110:113], v[196:199], v[164:167], v[110:113]
	v_mfma_f32_16x16x32_bf16 v[106:109], v[196:199], v[172:175], v[106:109]
	v_mfma_f32_16x16x32_bf16 v[102:105], v[206:209], v[164:167], v[102:105]
	v_mfma_f32_16x16x32_bf16 v[98:101], v[206:209], v[172:175], v[98:101]
	v_mfma_f32_16x16x32_bf16 v[94:97], v[176:179], v[210:213], v[94:97]
	v_mfma_f32_16x16x32_bf16 v[90:93], v[176:179], v[218:221], v[90:93]
	v_mfma_f32_16x16x32_bf16 v[86:89], v[184:187], v[210:213], v[86:89]
	v_mfma_f32_16x16x32_bf16 v[82:85], v[184:187], v[218:221], v[82:85]
	v_mfma_f32_16x16x32_bf16 v[78:81], v[192:195], v[210:213], v[78:81]
	v_mfma_f32_16x16x32_bf16 v[74:77], v[192:195], v[218:221], v[74:77]
	v_mfma_f32_16x16x32_bf16 v[70:73], v[200:203], v[210:213], v[70:73]
	v_mfma_f32_16x16x32_bf16 v[66:69], v[200:203], v[218:221], v[66:69]
	v_mfma_f32_16x16x32_bf16 v[94:97], v[180:183], v[214:217], v[94:97]
	v_mfma_f32_16x16x32_bf16 v[90:93], v[180:183], v[222:225], v[90:93]
	v_mfma_f32_16x16x32_bf16 v[86:89], v[188:191], v[214:217], v[86:89]
	v_mfma_f32_16x16x32_bf16 v[82:85], v[188:191], v[222:225], v[82:85]
	v_mfma_f32_16x16x32_bf16 v[78:81], v[196:199], v[214:217], v[78:81]
	v_mfma_f32_16x16x32_bf16 v[74:77], v[196:199], v[222:225], v[74:77]
	v_mfma_f32_16x16x32_bf16 v[70:73], v[206:209], v[214:217], v[70:73]
	v_mfma_f32_16x16x32_bf16 v[66:69], v[206:209], v[222:225], v[66:69]
	s_setprio 0
	s_barrier
	ds_read_b128 v[176:179], v0 offset:49152
	ds_read_b128 v[180:183], v0 offset:50176
	ds_read_b128 v[184:187], v155 offset:49152
	ds_read_b128 v[188:191], v155 offset:50176
	ds_read_b128 v[192:195], v156 offset:49152
	ds_read_b128 v[196:199], v156 offset:50176
	ds_read_b128 v[200:203], v157 offset:49152
	ds_read_b128 v[206:209], v157 offset:50176
	v_lshl_add_u64 v[228:229], s[10:11], 0, v[132:133]
	s_mov_b64 s[14:15], 0x2380
	v_lshl_add_u64 v[226:227], v[228:229], 0, s[14:15]
	v_readfirstlane_b32 s13, v146
	s_mov_b32 m0, s13
	s_nop 0
	global_load_lds_dwordx4 v[226:227], off
	v_lshl_add_u64 v[228:229], s[10:11], 0, v[132:133]
	s_mov_b64 s[14:15], 0x9a380
	v_lshl_add_u64 v[226:227], v[228:229], 0, s[14:15]
	v_readfirstlane_b32 s13, v147
	s_mov_b32 m0, s13
	s_nop 0
	global_load_lds_dwordx4 v[226:227], off
	v_lshl_add_u64 v[228:229], s[10:11], 0, v[134:135]
	s_mov_b64 s[14:15], 0x1f900180
	v_lshl_add_u64 v[226:227], v[228:229], 0, s[14:15]
	v_readfirstlane_b32 s13, v148
	s_mov_b32 m0, s13
	s_nop 0
	global_load_lds_dwordx4 v[226:227], off
	v_lshl_add_u64 v[228:229], s[10:11], 0, v[134:135]
	s_mov_b64 s[14:15], 0x1f910180
	v_lshl_add_u64 v[226:227], v[228:229], 0, s[14:15]
	v_readfirstlane_b32 s13, v149
	s_mov_b32 m0, s13
	s_nop 0
	global_load_lds_dwordx4 v[226:227], off
	v_lshl_add_u64 v[228:229], s[10:11], 0, v[132:133]
	s_mov_b64 s[14:15], 0x132380
	v_lshl_add_u64 v[226:227], v[228:229], 0, s[14:15]
	v_readfirstlane_b32 s13, v150
	s_mov_b32 m0, s13
	s_nop 0
	global_load_lds_dwordx4 v[226:227], off
	v_lshl_add_u64 v[228:229], s[10:11], 0, v[132:133]
	s_mov_b64 s[14:15], 0x1ca380
	v_lshl_add_u64 v[226:227], v[228:229], 0, s[14:15]
	v_readfirstlane_b32 s13, v152
	s_mov_b32 m0, s13
	s_nop 0
	global_load_lds_dwordx4 v[226:227], off
	s_waitcnt vmcnt(8)
	s_waitcnt lgkmcnt(0)
	s_barrier
	s_setprio 1
	v_mfma_f32_16x16x32_bf16 v[62:65], v[176:179], v[160:163], v[62:65]
	v_mfma_f32_16x16x32_bf16 v[58:61], v[176:179], v[168:171], v[58:61]
	v_mfma_f32_16x16x32_bf16 v[54:57], v[184:187], v[160:163], v[54:57]
	v_mfma_f32_16x16x32_bf16 v[50:53], v[184:187], v[168:171], v[50:53]
	v_mfma_f32_16x16x32_bf16 v[46:49], v[192:195], v[160:163], v[46:49]
	v_mfma_f32_16x16x32_bf16 v[42:45], v[192:195], v[168:171], v[42:45]
	v_mfma_f32_16x16x32_bf16 v[38:41], v[200:203], v[160:163], v[38:41]
	v_mfma_f32_16x16x32_bf16 v[34:37], v[200:203], v[168:171], v[34:37]
	v_mfma_f32_16x16x32_bf16 v[62:65], v[180:183], v[164:167], v[62:65]
	v_mfma_f32_16x16x32_bf16 v[58:61], v[180:183], v[172:175], v[58:61]
	v_mfma_f32_16x16x32_bf16 v[54:57], v[188:191], v[164:167], v[54:57]
	v_mfma_f32_16x16x32_bf16 v[50:53], v[188:191], v[172:175], v[50:53]
	v_mfma_f32_16x16x32_bf16 v[46:49], v[196:199], v[164:167], v[46:49]
	v_mfma_f32_16x16x32_bf16 v[42:45], v[196:199], v[172:175], v[42:45]
	v_mfma_f32_16x16x32_bf16 v[38:41], v[206:209], v[164:167], v[38:41]
	v_mfma_f32_16x16x32_bf16 v[34:37], v[206:209], v[172:175], v[34:37]
	v_mfma_f32_16x16x32_bf16 v[30:33], v[176:179], v[210:213], v[30:33]
	v_mfma_f32_16x16x32_bf16 v[26:29], v[176:179], v[218:221], v[26:29]
	v_mfma_f32_16x16x32_bf16 v[22:25], v[184:187], v[210:213], v[22:25]
	v_mfma_f32_16x16x32_bf16 v[18:21], v[184:187], v[218:221], v[18:21]
	v_mfma_f32_16x16x32_bf16 v[14:17], v[192:195], v[210:213], v[14:17]
	v_mfma_f32_16x16x32_bf16 v[10:13], v[192:195], v[218:221], v[10:13]
	v_mfma_f32_16x16x32_bf16 v[6:9], v[200:203], v[210:213], v[6:9]
	v_mfma_f32_16x16x32_bf16 v[2:5], v[200:203], v[218:221], v[2:5]
	v_mfma_f32_16x16x32_bf16 v[30:33], v[180:183], v[214:217], v[30:33]
	v_mfma_f32_16x16x32_bf16 v[26:29], v[180:183], v[222:225], v[26:29]
	v_mfma_f32_16x16x32_bf16 v[22:25], v[188:191], v[214:217], v[22:25]
	v_mfma_f32_16x16x32_bf16 v[18:21], v[188:191], v[222:225], v[18:21]
	v_mfma_f32_16x16x32_bf16 v[14:17], v[196:199], v[214:217], v[14:17]
	v_mfma_f32_16x16x32_bf16 v[10:13], v[196:199], v[222:225], v[10:13]
	v_mfma_f32_16x16x32_bf16 v[6:9], v[206:209], v[214:217], v[6:9]
	v_mfma_f32_16x16x32_bf16 v[2:5], v[206:209], v[222:225], v[2:5]
	s_setprio 0
	s_add_i32 s12, s12, 2
	s_add_u32 s10, s10, 0x100
	s_addc_u32 s11, s11, 0
	s_cmp_lt_u32 s12, 4
	s_barrier
; #define STAGE_A(P, br, kt) do { const char* _g = (const char*)(A + (long)(br) * lda + (long)(kt) * BK); \
;     __builtin_amdgcn_global_load_lds((const unsigned*)(_g + (size_t)offA0), (unsigned*)((char*)(P) + sb0), 16, 0, 0); \
;     __builtin_amdgcn_global_load_lds((const unsigned*)(_g + (size_t)lda * 128 + (size_t)offA0), (unsigned*)((char*)(P) + sb1), 16, 0, 0); } while (0)
; #define LDA(dst, b, h) for (int m = 0; m < 4; ++m) for (int k = 0; k < 2; ++k) \
;     dst[m][k] = *reinterpret_cast<const bf16x8*>((char*)SA(b, h) + lds_byte(wr * 64 + m * 16 + fr, k * 32 + fq * 8))
; #define LDB(dst, b, h) for (int n = 0; n < 2; ++n) for (int k = 0; k < 2; ++k) \
;     dst[n][k] = *reinterpret_cast<const bf16x8*>((char*)SB(b, h) + lds_byte(wc * 32 + n * 16 + fr, k * 32 + fq * 8))
; #define MMA(ai, bj, At_, Bt_) do { __builtin_amdgcn_s_setprio(1); \
;     for (int m = 0; m < 4; ++m) for (int n = 0; n < 2; ++n) for (int k = 0; k < 2; ++k) \
;       acc[ai][bj][m][n] = MFMA16(At_[m][k], Bt_[n][k], acc[ai][bj][m][n]); \
;     __builtin_amdgcn_s_setprio(0); } while (0)
; #define WAIT_V(n) asm volatile("s_waitcnt vmcnt(" #n ")" ::: "memory")
; #define WAIT_L(n) asm volatile("s_waitcnt lgkmcnt(" #n ")" ::: "memory")
; #define BAR __builtin_amdgcn_s_barrier()
; DI void gemm_core(WVP char* smem, const u16* __restrict__ A, int lda, int ar0, int ar1,
;                   const u16* __restrict__ B, int ldb, int bc0, int K, AccT& acc) {
;     ...
;   { LDB(B0, 0, 0); LDA(At, 0, 0); STAGE_A(SA(1, 1), ac1, nt - 1);
;     BAR; WAIT_L(0); MMA(0, 0, At, B0); BAR;
;     LDB(B1, 0, 1); BAR; WAIT_L(0); MMA(0, 1, At, B1); BAR;
;     LDA(At, 0, 1); WAIT_V(4); BAR; WAIT_L(0); MMA(1, 0, At, B0); MMA(1, 1, At, B1); BAR; }
	s_cbranch_scc1 .LBB0_273
	s_mov_b64 s[0:1], 0x380
	v_lshl_add_u64 v[136:137], v[130:131], 0, s[0:1]
	v_readfirstlane_b32 s0, v158
	s_mov_b32 m0, s0
	s_mov_b64 s[0:1], 0x10380
	v_lshl_add_u64 v[130:131], v[130:131], 0, s[0:1]
	v_readfirstlane_b32 s0, v159
	ds_read_b128 v[132:135], v154
	ds_read_b128 v[144:147], v154 offset:1024
	ds_read_b128 v[160:163], v154 offset:2048
	ds_read_b128 v[164:167], v154 offset:3072
	ds_read_b128 v[168:171], v0
	ds_read_b128 v[172:175], v0 offset:1024
	ds_read_b128 v[176:179], v155
	ds_read_b128 v[180:183], v155 offset:1024
	ds_read_b128 v[184:187], v156
	ds_read_b128 v[188:191], v156 offset:1024
	ds_read_b128 v[192:195], v157
	ds_read_b128 v[196:199], v157 offset:1024
	global_load_lds_dwordx4 v[136:137], off
	s_mov_b32 m0, s0
	s_nop 0
	global_load_lds_dwordx4 v[130:131], off
	s_waitcnt vmcnt(8)
	s_barrier
	s_waitcnt lgkmcnt(0)
	s_setprio 1
	s_waitcnt lgkmcnt(0)
	v_mfma_f32_16x16x32_bf16 v[126:129], v[168:171], v[132:135], v[126:129]
	v_mfma_f32_16x16x32_bf16 v[122:125], v[168:171], v[160:163], v[122:125]
	v_mfma_f32_16x16x32_bf16 v[118:121], v[176:179], v[132:135], v[118:121]
	v_mfma_f32_16x16x32_bf16 v[110:113], v[184:187], v[132:135], v[110:113]
	v_mfma_f32_16x16x32_bf16 v[98:101], v[192:195], v[160:163], v[98:101]
	v_mfma_f32_16x16x32_bf16 v[126:129], v[172:175], v[144:147], v[126:129]
	v_mfma_f32_16x16x32_bf16 v[122:125], v[172:175], v[164:167], v[122:125]
	v_mfma_f32_16x16x32_bf16 v[118:121], v[180:183], v[144:147], v[118:121]
	v_mfma_f32_16x16x32_bf16 v[114:117], v[176:179], v[160:163], v[114:117]
	v_mfma_f32_16x16x32_bf16 v[110:113], v[188:191], v[144:147], v[110:113]
	v_mfma_f32_16x16x32_bf16 v[106:109], v[184:187], v[160:163], v[106:109]
	v_mfma_f32_16x16x32_bf16 v[102:105], v[192:195], v[132:135], v[102:105]
	v_mfma_f32_16x16x32_bf16 v[98:101], v[196:199], v[164:167], v[98:101]
	v_mfma_f32_16x16x32_bf16 v[200:203], v[180:183], v[164:167], v[114:117]
	v_mfma_f32_16x16x32_bf16 v[206:209], v[188:191], v[164:167], v[106:109]
	v_mfma_f32_16x16x32_bf16 v[210:213], v[196:199], v[144:147], v[102:105]
	s_setprio 0
	s_barrier
	s_nop 1
	ds_read_b128 v[102:105], v151
	ds_read_b128 v[106:109], v151 offset:1024
	ds_read_b128 v[114:117], v151 offset:2048
	ds_read_b128 v[148:151], v151 offset:3072
	s_barrier
	s_waitcnt lgkmcnt(0)
	s_setprio 1
	s_waitcnt lgkmcnt(0)
	v_mfma_f32_16x16x32_bf16 v[90:93], v[168:171], v[114:117], v[90:93]
	v_mfma_f32_16x16x32_bf16 v[86:89], v[176:179], v[102:105], v[86:89]
	v_mfma_f32_16x16x32_bf16 v[78:81], v[184:187], v[102:105], v[78:81]
	v_mfma_f32_16x16x32_bf16 v[66:69], v[192:195], v[114:117], v[66:69]
	v_mfma_f32_16x16x32_bf16 v[94:97], v[168:171], v[102:105], v[94:97]
	v_mfma_f32_16x16x32_bf16 v[90:93], v[172:175], v[148:151], v[90:93]
	v_mfma_f32_16x16x32_bf16 v[86:89], v[180:183], v[106:109], v[86:89]
	v_mfma_f32_16x16x32_bf16 v[82:85], v[176:179], v[114:117], v[82:85]
	v_mfma_f32_16x16x32_bf16 v[78:81], v[188:191], v[106:109], v[78:81]
	v_mfma_f32_16x16x32_bf16 v[74:77], v[184:187], v[114:117], v[74:77]
	v_mfma_f32_16x16x32_bf16 v[70:73], v[192:195], v[102:105], v[70:73]
	v_mfma_f32_16x16x32_bf16 v[66:69], v[196:199], v[148:151], v[66:69]
	v_mfma_f32_16x16x32_bf16 v[214:217], v[172:175], v[106:109], v[94:97]
	v_mfma_f32_16x16x32_bf16 v[168:171], v[180:183], v[148:151], v[82:85]
	v_mfma_f32_16x16x32_bf16 v[172:175], v[188:191], v[148:151], v[74:77]
	v_mfma_f32_16x16x32_bf16 v[176:179], v[196:199], v[106:109], v[70:73]
	s_setprio 0
	s_barrier
	s_nop 0
	ds_read_b128 v[70:73], v0 offset:16384
	ds_read_b128 v[74:77], v0 offset:17408
	ds_read_b128 v[82:85], v155 offset:16384
	ds_read_b128 v[94:97], v155 offset:17408
	ds_read_b128 v[180:183], v156 offset:16384
	ds_read_b128 v[184:187], v156 offset:17408
	ds_read_b128 v[188:191], v157 offset:16384
	ds_read_b128 v[192:195], v157 offset:17408
	s_waitcnt vmcnt(4)
	s_barrier
	s_waitcnt lgkmcnt(0)
	s_setprio 1
	s_waitcnt lgkmcnt(0)
	v_mfma_f32_16x16x32_bf16 v[62:65], v[70:73], v[132:135], v[62:65]
	v_mfma_f32_16x16x32_bf16 v[50:53], v[82:85], v[160:163], v[50:53]
	v_mfma_f32_16x16x32_bf16 v[46:49], v[180:183], v[132:135], v[46:49]
	v_mfma_f32_16x16x32_bf16 v[34:37], v[188:191], v[160:163], v[34:37]
	v_mfma_f32_16x16x32_bf16 v[62:65], v[74:77], v[144:147], v[62:65]
	v_mfma_f32_16x16x32_bf16 v[58:61], v[70:73], v[160:163], v[58:61]
	v_mfma_f32_16x16x32_bf16 v[54:57], v[82:85], v[132:135], v[54:57]
	v_mfma_f32_16x16x32_bf16 v[50:53], v[94:97], v[164:167], v[50:53]
	v_mfma_f32_16x16x32_bf16 v[46:49], v[184:187], v[144:147], v[46:49]
	v_mfma_f32_16x16x32_bf16 v[42:45], v[180:183], v[160:163], v[42:45]
	v_mfma_f32_16x16x32_bf16 v[38:41], v[188:191], v[132:135], v[38:41]
	v_mfma_f32_16x16x32_bf16 v[34:37], v[192:195], v[164:167], v[34:37]
	v_mfma_f32_16x16x32_bf16 v[196:199], v[74:77], v[164:167], v[58:61]
	v_mfma_f32_16x16x32_bf16 v[218:221], v[94:97], v[144:147], v[54:57]
	v_mfma_f32_16x16x32_bf16 v[222:225], v[184:187], v[164:167], v[42:45]
	v_mfma_f32_16x16x32_bf16 v[130:133], v[192:195], v[144:147], v[38:41]
	s_setprio 0
	s_setprio 1
	v_mfma_f32_16x16x32_bf16 v[26:29], v[70:73], v[114:117], v[26:29]
	v_mfma_f32_16x16x32_bf16 v[18:21], v[82:85], v[114:117], v[18:21]
	v_mfma_f32_16x16x32_bf16 v[14:17], v[180:183], v[102:105], v[14:17]
	v_mfma_f32_16x16x32_bf16 v[30:33], v[70:73], v[102:105], v[30:33]
	v_mfma_f32_16x16x32_bf16 v[26:29], v[74:77], v[148:151], v[26:29]
	v_mfma_f32_16x16x32_bf16 v[22:25], v[82:85], v[102:105], v[22:25]
	v_mfma_f32_16x16x32_bf16 v[18:21], v[94:97], v[148:151], v[18:21]
	v_mfma_f32_16x16x32_bf16 v[14:17], v[184:187], v[106:109], v[14:17]
	v_mfma_f32_16x16x32_bf16 v[10:13], v[180:183], v[114:117], v[10:13]
	v_mfma_f32_16x16x32_bf16 v[6:9], v[188:191], v[102:105], v[6:9]
	v_mfma_f32_16x16x32_bf16 v[2:5], v[188:191], v[114:117], v[2:5]
	v_mfma_f32_16x16x32_bf16 v[134:137], v[74:77], v[106:109], v[30:33]
	v_mfma_f32_16x16x32_bf16 v[144:147], v[94:97], v[106:109], v[22:25]
	v_mfma_f32_16x16x32_bf16 v[158:161], v[184:187], v[148:151], v[10:13]
	v_mfma_f32_16x16x32_bf16 v[162:165], v[192:195], v[106:109], v[6:9]
	v_mfma_f32_16x16x32_bf16 v[148:151], v[192:195], v[148:151], v[2:5]
	s_setprio 0
	s_barrier
; #define LDA(dst, b, h) for (int m = 0; m < 4; ++m) for (int k = 0; k < 2; ++k) \
;     dst[m][k] = *reinterpret_cast<const bf16x8*>((char*)SA(b, h) + lds_byte(wr * 64 + m * 16 + fr, k * 32 + fq * 8))
; #define LDB(dst, b, h) for (int n = 0; n < 2; ++n) for (int k = 0; k < 2; ++k) \
;     dst[n][k] = *reinterpret_cast<const bf16x8*>((char*)SB(b, h) + lds_byte(wc * 32 + n * 16 + fr, k * 32 + fq * 8))
; #define MMA(ai, bj, At_, Bt_) do { __builtin_amdgcn_s_setprio(1); \
;     for (int m = 0; m < 4; ++m) for (int n = 0; n < 2; ++n) for (int k = 0; k < 2; ++k) \
;       acc[ai][bj][m][n] = MFMA16(At_[m][k], Bt_[n][k], acc[ai][bj][m][n]); \
;     __builtin_amdgcn_s_setprio(0); } while (0)
; #define WAIT_V(n) asm volatile("s_waitcnt vmcnt(" #n ")" ::: "memory")
; #define WAIT_L(n) asm volatile("s_waitcnt lgkmcnt(" #n ")" ::: "memory")
; #define BAR __builtin_amdgcn_s_barrier()
; DI void gemm_core(WVP char* smem, const u16* __restrict__ A, int lda, int ar0, int ar1,
;                   const u16* __restrict__ B, int ldb, int bc0, int K, AccT& acc) {
;     ...
;   { LDB(B0, 1, 0); LDA(At, 1, 0); WAIT_V(2); BAR; WAIT_L(0); MMA(0, 0, At, B0); BAR;
;     LDB(B1, 1, 1); WAIT_V(0); BAR; WAIT_L(0); MMA(0, 1, At, B1); BAR;
;     LDA(At, 1, 1); BAR; WAIT_L(0); MMA(1, 0, At, B0); MMA(1, 1, At, B1); BAR; }
;   if (wr == 0) BAR;
	ds_read_b128 v[180:183], v142
	ds_read_b128 v[184:187], v142 offset:1024
	ds_read_b128 v[188:191], v142 offset:2048
	ds_read_b128 v[140:143], v142 offset:3072
	ds_read_b128 v[2:5], v0 offset:32768
	ds_read_b128 v[6:9], v0 offset:33792
	ds_read_b128 v[10:13], v155 offset:32768
	ds_read_b128 v[22:25], v155 offset:33792
	ds_read_b128 v[192:195], v156 offset:32768
	ds_read_b128 v[226:229], v156 offset:33792
	ds_read_b128 v[230:233], v157 offset:32768
	ds_read_b128 v[234:237], v157 offset:33792
	s_waitcnt vmcnt(2)
	s_barrier
	s_waitcnt lgkmcnt(0)
	s_setprio 1
	s_waitcnt lgkmcnt(0)
	v_mfma_f32_16x16x32_bf16 v[30:33], v[2:5], v[180:183], v[126:129]
	v_mfma_f32_16x16x32_bf16 v[114:117], v[6:9], v[184:187], v[30:33]
	v_mfma_f32_16x16x32_bf16 v[30:33], v[2:5], v[188:191], v[122:125]
	v_mfma_f32_16x16x32_bf16 v[106:109], v[6:9], v[140:143], v[30:33]
	v_mfma_f32_16x16x32_bf16 v[30:33], v[10:13], v[180:183], v[118:121]
	v_mfma_f32_16x16x32_bf16 v[102:105], v[22:25], v[184:187], v[30:33]
	v_mfma_f32_16x16x32_bf16 v[30:33], v[10:13], v[188:191], v[200:203]
	v_mfma_f32_16x16x32_bf16 v[94:97], v[22:25], v[140:143], v[30:33]
	v_mfma_f32_16x16x32_bf16 v[30:33], v[192:195], v[180:183], v[110:113]
	v_mfma_f32_16x16x32_bf16 v[82:85], v[226:229], v[184:187], v[30:33]
	v_mfma_f32_16x16x32_bf16 v[30:33], v[192:195], v[188:191], v[206:209]
	v_mfma_f32_16x16x32_bf16 v[74:77], v[226:229], v[140:143], v[30:33]
	v_mfma_f32_16x16x32_bf16 v[30:33], v[230:233], v[180:183], v[210:213]
	v_mfma_f32_16x16x32_bf16 v[70:73], v[234:237], v[184:187], v[30:33]
	v_mfma_f32_16x16x32_bf16 v[30:33], v[230:233], v[188:191], v[98:101]
	v_mfma_f32_16x16x32_bf16 v[58:61], v[234:237], v[140:143], v[30:33]
	s_setprio 0
	s_barrier
	ds_read_b128 v[200:203], v139
	ds_read_b128 v[206:209], v139 offset:1024
	ds_read_b128 v[210:213], v139 offset:2048
	ds_read_b128 v[238:241], v139 offset:3072
	s_waitcnt vmcnt(0)
	s_barrier
	s_waitcnt lgkmcnt(0)
	s_setprio 1
	s_waitcnt lgkmcnt(0)
	v_mfma_f32_16x16x32_bf16 v[30:33], v[2:5], v[200:203], v[214:217]
	v_mfma_f32_16x16x32_bf16 v[2:5], v[2:5], v[210:213], v[90:93]
	v_mfma_f32_16x16x32_bf16 v[42:45], v[6:9], v[238:241], v[2:5]
	v_mfma_f32_16x16x32_bf16 v[2:5], v[10:13], v[200:203], v[86:89]
	v_mfma_f32_16x16x32_bf16 v[38:41], v[22:25], v[206:209], v[2:5]
	v_mfma_f32_16x16x32_bf16 v[2:5], v[10:13], v[210:213], v[168:171]
	v_mfma_f32_16x16x32_bf16 v[54:57], v[6:9], v[206:209], v[30:33]
	v_mfma_f32_16x16x32_bf16 v[30:33], v[22:25], v[238:241], v[2:5]
	v_mfma_f32_16x16x32_bf16 v[2:5], v[192:195], v[200:203], v[78:81]
	v_mfma_f32_16x16x32_bf16 v[22:25], v[226:229], v[206:209], v[2:5]
	v_mfma_f32_16x16x32_bf16 v[2:5], v[192:195], v[210:213], v[172:175]
	v_mfma_f32_16x16x32_bf16 v[10:13], v[226:229], v[238:241], v[2:5]
	v_mfma_f32_16x16x32_bf16 v[2:5], v[230:233], v[200:203], v[176:179]
	v_mfma_f32_16x16x32_bf16 v[6:9], v[234:237], v[206:209], v[2:5]
	v_mfma_f32_16x16x32_bf16 v[2:5], v[230:233], v[210:213], v[66:69]
	v_mfma_f32_16x16x32_bf16 v[2:5], v[234:237], v[238:241], v[2:5]
	s_setprio 0
	s_barrier
	ds_read_b128 v[166:169], v0 offset:49152
	ds_read_b128 v[170:173], v0 offset:50176
	ds_read_b128 v[174:177], v155 offset:49152
	ds_read_b128 v[152:155], v155 offset:50176
	ds_read_b128 v[192:195], v156 offset:49152
	ds_read_b128 v[214:217], v156 offset:50176
	ds_read_b128 v[226:229], v157 offset:49152
	ds_read_b128 v[230:233], v157 offset:50176
	s_barrier
	s_waitcnt lgkmcnt(0)
	s_setprio 1
	s_waitcnt lgkmcnt(0)
	v_mfma_f32_16x16x32_bf16 v[62:65], v[166:169], v[180:183], v[62:65]
	v_mfma_f32_16x16x32_bf16 v[46:49], v[192:195], v[180:183], v[46:49]
	v_mfma_f32_16x16x32_bf16 v[126:129], v[170:173], v[184:187], v[62:65]
	v_mfma_f32_16x16x32_bf16 v[62:65], v[166:169], v[188:191], v[196:199]
	v_mfma_f32_16x16x32_bf16 v[98:101], v[214:217], v[184:187], v[46:49]
	v_mfma_f32_16x16x32_bf16 v[46:49], v[192:195], v[188:191], v[222:225]
	v_mfma_f32_16x16x32_bf16 v[122:125], v[170:173], v[140:143], v[62:65]
	v_mfma_f32_16x16x32_bf16 v[62:65], v[174:177], v[180:183], v[218:221]
	v_mfma_f32_16x16x32_bf16 v[50:53], v[174:177], v[188:191], v[50:53]
	v_mfma_f32_16x16x32_bf16 v[90:93], v[214:217], v[140:143], v[46:49]
	v_mfma_f32_16x16x32_bf16 v[46:49], v[226:229], v[180:183], v[130:133]
	v_mfma_f32_16x16x32_bf16 v[34:37], v[226:229], v[188:191], v[34:37]
	v_mfma_f32_16x16x32_bf16 v[118:121], v[152:155], v[184:187], v[62:65]
	v_mfma_f32_16x16x32_bf16 v[110:113], v[152:155], v[140:143], v[50:53]
	v_mfma_f32_16x16x32_bf16 v[86:89], v[230:233], v[184:187], v[46:49]
	v_mfma_f32_16x16x32_bf16 v[78:81], v[230:233], v[140:143], v[34:37]
	s_setprio 0
	s_setprio 1
	v_mfma_f32_16x16x32_bf16 v[34:37], v[166:169], v[200:203], v[134:137]
	v_mfma_f32_16x16x32_bf16 v[26:29], v[166:169], v[210:213], v[26:29]
	v_mfma_f32_16x16x32_bf16 v[14:17], v[192:195], v[200:203], v[14:17]
	v_mfma_f32_16x16x32_bf16 v[66:69], v[170:173], v[206:209], v[34:37]
	v_mfma_f32_16x16x32_bf16 v[62:65], v[170:173], v[238:241], v[26:29]
	v_mfma_f32_16x16x32_bf16 v[26:29], v[174:177], v[200:203], v[144:147]
	v_mfma_f32_16x16x32_bf16 v[34:37], v[214:217], v[206:209], v[14:17]
	v_mfma_f32_16x16x32_bf16 v[14:17], v[192:195], v[210:213], v[158:161]
	v_mfma_f32_16x16x32_bf16 v[50:53], v[152:155], v[206:209], v[26:29]
	v_mfma_f32_16x16x32_bf16 v[18:21], v[174:177], v[210:213], v[18:21]
	v_mfma_f32_16x16x32_bf16 v[26:29], v[214:217], v[238:241], v[14:17]
	v_mfma_f32_16x16x32_bf16 v[14:17], v[226:229], v[200:203], v[162:165]
	v_mfma_f32_16x16x32_bf16 v[46:49], v[152:155], v[238:241], v[18:21]
	v_mfma_f32_16x16x32_bf16 v[18:21], v[230:233], v[206:209], v[14:17]
	v_mfma_f32_16x16x32_bf16 v[14:17], v[226:229], v[210:213], v[148:151]
	v_mfma_f32_16x16x32_bf16 v[14:17], v[230:233], v[238:241], v[14:17]
	s_setprio 0
	s_cmp_gt_u32 s18, 3
	s_barrier
	s_cbranch_scc1 .LBB0_265
	s_barrier
	s_branch .LBB0_265

; #define STAGE_A(P, br, kt) do { const char* _g = (const char*)(A + (long)(br) * lda + (long)(kt) * BK); \
;     __builtin_amdgcn_global_load_lds((const unsigned*)(_g + (size_t)offA0), (unsigned*)((char*)(P) + sb0), 16, 0, 0); \
;     __builtin_amdgcn_global_load_lds((const unsigned*)(_g + (size_t)lda * 128 + (size_t)offA0), (unsigned*)((char*)(P) + sb1), 16, 0, 0); } while (0)
; #define STAGE_B(P, br, kt) do { const char* _g = (const char*)(B + (long)(br) * ldb + (long)(kt) * BK); \
;     __builtin_amdgcn_global_load_lds((const unsigned*)(_g + (size_t)offB0), (unsigned*)((char*)(P) + sb0), 16, 0, 0); \
;     __builtin_amdgcn_global_load_lds((const unsigned*)(_g + (size_t)ldb * 128 + (size_t)offB0), (unsigned*)((char*)(P) + sb1), 16, 0, 0); } while (0)
; #define LDA(dst, b, h) for (int m = 0; m < 4; ++m) for (int k = 0; k < 2; ++k) \
;     dst[m][k] = *reinterpret_cast<const bf16x8*>((char*)SA(b, h) + lds_byte(wr * 64 + m * 16 + fr, k * 32 + fq * 8))
; #define LDB(dst, b, h) for (int n = 0; n < 2; ++n) for (int k = 0; k < 2; ++k) \
;     dst[n][k] = *reinterpret_cast<const bf16x8*>((char*)SB(b, h) + lds_byte(wc * 32 + n * 16 + fr, k * 32 + fq * 8))
; #define WAIT_V(n) asm volatile("s_waitcnt vmcnt(" #n ")" ::: "memory")
; #define WAIT_L(n) asm volatile("s_waitcnt lgkmcnt(" #n ")" ::: "memory")
; DI void gemm_core(WVP char* smem, const u16* __restrict__ A, int lda, int ar0, int ar1,
;                   const u16* __restrict__ B, int ldb, int bc0, int K, AccT& acc) {
;     ...
;   const int sb0 = tid * 16, sb1 = sb0 + 8192;
;   int R0, C0; stage_rc(sb0, R0, C0);
;   const unsigned offA0 = (unsigned)(R0 * lda + C0) * 2u, offB0 = (unsigned)(R0 * ldb + C0) * 2u;
;   const int ac0 = ar0, ac1 = ar1, bb0 = bc0, bb1 = bc0 + HALF;
;   bf16x8 At[4][2], B0[2][2], B1[2][2];
;   const int nt = K / BK;
;   __syncthreads();
;   STAGE_B(SB(0, 0), bb0, 0); STAGE_A(SA(0, 0), ac0, 0);
;   STAGE_B(SB(0, 1), bb1, 0); STAGE_A(SA(0, 1), ac1, 0);
;   if (wr == 1) BAR;
;   WAIT_V(4); BAR;
;   STAGE_B(SB(1, 0), bb0, 1); STAGE_A(SA(1, 0), ac0, 1); STAGE_B(SB(1, 1), bb1, 1);
;   WAIT_V(6); BAR;
;   for (int t = 0; t < nt - 2; t += 2) {
;     LDB(B0, 0, 0); SCHED; LDA(At, 0, 0); STAGE_A(SA(1, 1), ac1, t + 1);
;     WAIT_L(8); BAR; WAIT_L(0); MMA(0, 0, At, B0); BAR; SCHED;
;     LDB(B1, 0, 1); STAGE_B(SB(0, 0), bb0, t + 2);
;     BAR; WAIT_L(0); MMA(0, 1, At, B1); BAR;
.LBB0_426:
	v_add_u32_e32 v141, s61, v12
	s_ashr_i32 s4, s1, 6
	v_readfirstlane_b32 s1, v141
	v_add_u32_e32 v142, 0x2000, v141
	v_lshl_add_u64 v[14:15], v[2:3], 0, s[64:65]
	s_mov_b32 m0, s1
	v_readfirstlane_b32 s1, v142
	v_add_u32_e32 v143, 0x8000, v135
	s_waitcnt vmcnt(2)
	s_barrier
	global_load_lds_dwordx4 v[14:15], off
	v_lshl_add_u64 v[2:3], v[2:3], 0, s[78:79]
	s_mov_b32 m0, s1
	v_readfirstlane_b32 s1, v143
	v_add_u32_e32 v144, 0xa000, v135
	global_load_lds_dwordx4 v[2:3], off
	v_lshl_add_u64 v[2:3], v[4:5], 0, s[64:65]
	s_mov_b32 m0, s1
	v_readfirstlane_b32 s1, v144
	v_add_u32_e32 v145, s84, v12
	global_load_lds_dwordx4 v[2:3], off
	v_lshl_add_u64 v[2:3], v[4:5], 0, s[78:79]
	s_mov_b32 m0, s1
	v_readfirstlane_b32 s1, v145
	v_add_u32_e32 v146, 0x2000, v145
	global_load_lds_dwordx4 v[2:3], off
	v_lshl_add_u64 v[2:3], v[6:7], 0, s[64:65]
	s_mov_b32 m0, s1
	v_readfirstlane_b32 s1, v146
	global_load_lds_dwordx4 v[2:3], off
	v_lshl_add_u64 v[2:3], v[6:7], 0, s[78:79]
	s_mov_b32 m0, s1
	v_and_b32_e32 v0, 15, v9
	global_load_lds_dwordx4 v[2:3], off
	v_lshlrev_b32_e32 v2, 2, v9
	v_and_b32_e32 v13, 48, v9
	v_lshlrev_b32_e32 v0, 6, v0
	v_and_b32_e32 v2, 32, v2
	s_lshl_b32 s1, s4, 12
	v_bitop3_b32 v0, v0, v2, v13 bitop3:0x36
	s_lshl_b32 s17, s0, 13
	s_and_b32 s11, s1, 0x3000
	v_add_u32_e32 v3, s5, v0
	s_or_b32 s0, s17, 0x800
	s_or_b32 s1, s17, 0x1000
	s_or_b32 s5, s17, 0x1800
	s_add_u32 s12, s54, s12
	s_addc_u32 s13, s55, s13
	s_lshl_b32 s9, s15, 10
	s_sub_i32 s14, s14, s16
	s_lshl_b32 s15, s15, 9
	s_sub_i32 s14, s14, s15
	v_add_u32_e32 v4, s60, v0
	v_add_u32_e32 v5, s61, v0
	v_add_u32_e32 v6, s84, v0
	v_add_u32_e32 v7, 0, v0
	v_lshlrev_b32_e32 v0, 6, v9
	s_sext_i32_i16 s14, s14
	v_and_or_b32 v0, v0, s74, v13
	s_lshl_b32 s14, s14, 8
	v_xad_u32 v148, v0, v2, 0
	v_lshlrev_b32_e32 v0, 14, v8
	s_add_i32 s14, s9, s14
	v_and_b32_e32 v0, 0xffff8000, v0
	s_ashr_i32 s15, s14, 31
	s_waitcnt vmcnt(6)
	v_lshl_add_u32 v0, v10, 11, v0
	v_and_b32_e32 v2, 1, v8
	s_lshl_b64 s[14:15], s[14:15], 11
	v_lshl_or_b32 v0, v2, 6, v0
	s_add_u32 s14, s54, s14
	v_mov_b32_e32 v2, 0
	v_mov_b32_e32 v205, 0x358637bd
	v_lshl_add_u32 v0, v11, 1, v0
	s_addc_u32 s15, s55, s15
	s_mov_b32 s9, -2
	v_add_u32_e32 v149, s11, v3
	v_add_u32_e32 v132, s17, v7
	v_add_u32_e32 v147, s11, v4
	v_add_u32_e32 v138, s11, v5
	v_add_u32_e32 v134, s11, v6
	v_mov_b32_e32 v3, v2
	v_mov_b32_e32 v4, v2
	v_mov_b32_e32 v5, v2
	v_mov_b32_e32 v6, v2
	v_mov_b32_e32 v7, v2
	v_mov_b32_e32 v8, v2
	v_mov_b32_e32 v9, v2
	v_mov_b32_e32 v10, v2
	v_mov_b32_e32 v11, v2
	v_mov_b32_e32 v12, v2
	v_mov_b32_e32 v13, v2
	v_mov_b32_e32 v14, v2
	v_mov_b32_e32 v15, v2
	s_barrier
.LBB0_427:
	v_add_u32_e32 v150, s0, v148
	v_add_u32_e32 v151, s1, v148
	v_add_u32_e32 v152, s5, v148
	ds_read_b128 v[156:159], v149
	ds_read_b128 v[160:163], v149 offset:1024
	ds_read_b128 v[164:167], v149 offset:2048
	ds_read_b128 v[168:171], v149 offset:3072
	ds_read_b128 v[172:175], v132
	ds_read_b128 v[176:179], v132 offset:1024
	ds_read_b128 v[180:183], v150
	ds_read_b128 v[184:187], v150 offset:1024
	ds_read_b128 v[188:191], v151
	ds_read_b128 v[206:209], v151 offset:1024
	ds_read_b128 v[210:213], v152
	ds_read_b128 v[214:217], v152 offset:1024
	ds_read_b128 v[218:221], v147
	ds_read_b128 v[222:225], v147 offset:1024
	ds_read_b128 v[226:229], v147 offset:2048
	ds_read_b128 v[230:233], v147 offset:3072
	v_add_u32_e32 v153, 0xc000, v135
	v_lshl_add_u64 v[194:195], s[14:15], 0, v[0:1]
	s_mov_b64 s[16:17], 0x1d1c0080
	v_lshl_add_u64 v[192:193], v[194:195], 0, s[16:17]
	v_readfirstlane_b32 s11, v153
	s_mov_b32 m0, s11
	s_nop 0
	global_load_lds_dwordx4 v[192:193], off
	v_add_u32_e32 v154, 0xe000, v135
	v_lshl_add_u64 v[194:195], s[14:15], 0, v[0:1]
	s_mov_b64 s[16:17], 0x1d1e0080
	v_lshl_add_u64 v[192:193], v[194:195], 0, s[16:17]
	v_readfirstlane_b32 s11, v154
	s_mov_b32 m0, s11
	s_nop 0
	global_load_lds_dwordx4 v[192:193], off
	s_waitcnt vmcnt(8)
	s_waitcnt lgkmcnt(0)
	s_barrier
	s_setprio 1
	v_mfma_f32_16x16x32_bf16 v[126:129], v[172:175], v[156:159], v[126:129]
	v_mfma_f32_16x16x32_bf16 v[122:125], v[172:175], v[164:167], v[122:125]
	v_mfma_f32_16x16x32_bf16 v[118:121], v[180:183], v[156:159], v[118:121]
	v_mfma_f32_16x16x32_bf16 v[114:117], v[180:183], v[164:167], v[114:117]
	v_mfma_f32_16x16x32_bf16 v[110:113], v[188:191], v[156:159], v[110:113]
	v_mfma_f32_16x16x32_bf16 v[106:109], v[188:191], v[164:167], v[106:109]
	v_mfma_f32_16x16x32_bf16 v[102:105], v[210:213], v[156:159], v[102:105]
	v_mfma_f32_16x16x32_bf16 v[98:101], v[210:213], v[164:167], v[98:101]
	v_mfma_f32_16x16x32_bf16 v[126:129], v[176:179], v[160:163], v[126:129]
	v_mfma_f32_16x16x32_bf16 v[122:125], v[176:179], v[168:171], v[122:125]
	v_mfma_f32_16x16x32_bf16 v[118:121], v[184:187], v[160:163], v[118:121]
	v_mfma_f32_16x16x32_bf16 v[114:117], v[184:187], v[168:171], v[114:117]
	v_mfma_f32_16x16x32_bf16 v[110:113], v[206:209], v[160:163], v[110:113]
	v_mfma_f32_16x16x32_bf16 v[106:109], v[206:209], v[168:171], v[106:109]
	v_mfma_f32_16x16x32_bf16 v[102:105], v[214:217], v[160:163], v[102:105]
	v_mfma_f32_16x16x32_bf16 v[98:101], v[214:217], v[168:171], v[98:101]
	v_mfma_f32_16x16x32_bf16 v[94:97], v[172:175], v[218:221], v[94:97]
	v_mfma_f32_16x16x32_bf16 v[90:93], v[172:175], v[226:229], v[90:93]
	v_mfma_f32_16x16x32_bf16 v[86:89], v[180:183], v[218:221], v[86:89]
	v_mfma_f32_16x16x32_bf16 v[82:85], v[180:183], v[226:229], v[82:85]
	v_mfma_f32_16x16x32_bf16 v[78:81], v[188:191], v[218:221], v[78:81]
	v_mfma_f32_16x16x32_bf16 v[74:77], v[188:191], v[226:229], v[74:77]
	v_mfma_f32_16x16x32_bf16 v[70:73], v[210:213], v[218:221], v[70:73]
	v_mfma_f32_16x16x32_bf16 v[66:69], v[210:213], v[226:229], v[66:69]
	v_mfma_f32_16x16x32_bf16 v[94:97], v[176:179], v[222:225], v[94:97]
	v_mfma_f32_16x16x32_bf16 v[90:93], v[176:179], v[230:233], v[90:93]
	v_mfma_f32_16x16x32_bf16 v[86:89], v[184:187], v[222:225], v[86:89]
	v_mfma_f32_16x16x32_bf16 v[82:85], v[184:187], v[230:233], v[82:85]
	v_mfma_f32_16x16x32_bf16 v[78:81], v[206:209], v[222:225], v[78:81]
	v_mfma_f32_16x16x32_bf16 v[74:77], v[206:209], v[230:233], v[74:77]
	v_mfma_f32_16x16x32_bf16 v[70:73], v[214:217], v[222:225], v[70:73]
	v_mfma_f32_16x16x32_bf16 v[66:69], v[214:217], v[230:233], v[66:69]
	s_setprio 0
	s_barrier
; #define STAGE_A(P, br, kt) do { const char* _g = (const char*)(A + (long)(br) * lda + (long)(kt) * BK); \
;     __builtin_amdgcn_global_load_lds((const unsigned*)(_g + (size_t)offA0), (unsigned*)((char*)(P) + sb0), 16, 0, 0); \
;     __builtin_amdgcn_global_load_lds((const unsigned*)(_g + (size_t)lda * 128 + (size_t)offA0), (unsigned*)((char*)(P) + sb1), 16, 0, 0); } while (0)
; #define STAGE_B(P, br, kt) do { const char* _g = (const char*)(B + (long)(br) * ldb + (long)(kt) * BK); \
;     __builtin_amdgcn_global_load_lds((const unsigned*)(_g + (size_t)offB0), (unsigned*)((char*)(P) + sb0), 16, 0, 0); \
;     __builtin_amdgcn_global_load_lds((const unsigned*)(_g + (size_t)ldb * 128 + (size_t)offB0), (unsigned*)((char*)(P) + sb1), 16, 0, 0); } while (0)
; #define LDA(dst, b, h) for (int m = 0; m < 4; ++m) for (int k = 0; k < 2; ++k) \
;     dst[m][k] = *reinterpret_cast<const bf16x8*>((char*)SA(b, h) + lds_byte(wr * 64 + m * 16 + fr, k * 32 + fq * 8))
; #define LDB(dst, b, h) for (int n = 0; n < 2; ++n) for (int k = 0; k < 2; ++k) \
;     dst[n][k] = *reinterpret_cast<const bf16x8*>((char*)SB(b, h) + lds_byte(wc * 32 + n * 16 + fr, k * 32 + fq * 8))
; #define MMA(ai, bj, At_, Bt_) do { __builtin_amdgcn_s_setprio(1); \
;     for (int m = 0; m < 4; ++m) for (int n = 0; n < 2; ++n) for (int k = 0; k < 2; ++k) \
;       acc[ai][bj][m][n] = MFMA16(At_[m][k], Bt_[n][k], acc[ai][bj][m][n]); \
;     __builtin_amdgcn_s_setprio(0); } while (0)
; #define WAIT_V(n) asm volatile("s_waitcnt vmcnt(" #n ")" ::: "memory")
; #define WAIT_L(n) asm volatile("s_waitcnt lgkmcnt(" #n ")" ::: "memory")
; #define BAR __builtin_amdgcn_s_barrier()
; #define SCHED __builtin_amdgcn_sched_barrier(0)
; DI void gemm_core(WVP char* smem, const u16* __restrict__ A, int lda, int ar0, int ar1,
;                   const u16* __restrict__ B, int ldb, int bc0, int K, AccT& acc) {
;     ...
;     LDA(At, 0, 1); STAGE_A(SA(0, 0), ac0, t + 2);
;     BAR; WAIT_L(0); MMA(1, 0, At, B0); BAR; SCHED;
;     STAGE_B(SB(0, 1), bb1, t + 2);
;     WAIT_V(6); BAR; MMA(1, 1, At, B1); BAR;
;     LDB(B0, 1, 0); SCHED; LDA(At, 1, 0); STAGE_A(SA(0, 1), ac1, t + 2);
;     WAIT_L(8); BAR; WAIT_L(0); MMA(0, 0, At, B0); BAR; SCHED;
	ds_read_b128 v[172:175], v132 offset:16384
	ds_read_b128 v[176:179], v132 offset:17408
	ds_read_b128 v[180:183], v150 offset:16384
	ds_read_b128 v[184:187], v150 offset:17408
	ds_read_b128 v[188:191], v151 offset:16384
	ds_read_b128 v[206:209], v151 offset:17408
	ds_read_b128 v[210:213], v152 offset:16384
	ds_read_b128 v[214:217], v152 offset:17408
	v_lshl_add_u64 v[194:195], s[12:13], 0, v[0:1]
	v_lshl_add_u64 v[192:193], v[194:195], 0, s[80:81]
	v_readfirstlane_b32 s11, v133
	s_mov_b32 m0, s11
	s_nop 0
	global_load_lds_dwordx4 v[192:193], off
	v_add_u32_e32 v155, 0x2000, v133
	v_lshl_add_u64 v[194:195], s[12:13], 0, v[0:1]
	v_lshl_add_u64 v[192:193], v[194:195], 0, s[82:83]
	v_readfirstlane_b32 s11, v155
	s_mov_b32 m0, s11
	s_nop 0
	global_load_lds_dwordx4 v[192:193], off
	v_lshl_add_u64 v[194:195], s[14:15], 0, v[0:1]
	s_mov_b64 s[16:17], 0x1d180100
	v_lshl_add_u64 v[192:193], v[194:195], 0, s[16:17]
	v_readfirstlane_b32 s11, v135
	s_mov_b32 m0, s11
	s_nop 0
	global_load_lds_dwordx4 v[192:193], off
	v_lshl_add_u64 v[194:195], s[14:15], 0, v[0:1]
	s_mov_b64 s[16:17], 0x1d1a0100
	v_lshl_add_u64 v[192:193], v[194:195], 0, s[16:17]
	v_readfirstlane_b32 s11, v136
	s_mov_b32 m0, s11
	s_nop 0
	global_load_lds_dwordx4 v[192:193], off
	v_lshl_add_u64 v[194:195], s[12:13], 0, v[0:1]
	v_lshl_add_u64 v[192:193], v[194:195], 0, s[88:89]
	v_readfirstlane_b32 s11, v137
	s_mov_b32 m0, s11
	s_nop 0
	global_load_lds_dwordx4 v[192:193], off
	v_add_u32_e32 v155, 0x2000, v137
	v_lshl_add_u64 v[194:195], s[12:13], 0, v[0:1]
	v_lshl_add_u64 v[192:193], v[194:195], 0, s[90:91]
	v_readfirstlane_b32 s11, v155
	s_mov_b32 m0, s11
	s_nop 0
	global_load_lds_dwordx4 v[192:193], off
	s_waitcnt vmcnt(8)
	s_waitcnt lgkmcnt(0)
	s_barrier
	s_setprio 1
	v_mfma_f32_16x16x32_bf16 v[62:65], v[172:175], v[156:159], v[62:65]
	v_mfma_f32_16x16x32_bf16 v[58:61], v[172:175], v[164:167], v[58:61]
	v_mfma_f32_16x16x32_bf16 v[54:57], v[180:183], v[156:159], v[54:57]
	v_mfma_f32_16x16x32_bf16 v[50:53], v[180:183], v[164:167], v[50:53]
	v_mfma_f32_16x16x32_bf16 v[46:49], v[188:191], v[156:159], v[46:49]
	v_mfma_f32_16x16x32_bf16 v[42:45], v[188:191], v[164:167], v[42:45]
	v_mfma_f32_16x16x32_bf16 v[38:41], v[210:213], v[156:159], v[38:41]
	v_mfma_f32_16x16x32_bf16 v[34:37], v[210:213], v[164:167], v[34:37]
	v_mfma_f32_16x16x32_bf16 v[62:65], v[176:179], v[160:163], v[62:65]
	v_mfma_f32_16x16x32_bf16 v[58:61], v[176:179], v[168:171], v[58:61]
	v_mfma_f32_16x16x32_bf16 v[54:57], v[184:187], v[160:163], v[54:57]
	v_mfma_f32_16x16x32_bf16 v[50:53], v[184:187], v[168:171], v[50:53]
	v_mfma_f32_16x16x32_bf16 v[46:49], v[206:209], v[160:163], v[46:49]
	v_mfma_f32_16x16x32_bf16 v[42:45], v[206:209], v[168:171], v[42:45]
	v_mfma_f32_16x16x32_bf16 v[38:41], v[214:217], v[160:163], v[38:41]
	v_mfma_f32_16x16x32_bf16 v[34:37], v[214:217], v[168:171], v[34:37]
	v_mfma_f32_16x16x32_bf16 v[30:33], v[172:175], v[218:221], v[30:33]
	v_mfma_f32_16x16x32_bf16 v[26:29], v[172:175], v[226:229], v[26:29]
	v_mfma_f32_16x16x32_bf16 v[22:25], v[180:183], v[218:221], v[22:25]
	v_mfma_f32_16x16x32_bf16 v[18:21], v[180:183], v[226:229], v[18:21]
	v_mfma_f32_16x16x32_bf16 v[14:17], v[188:191], v[218:221], v[14:17]
	v_mfma_f32_16x16x32_bf16 v[10:13], v[188:191], v[226:229], v[10:13]
	v_mfma_f32_16x16x32_bf16 v[6:9], v[210:213], v[218:221], v[6:9]
	v_mfma_f32_16x16x32_bf16 v[2:5], v[210:213], v[226:229], v[2:5]
	v_mfma_f32_16x16x32_bf16 v[30:33], v[176:179], v[222:225], v[30:33]
	v_mfma_f32_16x16x32_bf16 v[26:29], v[176:179], v[230:233], v[26:29]
	v_mfma_f32_16x16x32_bf16 v[22:25], v[184:187], v[222:225], v[22:25]
	v_mfma_f32_16x16x32_bf16 v[18:21], v[184:187], v[230:233], v[18:21]
	v_mfma_f32_16x16x32_bf16 v[14:17], v[206:209], v[222:225], v[14:17]
	v_mfma_f32_16x16x32_bf16 v[10:13], v[206:209], v[230:233], v[10:13]
	v_mfma_f32_16x16x32_bf16 v[6:9], v[214:217], v[222:225], v[6:9]
	v_mfma_f32_16x16x32_bf16 v[2:5], v[214:217], v[230:233], v[2:5]
	s_setprio 0
	s_barrier
	ds_read_b128 v[156:159], v138
	ds_read_b128 v[160:163], v138 offset:1024
	ds_read_b128 v[164:167], v138 offset:2048
	ds_read_b128 v[168:171], v138 offset:3072
	ds_read_b128 v[172:175], v132 offset:32768
	ds_read_b128 v[176:179], v132 offset:33792
	ds_read_b128 v[180:183], v150 offset:32768
	ds_read_b128 v[184:187], v150 offset:33792
	ds_read_b128 v[188:191], v151 offset:32768
	ds_read_b128 v[206:209], v151 offset:33792
	ds_read_b128 v[210:213], v152 offset:32768
	ds_read_b128 v[214:217], v152 offset:33792
	ds_read_b128 v[218:221], v134
	ds_read_b128 v[222:225], v134 offset:1024
	ds_read_b128 v[226:229], v134 offset:2048
	ds_read_b128 v[230:233], v134 offset:3072
	v_lshl_add_u64 v[194:195], s[14:15], 0, v[0:1]
	s_mov_b64 s[16:17], 0x1d1c0100
	v_lshl_add_u64 v[192:193], v[194:195], 0, s[16:17]
	v_readfirstlane_b32 s11, v139
	s_mov_b32 m0, s11
	s_nop 0
	global_load_lds_dwordx4 v[192:193], off
	v_lshl_add_u64 v[194:195], s[14:15], 0, v[0:1]
	s_mov_b64 s[16:17], 0x1d1e0100
	v_lshl_add_u64 v[192:193], v[194:195], 0, s[16:17]
	v_readfirstlane_b32 s11, v140
	s_mov_b32 m0, s11
	s_nop 0
	global_load_lds_dwordx4 v[192:193], off
	s_waitcnt vmcnt(8)
	s_waitcnt lgkmcnt(0)
	s_barrier
; #define STAGE_A(P, br, kt) do { const char* _g = (const char*)(A + (long)(br) * lda + (long)(kt) * BK); \
;     __builtin_amdgcn_global_load_lds((const unsigned*)(_g + (size_t)offA0), (unsigned*)((char*)(P) + sb0), 16, 0, 0); \
;     __builtin_amdgcn_global_load_lds((const unsigned*)(_g + (size_t)lda * 128 + (size_t)offA0), (unsigned*)((char*)(P) + sb1), 16, 0, 0); } while (0)
; #define STAGE_B(P, br, kt) do { const char* _g = (const char*)(B + (long)(br) * ldb + (long)(kt) * BK); \
;     __builtin_amdgcn_global_load_lds((const unsigned*)(_g + (size_t)offB0), (unsigned*)((char*)(P) + sb0), 16, 0, 0); \
;     __builtin_amdgcn_global_load_lds((const unsigned*)(_g + (size_t)ldb * 128 + (size_t)offB0), (unsigned*)((char*)(P) + sb1), 16, 0, 0); } while (0)
; #define LDA(dst, b, h) for (int m = 0; m < 4; ++m) for (int k = 0; k < 2; ++k) \
;     dst[m][k] = *reinterpret_cast<const bf16x8*>((char*)SA(b, h) + lds_byte(wr * 64 + m * 16 + fr, k * 32 + fq * 8))
; #define LDB(dst, b, h) for (int n = 0; n < 2; ++n) for (int k = 0; k < 2; ++k) \
;     dst[n][k] = *reinterpret_cast<const bf16x8*>((char*)SB(b, h) + lds_byte(wc * 32 + n * 16 + fr, k * 32 + fq * 8))
; #define MMA(ai, bj, At_, Bt_) do { __builtin_amdgcn_s_setprio(1); \
;     for (int m = 0; m < 4; ++m) for (int n = 0; n < 2; ++n) for (int k = 0; k < 2; ++k) \
;       acc[ai][bj][m][n] = MFMA16(At_[m][k], Bt_[n][k], acc[ai][bj][m][n]); \
;     __builtin_amdgcn_s_setprio(0); } while (0)
; #define WAIT_V(n) asm volatile("s_waitcnt vmcnt(" #n ")" ::: "memory")
; #define WAIT_L(n) asm volatile("s_waitcnt lgkmcnt(" #n ")" ::: "memory")
; #define BAR __builtin_amdgcn_s_barrier()
; #define SCHED __builtin_amdgcn_sched_barrier(0)
; DI void gemm_core(WVP char* smem, const u16* __restrict__ A, int lda, int ar0, int ar1,
;                   const u16* __restrict__ B, int ldb, int bc0, int K, AccT& acc) {
;     ...
;     LDB(B0, 1, 0); SCHED; LDA(At, 1, 0); STAGE_A(SA(0, 1), ac1, t + 2);
;     WAIT_L(8); BAR; WAIT_L(0); MMA(0, 0, At, B0); BAR; SCHED;
;     LDB(B1, 1, 1); STAGE_B(SB(1, 0), bb0, t + 3);
;     BAR; WAIT_L(0); MMA(0, 1, At, B1); BAR;
;     LDA(At, 1, 1); STAGE_A(SA(1, 0), ac0, t + 3);
;     BAR; WAIT_L(0); MMA(1, 0, At, B0); BAR; SCHED;
;     STAGE_B(SB(1, 1), bb1, t + 3);
;     WAIT_V(6); BAR; MMA(1, 1, At, B1); BAR;
	s_setprio 1
	v_mfma_f32_16x16x32_bf16 v[126:129], v[172:175], v[156:159], v[126:129]
	v_mfma_f32_16x16x32_bf16 v[122:125], v[172:175], v[164:167], v[122:125]
	v_mfma_f32_16x16x32_bf16 v[118:121], v[180:183], v[156:159], v[118:121]
	v_mfma_f32_16x16x32_bf16 v[114:117], v[180:183], v[164:167], v[114:117]
	v_mfma_f32_16x16x32_bf16 v[110:113], v[188:191], v[156:159], v[110:113]
	v_mfma_f32_16x16x32_bf16 v[106:109], v[188:191], v[164:167], v[106:109]
	v_mfma_f32_16x16x32_bf16 v[102:105], v[210:213], v[156:159], v[102:105]
	v_mfma_f32_16x16x32_bf16 v[98:101], v[210:213], v[164:167], v[98:101]
	v_mfma_f32_16x16x32_bf16 v[126:129], v[176:179], v[160:163], v[126:129]
	v_mfma_f32_16x16x32_bf16 v[122:125], v[176:179], v[168:171], v[122:125]
	v_mfma_f32_16x16x32_bf16 v[118:121], v[184:187], v[160:163], v[118:121]
	v_mfma_f32_16x16x32_bf16 v[114:117], v[184:187], v[168:171], v[114:117]
	v_mfma_f32_16x16x32_bf16 v[110:113], v[206:209], v[160:163], v[110:113]
	v_mfma_f32_16x16x32_bf16 v[106:109], v[206:209], v[168:171], v[106:109]
	v_mfma_f32_16x16x32_bf16 v[102:105], v[214:217], v[160:163], v[102:105]
	v_mfma_f32_16x16x32_bf16 v[98:101], v[214:217], v[168:171], v[98:101]
	v_mfma_f32_16x16x32_bf16 v[94:97], v[172:175], v[218:221], v[94:97]
	v_mfma_f32_16x16x32_bf16 v[90:93], v[172:175], v[226:229], v[90:93]
	v_mfma_f32_16x16x32_bf16 v[86:89], v[180:183], v[218:221], v[86:89]
	v_mfma_f32_16x16x32_bf16 v[82:85], v[180:183], v[226:229], v[82:85]
	v_mfma_f32_16x16x32_bf16 v[78:81], v[188:191], v[218:221], v[78:81]
	v_mfma_f32_16x16x32_bf16 v[74:77], v[188:191], v[226:229], v[74:77]
	v_mfma_f32_16x16x32_bf16 v[70:73], v[210:213], v[218:221], v[70:73]
	v_mfma_f32_16x16x32_bf16 v[66:69], v[210:213], v[226:229], v[66:69]
	v_mfma_f32_16x16x32_bf16 v[94:97], v[176:179], v[222:225], v[94:97]
	v_mfma_f32_16x16x32_bf16 v[90:93], v[176:179], v[230:233], v[90:93]
	v_mfma_f32_16x16x32_bf16 v[86:89], v[184:187], v[222:225], v[86:89]
	v_mfma_f32_16x16x32_bf16 v[82:85], v[184:187], v[230:233], v[82:85]
	v_mfma_f32_16x16x32_bf16 v[78:81], v[206:209], v[222:225], v[78:81]
	v_mfma_f32_16x16x32_bf16 v[74:77], v[206:209], v[230:233], v[74:77]
	v_mfma_f32_16x16x32_bf16 v[70:73], v[214:217], v[222:225], v[70:73]
	v_mfma_f32_16x16x32_bf16 v[66:69], v[214:217], v[230:233], v[66:69]
	s_setprio 0
	s_barrier
	ds_read_b128 v[172:175], v132 offset:49152
	ds_read_b128 v[176:179], v132 offset:50176
	ds_read_b128 v[180:183], v150 offset:49152
	ds_read_b128 v[184:187], v150 offset:50176
	ds_read_b128 v[188:191], v151 offset:49152
	ds_read_b128 v[206:209], v151 offset:50176
	ds_read_b128 v[210:213], v152 offset:49152
	ds_read_b128 v[214:217], v152 offset:50176
	v_lshl_add_u64 v[194:195], s[12:13], 0, v[0:1]
	v_lshl_add_u64 v[192:193], v[194:195], 0, s[92:93]
	v_readfirstlane_b32 s11, v141
	s_mov_b32 m0, s11
	s_nop 0
	global_load_lds_dwordx4 v[192:193], off
	v_lshl_add_u64 v[194:195], s[12:13], 0, v[0:1]
	v_lshl_add_u64 v[192:193], v[194:195], 0, s[94:95]
	v_readfirstlane_b32 s11, v142
	s_mov_b32 m0, s11
	s_nop 0
	global_load_lds_dwordx4 v[192:193], off
	v_lshl_add_u64 v[194:195], s[14:15], 0, v[0:1]
	s_mov_b64 s[16:17], 0x1d180180
	v_lshl_add_u64 v[192:193], v[194:195], 0, s[16:17]
	v_readfirstlane_b32 s11, v143
	s_mov_b32 m0, s11
	s_nop 0
	global_load_lds_dwordx4 v[192:193], off
	v_lshl_add_u64 v[194:195], s[14:15], 0, v[0:1]
	s_mov_b64 s[16:17], 0x1d1a0180
	v_lshl_add_u64 v[192:193], v[194:195], 0, s[16:17]
	v_readfirstlane_b32 s11, v144
	s_mov_b32 m0, s11
	s_nop 0
	global_load_lds_dwordx4 v[192:193], off
	v_lshl_add_u64 v[194:195], s[12:13], 0, v[0:1]
	v_lshl_add_u64 v[192:193], v[194:195], 0, s[96:97]
	v_readfirstlane_b32 s11, v145
	s_mov_b32 m0, s11
	s_nop 0
	global_load_lds_dwordx4 v[192:193], off
	v_lshl_add_u64 v[194:195], s[12:13], 0, v[0:1]
	v_lshl_add_u64 v[192:193], v[194:195], 0, s[72:73]
	v_readfirstlane_b32 s11, v146
	s_mov_b32 m0, s11
	s_nop 0
	global_load_lds_dwordx4 v[192:193], off
	s_waitcnt vmcnt(8)
	s_waitcnt lgkmcnt(0)
	s_barrier
	s_setprio 1
	v_mfma_f32_16x16x32_bf16 v[62:65], v[172:175], v[156:159], v[62:65]
	v_mfma_f32_16x16x32_bf16 v[58:61], v[172:175], v[164:167], v[58:61]
	v_mfma_f32_16x16x32_bf16 v[54:57], v[180:183], v[156:159], v[54:57]
	v_mfma_f32_16x16x32_bf16 v[50:53], v[180:183], v[164:167], v[50:53]
	v_mfma_f32_16x16x32_bf16 v[46:49], v[188:191], v[156:159], v[46:49]
	v_mfma_f32_16x16x32_bf16 v[42:45], v[188:191], v[164:167], v[42:45]
	v_mfma_f32_16x16x32_bf16 v[38:41], v[210:213], v[156:159], v[38:41]
	v_mfma_f32_16x16x32_bf16 v[34:37], v[210:213], v[164:167], v[34:37]
	v_mfma_f32_16x16x32_bf16 v[62:65], v[176:179], v[160:163], v[62:65]
	v_mfma_f32_16x16x32_bf16 v[58:61], v[176:179], v[168:171], v[58:61]
	v_mfma_f32_16x16x32_bf16 v[54:57], v[184:187], v[160:163], v[54:57]
	v_mfma_f32_16x16x32_bf16 v[50:53], v[184:187], v[168:171], v[50:53]
	v_mfma_f32_16x16x32_bf16 v[46:49], v[206:209], v[160:163], v[46:49]
	v_mfma_f32_16x16x32_bf16 v[42:45], v[206:209], v[168:171], v[42:45]
	v_mfma_f32_16x16x32_bf16 v[38:41], v[214:217], v[160:163], v[38:41]
	v_mfma_f32_16x16x32_bf16 v[34:37], v[214:217], v[168:171], v[34:37]
	v_mfma_f32_16x16x32_bf16 v[30:33], v[172:175], v[218:221], v[30:33]
	v_mfma_f32_16x16x32_bf16 v[26:29], v[172:175], v[226:229], v[26:29]
	v_mfma_f32_16x16x32_bf16 v[22:25], v[180:183], v[218:221], v[22:25]
	v_mfma_f32_16x16x32_bf16 v[18:21], v[180:183], v[226:229], v[18:21]
	v_mfma_f32_16x16x32_bf16 v[14:17], v[188:191], v[218:221], v[14:17]
	v_mfma_f32_16x16x32_bf16 v[10:13], v[188:191], v[226:229], v[10:13]
	v_mfma_f32_16x16x32_bf16 v[6:9], v[210:213], v[218:221], v[6:9]
	v_mfma_f32_16x16x32_bf16 v[2:5], v[210:213], v[226:229], v[2:5]
	v_mfma_f32_16x16x32_bf16 v[30:33], v[176:179], v[222:225], v[30:33]
	v_mfma_f32_16x16x32_bf16 v[26:29], v[176:179], v[230:233], v[26:29]
	v_mfma_f32_16x16x32_bf16 v[22:25], v[184:187], v[222:225], v[22:25]
	v_mfma_f32_16x16x32_bf16 v[18:21], v[184:187], v[230:233], v[18:21]
	v_mfma_f32_16x16x32_bf16 v[14:17], v[206:209], v[222:225], v[14:17]
	v_mfma_f32_16x16x32_bf16 v[10:13], v[206:209], v[230:233], v[10:13]
	v_mfma_f32_16x16x32_bf16 v[6:9], v[214:217], v[222:225], v[6:9]
	v_mfma_f32_16x16x32_bf16 v[2:5], v[214:217], v[230:233], v[2:5]
	s_setprio 0
	s_add_i32 s9, s9, 2
	s_add_u32 s12, s12, 0x100
	s_addc_u32 s13, s13, 0
	s_add_u32 s14, s14, 0x100
	s_addc_u32 s15, s15, 0
	s_cmp_lt_u32 s9, 12
	s_barrier
; #define STAGE_A(P, br, kt) do { const char* _g = (const char*)(A + (long)(br) * lda + (long)(kt) * BK); \
;     __builtin_amdgcn_global_load_lds((const unsigned*)(_g + (size_t)offA0), (unsigned*)((char*)(P) + sb0), 16, 0, 0); \
;     __builtin_amdgcn_global_load_lds((const unsigned*)(_g + (size_t)lda * 128 + (size_t)offA0), (unsigned*)((char*)(P) + sb1), 16, 0, 0); } while (0)
; #define LDA(dst, b, h) for (int m = 0; m < 4; ++m) for (int k = 0; k < 2; ++k) \
;     dst[m][k] = *reinterpret_cast<const bf16x8*>((char*)SA(b, h) + lds_byte(wr * 64 + m * 16 + fr, k * 32 + fq * 8))
; #define LDB(dst, b, h) for (int n = 0; n < 2; ++n) for (int k = 0; k < 2; ++k) \
;     dst[n][k] = *reinterpret_cast<const bf16x8*>((char*)SB(b, h) + lds_byte(wc * 32 + n * 16 + fr, k * 32 + fq * 8))
; #define MMA(ai, bj, At_, Bt_) do { __builtin_amdgcn_s_setprio(1); \
;     for (int m = 0; m < 4; ++m) for (int n = 0; n < 2; ++n) for (int k = 0; k < 2; ++k) \
;       acc[ai][bj][m][n] = MFMA16(At_[m][k], Bt_[n][k], acc[ai][bj][m][n]); \
;     __builtin_amdgcn_s_setprio(0); } while (0)
; #define WAIT_V(n) asm volatile("s_waitcnt vmcnt(" #n ")" ::: "memory")
; #define WAIT_L(n) asm volatile("s_waitcnt lgkmcnt(" #n ")" ::: "memory")
; #define BAR __builtin_amdgcn_s_barrier()
; DI void gemm_core(WVP char* smem, const u16* __restrict__ A, int lda, int ar0, int ar1,
;                   const u16* __restrict__ B, int ldb, int bc0, int K, AccT& acc) {
;     ...
;   { LDB(B0, 0, 0); LDA(At, 0, 0); STAGE_A(SA(1, 1), ac1, nt - 1);
;     BAR; WAIT_L(0); MMA(0, 0, At, B0); BAR;
;     LDB(B1, 0, 1); BAR; WAIT_L(0); MMA(0, 1, At, B1); BAR;
;     LDA(At, 0, 1); WAIT_V(4); BAR; WAIT_L(0); MMA(1, 0, At, B0); MMA(1, 1, At, B1); BAR; }
	s_cbranch_scc1 .LBB0_427
	s_mov_b64 s[0:1], 0x780
	v_lshl_add_u64 v[136:137], v[130:131], 0, s[0:1]
	v_readfirstlane_b32 s0, v153
	s_mov_b32 m0, s0
	s_mov_b64 s[0:1], 0x20780
	v_lshl_add_u64 v[130:131], v[130:131], 0, s[0:1]
	v_readfirstlane_b32 s0, v154
	ds_read_b128 v[140:143], v149
	ds_read_b128 v[156:159], v149 offset:1024
	ds_read_b128 v[160:163], v149 offset:2048
	ds_read_b128 v[164:167], v149 offset:3072
	ds_read_b128 v[168:171], v132
	ds_read_b128 v[172:175], v132 offset:1024
	ds_read_b128 v[176:179], v150
	ds_read_b128 v[180:183], v150 offset:1024
	ds_read_b128 v[184:187], v151
	ds_read_b128 v[188:191], v151 offset:1024
	ds_read_b128 v[206:209], v152
	ds_read_b128 v[210:213], v152 offset:1024
	global_load_lds_dwordx4 v[136:137], off
	s_mov_b32 m0, s0
	s_nop 0
	global_load_lds_dwordx4 v[130:131], off
	s_waitcnt vmcnt(8)
	s_barrier
	s_waitcnt lgkmcnt(0)
	s_setprio 1
	s_waitcnt lgkmcnt(0)
	v_mfma_f32_16x16x32_bf16 v[126:129], v[168:171], v[140:143], v[126:129]
	v_mfma_f32_16x16x32_bf16 v[122:125], v[168:171], v[160:163], v[122:125]
	v_mfma_f32_16x16x32_bf16 v[118:121], v[176:179], v[140:143], v[118:121]
	v_mfma_f32_16x16x32_bf16 v[114:117], v[176:179], v[160:163], v[114:117]
	v_mfma_f32_16x16x32_bf16 v[110:113], v[184:187], v[140:143], v[110:113]
	v_mfma_f32_16x16x32_bf16 v[106:109], v[184:187], v[160:163], v[106:109]
	v_mfma_f32_16x16x32_bf16 v[102:105], v[206:209], v[140:143], v[102:105]
	v_mfma_f32_16x16x32_bf16 v[126:129], v[172:175], v[156:159], v[126:129]
	v_mfma_f32_16x16x32_bf16 v[122:125], v[172:175], v[164:167], v[122:125]
	v_mfma_f32_16x16x32_bf16 v[118:121], v[180:183], v[156:159], v[118:121]
	v_mfma_f32_16x16x32_bf16 v[114:117], v[180:183], v[164:167], v[114:117]
	v_mfma_f32_16x16x32_bf16 v[110:113], v[188:191], v[156:159], v[110:113]
	v_mfma_f32_16x16x32_bf16 v[106:109], v[188:191], v[164:167], v[106:109]
	v_mfma_f32_16x16x32_bf16 v[102:105], v[210:213], v[156:159], v[102:105]
	v_mfma_f32_16x16x32_bf16 v[98:101], v[206:209], v[160:163], v[98:101]
	v_mfma_f32_16x16x32_bf16 v[214:217], v[210:213], v[164:167], v[98:101]
	s_setprio 0
	s_barrier
	s_nop 4
	ds_read_b128 v[98:101], v147
	ds_read_b128 v[218:221], v147 offset:1024
	ds_read_b128 v[222:225], v147 offset:2048
	ds_read_b128 v[144:147], v147 offset:3072
	s_barrier
	s_waitcnt lgkmcnt(0)
	s_setprio 1
	s_waitcnt lgkmcnt(0)
	v_mfma_f32_16x16x32_bf16 v[94:97], v[168:171], v[98:101], v[94:97]
	v_mfma_f32_16x16x32_bf16 v[86:89], v[176:179], v[98:101], v[86:89]
	v_mfma_f32_16x16x32_bf16 v[78:81], v[184:187], v[98:101], v[78:81]
	v_mfma_f32_16x16x32_bf16 v[70:73], v[206:209], v[98:101], v[70:73]
	v_mfma_f32_16x16x32_bf16 v[94:97], v[172:175], v[218:221], v[94:97]
	v_mfma_f32_16x16x32_bf16 v[90:93], v[168:171], v[222:225], v[90:93]
	v_mfma_f32_16x16x32_bf16 v[86:89], v[180:183], v[218:221], v[86:89]
	v_mfma_f32_16x16x32_bf16 v[82:85], v[176:179], v[222:225], v[82:85]
	v_mfma_f32_16x16x32_bf16 v[78:81], v[188:191], v[218:221], v[78:81]
	v_mfma_f32_16x16x32_bf16 v[74:77], v[184:187], v[222:225], v[74:77]
	v_mfma_f32_16x16x32_bf16 v[70:73], v[210:213], v[218:221], v[70:73]
	v_mfma_f32_16x16x32_bf16 v[66:69], v[206:209], v[222:225], v[66:69]
	v_mfma_f32_16x16x32_bf16 v[168:171], v[172:175], v[144:147], v[90:93]
	v_mfma_f32_16x16x32_bf16 v[172:175], v[180:183], v[144:147], v[82:85]
	v_mfma_f32_16x16x32_bf16 v[176:179], v[188:191], v[144:147], v[74:77]
	v_mfma_f32_16x16x32_bf16 v[180:183], v[210:213], v[144:147], v[66:69]
	s_setprio 0
	s_barrier
	s_nop 1
	ds_read_b128 v[66:69], v132 offset:16384
	ds_read_b128 v[74:77], v132 offset:17408
	ds_read_b128 v[82:85], v150 offset:16384
	ds_read_b128 v[90:93], v150 offset:17408
	ds_read_b128 v[184:187], v151 offset:16384
	ds_read_b128 v[188:191], v151 offset:17408
	ds_read_b128 v[206:209], v152 offset:16384
	ds_read_b128 v[210:213], v152 offset:17408
	s_waitcnt vmcnt(4)
	s_barrier
	s_waitcnt lgkmcnt(0)
	s_setprio 1
	s_waitcnt lgkmcnt(0)
	v_mfma_f32_16x16x32_bf16 v[62:65], v[66:69], v[140:143], v[62:65]
	v_mfma_f32_16x16x32_bf16 v[54:57], v[82:85], v[140:143], v[54:57]
	v_mfma_f32_16x16x32_bf16 v[42:45], v[184:187], v[160:163], v[42:45]
	v_mfma_f32_16x16x32_bf16 v[34:37], v[206:209], v[160:163], v[34:37]
	v_mfma_f32_16x16x32_bf16 v[62:65], v[74:77], v[156:159], v[62:65]
	v_mfma_f32_16x16x32_bf16 v[58:61], v[66:69], v[160:163], v[58:61]
	v_mfma_f32_16x16x32_bf16 v[54:57], v[90:93], v[156:159], v[54:57]
	v_mfma_f32_16x16x32_bf16 v[50:53], v[82:85], v[160:163], v[50:53]
	v_mfma_f32_16x16x32_bf16 v[46:49], v[184:187], v[140:143], v[46:49]
	v_mfma_f32_16x16x32_bf16 v[42:45], v[188:191], v[164:167], v[42:45]
	v_mfma_f32_16x16x32_bf16 v[38:41], v[206:209], v[140:143], v[38:41]
	v_mfma_f32_16x16x32_bf16 v[34:37], v[210:213], v[164:167], v[34:37]
	v_mfma_f32_16x16x32_bf16 v[226:229], v[74:77], v[164:167], v[58:61]
	v_mfma_f32_16x16x32_bf16 v[230:233], v[90:93], v[164:167], v[50:53]
	v_mfma_f32_16x16x32_bf16 v[234:237], v[188:191], v[156:159], v[46:49]
	v_mfma_f32_16x16x32_bf16 v[140:143], v[210:213], v[156:159], v[38:41]
	s_setprio 0
	s_setprio 1
	v_mfma_f32_16x16x32_bf16 v[26:29], v[66:69], v[222:225], v[26:29]
	v_mfma_f32_16x16x32_bf16 v[30:33], v[66:69], v[98:101], v[30:33]
	v_mfma_f32_16x16x32_bf16 v[26:29], v[74:77], v[144:147], v[26:29]
	v_mfma_f32_16x16x32_bf16 v[22:25], v[82:85], v[98:101], v[22:25]
	v_mfma_f32_16x16x32_bf16 v[18:21], v[82:85], v[222:225], v[18:21]
	v_mfma_f32_16x16x32_bf16 v[14:17], v[184:187], v[98:101], v[14:17]
	v_mfma_f32_16x16x32_bf16 v[10:13], v[184:187], v[222:225], v[10:13]
	v_mfma_f32_16x16x32_bf16 v[6:9], v[206:209], v[98:101], v[6:9]
	v_mfma_f32_16x16x32_bf16 v[2:5], v[206:209], v[222:225], v[2:5]
	v_mfma_f32_16x16x32_bf16 v[154:157], v[74:77], v[218:221], v[30:33]
	v_mfma_f32_16x16x32_bf16 v[158:161], v[90:93], v[218:221], v[22:25]
	v_mfma_f32_16x16x32_bf16 v[162:165], v[90:93], v[144:147], v[18:21]
	v_mfma_f32_16x16x32_bf16 v[238:241], v[188:191], v[218:221], v[14:17]
	v_mfma_f32_16x16x32_bf16 v[184:187], v[188:191], v[144:147], v[10:13]
	v_mfma_f32_16x16x32_bf16 v[188:191], v[210:213], v[218:221], v[6:9]
	v_mfma_f32_16x16x32_bf16 v[144:147], v[210:213], v[144:147], v[2:5]
	s_setprio 0
	s_barrier
; #define LDA(dst, b, h) for (int m = 0; m < 4; ++m) for (int k = 0; k < 2; ++k) \
;     dst[m][k] = *reinterpret_cast<const bf16x8*>((char*)SA(b, h) + lds_byte(wr * 64 + m * 16 + fr, k * 32 + fq * 8))
; #define LDB(dst, b, h) for (int n = 0; n < 2; ++n) for (int k = 0; k < 2; ++k) \
;     dst[n][k] = *reinterpret_cast<const bf16x8*>((char*)SB(b, h) + lds_byte(wc * 32 + n * 16 + fr, k * 32 + fq * 8))
; #define MMA(ai, bj, At_, Bt_) do { __builtin_amdgcn_s_setprio(1); \
;     for (int m = 0; m < 4; ++m) for (int n = 0; n < 2; ++n) for (int k = 0; k < 2; ++k) \
;       acc[ai][bj][m][n] = MFMA16(At_[m][k], Bt_[n][k], acc[ai][bj][m][n]); \
;     __builtin_amdgcn_s_setprio(0); } while (0)
; #define WAIT_V(n) asm volatile("s_waitcnt vmcnt(" #n ")" ::: "memory")
; #define WAIT_L(n) asm volatile("s_waitcnt lgkmcnt(" #n ")" ::: "memory")
; #define BAR __builtin_amdgcn_s_barrier()
; DI void gemm_core(WVP char* smem, const u16* __restrict__ A, int lda, int ar0, int ar1,
;                   const u16* __restrict__ B, int ldb, int bc0, int K, AccT& acc) {
;     ...
;   { LDB(B0, 1, 0); LDA(At, 1, 0); WAIT_V(2); BAR; WAIT_L(0); MMA(0, 0, At, B0); BAR;
;     LDB(B1, 1, 1); WAIT_V(0); BAR; WAIT_L(0); MMA(0, 1, At, B1); BAR;
;     LDA(At, 1, 1); BAR; WAIT_L(0); MMA(1, 0, At, B0); MMA(1, 1, At, B1); BAR; }
;   if (wr == 0) BAR;
	ds_read_b128 v[206:209], v138
	ds_read_b128 v[210:213], v138 offset:1024
	ds_read_b128 v[218:221], v138 offset:2048
	ds_read_b128 v[136:139], v138 offset:3072
	ds_read_b128 v[2:5], v132 offset:32768
	ds_read_b128 v[6:9], v132 offset:33792
	ds_read_b128 v[10:13], v150 offset:32768
	ds_read_b128 v[14:17], v150 offset:33792
	ds_read_b128 v[222:225], v151 offset:32768
	ds_read_b128 v[242:245], v151 offset:33792
	ds_read_b128 v[246:249], v152 offset:32768
	ds_read_b128 v[250:253], v152 offset:33792
	s_waitcnt vmcnt(2)
	s_barrier
	s_waitcnt lgkmcnt(0)
	s_setprio 1
	s_waitcnt lgkmcnt(0)
	v_mfma_f32_16x16x32_bf16 v[18:21], v[2:5], v[206:209], v[126:129]
	v_mfma_f32_16x16x32_bf16 v[98:101], v[6:9], v[210:213], v[18:21]
	v_mfma_f32_16x16x32_bf16 v[18:21], v[2:5], v[218:221], v[122:125]
	v_mfma_f32_16x16x32_bf16 v[90:93], v[6:9], v[136:139], v[18:21]
	v_mfma_f32_16x16x32_bf16 v[18:21], v[10:13], v[206:209], v[118:121]
	v_mfma_f32_16x16x32_bf16 v[82:85], v[14:17], v[210:213], v[18:21]
	v_mfma_f32_16x16x32_bf16 v[18:21], v[10:13], v[218:221], v[114:117]
	v_mfma_f32_16x16x32_bf16 v[74:77], v[14:17], v[136:139], v[18:21]
	v_mfma_f32_16x16x32_bf16 v[18:21], v[222:225], v[206:209], v[110:113]
	v_mfma_f32_16x16x32_bf16 v[66:69], v[242:245], v[210:213], v[18:21]
	v_mfma_f32_16x16x32_bf16 v[18:21], v[222:225], v[218:221], v[106:109]
	v_mfma_f32_16x16x32_bf16 v[58:61], v[242:245], v[136:139], v[18:21]
	v_mfma_f32_16x16x32_bf16 v[18:21], v[246:249], v[206:209], v[102:105]
	v_mfma_f32_16x16x32_bf16 v[50:53], v[250:253], v[210:213], v[18:21]
	v_mfma_f32_16x16x32_bf16 v[18:21], v[246:249], v[218:221], v[214:217]
	v_mfma_f32_16x16x32_bf16 v[38:41], v[250:253], v[136:139], v[18:21]
	s_setprio 0
	s_barrier
	ds_read_b128 v[214:217], v134
	ds_read_b128 v[196:199], v134 offset:1024
	ds_read_b128 v[192:195], v134 offset:2048
	ds_read_b128 v[200:203], v134 offset:3072
	s_waitcnt vmcnt(0)
	s_barrier
	s_waitcnt lgkmcnt(0)
	s_setprio 1
	s_waitcnt lgkmcnt(0)
	v_mfma_f32_16x16x32_bf16 v[18:21], v[2:5], v[214:217], v[94:97]
	v_mfma_f32_16x16x32_bf16 v[2:5], v[2:5], v[192:195], v[168:171]
	v_mfma_f32_16x16x32_bf16 v[30:33], v[6:9], v[200:203], v[2:5]
	v_mfma_f32_16x16x32_bf16 v[2:5], v[10:13], v[214:217], v[86:89]
	v_mfma_f32_16x16x32_bf16 v[22:25], v[14:17], v[196:199], v[2:5]
	v_mfma_f32_16x16x32_bf16 v[2:5], v[10:13], v[192:195], v[172:175]
	v_mfma_f32_16x16x32_bf16 v[46:49], v[6:9], v[196:199], v[18:21]
	v_mfma_f32_16x16x32_bf16 v[18:21], v[14:17], v[200:203], v[2:5]
	v_mfma_f32_16x16x32_bf16 v[2:5], v[222:225], v[214:217], v[78:81]
	v_mfma_f32_16x16x32_bf16 v[14:17], v[242:245], v[196:199], v[2:5]
	v_mfma_f32_16x16x32_bf16 v[2:5], v[222:225], v[192:195], v[176:179]
	v_mfma_f32_16x16x32_bf16 v[10:13], v[242:245], v[200:203], v[2:5]
	v_mfma_f32_16x16x32_bf16 v[2:5], v[246:249], v[214:217], v[70:73]
	v_mfma_f32_16x16x32_bf16 v[6:9], v[250:253], v[196:199], v[2:5]
	v_mfma_f32_16x16x32_bf16 v[2:5], v[246:249], v[192:195], v[180:183]
	v_mfma_f32_16x16x32_bf16 v[2:5], v[250:253], v[200:203], v[2:5]
	s_setprio 0
	s_barrier
	ds_read_b128 v[70:73], v132 offset:49152
	ds_read_b128 v[78:81], v132 offset:50176
	ds_read_b128 v[130:133], v150 offset:49152
	ds_read_b128 v[166:169], v150 offset:50176
	ds_read_b128 v[170:173], v151 offset:49152
	ds_read_b128 v[148:151], v151 offset:50176
	ds_read_b128 v[174:177], v152 offset:49152
	ds_read_b128 v[178:181], v152 offset:50176
	s_barrier
	s_waitcnt lgkmcnt(0)
	s_setprio 1
	s_waitcnt lgkmcnt(0)
	v_mfma_f32_16x16x32_bf16 v[54:57], v[130:133], v[206:209], v[54:57]
	v_mfma_f32_16x16x32_bf16 v[62:65], v[70:73], v[206:209], v[62:65]
	v_mfma_f32_16x16x32_bf16 v[118:121], v[166:169], v[210:213], v[54:57]
	v_mfma_f32_16x16x32_bf16 v[54:57], v[130:133], v[218:221], v[230:233]
	v_mfma_f32_16x16x32_bf16 v[42:45], v[170:173], v[218:221], v[42:45]
	v_mfma_f32_16x16x32_bf16 v[126:129], v[78:81], v[210:213], v[62:65]
	v_mfma_f32_16x16x32_bf16 v[62:65], v[70:73], v[218:221], v[226:229]
	v_mfma_f32_16x16x32_bf16 v[114:117], v[166:169], v[136:139], v[54:57]
	v_mfma_f32_16x16x32_bf16 v[54:57], v[170:173], v[206:209], v[234:237]
	v_mfma_f32_16x16x32_bf16 v[106:109], v[148:151], v[136:139], v[42:45]
	v_mfma_f32_16x16x32_bf16 v[42:45], v[174:177], v[206:209], v[140:143]
	v_mfma_f32_16x16x32_bf16 v[34:37], v[174:177], v[218:221], v[34:37]
	v_mfma_f32_16x16x32_bf16 v[122:125], v[78:81], v[136:139], v[62:65]
	v_mfma_f32_16x16x32_bf16 v[110:113], v[148:151], v[210:213], v[54:57]
	v_mfma_f32_16x16x32_bf16 v[102:105], v[178:181], v[210:213], v[42:45]
	v_mfma_f32_16x16x32_bf16 v[94:97], v[178:181], v[136:139], v[34:37]
	s_setprio 0
	s_setprio 1
	v_mfma_f32_16x16x32_bf16 v[34:37], v[70:73], v[214:217], v[154:157]
	v_mfma_f32_16x16x32_bf16 v[26:29], v[70:73], v[192:195], v[26:29]
	v_mfma_f32_16x16x32_bf16 v[86:89], v[78:81], v[196:199], v[34:37]
	v_mfma_f32_16x16x32_bf16 v[78:81], v[78:81], v[200:203], v[26:29]
	v_mfma_f32_16x16x32_bf16 v[26:29], v[130:133], v[214:217], v[158:161]
	v_mfma_f32_16x16x32_bf16 v[70:73], v[166:169], v[196:199], v[26:29]
	v_mfma_f32_16x16x32_bf16 v[26:29], v[130:133], v[192:195], v[162:165]
	v_mfma_f32_16x16x32_bf16 v[62:65], v[166:169], v[200:203], v[26:29]
	v_mfma_f32_16x16x32_bf16 v[26:29], v[170:173], v[214:217], v[238:241]
	v_mfma_f32_16x16x32_bf16 v[54:57], v[148:151], v[196:199], v[26:29]
	v_mfma_f32_16x16x32_bf16 v[26:29], v[170:173], v[192:195], v[184:187]
	v_mfma_f32_16x16x32_bf16 v[42:45], v[148:151], v[200:203], v[26:29]
	v_mfma_f32_16x16x32_bf16 v[26:29], v[174:177], v[214:217], v[188:191]
	v_mfma_f32_16x16x32_bf16 v[34:37], v[178:181], v[196:199], v[26:29]
	v_mfma_f32_16x16x32_bf16 v[26:29], v[174:177], v[192:195], v[144:147]
	v_mfma_f32_16x16x32_bf16 v[26:29], v[178:181], v[200:203], v[26:29]
	s_setprio 0
	s_cmp_gt_u32 s4, 3
	s_barrier
	s_cbranch_scc1 .LBB0_423
	s_barrier
	s_branch .LBB0_423
